# scan phase rewritten by hand: all 64 chunk loads issued up front, straight-line 64-step recurrences with counted vmcnt waits (on top of prep hoist)
# baseline (speedup 1.0000x reference)
; __device__ __forceinline__ int ltid() { int t = threadIdx.x; asm volatile("" : "+v"(t)); return t; }
; __device__ __forceinline__ int lbid() { int t = blockIdx.x; asm volatile("" : "+s"(t)); return t; }
; __device__ __forceinline__ bf16_t f2bf(float f) { return (bf16_t)(cvt_pk_bf16(f, 0.f) & 0xffffu); }
; __device__ __forceinline__ void scan_phase(const Bufs& B) {
;     const int gt = lbid() * 512 + ltid();
;     if (gt < 131072) {
;         const int dh = gt >> 14, idx = gt & 16383, dir = dh >> 2;
;         float cst = 0.f, nst = 0.f, m = -1e30f;
; #pragma unroll 1
;         for (int s0 = 0; s0 < 64; s0 += 16) {
;             float cl[16], ml[16], bl[16], nl[16];
; #pragma unroll
;             for (int u = 0; u < 16; ++u) { const int ch = dir ? 63 - (s0 + u) : s0 + u, it = dh * 64 + ch;
;                 cl[u] = B.CLOC[(size_t)it * 16384 + idx]; ml[u] = B.MLOC[it]; bl[u] = B.BLAST[it]; nl[u] = idx < 128 ? B.NLOC[(size_t)it * 128 + idx] : 0.f; }
; #pragma unroll
;             for (int u = 0; u < 16; ++u) { const int ch = dir ? 63 - (s0 + u) : s0 + u, it = dh * 64 + ch;
;                 B.CST[(size_t)it * 16384 + idx] = f2bf(cst);
;                 if (idx < 128) { B.NST[(size_t)it * 128 + idx] = nst; if (idx == 0) B.MST[it] = m; }
;                 const float mnew = fmaxf(bl[u] + m, ml[u]), a = __expf(bl[u] + m - mnew), g = __expf(ml[u] - mnew);
;                 cst = a * cst + g * cl[u]; nst = a * nst + g * nl[u]; m = mnew; }
;     ...
;     if (gt < 65536) {
;         const int dh = gt >> 13, idx = gt & 8191, dir = dh >> 2, h = dh & 3, hd = dir ? 3 - h : h;
;         const float cd = __expf(128.f * log1pf(-exp2f(-5.f - (float)hd)));
.LBB0_298:
	s_andn2_b64 vcc, exec, s[0:1]
	s_cbranch_vccnz .LBB0_536
	v_readlane_b32 s4, v254, 6
	v_readlane_b32 s5, v254, 7
	s_add_u32 s12, s4, 0x20c80000
	s_addc_u32 s13, s5, 0
	s_add_u32 s14, s4, 0x21480000
	s_addc_u32 s15, s5, 0
	s_add_u32 s2, s4, 0x1f200000
	s_addc_u32 s3, s5, 0
	s_add_u32 s10, s4, 0x1f300000
	s_addc_u32 s11, s5, 0
	v_readlane_b32 s0, v254, 41
	s_cmp_lt_i32 s0, 2
	s_mov_b64 s[0:1], -1
	s_cbranch_scc1 .LBB0_466
	s_add_u32 s8, s4, 0x21880000
	s_addc_u32 s9, s5, 0
	s_add_u32 s16, s4, 0x24880000
	s_addc_u32 s17, s5, 0
	s_add_u32 s18, s4, 0x24900000
	s_addc_u32 s19, s5, 0
	s_add_u32 s20, s4, 0x24900800
	s_addc_u32 s21, s5, 0
	s_add_u32 s22, s4, 0x24901800
	s_addc_u32 s23, s5, 0
	v_readlane_b32 s0, v254, 41
	s_cmp_gt_i32 s0, 2
	s_mov_b64 s[0:1], -1
	s_cbranch_scc0 .LBB0_391
	s_mov_b64 exec, -1
.Lscan_entry:
	v_readlane_b32 s0, v252, 0
	v_readlane_b32 s4, v254, 6
	v_readlane_b32 s5, v254, 7
	v_lshrrev_b32_e32 v214, 6, v192
	v_and_b32_e32 v222, 63, v192
	v_readfirstlane_b32 s3, v214
	s_lshr_b32 s1, s0, 5
	s_lshr_b32 s2, s1, 2
	s_and_b32 s33, s0, 31
	s_lshl_b32 s34, s33, 9
	v_add_u32_e32 v221, s34, v192
	v_lshlrev_b32_e32 v201, 2, v221
	v_lshlrev_b32_e32 v202, 1, v221
	v_lshlrev_b32_e32 v205, 2, v221
	s_cmp_eq_u32 s33, 0
	s_cselect_b32 s35, 1, 0
	s_cmp_lt_u32 s3, 2
	s_cselect_b32 s35, s35, 0
	s_cmp_eq_u32 s3, 0
	s_cselect_b32 s46, 1, 0
	s_mov_b32 s47, 0
	s_lshl_b32 s36, s1, 6
	s_mul_i32 s37, s2, 63
	s_add_i32 s36, s36, s37
	s_lshl_b32 s38, s2, 1
	s_sub_i32 s38, 1, s38
	v_xor_b32_e32 v222, s37, v222
	v_lshlrev_b32_e32 v222, 2, v222
	s_lshl_b32 s39, s36, 16
	s_add_u32 s6, s4, 0x21880000
	s_addc_u32 s7, s5, 0
	s_add_u32 s6, s6, s39
	s_addc_u32 s7, s7, 0
	s_lshl_b32 s10, s38, 16
	s_ashr_i32 s11, s38, 31
	s_lshl_b32 s39, s36, 15
	s_add_u32 s8, s4, 0x23880000
	s_addc_u32 s9, s5, 0
	s_add_u32 s8, s8, s39
	s_addc_u32 s9, s9, 0
	s_lshl_b32 s12, s38, 15
	s_ashr_i32 s13, s38, 31
	s_lshl_b32 s39, s36, 9
	s_add_u32 s22, s4, 0x24880000
	s_addc_u32 s23, s5, 0
	s_add_u32 s22, s22, s39
	s_addc_u32 s23, s23, 0
	s_lshl_b32 s28, s38, 9
	s_ashr_i32 s29, s38, 31
	s_add_u32 s24, s4, 0x248c0000
	s_addc_u32 s25, s5, 0
	s_add_u32 s24, s24, s39
	s_addc_u32 s25, s25, 0
	s_lshl_b32 s39, s36, 2
	s_add_u32 s26, s4, 0x24901000
	s_addc_u32 s27, s5, 0
	s_add_u32 s26, s26, s39
	s_addc_u32 s27, s27, 0
	s_lshl_b32 s30, s38, 2
	s_ashr_i32 s31, s38, 31
	s_lshl_b32 s39, s1, 8
	s_add_u32 s50, s4, 0x24900000
	s_addc_u32 s51, s5, 0
	s_add_u32 s50, s50, s39
	s_addc_u32 s51, s51, 0
	s_lshr_b32 s36, s0, 4
	s_lshr_b32 s37, s36, 2
	s_and_b32 s38, s36, 3
	s_sub_i32 s39, 3, s38
	s_cmp_eq_u32 s37, 0
	s_cselect_b32 s38, s38, s39
	s_mov_b32 s48, 0xc0bb9ca6
	s_cmp_eq_u32 s38, 1
	s_cselect_b32 s48, 0xc03a1f74, s48
	s_cmp_eq_u32 s38, 2
	s_cselect_b32 s48, 0xbfb963dd, s48
	s_cmp_eq_u32 s38, 3
	s_cselect_b32 s48, 0xbf3906ce, s48
	v_exp_f32_e32 v219, s48
	s_and_b32 s38, s0, 15
	s_lshl_b32 s38, s38, 9
	v_add_u32_e32 v214, s38, v192
	v_lshlrev_b32_e32 v203, 2, v214
	v_lshlrev_b32_e32 v204, 1, v214
	s_lshl_b32 s38, s36, 6
	s_mul_i32 s39, s37, 63
	s_add_i32 s38, s38, s39
	s_lshl_b32 s39, s37, 1
	s_sub_i32 s39, 1, s39
	s_lshl_b32 s40, s38, 15
	s_add_u32 s14, s4, 0x24901800
	s_addc_u32 s15, s5, 0
	s_add_u32 s14, s14, s40
	s_addc_u32 s15, s15, 0
	s_lshl_b32 s18, s39, 15
	s_ashr_i32 s19, s39, 31
	s_lshl_b32 s40, s38, 14
	s_add_u32 s16, s4, 0x25901800
	s_addc_u32 s17, s5, 0
	s_add_u32 s16, s16, s40
	s_addc_u32 s17, s17, 0
	s_lshl_b32 s20, s39, 14
	s_ashr_i32 s21, s39, 31
	s_cmp_lt_u32 s0, 0x80
	s_cselect_b32 s36, 1, 0
	s_cmp_eq_u32 s35, 0
	s_cbranch_scc0 .Lscan_special
	s_cmp_eq_u32 s36, 0
	s_cbranch_scc1 .Lscan_v00
	s_branch .Lscan_v01
.Lscan_special:
	s_cmp_eq_u32 s36, 0
	s_cbranch_scc1 .Lscan_v10
	s_branch .Lscan_v11
.Lscan_v01:
	global_load_dword v206, v222, s[50:51]
	global_load_dword v207, v222, s[50:51] offset:2048
	global_load_dword v0, v201, s[6:7]
	s_add_u32 s6, s6, s10
	s_addc_u32 s7, s7, s11
	global_load_dword v1, v201, s[6:7]
	s_add_u32 s6, s6, s10
	s_addc_u32 s7, s7, s11
	global_load_dword v2, v201, s[6:7]
	s_add_u32 s6, s6, s10
	s_addc_u32 s7, s7, s11
	global_load_dword v3, v201, s[6:7]
	s_add_u32 s6, s6, s10
	s_addc_u32 s7, s7, s11
	global_load_dword v4, v201, s[6:7]
	s_add_u32 s6, s6, s10
	s_addc_u32 s7, s7, s11
	global_load_dword v5, v201, s[6:7]
	s_add_u32 s6, s6, s10
	s_addc_u32 s7, s7, s11
	global_load_dword v6, v201, s[6:7]
	s_add_u32 s6, s6, s10
	s_addc_u32 s7, s7, s11
	global_load_dword v7, v201, s[6:7]
	s_add_u32 s6, s6, s10
	s_addc_u32 s7, s7, s11
	global_load_dword v8, v201, s[6:7]
	s_add_u32 s6, s6, s10
	s_addc_u32 s7, s7, s11
	global_load_dword v9, v201, s[6:7]
	s_add_u32 s6, s6, s10
	s_addc_u32 s7, s7, s11
	global_load_dword v10, v201, s[6:7]
	s_add_u32 s6, s6, s10
	s_addc_u32 s7, s7, s11
	global_load_dword v11, v201, s[6:7]
	s_add_u32 s6, s6, s10
	s_addc_u32 s7, s7, s11
	global_load_dword v12, v201, s[6:7]
	s_add_u32 s6, s6, s10
	s_addc_u32 s7, s7, s11
	global_load_dword v13, v201, s[6:7]
	s_add_u32 s6, s6, s10
	s_addc_u32 s7, s7, s11
	global_load_dword v14, v201, s[6:7]
	s_add_u32 s6, s6, s10
	s_addc_u32 s7, s7, s11
	global_load_dword v15, v201, s[6:7]
	s_add_u32 s6, s6, s10
	s_addc_u32 s7, s7, s11
	global_load_dword v16, v201, s[6:7]
	s_add_u32 s6, s6, s10
	s_addc_u32 s7, s7, s11
	global_load_dword v17, v201, s[6:7]
	s_add_u32 s6, s6, s10
	s_addc_u32 s7, s7, s11
	global_load_dword v18, v201, s[6:7]
	s_add_u32 s6, s6, s10
	s_addc_u32 s7, s7, s11
	global_load_dword v19, v201, s[6:7]
	s_add_u32 s6, s6, s10
	s_addc_u32 s7, s7, s11
	global_load_dword v20, v201, s[6:7]
	s_add_u32 s6, s6, s10
	s_addc_u32 s7, s7, s11
	global_load_dword v21, v201, s[6:7]
; __device__ __forceinline__ void scan_phase(const Bufs& B) {
;     ...
;             for (int u = 0; u < 16; ++u) { const int ch = dir ? 63 - (s0 + u) : s0 + u, it = dh * 64 + ch;
;                 cl[u] = B.CLOC[(size_t)it * 16384 + idx]; ml[u] = B.MLOC[it]; bl[u] = B.BLAST[it]; nl[u] = idx < 128 ? B.NLOC[(size_t)it * 128 + idx] : 0.f; }
;     ...
;             for (int u = 0; u < 16; ++u) { const int ch = dir ? 63 - (s0 + u) : s0 + u; rl[u] = B.RLOC[(size_t)(dh * 64 + ch) * 8192 + idx]; }
	s_add_u32 s6, s6, s10
	s_addc_u32 s7, s7, s11
	global_load_dword v22, v201, s[6:7]
	s_add_u32 s6, s6, s10
	s_addc_u32 s7, s7, s11
	global_load_dword v23, v201, s[6:7]
	s_add_u32 s6, s6, s10
	s_addc_u32 s7, s7, s11
	global_load_dword v24, v201, s[6:7]
	s_add_u32 s6, s6, s10
	s_addc_u32 s7, s7, s11
	global_load_dword v25, v201, s[6:7]
	s_add_u32 s6, s6, s10
	s_addc_u32 s7, s7, s11
	global_load_dword v26, v201, s[6:7]
	s_add_u32 s6, s6, s10
	s_addc_u32 s7, s7, s11
	global_load_dword v27, v201, s[6:7]
	s_add_u32 s6, s6, s10
	s_addc_u32 s7, s7, s11
	global_load_dword v28, v201, s[6:7]
	s_add_u32 s6, s6, s10
	s_addc_u32 s7, s7, s11
	global_load_dword v29, v201, s[6:7]
	s_add_u32 s6, s6, s10
	s_addc_u32 s7, s7, s11
	global_load_dword v30, v201, s[6:7]
	s_add_u32 s6, s6, s10
	s_addc_u32 s7, s7, s11
	global_load_dword v31, v201, s[6:7]
	s_add_u32 s6, s6, s10
	s_addc_u32 s7, s7, s11
	global_load_dword v32, v201, s[6:7]
	s_add_u32 s6, s6, s10
	s_addc_u32 s7, s7, s11
	global_load_dword v33, v201, s[6:7]
	s_add_u32 s6, s6, s10
	s_addc_u32 s7, s7, s11
	global_load_dword v34, v201, s[6:7]
	s_add_u32 s6, s6, s10
	s_addc_u32 s7, s7, s11
	global_load_dword v35, v201, s[6:7]
	s_add_u32 s6, s6, s10
	s_addc_u32 s7, s7, s11
	global_load_dword v36, v201, s[6:7]
	s_add_u32 s6, s6, s10
	s_addc_u32 s7, s7, s11
	global_load_dword v37, v201, s[6:7]
	s_add_u32 s6, s6, s10
	s_addc_u32 s7, s7, s11
	global_load_dword v38, v201, s[6:7]
	s_add_u32 s6, s6, s10
	s_addc_u32 s7, s7, s11
	global_load_dword v39, v201, s[6:7]
	s_add_u32 s6, s6, s10
	s_addc_u32 s7, s7, s11
	global_load_dword v40, v201, s[6:7]
	s_add_u32 s6, s6, s10
	s_addc_u32 s7, s7, s11
	global_load_dword v41, v201, s[6:7]
	s_add_u32 s6, s6, s10
	s_addc_u32 s7, s7, s11
	global_load_dword v42, v201, s[6:7]
	s_add_u32 s6, s6, s10
	s_addc_u32 s7, s7, s11
	global_load_dword v43, v201, s[6:7]
	s_add_u32 s6, s6, s10
	s_addc_u32 s7, s7, s11
	global_load_dword v44, v201, s[6:7]
	s_add_u32 s6, s6, s10
	s_addc_u32 s7, s7, s11
	global_load_dword v45, v201, s[6:7]
	s_add_u32 s6, s6, s10
	s_addc_u32 s7, s7, s11
	global_load_dword v46, v201, s[6:7]
	s_add_u32 s6, s6, s10
	s_addc_u32 s7, s7, s11
	global_load_dword v47, v201, s[6:7]
	s_add_u32 s6, s6, s10
	s_addc_u32 s7, s7, s11
	global_load_dword v48, v201, s[6:7]
	s_add_u32 s6, s6, s10
	s_addc_u32 s7, s7, s11
	global_load_dword v49, v201, s[6:7]
	s_add_u32 s6, s6, s10
	s_addc_u32 s7, s7, s11
	global_load_dword v50, v201, s[6:7]
	s_add_u32 s6, s6, s10
	s_addc_u32 s7, s7, s11
	global_load_dword v51, v201, s[6:7]
	s_add_u32 s6, s6, s10
	s_addc_u32 s7, s7, s11
	global_load_dword v52, v201, s[6:7]
	s_add_u32 s6, s6, s10
	s_addc_u32 s7, s7, s11
	global_load_dword v53, v201, s[6:7]
	s_add_u32 s6, s6, s10
	s_addc_u32 s7, s7, s11
	global_load_dword v54, v201, s[6:7]
	s_add_u32 s6, s6, s10
	s_addc_u32 s7, s7, s11
	global_load_dword v55, v201, s[6:7]
	s_add_u32 s6, s6, s10
	s_addc_u32 s7, s7, s11
	global_load_dword v56, v201, s[6:7]
	s_add_u32 s6, s6, s10
	s_addc_u32 s7, s7, s11
	global_load_dword v57, v201, s[6:7]
	s_add_u32 s6, s6, s10
	s_addc_u32 s7, s7, s11
	global_load_dword v58, v201, s[6:7]
	s_add_u32 s6, s6, s10
	s_addc_u32 s7, s7, s11
	global_load_dword v59, v201, s[6:7]
	s_add_u32 s6, s6, s10
	s_addc_u32 s7, s7, s11
	global_load_dword v60, v201, s[6:7]
	s_add_u32 s6, s6, s10
	s_addc_u32 s7, s7, s11
	global_load_dword v61, v201, s[6:7]
	s_add_u32 s6, s6, s10
	s_addc_u32 s7, s7, s11
	global_load_dword v62, v201, s[6:7]
	s_add_u32 s6, s6, s10
	s_addc_u32 s7, s7, s11
	global_load_dword v63, v201, s[6:7]
	s_add_u32 s6, s6, s10
	s_addc_u32 s7, s7, s11
	global_load_dword v64, v203, s[14:15]
	s_add_u32 s14, s14, s18
	s_addc_u32 s15, s15, s19
	global_load_dword v65, v203, s[14:15]
	s_add_u32 s14, s14, s18
	s_addc_u32 s15, s15, s19
	global_load_dword v66, v203, s[14:15]
	s_add_u32 s14, s14, s18
	s_addc_u32 s15, s15, s19
	global_load_dword v67, v203, s[14:15]
	s_add_u32 s14, s14, s18
	s_addc_u32 s15, s15, s19
	global_load_dword v68, v203, s[14:15]
	s_add_u32 s14, s14, s18
	s_addc_u32 s15, s15, s19
	global_load_dword v69, v203, s[14:15]
	s_add_u32 s14, s14, s18
	s_addc_u32 s15, s15, s19
	global_load_dword v70, v203, s[14:15]
	s_add_u32 s14, s14, s18
	s_addc_u32 s15, s15, s19
	global_load_dword v71, v203, s[14:15]
	s_add_u32 s14, s14, s18
	s_addc_u32 s15, s15, s19
	global_load_dword v72, v203, s[14:15]
	s_add_u32 s14, s14, s18
	s_addc_u32 s15, s15, s19
	global_load_dword v73, v203, s[14:15]
	s_add_u32 s14, s14, s18
	s_addc_u32 s15, s15, s19
	global_load_dword v74, v203, s[14:15]
	s_add_u32 s14, s14, s18
	s_addc_u32 s15, s15, s19
	global_load_dword v75, v203, s[14:15]
	s_add_u32 s14, s14, s18
	s_addc_u32 s15, s15, s19
	global_load_dword v76, v203, s[14:15]
	s_add_u32 s14, s14, s18
	s_addc_u32 s15, s15, s19
	global_load_dword v77, v203, s[14:15]
	s_add_u32 s14, s14, s18
	s_addc_u32 s15, s15, s19
	global_load_dword v78, v203, s[14:15]
	s_add_u32 s14, s14, s18
	s_addc_u32 s15, s15, s19
	global_load_dword v79, v203, s[14:15]
	s_add_u32 s14, s14, s18
	s_addc_u32 s15, s15, s19
	global_load_dword v80, v203, s[14:15]
	s_add_u32 s14, s14, s18
	s_addc_u32 s15, s15, s19
	global_load_dword v81, v203, s[14:15]
	s_add_u32 s14, s14, s18
	s_addc_u32 s15, s15, s19
	global_load_dword v82, v203, s[14:15]
	s_add_u32 s14, s14, s18
	s_addc_u32 s15, s15, s19
	global_load_dword v83, v203, s[14:15]
	s_add_u32 s14, s14, s18
	s_addc_u32 s15, s15, s19
	global_load_dword v84, v203, s[14:15]
	s_add_u32 s14, s14, s18
	s_addc_u32 s15, s15, s19
	global_load_dword v85, v203, s[14:15]
	s_add_u32 s14, s14, s18
	s_addc_u32 s15, s15, s19
	global_load_dword v86, v203, s[14:15]
	s_add_u32 s14, s14, s18
	s_addc_u32 s15, s15, s19
; __device__ __forceinline__ bf16_t f2bf(float f) { return (bf16_t)(cvt_pk_bf16(f, 0.f) & 0xffffu); }
; __device__ __forceinline__ void scan_phase(const Bufs& B) {
;     ...
;         float cst = 0.f, nst = 0.f, m = -1e30f;
;     ...
;             for (int u = 0; u < 16; ++u) { const int ch = dir ? 63 - (s0 + u) : s0 + u, it = dh * 64 + ch;
;                 B.CST[(size_t)it * 16384 + idx] = f2bf(cst);
;                 if (idx < 128) { B.NST[(size_t)it * 128 + idx] = nst; if (idx == 0) B.MST[it] = m; }
;                 const float mnew = fmaxf(bl[u] + m, ml[u]), a = __expf(bl[u] + m - mnew), g = __expf(ml[u] - mnew);
;                 cst = a * cst + g * cl[u]; nst = a * nst + g * nl[u]; m = mnew; }
;     ...
;         float r = 0.f;
	global_load_dword v87, v203, s[14:15]
	s_add_u32 s14, s14, s18
	s_addc_u32 s15, s15, s19
	global_load_dword v88, v203, s[14:15]
	s_add_u32 s14, s14, s18
	s_addc_u32 s15, s15, s19
	global_load_dword v89, v203, s[14:15]
	s_add_u32 s14, s14, s18
	s_addc_u32 s15, s15, s19
	global_load_dword v90, v203, s[14:15]
	s_add_u32 s14, s14, s18
	s_addc_u32 s15, s15, s19
	global_load_dword v91, v203, s[14:15]
	s_add_u32 s14, s14, s18
	s_addc_u32 s15, s15, s19
	global_load_dword v92, v203, s[14:15]
	s_add_u32 s14, s14, s18
	s_addc_u32 s15, s15, s19
	global_load_dword v93, v203, s[14:15]
	s_add_u32 s14, s14, s18
	s_addc_u32 s15, s15, s19
	global_load_dword v94, v203, s[14:15]
	s_add_u32 s14, s14, s18
	s_addc_u32 s15, s15, s19
	global_load_dword v95, v203, s[14:15]
	s_add_u32 s14, s14, s18
	s_addc_u32 s15, s15, s19
	global_load_dword v96, v203, s[14:15]
	s_add_u32 s14, s14, s18
	s_addc_u32 s15, s15, s19
	global_load_dword v97, v203, s[14:15]
	s_add_u32 s14, s14, s18
	s_addc_u32 s15, s15, s19
	global_load_dword v98, v203, s[14:15]
	s_add_u32 s14, s14, s18
	s_addc_u32 s15, s15, s19
	global_load_dword v99, v203, s[14:15]
	s_add_u32 s14, s14, s18
	s_addc_u32 s15, s15, s19
	global_load_dword v100, v203, s[14:15]
	s_add_u32 s14, s14, s18
	s_addc_u32 s15, s15, s19
	global_load_dword v101, v203, s[14:15]
	s_add_u32 s14, s14, s18
	s_addc_u32 s15, s15, s19
	global_load_dword v102, v203, s[14:15]
	s_add_u32 s14, s14, s18
	s_addc_u32 s15, s15, s19
	global_load_dword v103, v203, s[14:15]
	s_add_u32 s14, s14, s18
	s_addc_u32 s15, s15, s19
	global_load_dword v104, v203, s[14:15]
	s_add_u32 s14, s14, s18
	s_addc_u32 s15, s15, s19
	global_load_dword v105, v203, s[14:15]
	s_add_u32 s14, s14, s18
	s_addc_u32 s15, s15, s19
	global_load_dword v106, v203, s[14:15]
	s_add_u32 s14, s14, s18
	s_addc_u32 s15, s15, s19
	global_load_dword v107, v203, s[14:15]
	s_add_u32 s14, s14, s18
	s_addc_u32 s15, s15, s19
	global_load_dword v108, v203, s[14:15]
	s_add_u32 s14, s14, s18
	s_addc_u32 s15, s15, s19
	global_load_dword v109, v203, s[14:15]
	s_add_u32 s14, s14, s18
	s_addc_u32 s15, s15, s19
	global_load_dword v110, v203, s[14:15]
	s_add_u32 s14, s14, s18
	s_addc_u32 s15, s15, s19
	global_load_dword v111, v203, s[14:15]
	s_add_u32 s14, s14, s18
	s_addc_u32 s15, s15, s19
	global_load_dword v112, v203, s[14:15]
	s_add_u32 s14, s14, s18
	s_addc_u32 s15, s15, s19
	global_load_dword v113, v203, s[14:15]
	s_add_u32 s14, s14, s18
	s_addc_u32 s15, s15, s19
	global_load_dword v114, v203, s[14:15]
	s_add_u32 s14, s14, s18
	s_addc_u32 s15, s15, s19
	global_load_dword v115, v203, s[14:15]
	s_add_u32 s14, s14, s18
	s_addc_u32 s15, s15, s19
	global_load_dword v116, v203, s[14:15]
	s_add_u32 s14, s14, s18
	s_addc_u32 s15, s15, s19
	global_load_dword v117, v203, s[14:15]
	s_add_u32 s14, s14, s18
	s_addc_u32 s15, s15, s19
	global_load_dword v118, v203, s[14:15]
	s_add_u32 s14, s14, s18
	s_addc_u32 s15, s15, s19
	global_load_dword v119, v203, s[14:15]
	s_add_u32 s14, s14, s18
	s_addc_u32 s15, s15, s19
	global_load_dword v120, v203, s[14:15]
	s_add_u32 s14, s14, s18
	s_addc_u32 s15, s15, s19
	global_load_dword v121, v203, s[14:15]
	s_add_u32 s14, s14, s18
	s_addc_u32 s15, s15, s19
	global_load_dword v122, v203, s[14:15]
	s_add_u32 s14, s14, s18
	s_addc_u32 s15, s15, s19
	global_load_dword v123, v203, s[14:15]
	s_add_u32 s14, s14, s18
	s_addc_u32 s15, s15, s19
	global_load_dword v124, v203, s[14:15]
	s_add_u32 s14, s14, s18
	s_addc_u32 s15, s15, s19
	global_load_dword v125, v203, s[14:15]
	s_add_u32 s14, s14, s18
	s_addc_u32 s15, s15, s19
	global_load_dword v126, v203, s[14:15]
	s_add_u32 s14, s14, s18
	s_addc_u32 s15, s15, s19
	global_load_dword v127, v203, s[14:15]
	s_add_u32 s14, s14, s18
	s_addc_u32 s15, s15, s19
	v_mov_b32_e32 v208, 0xf149f2ca
	v_mov_b32_e32 v210, 0
	v_mov_b32_e32 v218, 0
	s_waitcnt vmcnt(63)
	s_nop 0
	v_readlane_b32 s41, v206, 0
	v_readlane_b32 s42, v207, 0
	s_waitcnt vmcnt(63)
	v_cvt_pk_bf16_f32 v215, v210, v195
	v_readlane_b32 s43, v206, 1
	v_readlane_b32 s44, v207, 1
	global_store_short v202, v215, s[8:9]
	s_add_u32 s8, s8, s12
	s_addc_u32 s9, s9, s13
	v_add_f32_e32 v211, s42, v208
	v_max_f32_e32 v209, s41, v211
	v_sub_f32_e32 v212, v211, v209
	v_sub_f32_e32 v213, s41, v209
	v_mul_f32_e32 v212, 0x3fb8aa3b, v212
	v_mul_f32_e32 v213, 0x3fb8aa3b, v213
	v_exp_f32_e32 v213, v213
	v_exp_f32_e32 v212, v212
	s_nop 0
	v_mul_f32_e32 v214, v213, v0
	v_fma_f32 v210, v210, v212, v214
	v_cvt_pk_bf16_f32 v215, v210, v195
	v_readlane_b32 s41, v206, 2
	v_readlane_b32 s42, v207, 2
	global_store_short v202, v215, s[8:9]
	s_add_u32 s8, s8, s12
	s_addc_u32 s9, s9, s13
	v_add_f32_e32 v211, s44, v209
	v_max_f32_e32 v208, s43, v211
	v_sub_f32_e32 v212, v211, v208
	v_sub_f32_e32 v213, s43, v208
	v_mul_f32_e32 v212, 0x3fb8aa3b, v212
	v_mul_f32_e32 v213, 0x3fb8aa3b, v213
	v_exp_f32_e32 v213, v213
	v_exp_f32_e32 v212, v212
	s_nop 0
	v_mul_f32_e32 v214, v213, v1
	v_fma_f32 v210, v210, v212, v214
	v_cvt_pk_bf16_f32 v215, v210, v195
	v_readlane_b32 s43, v206, 3
	v_readlane_b32 s44, v207, 3
	global_store_short v202, v215, s[8:9]
	s_add_u32 s8, s8, s12
	s_addc_u32 s9, s9, s13
	v_add_f32_e32 v211, s42, v208
	v_max_f32_e32 v209, s41, v211
	v_sub_f32_e32 v212, v211, v209
	v_sub_f32_e32 v213, s41, v209
	v_mul_f32_e32 v212, 0x3fb8aa3b, v212
	v_mul_f32_e32 v213, 0x3fb8aa3b, v213
	v_exp_f32_e32 v213, v213
	v_exp_f32_e32 v212, v212
	s_nop 0
	v_mul_f32_e32 v214, v213, v2
	v_fma_f32 v210, v210, v212, v214
	v_cvt_pk_bf16_f32 v215, v210, v195
	v_readlane_b32 s41, v206, 4
	v_readlane_b32 s42, v207, 4
	global_store_short v202, v215, s[8:9]
	s_add_u32 s8, s8, s12
	s_addc_u32 s9, s9, s13
	v_add_f32_e32 v211, s44, v209
; __device__ __forceinline__ bf16_t f2bf(float f) { return (bf16_t)(cvt_pk_bf16(f, 0.f) & 0xffffu); }
; __device__ __forceinline__ void scan_phase(const Bufs& B) {
;     ...
;             for (int u = 0; u < 16; ++u) { const int ch = dir ? 63 - (s0 + u) : s0 + u, it = dh * 64 + ch;
;                 B.CST[(size_t)it * 16384 + idx] = f2bf(cst);
;                 if (idx < 128) { B.NST[(size_t)it * 128 + idx] = nst; if (idx == 0) B.MST[it] = m; }
;                 const float mnew = fmaxf(bl[u] + m, ml[u]), a = __expf(bl[u] + m - mnew), g = __expf(ml[u] - mnew);
;                 cst = a * cst + g * cl[u]; nst = a * nst + g * nl[u]; m = mnew; }
	v_max_f32_e32 v208, s43, v211
	v_sub_f32_e32 v212, v211, v208
	v_sub_f32_e32 v213, s43, v208
	v_mul_f32_e32 v212, 0x3fb8aa3b, v212
	v_mul_f32_e32 v213, 0x3fb8aa3b, v213
	v_exp_f32_e32 v213, v213
	v_exp_f32_e32 v212, v212
	s_nop 0
	v_mul_f32_e32 v214, v213, v3
	v_fma_f32 v210, v210, v212, v214
	v_cvt_pk_bf16_f32 v215, v210, v195
	v_readlane_b32 s43, v206, 5
	v_readlane_b32 s44, v207, 5
	global_store_short v202, v215, s[8:9]
	s_add_u32 s8, s8, s12
	s_addc_u32 s9, s9, s13
	v_add_f32_e32 v211, s42, v208
	v_max_f32_e32 v209, s41, v211
	v_sub_f32_e32 v212, v211, v209
	v_sub_f32_e32 v213, s41, v209
	v_mul_f32_e32 v212, 0x3fb8aa3b, v212
	v_mul_f32_e32 v213, 0x3fb8aa3b, v213
	v_exp_f32_e32 v213, v213
	v_exp_f32_e32 v212, v212
	s_nop 0
	v_mul_f32_e32 v214, v213, v4
	v_fma_f32 v210, v210, v212, v214
	v_cvt_pk_bf16_f32 v215, v210, v195
	v_readlane_b32 s41, v206, 6
	v_readlane_b32 s42, v207, 6
	global_store_short v202, v215, s[8:9]
	s_add_u32 s8, s8, s12
	s_addc_u32 s9, s9, s13
	v_add_f32_e32 v211, s44, v209
	v_max_f32_e32 v208, s43, v211
	v_sub_f32_e32 v212, v211, v208
	v_sub_f32_e32 v213, s43, v208
	v_mul_f32_e32 v212, 0x3fb8aa3b, v212
	v_mul_f32_e32 v213, 0x3fb8aa3b, v213
	v_exp_f32_e32 v213, v213
	v_exp_f32_e32 v212, v212
	s_nop 0
	v_mul_f32_e32 v214, v213, v5
	v_fma_f32 v210, v210, v212, v214
	v_cvt_pk_bf16_f32 v215, v210, v195
	v_readlane_b32 s43, v206, 7
	v_readlane_b32 s44, v207, 7
	global_store_short v202, v215, s[8:9]
	s_add_u32 s8, s8, s12
	s_addc_u32 s9, s9, s13
	v_add_f32_e32 v211, s42, v208
	v_max_f32_e32 v209, s41, v211
	v_sub_f32_e32 v212, v211, v209
	v_sub_f32_e32 v213, s41, v209
	v_mul_f32_e32 v212, 0x3fb8aa3b, v212
	v_mul_f32_e32 v213, 0x3fb8aa3b, v213
	v_exp_f32_e32 v213, v213
	v_exp_f32_e32 v212, v212
	s_nop 0
	v_mul_f32_e32 v214, v213, v6
	v_fma_f32 v210, v210, v212, v214
	v_cvt_pk_bf16_f32 v215, v210, v195
	v_readlane_b32 s41, v206, 8
	v_readlane_b32 s42, v207, 8
	global_store_short v202, v215, s[8:9]
	s_add_u32 s8, s8, s12
	s_addc_u32 s9, s9, s13
	v_add_f32_e32 v211, s44, v209
	v_max_f32_e32 v208, s43, v211
	v_sub_f32_e32 v212, v211, v208
	v_sub_f32_e32 v213, s43, v208
	v_mul_f32_e32 v212, 0x3fb8aa3b, v212
	v_mul_f32_e32 v213, 0x3fb8aa3b, v213
	v_exp_f32_e32 v213, v213
	v_exp_f32_e32 v212, v212
	s_nop 0
	v_mul_f32_e32 v214, v213, v7
	v_fma_f32 v210, v210, v212, v214
	v_cvt_pk_bf16_f32 v215, v210, v195
	v_readlane_b32 s43, v206, 9
	v_readlane_b32 s44, v207, 9
	global_store_short v202, v215, s[8:9]
	s_add_u32 s8, s8, s12
	s_addc_u32 s9, s9, s13
	v_add_f32_e32 v211, s42, v208
	v_max_f32_e32 v209, s41, v211
	v_sub_f32_e32 v212, v211, v209
	v_sub_f32_e32 v213, s41, v209
	v_mul_f32_e32 v212, 0x3fb8aa3b, v212
	v_mul_f32_e32 v213, 0x3fb8aa3b, v213
	v_exp_f32_e32 v213, v213
	v_exp_f32_e32 v212, v212
	s_nop 0
	v_mul_f32_e32 v214, v213, v8
	v_fma_f32 v210, v210, v212, v214
	v_cvt_pk_bf16_f32 v215, v210, v195
	v_readlane_b32 s41, v206, 10
	v_readlane_b32 s42, v207, 10
	global_store_short v202, v215, s[8:9]
	s_add_u32 s8, s8, s12
	s_addc_u32 s9, s9, s13
	v_add_f32_e32 v211, s44, v209
	v_max_f32_e32 v208, s43, v211
	v_sub_f32_e32 v212, v211, v208
	v_sub_f32_e32 v213, s43, v208
	v_mul_f32_e32 v212, 0x3fb8aa3b, v212
	v_mul_f32_e32 v213, 0x3fb8aa3b, v213
	v_exp_f32_e32 v213, v213
	v_exp_f32_e32 v212, v212
	s_nop 0
	v_mul_f32_e32 v214, v213, v9
	v_fma_f32 v210, v210, v212, v214
	v_cvt_pk_bf16_f32 v215, v210, v195
	v_readlane_b32 s43, v206, 11
	v_readlane_b32 s44, v207, 11
	global_store_short v202, v215, s[8:9]
	s_add_u32 s8, s8, s12
	s_addc_u32 s9, s9, s13
	v_add_f32_e32 v211, s42, v208
	v_max_f32_e32 v209, s41, v211
	v_sub_f32_e32 v212, v211, v209
	v_sub_f32_e32 v213, s41, v209
	v_mul_f32_e32 v212, 0x3fb8aa3b, v212
	v_mul_f32_e32 v213, 0x3fb8aa3b, v213
	v_exp_f32_e32 v213, v213
	v_exp_f32_e32 v212, v212
	s_nop 0
	v_mul_f32_e32 v214, v213, v10
	v_fma_f32 v210, v210, v212, v214
	v_cvt_pk_bf16_f32 v215, v210, v195
	v_readlane_b32 s41, v206, 12
	v_readlane_b32 s42, v207, 12
	global_store_short v202, v215, s[8:9]
	s_add_u32 s8, s8, s12
	s_addc_u32 s9, s9, s13
	v_add_f32_e32 v211, s44, v209
	v_max_f32_e32 v208, s43, v211
	v_sub_f32_e32 v212, v211, v208
	v_sub_f32_e32 v213, s43, v208
	v_mul_f32_e32 v212, 0x3fb8aa3b, v212
	v_mul_f32_e32 v213, 0x3fb8aa3b, v213
	v_exp_f32_e32 v213, v213
	v_exp_f32_e32 v212, v212
	s_nop 0
	v_mul_f32_e32 v214, v213, v11
	v_fma_f32 v210, v210, v212, v214
	v_cvt_pk_bf16_f32 v215, v210, v195
	v_readlane_b32 s43, v206, 13
	v_readlane_b32 s44, v207, 13
	global_store_short v202, v215, s[8:9]
	s_add_u32 s8, s8, s12
	s_addc_u32 s9, s9, s13
	v_add_f32_e32 v211, s42, v208
	v_max_f32_e32 v209, s41, v211
	v_sub_f32_e32 v212, v211, v209
	v_sub_f32_e32 v213, s41, v209
	v_mul_f32_e32 v212, 0x3fb8aa3b, v212
	v_mul_f32_e32 v213, 0x3fb8aa3b, v213
	v_exp_f32_e32 v213, v213
	v_exp_f32_e32 v212, v212
	s_nop 0
	v_mul_f32_e32 v214, v213, v12
	v_fma_f32 v210, v210, v212, v214
	v_cvt_pk_bf16_f32 v215, v210, v195
	v_readlane_b32 s41, v206, 14
	v_readlane_b32 s42, v207, 14
	global_store_short v202, v215, s[8:9]
	s_add_u32 s8, s8, s12
	s_addc_u32 s9, s9, s13
	v_add_f32_e32 v211, s44, v209
	v_max_f32_e32 v208, s43, v211
	v_sub_f32_e32 v212, v211, v208
	v_sub_f32_e32 v213, s43, v208
	v_mul_f32_e32 v212, 0x3fb8aa3b, v212
	v_mul_f32_e32 v213, 0x3fb8aa3b, v213
	v_exp_f32_e32 v213, v213
	v_exp_f32_e32 v212, v212
	s_nop 0
	v_mul_f32_e32 v214, v213, v13
	v_fma_f32 v210, v210, v212, v214
	v_cvt_pk_bf16_f32 v215, v210, v195
	v_readlane_b32 s43, v206, 15
	v_readlane_b32 s44, v207, 15
	global_store_short v202, v215, s[8:9]
	s_add_u32 s8, s8, s12
	s_addc_u32 s9, s9, s13
	v_add_f32_e32 v211, s42, v208
	v_max_f32_e32 v209, s41, v211
	v_sub_f32_e32 v212, v211, v209
	v_sub_f32_e32 v213, s41, v209
	v_mul_f32_e32 v212, 0x3fb8aa3b, v212
	v_mul_f32_e32 v213, 0x3fb8aa3b, v213
	v_exp_f32_e32 v213, v213
	v_exp_f32_e32 v212, v212
	s_nop 0
	v_mul_f32_e32 v214, v213, v14
	v_fma_f32 v210, v210, v212, v214
	v_cvt_pk_bf16_f32 v215, v210, v195
	v_readlane_b32 s41, v206, 16
	v_readlane_b32 s42, v207, 16
	global_store_short v202, v215, s[8:9]
	s_add_u32 s8, s8, s12
	s_addc_u32 s9, s9, s13
	v_add_f32_e32 v211, s44, v209
	v_max_f32_e32 v208, s43, v211
	v_sub_f32_e32 v212, v211, v208
	v_sub_f32_e32 v213, s43, v208
	v_mul_f32_e32 v212, 0x3fb8aa3b, v212
	v_mul_f32_e32 v213, 0x3fb8aa3b, v213
	v_exp_f32_e32 v213, v213
	v_exp_f32_e32 v212, v212
	s_nop 0
	v_mul_f32_e32 v214, v213, v15
	v_fma_f32 v210, v210, v212, v214
	s_waitcnt vmcnt(63)
; __device__ __forceinline__ bf16_t f2bf(float f) { return (bf16_t)(cvt_pk_bf16(f, 0.f) & 0xffffu); }
; __device__ __forceinline__ void scan_phase(const Bufs& B) {
;     ...
;             for (int u = 0; u < 16; ++u) { const int ch = dir ? 63 - (s0 + u) : s0 + u, it = dh * 64 + ch;
;                 B.CST[(size_t)it * 16384 + idx] = f2bf(cst);
;                 if (idx < 128) { B.NST[(size_t)it * 128 + idx] = nst; if (idx == 0) B.MST[it] = m; }
;                 const float mnew = fmaxf(bl[u] + m, ml[u]), a = __expf(bl[u] + m - mnew), g = __expf(ml[u] - mnew);
;                 cst = a * cst + g * cl[u]; nst = a * nst + g * nl[u]; m = mnew; }
	v_cvt_pk_bf16_f32 v215, v210, v195
	v_readlane_b32 s43, v206, 17
	v_readlane_b32 s44, v207, 17
	global_store_short v202, v215, s[8:9]
	s_add_u32 s8, s8, s12
	s_addc_u32 s9, s9, s13
	v_add_f32_e32 v211, s42, v208
	v_max_f32_e32 v209, s41, v211
	v_sub_f32_e32 v212, v211, v209
	v_sub_f32_e32 v213, s41, v209
	v_mul_f32_e32 v212, 0x3fb8aa3b, v212
	v_mul_f32_e32 v213, 0x3fb8aa3b, v213
	v_exp_f32_e32 v213, v213
	v_exp_f32_e32 v212, v212
	s_nop 0
	v_mul_f32_e32 v214, v213, v16
	v_fma_f32 v210, v210, v212, v214
	v_cvt_pk_bf16_f32 v215, v210, v195
	v_readlane_b32 s41, v206, 18
	v_readlane_b32 s42, v207, 18
	global_store_short v202, v215, s[8:9]
	s_add_u32 s8, s8, s12
	s_addc_u32 s9, s9, s13
	v_add_f32_e32 v211, s44, v209
	v_max_f32_e32 v208, s43, v211
	v_sub_f32_e32 v212, v211, v208
	v_sub_f32_e32 v213, s43, v208
	v_mul_f32_e32 v212, 0x3fb8aa3b, v212
	v_mul_f32_e32 v213, 0x3fb8aa3b, v213
	v_exp_f32_e32 v213, v213
	v_exp_f32_e32 v212, v212
	s_nop 0
	v_mul_f32_e32 v214, v213, v17
	v_fma_f32 v210, v210, v212, v214
	v_cvt_pk_bf16_f32 v215, v210, v195
	v_readlane_b32 s43, v206, 19
	v_readlane_b32 s44, v207, 19
	global_store_short v202, v215, s[8:9]
	s_add_u32 s8, s8, s12
	s_addc_u32 s9, s9, s13
	v_add_f32_e32 v211, s42, v208
	v_max_f32_e32 v209, s41, v211
	v_sub_f32_e32 v212, v211, v209
	v_sub_f32_e32 v213, s41, v209
	v_mul_f32_e32 v212, 0x3fb8aa3b, v212
	v_mul_f32_e32 v213, 0x3fb8aa3b, v213
	v_exp_f32_e32 v213, v213
	v_exp_f32_e32 v212, v212
	s_nop 0
	v_mul_f32_e32 v214, v213, v18
	v_fma_f32 v210, v210, v212, v214
	v_cvt_pk_bf16_f32 v215, v210, v195
	v_readlane_b32 s41, v206, 20
	v_readlane_b32 s42, v207, 20
	global_store_short v202, v215, s[8:9]
	s_add_u32 s8, s8, s12
	s_addc_u32 s9, s9, s13
	v_add_f32_e32 v211, s44, v209
	v_max_f32_e32 v208, s43, v211
	v_sub_f32_e32 v212, v211, v208
	v_sub_f32_e32 v213, s43, v208
	v_mul_f32_e32 v212, 0x3fb8aa3b, v212
	v_mul_f32_e32 v213, 0x3fb8aa3b, v213
	v_exp_f32_e32 v213, v213
	v_exp_f32_e32 v212, v212
	s_nop 0
	v_mul_f32_e32 v214, v213, v19
	v_fma_f32 v210, v210, v212, v214
	v_cvt_pk_bf16_f32 v215, v210, v195
	v_readlane_b32 s43, v206, 21
	v_readlane_b32 s44, v207, 21
	global_store_short v202, v215, s[8:9]
	s_add_u32 s8, s8, s12
	s_addc_u32 s9, s9, s13
	v_add_f32_e32 v211, s42, v208
	v_max_f32_e32 v209, s41, v211
	v_sub_f32_e32 v212, v211, v209
	v_sub_f32_e32 v213, s41, v209
	v_mul_f32_e32 v212, 0x3fb8aa3b, v212
	v_mul_f32_e32 v213, 0x3fb8aa3b, v213
	v_exp_f32_e32 v213, v213
	v_exp_f32_e32 v212, v212
	s_nop 0
	v_mul_f32_e32 v214, v213, v20
	v_fma_f32 v210, v210, v212, v214
	v_cvt_pk_bf16_f32 v215, v210, v195
	v_readlane_b32 s41, v206, 22
	v_readlane_b32 s42, v207, 22
	global_store_short v202, v215, s[8:9]
	s_add_u32 s8, s8, s12
	s_addc_u32 s9, s9, s13
	v_add_f32_e32 v211, s44, v209
	v_max_f32_e32 v208, s43, v211
	v_sub_f32_e32 v212, v211, v208
	v_sub_f32_e32 v213, s43, v208
	v_mul_f32_e32 v212, 0x3fb8aa3b, v212
	v_mul_f32_e32 v213, 0x3fb8aa3b, v213
	v_exp_f32_e32 v213, v213
	v_exp_f32_e32 v212, v212
	s_nop 0
	v_mul_f32_e32 v214, v213, v21
	v_fma_f32 v210, v210, v212, v214
	v_cvt_pk_bf16_f32 v215, v210, v195
	v_readlane_b32 s43, v206, 23
	v_readlane_b32 s44, v207, 23
	global_store_short v202, v215, s[8:9]
	s_add_u32 s8, s8, s12
	s_addc_u32 s9, s9, s13
	v_add_f32_e32 v211, s42, v208
	v_max_f32_e32 v209, s41, v211
	v_sub_f32_e32 v212, v211, v209
	v_sub_f32_e32 v213, s41, v209
	v_mul_f32_e32 v212, 0x3fb8aa3b, v212
	v_mul_f32_e32 v213, 0x3fb8aa3b, v213
	v_exp_f32_e32 v213, v213
	v_exp_f32_e32 v212, v212
	s_nop 0
	v_mul_f32_e32 v214, v213, v22
	v_fma_f32 v210, v210, v212, v214
	v_cvt_pk_bf16_f32 v215, v210, v195
	v_readlane_b32 s41, v206, 24
	v_readlane_b32 s42, v207, 24
	global_store_short v202, v215, s[8:9]
	s_add_u32 s8, s8, s12
	s_addc_u32 s9, s9, s13
	v_add_f32_e32 v211, s44, v209
	v_max_f32_e32 v208, s43, v211
	v_sub_f32_e32 v212, v211, v208
	v_sub_f32_e32 v213, s43, v208
	v_mul_f32_e32 v212, 0x3fb8aa3b, v212
	v_mul_f32_e32 v213, 0x3fb8aa3b, v213
	v_exp_f32_e32 v213, v213
	v_exp_f32_e32 v212, v212
	s_nop 0
	v_mul_f32_e32 v214, v213, v23
	v_fma_f32 v210, v210, v212, v214
	v_cvt_pk_bf16_f32 v215, v210, v195
	v_readlane_b32 s43, v206, 25
	v_readlane_b32 s44, v207, 25
	global_store_short v202, v215, s[8:9]
	s_add_u32 s8, s8, s12
	s_addc_u32 s9, s9, s13
	v_add_f32_e32 v211, s42, v208
	v_max_f32_e32 v209, s41, v211
	v_sub_f32_e32 v212, v211, v209
	v_sub_f32_e32 v213, s41, v209
	v_mul_f32_e32 v212, 0x3fb8aa3b, v212
	v_mul_f32_e32 v213, 0x3fb8aa3b, v213
	v_exp_f32_e32 v213, v213
	v_exp_f32_e32 v212, v212
	s_nop 0
	v_mul_f32_e32 v214, v213, v24
	v_fma_f32 v210, v210, v212, v214
	v_cvt_pk_bf16_f32 v215, v210, v195
	v_readlane_b32 s41, v206, 26
	v_readlane_b32 s42, v207, 26
	global_store_short v202, v215, s[8:9]
	s_add_u32 s8, s8, s12
	s_addc_u32 s9, s9, s13
	v_add_f32_e32 v211, s44, v209
	v_max_f32_e32 v208, s43, v211
	v_sub_f32_e32 v212, v211, v208
	v_sub_f32_e32 v213, s43, v208
	v_mul_f32_e32 v212, 0x3fb8aa3b, v212
	v_mul_f32_e32 v213, 0x3fb8aa3b, v213
	v_exp_f32_e32 v213, v213
	v_exp_f32_e32 v212, v212
	s_nop 0
	v_mul_f32_e32 v214, v213, v25
	v_fma_f32 v210, v210, v212, v214
	v_cvt_pk_bf16_f32 v215, v210, v195
	v_readlane_b32 s43, v206, 27
	v_readlane_b32 s44, v207, 27
	global_store_short v202, v215, s[8:9]
	s_add_u32 s8, s8, s12
	s_addc_u32 s9, s9, s13
	v_add_f32_e32 v211, s42, v208
	v_max_f32_e32 v209, s41, v211
	v_sub_f32_e32 v212, v211, v209
	v_sub_f32_e32 v213, s41, v209
	v_mul_f32_e32 v212, 0x3fb8aa3b, v212
	v_mul_f32_e32 v213, 0x3fb8aa3b, v213
	v_exp_f32_e32 v213, v213
	v_exp_f32_e32 v212, v212
	s_nop 0
	v_mul_f32_e32 v214, v213, v26
	v_fma_f32 v210, v210, v212, v214
	v_cvt_pk_bf16_f32 v215, v210, v195
; __device__ __forceinline__ bf16_t f2bf(float f) { return (bf16_t)(cvt_pk_bf16(f, 0.f) & 0xffffu); }
; __device__ __forceinline__ void scan_phase(const Bufs& B) {
;     ...
;             for (int u = 0; u < 16; ++u) { const int ch = dir ? 63 - (s0 + u) : s0 + u, it = dh * 64 + ch;
;                 B.CST[(size_t)it * 16384 + idx] = f2bf(cst);
;                 if (idx < 128) { B.NST[(size_t)it * 128 + idx] = nst; if (idx == 0) B.MST[it] = m; }
;                 const float mnew = fmaxf(bl[u] + m, ml[u]), a = __expf(bl[u] + m - mnew), g = __expf(ml[u] - mnew);
;                 cst = a * cst + g * cl[u]; nst = a * nst + g * nl[u]; m = mnew; }
	v_readlane_b32 s41, v206, 28
	v_readlane_b32 s42, v207, 28
	global_store_short v202, v215, s[8:9]
	s_add_u32 s8, s8, s12
	s_addc_u32 s9, s9, s13
	v_add_f32_e32 v211, s44, v209
	v_max_f32_e32 v208, s43, v211
	v_sub_f32_e32 v212, v211, v208
	v_sub_f32_e32 v213, s43, v208
	v_mul_f32_e32 v212, 0x3fb8aa3b, v212
	v_mul_f32_e32 v213, 0x3fb8aa3b, v213
	v_exp_f32_e32 v213, v213
	v_exp_f32_e32 v212, v212
	s_nop 0
	v_mul_f32_e32 v214, v213, v27
	v_fma_f32 v210, v210, v212, v214
	v_cvt_pk_bf16_f32 v215, v210, v195
	v_readlane_b32 s43, v206, 29
	v_readlane_b32 s44, v207, 29
	global_store_short v202, v215, s[8:9]
	s_add_u32 s8, s8, s12
	s_addc_u32 s9, s9, s13
	v_add_f32_e32 v211, s42, v208
	v_max_f32_e32 v209, s41, v211
	v_sub_f32_e32 v212, v211, v209
	v_sub_f32_e32 v213, s41, v209
	v_mul_f32_e32 v212, 0x3fb8aa3b, v212
	v_mul_f32_e32 v213, 0x3fb8aa3b, v213
	v_exp_f32_e32 v213, v213
	v_exp_f32_e32 v212, v212
	s_nop 0
	v_mul_f32_e32 v214, v213, v28
	v_fma_f32 v210, v210, v212, v214
	v_cvt_pk_bf16_f32 v215, v210, v195
	v_readlane_b32 s41, v206, 30
	v_readlane_b32 s42, v207, 30
	global_store_short v202, v215, s[8:9]
	s_add_u32 s8, s8, s12
	s_addc_u32 s9, s9, s13
	v_add_f32_e32 v211, s44, v209
	v_max_f32_e32 v208, s43, v211
	v_sub_f32_e32 v212, v211, v208
	v_sub_f32_e32 v213, s43, v208
	v_mul_f32_e32 v212, 0x3fb8aa3b, v212
	v_mul_f32_e32 v213, 0x3fb8aa3b, v213
	v_exp_f32_e32 v213, v213
	v_exp_f32_e32 v212, v212
	s_nop 0
	v_mul_f32_e32 v214, v213, v29
	v_fma_f32 v210, v210, v212, v214
	v_cvt_pk_bf16_f32 v215, v210, v195
	v_readlane_b32 s43, v206, 31
	v_readlane_b32 s44, v207, 31
	global_store_short v202, v215, s[8:9]
	s_add_u32 s8, s8, s12
	s_addc_u32 s9, s9, s13
	v_add_f32_e32 v211, s42, v208
	v_max_f32_e32 v209, s41, v211
	v_sub_f32_e32 v212, v211, v209
	v_sub_f32_e32 v213, s41, v209
	v_mul_f32_e32 v212, 0x3fb8aa3b, v212
	v_mul_f32_e32 v213, 0x3fb8aa3b, v213
	v_exp_f32_e32 v213, v213
	v_exp_f32_e32 v212, v212
	s_nop 0
	v_mul_f32_e32 v214, v213, v30
	v_fma_f32 v210, v210, v212, v214
	v_cvt_pk_bf16_f32 v215, v210, v195
	v_readlane_b32 s41, v206, 32
	v_readlane_b32 s42, v207, 32
	global_store_short v202, v215, s[8:9]
	s_add_u32 s8, s8, s12
	s_addc_u32 s9, s9, s13
	v_add_f32_e32 v211, s44, v209
	v_max_f32_e32 v208, s43, v211
	v_sub_f32_e32 v212, v211, v208
	v_sub_f32_e32 v213, s43, v208
	v_mul_f32_e32 v212, 0x3fb8aa3b, v212
	v_mul_f32_e32 v213, 0x3fb8aa3b, v213
	v_exp_f32_e32 v213, v213
	v_exp_f32_e32 v212, v212
	s_nop 0
	v_mul_f32_e32 v214, v213, v31
	v_fma_f32 v210, v210, v212, v214
	s_waitcnt vmcnt(63)
	v_cvt_pk_bf16_f32 v215, v210, v195
	v_readlane_b32 s43, v206, 33
	v_readlane_b32 s44, v207, 33
	global_store_short v202, v215, s[8:9]
	s_add_u32 s8, s8, s12
	s_addc_u32 s9, s9, s13
	v_add_f32_e32 v211, s42, v208
	v_max_f32_e32 v209, s41, v211
	v_sub_f32_e32 v212, v211, v209
	v_sub_f32_e32 v213, s41, v209
	v_mul_f32_e32 v212, 0x3fb8aa3b, v212
	v_mul_f32_e32 v213, 0x3fb8aa3b, v213
	v_exp_f32_e32 v213, v213
	v_exp_f32_e32 v212, v212
	s_nop 0
	v_mul_f32_e32 v214, v213, v32
	v_fma_f32 v210, v210, v212, v214
	v_cvt_pk_bf16_f32 v215, v210, v195
	v_readlane_b32 s41, v206, 34
	v_readlane_b32 s42, v207, 34
	global_store_short v202, v215, s[8:9]
	s_add_u32 s8, s8, s12
	s_addc_u32 s9, s9, s13
	v_add_f32_e32 v211, s44, v209
	v_max_f32_e32 v208, s43, v211
	v_sub_f32_e32 v212, v211, v208
	v_sub_f32_e32 v213, s43, v208
	v_mul_f32_e32 v212, 0x3fb8aa3b, v212
	v_mul_f32_e32 v213, 0x3fb8aa3b, v213
	v_exp_f32_e32 v213, v213
	v_exp_f32_e32 v212, v212
	s_nop 0
	v_mul_f32_e32 v214, v213, v33
	v_fma_f32 v210, v210, v212, v214
	v_cvt_pk_bf16_f32 v215, v210, v195
	v_readlane_b32 s43, v206, 35
	v_readlane_b32 s44, v207, 35
	global_store_short v202, v215, s[8:9]
	s_add_u32 s8, s8, s12
	s_addc_u32 s9, s9, s13
	v_add_f32_e32 v211, s42, v208
	v_max_f32_e32 v209, s41, v211
	v_sub_f32_e32 v212, v211, v209
	v_sub_f32_e32 v213, s41, v209
	v_mul_f32_e32 v212, 0x3fb8aa3b, v212
	v_mul_f32_e32 v213, 0x3fb8aa3b, v213
	v_exp_f32_e32 v213, v213
	v_exp_f32_e32 v212, v212
	s_nop 0
	v_mul_f32_e32 v214, v213, v34
	v_fma_f32 v210, v210, v212, v214
	v_cvt_pk_bf16_f32 v215, v210, v195
	v_readlane_b32 s41, v206, 36
	v_readlane_b32 s42, v207, 36
	global_store_short v202, v215, s[8:9]
	s_add_u32 s8, s8, s12
	s_addc_u32 s9, s9, s13
	v_add_f32_e32 v211, s44, v209
	v_max_f32_e32 v208, s43, v211
	v_sub_f32_e32 v212, v211, v208
	v_sub_f32_e32 v213, s43, v208
	v_mul_f32_e32 v212, 0x3fb8aa3b, v212
	v_mul_f32_e32 v213, 0x3fb8aa3b, v213
	v_exp_f32_e32 v213, v213
	v_exp_f32_e32 v212, v212
	s_nop 0
	v_mul_f32_e32 v214, v213, v35
	v_fma_f32 v210, v210, v212, v214
	v_cvt_pk_bf16_f32 v215, v210, v195
	v_readlane_b32 s43, v206, 37
	v_readlane_b32 s44, v207, 37
	global_store_short v202, v215, s[8:9]
	s_add_u32 s8, s8, s12
	s_addc_u32 s9, s9, s13
	v_add_f32_e32 v211, s42, v208
	v_max_f32_e32 v209, s41, v211
	v_sub_f32_e32 v212, v211, v209
	v_sub_f32_e32 v213, s41, v209
	v_mul_f32_e32 v212, 0x3fb8aa3b, v212
	v_mul_f32_e32 v213, 0x3fb8aa3b, v213
	v_exp_f32_e32 v213, v213
	v_exp_f32_e32 v212, v212
	s_nop 0
	v_mul_f32_e32 v214, v213, v36
	v_fma_f32 v210, v210, v212, v214
	v_cvt_pk_bf16_f32 v215, v210, v195
	v_readlane_b32 s41, v206, 38
	v_readlane_b32 s42, v207, 38
	global_store_short v202, v215, s[8:9]
	s_add_u32 s8, s8, s12
	s_addc_u32 s9, s9, s13
	v_add_f32_e32 v211, s44, v209
	v_max_f32_e32 v208, s43, v211
	v_sub_f32_e32 v212, v211, v208
	v_sub_f32_e32 v213, s43, v208
	v_mul_f32_e32 v212, 0x3fb8aa3b, v212
	v_mul_f32_e32 v213, 0x3fb8aa3b, v213
	v_exp_f32_e32 v213, v213
	v_exp_f32_e32 v212, v212
	s_nop 0
	v_mul_f32_e32 v214, v213, v37
	v_fma_f32 v210, v210, v212, v214
	v_cvt_pk_bf16_f32 v215, v210, v195
	v_readlane_b32 s43, v206, 39
; __device__ __forceinline__ bf16_t f2bf(float f) { return (bf16_t)(cvt_pk_bf16(f, 0.f) & 0xffffu); }
; __device__ __forceinline__ void scan_phase(const Bufs& B) {
;     ...
;             for (int u = 0; u < 16; ++u) { const int ch = dir ? 63 - (s0 + u) : s0 + u, it = dh * 64 + ch;
;                 B.CST[(size_t)it * 16384 + idx] = f2bf(cst);
;                 if (idx < 128) { B.NST[(size_t)it * 128 + idx] = nst; if (idx == 0) B.MST[it] = m; }
;                 const float mnew = fmaxf(bl[u] + m, ml[u]), a = __expf(bl[u] + m - mnew), g = __expf(ml[u] - mnew);
;                 cst = a * cst + g * cl[u]; nst = a * nst + g * nl[u]; m = mnew; }
	v_readlane_b32 s44, v207, 39
	global_store_short v202, v215, s[8:9]
	s_add_u32 s8, s8, s12
	s_addc_u32 s9, s9, s13
	v_add_f32_e32 v211, s42, v208
	v_max_f32_e32 v209, s41, v211
	v_sub_f32_e32 v212, v211, v209
	v_sub_f32_e32 v213, s41, v209
	v_mul_f32_e32 v212, 0x3fb8aa3b, v212
	v_mul_f32_e32 v213, 0x3fb8aa3b, v213
	v_exp_f32_e32 v213, v213
	v_exp_f32_e32 v212, v212
	s_nop 0
	v_mul_f32_e32 v214, v213, v38
	v_fma_f32 v210, v210, v212, v214
	v_cvt_pk_bf16_f32 v215, v210, v195
	v_readlane_b32 s41, v206, 40
	v_readlane_b32 s42, v207, 40
	global_store_short v202, v215, s[8:9]
	s_add_u32 s8, s8, s12
	s_addc_u32 s9, s9, s13
	v_add_f32_e32 v211, s44, v209
	v_max_f32_e32 v208, s43, v211
	v_sub_f32_e32 v212, v211, v208
	v_sub_f32_e32 v213, s43, v208
	v_mul_f32_e32 v212, 0x3fb8aa3b, v212
	v_mul_f32_e32 v213, 0x3fb8aa3b, v213
	v_exp_f32_e32 v213, v213
	v_exp_f32_e32 v212, v212
	s_nop 0
	v_mul_f32_e32 v214, v213, v39
	v_fma_f32 v210, v210, v212, v214
	v_cvt_pk_bf16_f32 v215, v210, v195
	v_readlane_b32 s43, v206, 41
	v_readlane_b32 s44, v207, 41
	global_store_short v202, v215, s[8:9]
	s_add_u32 s8, s8, s12
	s_addc_u32 s9, s9, s13
	v_add_f32_e32 v211, s42, v208
	v_max_f32_e32 v209, s41, v211
	v_sub_f32_e32 v212, v211, v209
	v_sub_f32_e32 v213, s41, v209
	v_mul_f32_e32 v212, 0x3fb8aa3b, v212
	v_mul_f32_e32 v213, 0x3fb8aa3b, v213
	v_exp_f32_e32 v213, v213
	v_exp_f32_e32 v212, v212
	s_nop 0
	v_mul_f32_e32 v214, v213, v40
	v_fma_f32 v210, v210, v212, v214
	v_cvt_pk_bf16_f32 v215, v210, v195
	v_readlane_b32 s41, v206, 42
	v_readlane_b32 s42, v207, 42
	global_store_short v202, v215, s[8:9]
	s_add_u32 s8, s8, s12
	s_addc_u32 s9, s9, s13
	v_add_f32_e32 v211, s44, v209
	v_max_f32_e32 v208, s43, v211
	v_sub_f32_e32 v212, v211, v208
	v_sub_f32_e32 v213, s43, v208
	v_mul_f32_e32 v212, 0x3fb8aa3b, v212
	v_mul_f32_e32 v213, 0x3fb8aa3b, v213
	v_exp_f32_e32 v213, v213
	v_exp_f32_e32 v212, v212
	s_nop 0
	v_mul_f32_e32 v214, v213, v41
	v_fma_f32 v210, v210, v212, v214
	v_cvt_pk_bf16_f32 v215, v210, v195
	v_readlane_b32 s43, v206, 43
	v_readlane_b32 s44, v207, 43
	global_store_short v202, v215, s[8:9]
	s_add_u32 s8, s8, s12
	s_addc_u32 s9, s9, s13
	v_add_f32_e32 v211, s42, v208
	v_max_f32_e32 v209, s41, v211
	v_sub_f32_e32 v212, v211, v209
	v_sub_f32_e32 v213, s41, v209
	v_mul_f32_e32 v212, 0x3fb8aa3b, v212
	v_mul_f32_e32 v213, 0x3fb8aa3b, v213
	v_exp_f32_e32 v213, v213
	v_exp_f32_e32 v212, v212
	s_nop 0
	v_mul_f32_e32 v214, v213, v42
	v_fma_f32 v210, v210, v212, v214
	v_cvt_pk_bf16_f32 v215, v210, v195
	v_readlane_b32 s41, v206, 44
	v_readlane_b32 s42, v207, 44
	global_store_short v202, v215, s[8:9]
	s_add_u32 s8, s8, s12
	s_addc_u32 s9, s9, s13
	v_add_f32_e32 v211, s44, v209
	v_max_f32_e32 v208, s43, v211
	v_sub_f32_e32 v212, v211, v208
	v_sub_f32_e32 v213, s43, v208
	v_mul_f32_e32 v212, 0x3fb8aa3b, v212
	v_mul_f32_e32 v213, 0x3fb8aa3b, v213
	v_exp_f32_e32 v213, v213
	v_exp_f32_e32 v212, v212
	s_nop 0
	v_mul_f32_e32 v214, v213, v43
	v_fma_f32 v210, v210, v212, v214
	v_cvt_pk_bf16_f32 v215, v210, v195
	v_readlane_b32 s43, v206, 45
	v_readlane_b32 s44, v207, 45
	global_store_short v202, v215, s[8:9]
	s_add_u32 s8, s8, s12
	s_addc_u32 s9, s9, s13
	v_add_f32_e32 v211, s42, v208
	v_max_f32_e32 v209, s41, v211
	v_sub_f32_e32 v212, v211, v209
	v_sub_f32_e32 v213, s41, v209
	v_mul_f32_e32 v212, 0x3fb8aa3b, v212
	v_mul_f32_e32 v213, 0x3fb8aa3b, v213
	v_exp_f32_e32 v213, v213
	v_exp_f32_e32 v212, v212
	s_nop 0
	v_mul_f32_e32 v214, v213, v44
	v_fma_f32 v210, v210, v212, v214
	v_cvt_pk_bf16_f32 v215, v210, v195
	v_readlane_b32 s41, v206, 46
	v_readlane_b32 s42, v207, 46
	global_store_short v202, v215, s[8:9]
	s_add_u32 s8, s8, s12
	s_addc_u32 s9, s9, s13
	v_add_f32_e32 v211, s44, v209
	v_max_f32_e32 v208, s43, v211
	v_sub_f32_e32 v212, v211, v208
	v_sub_f32_e32 v213, s43, v208
	v_mul_f32_e32 v212, 0x3fb8aa3b, v212
	v_mul_f32_e32 v213, 0x3fb8aa3b, v213
	v_exp_f32_e32 v213, v213
	v_exp_f32_e32 v212, v212
	s_nop 0
	v_mul_f32_e32 v214, v213, v45
	v_fma_f32 v210, v210, v212, v214
	v_cvt_pk_bf16_f32 v215, v210, v195
	v_readlane_b32 s43, v206, 47
	v_readlane_b32 s44, v207, 47
	global_store_short v202, v215, s[8:9]
	s_add_u32 s8, s8, s12
	s_addc_u32 s9, s9, s13
	v_add_f32_e32 v211, s42, v208
	v_max_f32_e32 v209, s41, v211
	v_sub_f32_e32 v212, v211, v209
	v_sub_f32_e32 v213, s41, v209
	v_mul_f32_e32 v212, 0x3fb8aa3b, v212
	v_mul_f32_e32 v213, 0x3fb8aa3b, v213
	v_exp_f32_e32 v213, v213
	v_exp_f32_e32 v212, v212
	s_nop 0
	v_mul_f32_e32 v214, v213, v46
	v_fma_f32 v210, v210, v212, v214
	v_cvt_pk_bf16_f32 v215, v210, v195
	v_readlane_b32 s41, v206, 48
	v_readlane_b32 s42, v207, 48
	global_store_short v202, v215, s[8:9]
	s_add_u32 s8, s8, s12
	s_addc_u32 s9, s9, s13
	v_add_f32_e32 v211, s44, v209
	v_max_f32_e32 v208, s43, v211
	v_sub_f32_e32 v212, v211, v208
	v_sub_f32_e32 v213, s43, v208
	v_mul_f32_e32 v212, 0x3fb8aa3b, v212
	v_mul_f32_e32 v213, 0x3fb8aa3b, v213
	v_exp_f32_e32 v213, v213
	v_exp_f32_e32 v212, v212
	s_nop 0
	v_mul_f32_e32 v214, v213, v47
	v_fma_f32 v210, v210, v212, v214
	s_waitcnt vmcnt(63)
; __device__ __forceinline__ bf16_t f2bf(float f) { return (bf16_t)(cvt_pk_bf16(f, 0.f) & 0xffffu); }
; __device__ __forceinline__ void scan_phase(const Bufs& B) {
;     ...
;             for (int u = 0; u < 16; ++u) { const int ch = dir ? 63 - (s0 + u) : s0 + u, it = dh * 64 + ch;
;                 B.CST[(size_t)it * 16384 + idx] = f2bf(cst);
;                 if (idx < 128) { B.NST[(size_t)it * 128 + idx] = nst; if (idx == 0) B.MST[it] = m; }
;                 const float mnew = fmaxf(bl[u] + m, ml[u]), a = __expf(bl[u] + m - mnew), g = __expf(ml[u] - mnew);
;                 cst = a * cst + g * cl[u]; nst = a * nst + g * nl[u]; m = mnew; }
	v_cvt_pk_bf16_f32 v215, v210, v195
	v_readlane_b32 s43, v206, 49
	v_readlane_b32 s44, v207, 49
	global_store_short v202, v215, s[8:9]
	s_add_u32 s8, s8, s12
	s_addc_u32 s9, s9, s13
	v_add_f32_e32 v211, s42, v208
	v_max_f32_e32 v209, s41, v211
	v_sub_f32_e32 v212, v211, v209
	v_sub_f32_e32 v213, s41, v209
	v_mul_f32_e32 v212, 0x3fb8aa3b, v212
	v_mul_f32_e32 v213, 0x3fb8aa3b, v213
	v_exp_f32_e32 v213, v213
	v_exp_f32_e32 v212, v212
	s_nop 0
	v_mul_f32_e32 v214, v213, v48
	v_fma_f32 v210, v210, v212, v214
	v_cvt_pk_bf16_f32 v215, v210, v195
	v_readlane_b32 s41, v206, 50
	v_readlane_b32 s42, v207, 50
	global_store_short v202, v215, s[8:9]
	s_add_u32 s8, s8, s12
	s_addc_u32 s9, s9, s13
	v_add_f32_e32 v211, s44, v209
	v_max_f32_e32 v208, s43, v211
	v_sub_f32_e32 v212, v211, v208
	v_sub_f32_e32 v213, s43, v208
	v_mul_f32_e32 v212, 0x3fb8aa3b, v212
	v_mul_f32_e32 v213, 0x3fb8aa3b, v213
	v_exp_f32_e32 v213, v213
	v_exp_f32_e32 v212, v212
	s_nop 0
	v_mul_f32_e32 v214, v213, v49
	v_fma_f32 v210, v210, v212, v214
	v_cvt_pk_bf16_f32 v215, v210, v195
	v_readlane_b32 s43, v206, 51
	v_readlane_b32 s44, v207, 51
	global_store_short v202, v215, s[8:9]
	s_add_u32 s8, s8, s12
	s_addc_u32 s9, s9, s13
	v_add_f32_e32 v211, s42, v208
	v_max_f32_e32 v209, s41, v211
	v_sub_f32_e32 v212, v211, v209
	v_sub_f32_e32 v213, s41, v209
	v_mul_f32_e32 v212, 0x3fb8aa3b, v212
	v_mul_f32_e32 v213, 0x3fb8aa3b, v213
	v_exp_f32_e32 v213, v213
	v_exp_f32_e32 v212, v212
	s_nop 0
	v_mul_f32_e32 v214, v213, v50
	v_fma_f32 v210, v210, v212, v214
	v_cvt_pk_bf16_f32 v215, v210, v195
	v_readlane_b32 s41, v206, 52
	v_readlane_b32 s42, v207, 52
	global_store_short v202, v215, s[8:9]
	s_add_u32 s8, s8, s12
	s_addc_u32 s9, s9, s13
	v_add_f32_e32 v211, s44, v209
	v_max_f32_e32 v208, s43, v211
	v_sub_f32_e32 v212, v211, v208
	v_sub_f32_e32 v213, s43, v208
	v_mul_f32_e32 v212, 0x3fb8aa3b, v212
	v_mul_f32_e32 v213, 0x3fb8aa3b, v213
	v_exp_f32_e32 v213, v213
	v_exp_f32_e32 v212, v212
	s_nop 0
	v_mul_f32_e32 v214, v213, v51
	v_fma_f32 v210, v210, v212, v214
	v_cvt_pk_bf16_f32 v215, v210, v195
	v_readlane_b32 s43, v206, 53
	v_readlane_b32 s44, v207, 53
	global_store_short v202, v215, s[8:9]
	s_add_u32 s8, s8, s12
	s_addc_u32 s9, s9, s13
	v_add_f32_e32 v211, s42, v208
	v_max_f32_e32 v209, s41, v211
	v_sub_f32_e32 v212, v211, v209
	v_sub_f32_e32 v213, s41, v209
	v_mul_f32_e32 v212, 0x3fb8aa3b, v212
	v_mul_f32_e32 v213, 0x3fb8aa3b, v213
	v_exp_f32_e32 v213, v213
	v_exp_f32_e32 v212, v212
	s_nop 0
	v_mul_f32_e32 v214, v213, v52
	v_fma_f32 v210, v210, v212, v214
	v_cvt_pk_bf16_f32 v215, v210, v195
	v_readlane_b32 s41, v206, 54
	v_readlane_b32 s42, v207, 54
	global_store_short v202, v215, s[8:9]
	s_add_u32 s8, s8, s12
	s_addc_u32 s9, s9, s13
	v_add_f32_e32 v211, s44, v209
	v_max_f32_e32 v208, s43, v211
	v_sub_f32_e32 v212, v211, v208
	v_sub_f32_e32 v213, s43, v208
	v_mul_f32_e32 v212, 0x3fb8aa3b, v212
	v_mul_f32_e32 v213, 0x3fb8aa3b, v213
	v_exp_f32_e32 v213, v213
	v_exp_f32_e32 v212, v212
	s_nop 0
	v_mul_f32_e32 v214, v213, v53
	v_fma_f32 v210, v210, v212, v214
	v_cvt_pk_bf16_f32 v215, v210, v195
	v_readlane_b32 s43, v206, 55
	v_readlane_b32 s44, v207, 55
	global_store_short v202, v215, s[8:9]
	s_add_u32 s8, s8, s12
	s_addc_u32 s9, s9, s13
	v_add_f32_e32 v211, s42, v208
	v_max_f32_e32 v209, s41, v211
	v_sub_f32_e32 v212, v211, v209
	v_sub_f32_e32 v213, s41, v209
	v_mul_f32_e32 v212, 0x3fb8aa3b, v212
	v_mul_f32_e32 v213, 0x3fb8aa3b, v213
	v_exp_f32_e32 v213, v213
	v_exp_f32_e32 v212, v212
	s_nop 0
	v_mul_f32_e32 v214, v213, v54
	v_fma_f32 v210, v210, v212, v214
	v_cvt_pk_bf16_f32 v215, v210, v195
	v_readlane_b32 s41, v206, 56
	v_readlane_b32 s42, v207, 56
	global_store_short v202, v215, s[8:9]
	s_add_u32 s8, s8, s12
	s_addc_u32 s9, s9, s13
	v_add_f32_e32 v211, s44, v209
	v_max_f32_e32 v208, s43, v211
	v_sub_f32_e32 v212, v211, v208
	v_sub_f32_e32 v213, s43, v208
	v_mul_f32_e32 v212, 0x3fb8aa3b, v212
	v_mul_f32_e32 v213, 0x3fb8aa3b, v213
	v_exp_f32_e32 v213, v213
	v_exp_f32_e32 v212, v212
	s_nop 0
	v_mul_f32_e32 v214, v213, v55
	v_fma_f32 v210, v210, v212, v214
	v_cvt_pk_bf16_f32 v215, v210, v195
	v_readlane_b32 s43, v206, 57
	v_readlane_b32 s44, v207, 57
	global_store_short v202, v215, s[8:9]
	s_add_u32 s8, s8, s12
	s_addc_u32 s9, s9, s13
	v_add_f32_e32 v211, s42, v208
	v_max_f32_e32 v209, s41, v211
	v_sub_f32_e32 v212, v211, v209
	v_sub_f32_e32 v213, s41, v209
	v_mul_f32_e32 v212, 0x3fb8aa3b, v212
	v_mul_f32_e32 v213, 0x3fb8aa3b, v213
	v_exp_f32_e32 v213, v213
	v_exp_f32_e32 v212, v212
	s_nop 0
	v_mul_f32_e32 v214, v213, v56
	v_fma_f32 v210, v210, v212, v214
	v_cvt_pk_bf16_f32 v215, v210, v195
	v_readlane_b32 s41, v206, 58
	v_readlane_b32 s42, v207, 58
	global_store_short v202, v215, s[8:9]
	s_add_u32 s8, s8, s12
	s_addc_u32 s9, s9, s13
	v_add_f32_e32 v211, s44, v209
	v_max_f32_e32 v208, s43, v211
	v_sub_f32_e32 v212, v211, v208
	v_sub_f32_e32 v213, s43, v208
	v_mul_f32_e32 v212, 0x3fb8aa3b, v212
	v_mul_f32_e32 v213, 0x3fb8aa3b, v213
	v_exp_f32_e32 v213, v213
	v_exp_f32_e32 v212, v212
	s_nop 0
	v_mul_f32_e32 v214, v213, v57
	v_fma_f32 v210, v210, v212, v214
	v_cvt_pk_bf16_f32 v215, v210, v195
	v_readlane_b32 s43, v206, 59
	v_readlane_b32 s44, v207, 59
	global_store_short v202, v215, s[8:9]
	s_add_u32 s8, s8, s12
	s_addc_u32 s9, s9, s13
	v_add_f32_e32 v211, s42, v208
	v_max_f32_e32 v209, s41, v211
	v_sub_f32_e32 v212, v211, v209
	v_sub_f32_e32 v213, s41, v209
	v_mul_f32_e32 v212, 0x3fb8aa3b, v212
	v_mul_f32_e32 v213, 0x3fb8aa3b, v213
	v_exp_f32_e32 v213, v213
	v_exp_f32_e32 v212, v212
	s_nop 0
	v_mul_f32_e32 v214, v213, v58
	v_fma_f32 v210, v210, v212, v214
	v_cvt_pk_bf16_f32 v215, v210, v195
; __device__ __forceinline__ bf16_t f2bf(float f) { return (bf16_t)(cvt_pk_bf16(f, 0.f) & 0xffffu); }
; __device__ __forceinline__ void scan_phase(const Bufs& B) {
;     ...
;             for (int u = 0; u < 16; ++u) { const int ch = dir ? 63 - (s0 + u) : s0 + u, it = dh * 64 + ch;
;                 B.CST[(size_t)it * 16384 + idx] = f2bf(cst);
;                 if (idx < 128) { B.NST[(size_t)it * 128 + idx] = nst; if (idx == 0) B.MST[it] = m; }
;                 const float mnew = fmaxf(bl[u] + m, ml[u]), a = __expf(bl[u] + m - mnew), g = __expf(ml[u] - mnew);
;                 cst = a * cst + g * cl[u]; nst = a * nst + g * nl[u]; m = mnew; }
;     ...
;             for (int u = 0; u < 16; ++u) { const int ch = dir ? 63 - (s0 + u) : s0 + u; rl[u] = B.RLOC[(size_t)(dh * 64 + ch) * 8192 + idx]; }
; #pragma unroll
;             for (int u = 0; u < 16; ++u) { const int ch = dir ? 63 - (s0 + u) : s0 + u; B.RST[(size_t)(dh * 64 + ch) * 8192 + idx] = f2bf(r); r = cd * r + rl[u]; }
	v_readlane_b32 s41, v206, 60
	v_readlane_b32 s42, v207, 60
	global_store_short v202, v215, s[8:9]
	s_add_u32 s8, s8, s12
	s_addc_u32 s9, s9, s13
	v_add_f32_e32 v211, s44, v209
	v_max_f32_e32 v208, s43, v211
	v_sub_f32_e32 v212, v211, v208
	v_sub_f32_e32 v213, s43, v208
	v_mul_f32_e32 v212, 0x3fb8aa3b, v212
	v_mul_f32_e32 v213, 0x3fb8aa3b, v213
	v_exp_f32_e32 v213, v213
	v_exp_f32_e32 v212, v212
	s_nop 0
	v_mul_f32_e32 v214, v213, v59
	v_fma_f32 v210, v210, v212, v214
	v_cvt_pk_bf16_f32 v215, v210, v195
	v_readlane_b32 s43, v206, 61
	v_readlane_b32 s44, v207, 61
	global_store_short v202, v215, s[8:9]
	s_add_u32 s8, s8, s12
	s_addc_u32 s9, s9, s13
	v_add_f32_e32 v211, s42, v208
	v_max_f32_e32 v209, s41, v211
	v_sub_f32_e32 v212, v211, v209
	v_sub_f32_e32 v213, s41, v209
	v_mul_f32_e32 v212, 0x3fb8aa3b, v212
	v_mul_f32_e32 v213, 0x3fb8aa3b, v213
	v_exp_f32_e32 v213, v213
	v_exp_f32_e32 v212, v212
	s_nop 0
	v_mul_f32_e32 v214, v213, v60
	v_fma_f32 v210, v210, v212, v214
	v_cvt_pk_bf16_f32 v215, v210, v195
	v_readlane_b32 s41, v206, 62
	v_readlane_b32 s42, v207, 62
	global_store_short v202, v215, s[8:9]
	s_add_u32 s8, s8, s12
	s_addc_u32 s9, s9, s13
	v_add_f32_e32 v211, s44, v209
	v_max_f32_e32 v208, s43, v211
	v_sub_f32_e32 v212, v211, v208
	v_sub_f32_e32 v213, s43, v208
	v_mul_f32_e32 v212, 0x3fb8aa3b, v212
	v_mul_f32_e32 v213, 0x3fb8aa3b, v213
	v_exp_f32_e32 v213, v213
	v_exp_f32_e32 v212, v212
	s_nop 0
	v_mul_f32_e32 v214, v213, v61
	v_fma_f32 v210, v210, v212, v214
	v_cvt_pk_bf16_f32 v215, v210, v195
	v_readlane_b32 s43, v206, 63
	v_readlane_b32 s44, v207, 63
	global_store_short v202, v215, s[8:9]
	s_add_u32 s8, s8, s12
	s_addc_u32 s9, s9, s13
	v_add_f32_e32 v211, s42, v208
	v_max_f32_e32 v209, s41, v211
	v_sub_f32_e32 v212, v211, v209
	v_sub_f32_e32 v213, s41, v209
	v_mul_f32_e32 v212, 0x3fb8aa3b, v212
	v_mul_f32_e32 v213, 0x3fb8aa3b, v213
	v_exp_f32_e32 v213, v213
	v_exp_f32_e32 v212, v212
	s_nop 0
	v_mul_f32_e32 v214, v213, v62
	v_fma_f32 v210, v210, v212, v214
	v_cvt_pk_bf16_f32 v215, v210, v195
	global_store_short v202, v215, s[8:9]
	s_add_u32 s8, s8, s12
	s_addc_u32 s9, s9, s13
	v_add_f32_e32 v211, s44, v209
	v_max_f32_e32 v208, s43, v211
	v_sub_f32_e32 v212, v211, v208
	v_sub_f32_e32 v213, s43, v208
	v_mul_f32_e32 v212, 0x3fb8aa3b, v212
	v_mul_f32_e32 v213, 0x3fb8aa3b, v213
	v_exp_f32_e32 v213, v213
	v_exp_f32_e32 v212, v212
	s_nop 0
	v_mul_f32_e32 v214, v213, v63
	v_fma_f32 v210, v210, v212, v214
	s_waitcnt vmcnt(63)
	v_cvt_pk_bf16_f32 v220, v218, v195
	v_fma_f32 v218, v219, v218, v64
	global_store_short v204, v220, s[16:17]
	s_add_u32 s16, s16, s20
	s_addc_u32 s17, s17, s21
	v_cvt_pk_bf16_f32 v220, v218, v195
	v_fma_f32 v218, v219, v218, v65
	global_store_short v204, v220, s[16:17]
	s_add_u32 s16, s16, s20
	s_addc_u32 s17, s17, s21
	v_cvt_pk_bf16_f32 v220, v218, v195
	v_fma_f32 v218, v219, v218, v66
	global_store_short v204, v220, s[16:17]
	s_add_u32 s16, s16, s20
	s_addc_u32 s17, s17, s21
	v_cvt_pk_bf16_f32 v220, v218, v195
	v_fma_f32 v218, v219, v218, v67
	global_store_short v204, v220, s[16:17]
	s_add_u32 s16, s16, s20
	s_addc_u32 s17, s17, s21
	v_cvt_pk_bf16_f32 v220, v218, v195
	v_fma_f32 v218, v219, v218, v68
	global_store_short v204, v220, s[16:17]
	s_add_u32 s16, s16, s20
	s_addc_u32 s17, s17, s21
	v_cvt_pk_bf16_f32 v220, v218, v195
	v_fma_f32 v218, v219, v218, v69
	global_store_short v204, v220, s[16:17]
	s_add_u32 s16, s16, s20
	s_addc_u32 s17, s17, s21
	v_cvt_pk_bf16_f32 v220, v218, v195
	v_fma_f32 v218, v219, v218, v70
	global_store_short v204, v220, s[16:17]
	s_add_u32 s16, s16, s20
	s_addc_u32 s17, s17, s21
	v_cvt_pk_bf16_f32 v220, v218, v195
	v_fma_f32 v218, v219, v218, v71
	global_store_short v204, v220, s[16:17]
	s_add_u32 s16, s16, s20
	s_addc_u32 s17, s17, s21
	v_cvt_pk_bf16_f32 v220, v218, v195
	v_fma_f32 v218, v219, v218, v72
	global_store_short v204, v220, s[16:17]
	s_add_u32 s16, s16, s20
	s_addc_u32 s17, s17, s21
	v_cvt_pk_bf16_f32 v220, v218, v195
	v_fma_f32 v218, v219, v218, v73
	global_store_short v204, v220, s[16:17]
	s_add_u32 s16, s16, s20
	s_addc_u32 s17, s17, s21
	v_cvt_pk_bf16_f32 v220, v218, v195
	v_fma_f32 v218, v219, v218, v74
	global_store_short v204, v220, s[16:17]
	s_add_u32 s16, s16, s20
	s_addc_u32 s17, s17, s21
	v_cvt_pk_bf16_f32 v220, v218, v195
	v_fma_f32 v218, v219, v218, v75
	global_store_short v204, v220, s[16:17]
	s_add_u32 s16, s16, s20
	s_addc_u32 s17, s17, s21
	v_cvt_pk_bf16_f32 v220, v218, v195
	v_fma_f32 v218, v219, v218, v76
	global_store_short v204, v220, s[16:17]
	s_add_u32 s16, s16, s20
	s_addc_u32 s17, s17, s21
	v_cvt_pk_bf16_f32 v220, v218, v195
	v_fma_f32 v218, v219, v218, v77
	global_store_short v204, v220, s[16:17]
	s_add_u32 s16, s16, s20
	s_addc_u32 s17, s17, s21
	v_cvt_pk_bf16_f32 v220, v218, v195
	v_fma_f32 v218, v219, v218, v78
	global_store_short v204, v220, s[16:17]
	s_add_u32 s16, s16, s20
	s_addc_u32 s17, s17, s21
	v_cvt_pk_bf16_f32 v220, v218, v195
	v_fma_f32 v218, v219, v218, v79
	global_store_short v204, v220, s[16:17]
	s_add_u32 s16, s16, s20
	s_addc_u32 s17, s17, s21
	s_waitcnt vmcnt(63)
; __device__ __forceinline__ bf16_t f2bf(float f) { return (bf16_t)(cvt_pk_bf16(f, 0.f) & 0xffffu); }
; __device__ __forceinline__ void scan_phase(const Bufs& B) {
;     ...
;             for (int u = 0; u < 16; ++u) { const int ch = dir ? 63 - (s0 + u) : s0 + u; rl[u] = B.RLOC[(size_t)(dh * 64 + ch) * 8192 + idx]; }
; #pragma unroll
;             for (int u = 0; u < 16; ++u) { const int ch = dir ? 63 - (s0 + u) : s0 + u; B.RST[(size_t)(dh * 64 + ch) * 8192 + idx] = f2bf(r); r = cd * r + rl[u]; }
	v_cvt_pk_bf16_f32 v220, v218, v195
	v_fma_f32 v218, v219, v218, v80
	global_store_short v204, v220, s[16:17]
	s_add_u32 s16, s16, s20
	s_addc_u32 s17, s17, s21
	v_cvt_pk_bf16_f32 v220, v218, v195
	v_fma_f32 v218, v219, v218, v81
	global_store_short v204, v220, s[16:17]
	s_add_u32 s16, s16, s20
	s_addc_u32 s17, s17, s21
	v_cvt_pk_bf16_f32 v220, v218, v195
	v_fma_f32 v218, v219, v218, v82
	global_store_short v204, v220, s[16:17]
	s_add_u32 s16, s16, s20
	s_addc_u32 s17, s17, s21
	v_cvt_pk_bf16_f32 v220, v218, v195
	v_fma_f32 v218, v219, v218, v83
	global_store_short v204, v220, s[16:17]
	s_add_u32 s16, s16, s20
	s_addc_u32 s17, s17, s21
	v_cvt_pk_bf16_f32 v220, v218, v195
	v_fma_f32 v218, v219, v218, v84
	global_store_short v204, v220, s[16:17]
	s_add_u32 s16, s16, s20
	s_addc_u32 s17, s17, s21
	v_cvt_pk_bf16_f32 v220, v218, v195
	v_fma_f32 v218, v219, v218, v85
	global_store_short v204, v220, s[16:17]
	s_add_u32 s16, s16, s20
	s_addc_u32 s17, s17, s21
	v_cvt_pk_bf16_f32 v220, v218, v195
	v_fma_f32 v218, v219, v218, v86
	global_store_short v204, v220, s[16:17]
	s_add_u32 s16, s16, s20
	s_addc_u32 s17, s17, s21
	v_cvt_pk_bf16_f32 v220, v218, v195
	v_fma_f32 v218, v219, v218, v87
	global_store_short v204, v220, s[16:17]
	s_add_u32 s16, s16, s20
	s_addc_u32 s17, s17, s21
	v_cvt_pk_bf16_f32 v220, v218, v195
	v_fma_f32 v218, v219, v218, v88
	global_store_short v204, v220, s[16:17]
	s_add_u32 s16, s16, s20
	s_addc_u32 s17, s17, s21
	v_cvt_pk_bf16_f32 v220, v218, v195
	v_fma_f32 v218, v219, v218, v89
	global_store_short v204, v220, s[16:17]
	s_add_u32 s16, s16, s20
	s_addc_u32 s17, s17, s21
	v_cvt_pk_bf16_f32 v220, v218, v195
	v_fma_f32 v218, v219, v218, v90
	global_store_short v204, v220, s[16:17]
	s_add_u32 s16, s16, s20
	s_addc_u32 s17, s17, s21
	v_cvt_pk_bf16_f32 v220, v218, v195
	v_fma_f32 v218, v219, v218, v91
	global_store_short v204, v220, s[16:17]
	s_add_u32 s16, s16, s20
	s_addc_u32 s17, s17, s21
	v_cvt_pk_bf16_f32 v220, v218, v195
	v_fma_f32 v218, v219, v218, v92
	global_store_short v204, v220, s[16:17]
	s_add_u32 s16, s16, s20
	s_addc_u32 s17, s17, s21
	v_cvt_pk_bf16_f32 v220, v218, v195
	v_fma_f32 v218, v219, v218, v93
	global_store_short v204, v220, s[16:17]
	s_add_u32 s16, s16, s20
	s_addc_u32 s17, s17, s21
	v_cvt_pk_bf16_f32 v220, v218, v195
	v_fma_f32 v218, v219, v218, v94
	global_store_short v204, v220, s[16:17]
	s_add_u32 s16, s16, s20
	s_addc_u32 s17, s17, s21
	v_cvt_pk_bf16_f32 v220, v218, v195
	v_fma_f32 v218, v219, v218, v95
	global_store_short v204, v220, s[16:17]
	s_add_u32 s16, s16, s20
	s_addc_u32 s17, s17, s21
	s_waitcnt vmcnt(63)
	v_cvt_pk_bf16_f32 v220, v218, v195
	v_fma_f32 v218, v219, v218, v96
	global_store_short v204, v220, s[16:17]
	s_add_u32 s16, s16, s20
	s_addc_u32 s17, s17, s21
	v_cvt_pk_bf16_f32 v220, v218, v195
	v_fma_f32 v218, v219, v218, v97
	global_store_short v204, v220, s[16:17]
	s_add_u32 s16, s16, s20
	s_addc_u32 s17, s17, s21
	v_cvt_pk_bf16_f32 v220, v218, v195
	v_fma_f32 v218, v219, v218, v98
	global_store_short v204, v220, s[16:17]
	s_add_u32 s16, s16, s20
	s_addc_u32 s17, s17, s21
	v_cvt_pk_bf16_f32 v220, v218, v195
	v_fma_f32 v218, v219, v218, v99
	global_store_short v204, v220, s[16:17]
	s_add_u32 s16, s16, s20
	s_addc_u32 s17, s17, s21
	v_cvt_pk_bf16_f32 v220, v218, v195
	v_fma_f32 v218, v219, v218, v100
	global_store_short v204, v220, s[16:17]
	s_add_u32 s16, s16, s20
	s_addc_u32 s17, s17, s21
	v_cvt_pk_bf16_f32 v220, v218, v195
	v_fma_f32 v218, v219, v218, v101
	global_store_short v204, v220, s[16:17]
	s_add_u32 s16, s16, s20
	s_addc_u32 s17, s17, s21
	v_cvt_pk_bf16_f32 v220, v218, v195
	v_fma_f32 v218, v219, v218, v102
	global_store_short v204, v220, s[16:17]
	s_add_u32 s16, s16, s20
	s_addc_u32 s17, s17, s21
	v_cvt_pk_bf16_f32 v220, v218, v195
	v_fma_f32 v218, v219, v218, v103
	global_store_short v204, v220, s[16:17]
	s_add_u32 s16, s16, s20
	s_addc_u32 s17, s17, s21
	v_cvt_pk_bf16_f32 v220, v218, v195
	v_fma_f32 v218, v219, v218, v104
	global_store_short v204, v220, s[16:17]
	s_add_u32 s16, s16, s20
	s_addc_u32 s17, s17, s21
	v_cvt_pk_bf16_f32 v220, v218, v195
	v_fma_f32 v218, v219, v218, v105
	global_store_short v204, v220, s[16:17]
	s_add_u32 s16, s16, s20
	s_addc_u32 s17, s17, s21
	v_cvt_pk_bf16_f32 v220, v218, v195
	v_fma_f32 v218, v219, v218, v106
	global_store_short v204, v220, s[16:17]
	s_add_u32 s16, s16, s20
	s_addc_u32 s17, s17, s21
	v_cvt_pk_bf16_f32 v220, v218, v195
	v_fma_f32 v218, v219, v218, v107
	global_store_short v204, v220, s[16:17]
	s_add_u32 s16, s16, s20
	s_addc_u32 s17, s17, s21
	v_cvt_pk_bf16_f32 v220, v218, v195
	v_fma_f32 v218, v219, v218, v108
	global_store_short v204, v220, s[16:17]
	s_add_u32 s16, s16, s20
	s_addc_u32 s17, s17, s21
	v_cvt_pk_bf16_f32 v220, v218, v195
	v_fma_f32 v218, v219, v218, v109
	global_store_short v204, v220, s[16:17]
	s_add_u32 s16, s16, s20
	s_addc_u32 s17, s17, s21
	v_cvt_pk_bf16_f32 v220, v218, v195
	v_fma_f32 v218, v219, v218, v110
	global_store_short v204, v220, s[16:17]
	s_add_u32 s16, s16, s20
	s_addc_u32 s17, s17, s21
	v_cvt_pk_bf16_f32 v220, v218, v195
	v_fma_f32 v218, v219, v218, v111
	global_store_short v204, v220, s[16:17]
	s_add_u32 s16, s16, s20
	s_addc_u32 s17, s17, s21
	s_waitcnt vmcnt(63)
; __device__ __forceinline__ bf16_t f2bf(float f) { return (bf16_t)(cvt_pk_bf16(f, 0.f) & 0xffffu); }
; __device__ __forceinline__ void scan_phase(const Bufs& B) {
;     ...
;             for (int u = 0; u < 16; ++u) { const int ch = dir ? 63 - (s0 + u) : s0 + u, it = dh * 64 + ch;
;                 cl[u] = B.CLOC[(size_t)it * 16384 + idx]; ml[u] = B.MLOC[it]; bl[u] = B.BLAST[it]; nl[u] = idx < 128 ? B.NLOC[(size_t)it * 128 + idx] : 0.f; }
;     ...
;             for (int u = 0; u < 16; ++u) { const int ch = dir ? 63 - (s0 + u) : s0 + u; rl[u] = B.RLOC[(size_t)(dh * 64 + ch) * 8192 + idx]; }
; #pragma unroll
;             for (int u = 0; u < 16; ++u) { const int ch = dir ? 63 - (s0 + u) : s0 + u; B.RST[(size_t)(dh * 64 + ch) * 8192 + idx] = f2bf(r); r = cd * r + rl[u]; }
	v_cvt_pk_bf16_f32 v220, v218, v195
	v_fma_f32 v218, v219, v218, v112
	global_store_short v204, v220, s[16:17]
	s_add_u32 s16, s16, s20
	s_addc_u32 s17, s17, s21
	v_cvt_pk_bf16_f32 v220, v218, v195
	v_fma_f32 v218, v219, v218, v113
	global_store_short v204, v220, s[16:17]
	s_add_u32 s16, s16, s20
	s_addc_u32 s17, s17, s21
	v_cvt_pk_bf16_f32 v220, v218, v195
	v_fma_f32 v218, v219, v218, v114
	global_store_short v204, v220, s[16:17]
	s_add_u32 s16, s16, s20
	s_addc_u32 s17, s17, s21
	v_cvt_pk_bf16_f32 v220, v218, v195
	v_fma_f32 v218, v219, v218, v115
	global_store_short v204, v220, s[16:17]
	s_add_u32 s16, s16, s20
	s_addc_u32 s17, s17, s21
	v_cvt_pk_bf16_f32 v220, v218, v195
	v_fma_f32 v218, v219, v218, v116
	global_store_short v204, v220, s[16:17]
	s_add_u32 s16, s16, s20
	s_addc_u32 s17, s17, s21
	v_cvt_pk_bf16_f32 v220, v218, v195
	v_fma_f32 v218, v219, v218, v117
	global_store_short v204, v220, s[16:17]
	s_add_u32 s16, s16, s20
	s_addc_u32 s17, s17, s21
	v_cvt_pk_bf16_f32 v220, v218, v195
	v_fma_f32 v218, v219, v218, v118
	global_store_short v204, v220, s[16:17]
	s_add_u32 s16, s16, s20
	s_addc_u32 s17, s17, s21
	v_cvt_pk_bf16_f32 v220, v218, v195
	v_fma_f32 v218, v219, v218, v119
	global_store_short v204, v220, s[16:17]
	s_add_u32 s16, s16, s20
	s_addc_u32 s17, s17, s21
	v_cvt_pk_bf16_f32 v220, v218, v195
	v_fma_f32 v218, v219, v218, v120
	global_store_short v204, v220, s[16:17]
	s_add_u32 s16, s16, s20
	s_addc_u32 s17, s17, s21
	v_cvt_pk_bf16_f32 v220, v218, v195
	v_fma_f32 v218, v219, v218, v121
	global_store_short v204, v220, s[16:17]
	s_add_u32 s16, s16, s20
	s_addc_u32 s17, s17, s21
	v_cvt_pk_bf16_f32 v220, v218, v195
	v_fma_f32 v218, v219, v218, v122
	global_store_short v204, v220, s[16:17]
	s_add_u32 s16, s16, s20
	s_addc_u32 s17, s17, s21
	v_cvt_pk_bf16_f32 v220, v218, v195
	v_fma_f32 v218, v219, v218, v123
	global_store_short v204, v220, s[16:17]
	s_add_u32 s16, s16, s20
	s_addc_u32 s17, s17, s21
	v_cvt_pk_bf16_f32 v220, v218, v195
	v_fma_f32 v218, v219, v218, v124
	global_store_short v204, v220, s[16:17]
	s_add_u32 s16, s16, s20
	s_addc_u32 s17, s17, s21
	v_cvt_pk_bf16_f32 v220, v218, v195
	v_fma_f32 v218, v219, v218, v125
	global_store_short v204, v220, s[16:17]
	s_add_u32 s16, s16, s20
	s_addc_u32 s17, s17, s21
	v_cvt_pk_bf16_f32 v220, v218, v195
	v_fma_f32 v218, v219, v218, v126
	global_store_short v204, v220, s[16:17]
	s_add_u32 s16, s16, s20
	s_addc_u32 s17, s17, s21
	v_cvt_pk_bf16_f32 v220, v218, v195
	v_fma_f32 v218, v219, v218, v127
	global_store_short v204, v220, s[16:17]
	s_add_u32 s16, s16, s20
	s_addc_u32 s17, s17, s21
	s_branch .Lscan_done
.Lscan_tramp13:
	s_branch .LBB0_13
.Lscan_tramp12:
	s_branch .LBB0_12
.Lscan_tramp537:
	s_branch .LBB0_537
.Lscan_v00:
	global_load_dword v206, v222, s[50:51]
	global_load_dword v207, v222, s[50:51] offset:2048
	global_load_dword v0, v201, s[6:7]
	s_add_u32 s6, s6, s10
	s_addc_u32 s7, s7, s11
	global_load_dword v1, v201, s[6:7]
	s_add_u32 s6, s6, s10
	s_addc_u32 s7, s7, s11
	global_load_dword v2, v201, s[6:7]
	s_add_u32 s6, s6, s10
	s_addc_u32 s7, s7, s11
	global_load_dword v3, v201, s[6:7]
	s_add_u32 s6, s6, s10
	s_addc_u32 s7, s7, s11
	global_load_dword v4, v201, s[6:7]
	s_add_u32 s6, s6, s10
	s_addc_u32 s7, s7, s11
	global_load_dword v5, v201, s[6:7]
	s_add_u32 s6, s6, s10
	s_addc_u32 s7, s7, s11
	global_load_dword v6, v201, s[6:7]
	s_add_u32 s6, s6, s10
	s_addc_u32 s7, s7, s11
	global_load_dword v7, v201, s[6:7]
	s_add_u32 s6, s6, s10
	s_addc_u32 s7, s7, s11
	global_load_dword v8, v201, s[6:7]
	s_add_u32 s6, s6, s10
	s_addc_u32 s7, s7, s11
	global_load_dword v9, v201, s[6:7]
	s_add_u32 s6, s6, s10
	s_addc_u32 s7, s7, s11
	global_load_dword v10, v201, s[6:7]
	s_add_u32 s6, s6, s10
	s_addc_u32 s7, s7, s11
	global_load_dword v11, v201, s[6:7]
	s_add_u32 s6, s6, s10
	s_addc_u32 s7, s7, s11
	global_load_dword v12, v201, s[6:7]
	s_add_u32 s6, s6, s10
	s_addc_u32 s7, s7, s11
	global_load_dword v13, v201, s[6:7]
	s_add_u32 s6, s6, s10
	s_addc_u32 s7, s7, s11
	global_load_dword v14, v201, s[6:7]
	s_add_u32 s6, s6, s10
	s_addc_u32 s7, s7, s11
	global_load_dword v15, v201, s[6:7]
	s_add_u32 s6, s6, s10
	s_addc_u32 s7, s7, s11
	global_load_dword v16, v201, s[6:7]
	s_add_u32 s6, s6, s10
	s_addc_u32 s7, s7, s11
	global_load_dword v17, v201, s[6:7]
	s_add_u32 s6, s6, s10
	s_addc_u32 s7, s7, s11
	global_load_dword v18, v201, s[6:7]
	s_add_u32 s6, s6, s10
	s_addc_u32 s7, s7, s11
	global_load_dword v19, v201, s[6:7]
	s_add_u32 s6, s6, s10
	s_addc_u32 s7, s7, s11
	global_load_dword v20, v201, s[6:7]
	s_add_u32 s6, s6, s10
	s_addc_u32 s7, s7, s11
	global_load_dword v21, v201, s[6:7]
	s_add_u32 s6, s6, s10
	s_addc_u32 s7, s7, s11
	global_load_dword v22, v201, s[6:7]
	s_add_u32 s6, s6, s10
	s_addc_u32 s7, s7, s11
	global_load_dword v23, v201, s[6:7]
	s_add_u32 s6, s6, s10
	s_addc_u32 s7, s7, s11
	global_load_dword v24, v201, s[6:7]
	s_add_u32 s6, s6, s10
	s_addc_u32 s7, s7, s11
	global_load_dword v25, v201, s[6:7]
	s_add_u32 s6, s6, s10
	s_addc_u32 s7, s7, s11
	global_load_dword v26, v201, s[6:7]
	s_add_u32 s6, s6, s10
	s_addc_u32 s7, s7, s11
	global_load_dword v27, v201, s[6:7]
	s_add_u32 s6, s6, s10
	s_addc_u32 s7, s7, s11
	global_load_dword v28, v201, s[6:7]
	s_add_u32 s6, s6, s10
	s_addc_u32 s7, s7, s11
	global_load_dword v29, v201, s[6:7]
	s_add_u32 s6, s6, s10
	s_addc_u32 s7, s7, s11
	global_load_dword v30, v201, s[6:7]
	s_add_u32 s6, s6, s10
	s_addc_u32 s7, s7, s11
	global_load_dword v31, v201, s[6:7]
	s_add_u32 s6, s6, s10
	s_addc_u32 s7, s7, s11
	global_load_dword v32, v201, s[6:7]
	s_add_u32 s6, s6, s10
	s_addc_u32 s7, s7, s11
	global_load_dword v33, v201, s[6:7]
	s_add_u32 s6, s6, s10
; __device__ __forceinline__ bf16_t f2bf(float f) { return (bf16_t)(cvt_pk_bf16(f, 0.f) & 0xffffu); }
; __device__ __forceinline__ void scan_phase(const Bufs& B) {
;     ...
;             for (int u = 0; u < 16; ++u) { const int ch = dir ? 63 - (s0 + u) : s0 + u, it = dh * 64 + ch;
;                 cl[u] = B.CLOC[(size_t)it * 16384 + idx]; ml[u] = B.MLOC[it]; bl[u] = B.BLAST[it]; nl[u] = idx < 128 ? B.NLOC[(size_t)it * 128 + idx] : 0.f; }
; #pragma unroll
;             for (int u = 0; u < 16; ++u) { const int ch = dir ? 63 - (s0 + u) : s0 + u, it = dh * 64 + ch;
;                 B.CST[(size_t)it * 16384 + idx] = f2bf(cst);
;                 if (idx < 128) { B.NST[(size_t)it * 128 + idx] = nst; if (idx == 0) B.MST[it] = m; }
;                 const float mnew = fmaxf(bl[u] + m, ml[u]), a = __expf(bl[u] + m - mnew), g = __expf(ml[u] - mnew);
;                 cst = a * cst + g * cl[u]; nst = a * nst + g * nl[u]; m = mnew; }
	s_addc_u32 s7, s7, s11
	global_load_dword v34, v201, s[6:7]
	s_add_u32 s6, s6, s10
	s_addc_u32 s7, s7, s11
	global_load_dword v35, v201, s[6:7]
	s_add_u32 s6, s6, s10
	s_addc_u32 s7, s7, s11
	global_load_dword v36, v201, s[6:7]
	s_add_u32 s6, s6, s10
	s_addc_u32 s7, s7, s11
	global_load_dword v37, v201, s[6:7]
	s_add_u32 s6, s6, s10
	s_addc_u32 s7, s7, s11
	global_load_dword v38, v201, s[6:7]
	s_add_u32 s6, s6, s10
	s_addc_u32 s7, s7, s11
	global_load_dword v39, v201, s[6:7]
	s_add_u32 s6, s6, s10
	s_addc_u32 s7, s7, s11
	global_load_dword v40, v201, s[6:7]
	s_add_u32 s6, s6, s10
	s_addc_u32 s7, s7, s11
	global_load_dword v41, v201, s[6:7]
	s_add_u32 s6, s6, s10
	s_addc_u32 s7, s7, s11
	global_load_dword v42, v201, s[6:7]
	s_add_u32 s6, s6, s10
	s_addc_u32 s7, s7, s11
	global_load_dword v43, v201, s[6:7]
	s_add_u32 s6, s6, s10
	s_addc_u32 s7, s7, s11
	global_load_dword v44, v201, s[6:7]
	s_add_u32 s6, s6, s10
	s_addc_u32 s7, s7, s11
	global_load_dword v45, v201, s[6:7]
	s_add_u32 s6, s6, s10
	s_addc_u32 s7, s7, s11
	global_load_dword v46, v201, s[6:7]
	s_add_u32 s6, s6, s10
	s_addc_u32 s7, s7, s11
	global_load_dword v47, v201, s[6:7]
	s_add_u32 s6, s6, s10
	s_addc_u32 s7, s7, s11
	global_load_dword v48, v201, s[6:7]
	s_add_u32 s6, s6, s10
	s_addc_u32 s7, s7, s11
	global_load_dword v49, v201, s[6:7]
	s_add_u32 s6, s6, s10
	s_addc_u32 s7, s7, s11
	global_load_dword v50, v201, s[6:7]
	s_add_u32 s6, s6, s10
	s_addc_u32 s7, s7, s11
	global_load_dword v51, v201, s[6:7]
	s_add_u32 s6, s6, s10
	s_addc_u32 s7, s7, s11
	global_load_dword v52, v201, s[6:7]
	s_add_u32 s6, s6, s10
	s_addc_u32 s7, s7, s11
	global_load_dword v53, v201, s[6:7]
	s_add_u32 s6, s6, s10
	s_addc_u32 s7, s7, s11
	global_load_dword v54, v201, s[6:7]
	s_add_u32 s6, s6, s10
	s_addc_u32 s7, s7, s11
	global_load_dword v55, v201, s[6:7]
	s_add_u32 s6, s6, s10
	s_addc_u32 s7, s7, s11
	global_load_dword v56, v201, s[6:7]
	s_add_u32 s6, s6, s10
	s_addc_u32 s7, s7, s11
	global_load_dword v57, v201, s[6:7]
	s_add_u32 s6, s6, s10
	s_addc_u32 s7, s7, s11
	global_load_dword v58, v201, s[6:7]
	s_add_u32 s6, s6, s10
	s_addc_u32 s7, s7, s11
	global_load_dword v59, v201, s[6:7]
	s_add_u32 s6, s6, s10
	s_addc_u32 s7, s7, s11
	global_load_dword v60, v201, s[6:7]
	s_add_u32 s6, s6, s10
	s_addc_u32 s7, s7, s11
	global_load_dword v61, v201, s[6:7]
	s_add_u32 s6, s6, s10
	s_addc_u32 s7, s7, s11
	global_load_dword v62, v201, s[6:7]
	s_add_u32 s6, s6, s10
	s_addc_u32 s7, s7, s11
	global_load_dword v63, v201, s[6:7]
	s_add_u32 s6, s6, s10
	s_addc_u32 s7, s7, s11
	v_mov_b32_e32 v208, 0xf149f2ca
	v_mov_b32_e32 v210, 0
	s_waitcnt vmcnt(63)
	s_nop 0
	v_readlane_b32 s41, v206, 0
	v_readlane_b32 s42, v207, 0
	s_waitcnt vmcnt(48)
	v_cvt_pk_bf16_f32 v215, v210, v195
	v_readlane_b32 s43, v206, 1
	v_readlane_b32 s44, v207, 1
	global_store_short v202, v215, s[8:9]
	s_add_u32 s8, s8, s12
	s_addc_u32 s9, s9, s13
	v_add_f32_e32 v211, s42, v208
	v_max_f32_e32 v209, s41, v211
	v_sub_f32_e32 v212, v211, v209
	v_sub_f32_e32 v213, s41, v209
	v_mul_f32_e32 v212, 0x3fb8aa3b, v212
	v_mul_f32_e32 v213, 0x3fb8aa3b, v213
	v_exp_f32_e32 v213, v213
	v_exp_f32_e32 v212, v212
	s_nop 0
	v_mul_f32_e32 v214, v213, v0
	v_fma_f32 v210, v210, v212, v214
	v_cvt_pk_bf16_f32 v215, v210, v195
	v_readlane_b32 s41, v206, 2
	v_readlane_b32 s42, v207, 2
	global_store_short v202, v215, s[8:9]
	s_add_u32 s8, s8, s12
	s_addc_u32 s9, s9, s13
	v_add_f32_e32 v211, s44, v209
	v_max_f32_e32 v208, s43, v211
	v_sub_f32_e32 v212, v211, v208
	v_sub_f32_e32 v213, s43, v208
	v_mul_f32_e32 v212, 0x3fb8aa3b, v212
	v_mul_f32_e32 v213, 0x3fb8aa3b, v213
	v_exp_f32_e32 v213, v213
	v_exp_f32_e32 v212, v212
	s_nop 0
	v_mul_f32_e32 v214, v213, v1
	v_fma_f32 v210, v210, v212, v214
	v_cvt_pk_bf16_f32 v215, v210, v195
	v_readlane_b32 s43, v206, 3
	v_readlane_b32 s44, v207, 3
	global_store_short v202, v215, s[8:9]
	s_add_u32 s8, s8, s12
	s_addc_u32 s9, s9, s13
	v_add_f32_e32 v211, s42, v208
	v_max_f32_e32 v209, s41, v211
	v_sub_f32_e32 v212, v211, v209
	v_sub_f32_e32 v213, s41, v209
	v_mul_f32_e32 v212, 0x3fb8aa3b, v212
	v_mul_f32_e32 v213, 0x3fb8aa3b, v213
	v_exp_f32_e32 v213, v213
	v_exp_f32_e32 v212, v212
	s_nop 0
	v_mul_f32_e32 v214, v213, v2
	v_fma_f32 v210, v210, v212, v214
	v_cvt_pk_bf16_f32 v215, v210, v195
	v_readlane_b32 s41, v206, 4
	v_readlane_b32 s42, v207, 4
	global_store_short v202, v215, s[8:9]
	s_add_u32 s8, s8, s12
	s_addc_u32 s9, s9, s13
	v_add_f32_e32 v211, s44, v209
	v_max_f32_e32 v208, s43, v211
	v_sub_f32_e32 v212, v211, v208
	v_sub_f32_e32 v213, s43, v208
	v_mul_f32_e32 v212, 0x3fb8aa3b, v212
	v_mul_f32_e32 v213, 0x3fb8aa3b, v213
	v_exp_f32_e32 v213, v213
	v_exp_f32_e32 v212, v212
	s_nop 0
	v_mul_f32_e32 v214, v213, v3
	v_fma_f32 v210, v210, v212, v214
	v_cvt_pk_bf16_f32 v215, v210, v195
	v_readlane_b32 s43, v206, 5
	v_readlane_b32 s44, v207, 5
	global_store_short v202, v215, s[8:9]
	s_add_u32 s8, s8, s12
	s_addc_u32 s9, s9, s13
	v_add_f32_e32 v211, s42, v208
	v_max_f32_e32 v209, s41, v211
	v_sub_f32_e32 v212, v211, v209
	v_sub_f32_e32 v213, s41, v209
	v_mul_f32_e32 v212, 0x3fb8aa3b, v212
	v_mul_f32_e32 v213, 0x3fb8aa3b, v213
	v_exp_f32_e32 v213, v213
	v_exp_f32_e32 v212, v212
	s_nop 0
	v_mul_f32_e32 v214, v213, v4
	v_fma_f32 v210, v210, v212, v214
	v_cvt_pk_bf16_f32 v215, v210, v195
	v_readlane_b32 s41, v206, 6
	v_readlane_b32 s42, v207, 6
	global_store_short v202, v215, s[8:9]
	s_add_u32 s8, s8, s12
	s_addc_u32 s9, s9, s13
	v_add_f32_e32 v211, s44, v209
	v_max_f32_e32 v208, s43, v211
	v_sub_f32_e32 v212, v211, v208
	v_sub_f32_e32 v213, s43, v208
	v_mul_f32_e32 v212, 0x3fb8aa3b, v212
	v_mul_f32_e32 v213, 0x3fb8aa3b, v213
	v_exp_f32_e32 v213, v213
; __device__ __forceinline__ bf16_t f2bf(float f) { return (bf16_t)(cvt_pk_bf16(f, 0.f) & 0xffffu); }
; __device__ __forceinline__ void scan_phase(const Bufs& B) {
;     ...
;             for (int u = 0; u < 16; ++u) { const int ch = dir ? 63 - (s0 + u) : s0 + u, it = dh * 64 + ch;
;                 B.CST[(size_t)it * 16384 + idx] = f2bf(cst);
;                 if (idx < 128) { B.NST[(size_t)it * 128 + idx] = nst; if (idx == 0) B.MST[it] = m; }
;                 const float mnew = fmaxf(bl[u] + m, ml[u]), a = __expf(bl[u] + m - mnew), g = __expf(ml[u] - mnew);
;                 cst = a * cst + g * cl[u]; nst = a * nst + g * nl[u]; m = mnew; }
	v_exp_f32_e32 v212, v212
	s_nop 0
	v_mul_f32_e32 v214, v213, v5
	v_fma_f32 v210, v210, v212, v214
	v_cvt_pk_bf16_f32 v215, v210, v195
	v_readlane_b32 s43, v206, 7
	v_readlane_b32 s44, v207, 7
	global_store_short v202, v215, s[8:9]
	s_add_u32 s8, s8, s12
	s_addc_u32 s9, s9, s13
	v_add_f32_e32 v211, s42, v208
	v_max_f32_e32 v209, s41, v211
	v_sub_f32_e32 v212, v211, v209
	v_sub_f32_e32 v213, s41, v209
	v_mul_f32_e32 v212, 0x3fb8aa3b, v212
	v_mul_f32_e32 v213, 0x3fb8aa3b, v213
	v_exp_f32_e32 v213, v213
	v_exp_f32_e32 v212, v212
	s_nop 0
	v_mul_f32_e32 v214, v213, v6
	v_fma_f32 v210, v210, v212, v214
	v_cvt_pk_bf16_f32 v215, v210, v195
	v_readlane_b32 s41, v206, 8
	v_readlane_b32 s42, v207, 8
	global_store_short v202, v215, s[8:9]
	s_add_u32 s8, s8, s12
	s_addc_u32 s9, s9, s13
	v_add_f32_e32 v211, s44, v209
	v_max_f32_e32 v208, s43, v211
	v_sub_f32_e32 v212, v211, v208
	v_sub_f32_e32 v213, s43, v208
	v_mul_f32_e32 v212, 0x3fb8aa3b, v212
	v_mul_f32_e32 v213, 0x3fb8aa3b, v213
	v_exp_f32_e32 v213, v213
	v_exp_f32_e32 v212, v212
	s_nop 0
	v_mul_f32_e32 v214, v213, v7
	v_fma_f32 v210, v210, v212, v214
	v_cvt_pk_bf16_f32 v215, v210, v195
	v_readlane_b32 s43, v206, 9
	v_readlane_b32 s44, v207, 9
	global_store_short v202, v215, s[8:9]
	s_add_u32 s8, s8, s12
	s_addc_u32 s9, s9, s13
	v_add_f32_e32 v211, s42, v208
	v_max_f32_e32 v209, s41, v211
	v_sub_f32_e32 v212, v211, v209
	v_sub_f32_e32 v213, s41, v209
	v_mul_f32_e32 v212, 0x3fb8aa3b, v212
	v_mul_f32_e32 v213, 0x3fb8aa3b, v213
	v_exp_f32_e32 v213, v213
	v_exp_f32_e32 v212, v212
	s_nop 0
	v_mul_f32_e32 v214, v213, v8
	v_fma_f32 v210, v210, v212, v214
	v_cvt_pk_bf16_f32 v215, v210, v195
	v_readlane_b32 s41, v206, 10
	v_readlane_b32 s42, v207, 10
	global_store_short v202, v215, s[8:9]
	s_add_u32 s8, s8, s12
	s_addc_u32 s9, s9, s13
	v_add_f32_e32 v211, s44, v209
	v_max_f32_e32 v208, s43, v211
	v_sub_f32_e32 v212, v211, v208
	v_sub_f32_e32 v213, s43, v208
	v_mul_f32_e32 v212, 0x3fb8aa3b, v212
	v_mul_f32_e32 v213, 0x3fb8aa3b, v213
	v_exp_f32_e32 v213, v213
	v_exp_f32_e32 v212, v212
	s_nop 0
	v_mul_f32_e32 v214, v213, v9
	v_fma_f32 v210, v210, v212, v214
	v_cvt_pk_bf16_f32 v215, v210, v195
	v_readlane_b32 s43, v206, 11
	v_readlane_b32 s44, v207, 11
	global_store_short v202, v215, s[8:9]
	s_add_u32 s8, s8, s12
	s_addc_u32 s9, s9, s13
	v_add_f32_e32 v211, s42, v208
	v_max_f32_e32 v209, s41, v211
	v_sub_f32_e32 v212, v211, v209
	v_sub_f32_e32 v213, s41, v209
	v_mul_f32_e32 v212, 0x3fb8aa3b, v212
	v_mul_f32_e32 v213, 0x3fb8aa3b, v213
	v_exp_f32_e32 v213, v213
	v_exp_f32_e32 v212, v212
	s_nop 0
	v_mul_f32_e32 v214, v213, v10
	v_fma_f32 v210, v210, v212, v214
	v_cvt_pk_bf16_f32 v215, v210, v195
	v_readlane_b32 s41, v206, 12
	v_readlane_b32 s42, v207, 12
	global_store_short v202, v215, s[8:9]
	s_add_u32 s8, s8, s12
	s_addc_u32 s9, s9, s13
	v_add_f32_e32 v211, s44, v209
	v_max_f32_e32 v208, s43, v211
	v_sub_f32_e32 v212, v211, v208
	v_sub_f32_e32 v213, s43, v208
	v_mul_f32_e32 v212, 0x3fb8aa3b, v212
	v_mul_f32_e32 v213, 0x3fb8aa3b, v213
	v_exp_f32_e32 v213, v213
	v_exp_f32_e32 v212, v212
	s_nop 0
	v_mul_f32_e32 v214, v213, v11
	v_fma_f32 v210, v210, v212, v214
	v_cvt_pk_bf16_f32 v215, v210, v195
	v_readlane_b32 s43, v206, 13
	v_readlane_b32 s44, v207, 13
	global_store_short v202, v215, s[8:9]
	s_add_u32 s8, s8, s12
	s_addc_u32 s9, s9, s13
	v_add_f32_e32 v211, s42, v208
	v_max_f32_e32 v209, s41, v211
	v_sub_f32_e32 v212, v211, v209
	v_sub_f32_e32 v213, s41, v209
	v_mul_f32_e32 v212, 0x3fb8aa3b, v212
	v_mul_f32_e32 v213, 0x3fb8aa3b, v213
	v_exp_f32_e32 v213, v213
	v_exp_f32_e32 v212, v212
	s_nop 0
	v_mul_f32_e32 v214, v213, v12
	v_fma_f32 v210, v210, v212, v214
	v_cvt_pk_bf16_f32 v215, v210, v195
	v_readlane_b32 s41, v206, 14
	v_readlane_b32 s42, v207, 14
	global_store_short v202, v215, s[8:9]
	s_add_u32 s8, s8, s12
	s_addc_u32 s9, s9, s13
	v_add_f32_e32 v211, s44, v209
	v_max_f32_e32 v208, s43, v211
	v_sub_f32_e32 v212, v211, v208
	v_sub_f32_e32 v213, s43, v208
	v_mul_f32_e32 v212, 0x3fb8aa3b, v212
	v_mul_f32_e32 v213, 0x3fb8aa3b, v213
	v_exp_f32_e32 v213, v213
	v_exp_f32_e32 v212, v212
	s_nop 0
	v_mul_f32_e32 v214, v213, v13
	v_fma_f32 v210, v210, v212, v214
	v_cvt_pk_bf16_f32 v215, v210, v195
	v_readlane_b32 s43, v206, 15
	v_readlane_b32 s44, v207, 15
	global_store_short v202, v215, s[8:9]
	s_add_u32 s8, s8, s12
	s_addc_u32 s9, s9, s13
	v_add_f32_e32 v211, s42, v208
	v_max_f32_e32 v209, s41, v211
	v_sub_f32_e32 v212, v211, v209
	v_sub_f32_e32 v213, s41, v209
	v_mul_f32_e32 v212, 0x3fb8aa3b, v212
	v_mul_f32_e32 v213, 0x3fb8aa3b, v213
	v_exp_f32_e32 v213, v213
	v_exp_f32_e32 v212, v212
	s_nop 0
	v_mul_f32_e32 v214, v213, v14
	v_fma_f32 v210, v210, v212, v214
	v_cvt_pk_bf16_f32 v215, v210, v195
	v_readlane_b32 s41, v206, 16
	v_readlane_b32 s42, v207, 16
	global_store_short v202, v215, s[8:9]
	s_add_u32 s8, s8, s12
	s_addc_u32 s9, s9, s13
	v_add_f32_e32 v211, s44, v209
	v_max_f32_e32 v208, s43, v211
	v_sub_f32_e32 v212, v211, v208
	v_sub_f32_e32 v213, s43, v208
	v_mul_f32_e32 v212, 0x3fb8aa3b, v212
	v_mul_f32_e32 v213, 0x3fb8aa3b, v213
	v_exp_f32_e32 v213, v213
	v_exp_f32_e32 v212, v212
	s_nop 0
	v_mul_f32_e32 v214, v213, v15
	v_fma_f32 v210, v210, v212, v214
	s_waitcnt vmcnt(48)
; __device__ __forceinline__ bf16_t f2bf(float f) { return (bf16_t)(cvt_pk_bf16(f, 0.f) & 0xffffu); }
; __device__ __forceinline__ void scan_phase(const Bufs& B) {
;     ...
;             for (int u = 0; u < 16; ++u) { const int ch = dir ? 63 - (s0 + u) : s0 + u, it = dh * 64 + ch;
;                 B.CST[(size_t)it * 16384 + idx] = f2bf(cst);
;                 if (idx < 128) { B.NST[(size_t)it * 128 + idx] = nst; if (idx == 0) B.MST[it] = m; }
;                 const float mnew = fmaxf(bl[u] + m, ml[u]), a = __expf(bl[u] + m - mnew), g = __expf(ml[u] - mnew);
;                 cst = a * cst + g * cl[u]; nst = a * nst + g * nl[u]; m = mnew; }
	v_cvt_pk_bf16_f32 v215, v210, v195
	v_readlane_b32 s43, v206, 17
	v_readlane_b32 s44, v207, 17
	global_store_short v202, v215, s[8:9]
	s_add_u32 s8, s8, s12
	s_addc_u32 s9, s9, s13
	v_add_f32_e32 v211, s42, v208
	v_max_f32_e32 v209, s41, v211
	v_sub_f32_e32 v212, v211, v209
	v_sub_f32_e32 v213, s41, v209
	v_mul_f32_e32 v212, 0x3fb8aa3b, v212
	v_mul_f32_e32 v213, 0x3fb8aa3b, v213
	v_exp_f32_e32 v213, v213
	v_exp_f32_e32 v212, v212
	s_nop 0
	v_mul_f32_e32 v214, v213, v16
	v_fma_f32 v210, v210, v212, v214
	v_cvt_pk_bf16_f32 v215, v210, v195
	v_readlane_b32 s41, v206, 18
	v_readlane_b32 s42, v207, 18
	global_store_short v202, v215, s[8:9]
	s_add_u32 s8, s8, s12
	s_addc_u32 s9, s9, s13
	v_add_f32_e32 v211, s44, v209
	v_max_f32_e32 v208, s43, v211
	v_sub_f32_e32 v212, v211, v208
	v_sub_f32_e32 v213, s43, v208
	v_mul_f32_e32 v212, 0x3fb8aa3b, v212
	v_mul_f32_e32 v213, 0x3fb8aa3b, v213
	v_exp_f32_e32 v213, v213
	v_exp_f32_e32 v212, v212
	s_nop 0
	v_mul_f32_e32 v214, v213, v17
	v_fma_f32 v210, v210, v212, v214
	v_cvt_pk_bf16_f32 v215, v210, v195
	v_readlane_b32 s43, v206, 19
	v_readlane_b32 s44, v207, 19
	global_store_short v202, v215, s[8:9]
	s_add_u32 s8, s8, s12
	s_addc_u32 s9, s9, s13
	v_add_f32_e32 v211, s42, v208
	v_max_f32_e32 v209, s41, v211
	v_sub_f32_e32 v212, v211, v209
	v_sub_f32_e32 v213, s41, v209
	v_mul_f32_e32 v212, 0x3fb8aa3b, v212
	v_mul_f32_e32 v213, 0x3fb8aa3b, v213
	v_exp_f32_e32 v213, v213
	v_exp_f32_e32 v212, v212
	s_nop 0
	v_mul_f32_e32 v214, v213, v18
	v_fma_f32 v210, v210, v212, v214
	v_cvt_pk_bf16_f32 v215, v210, v195
	v_readlane_b32 s41, v206, 20
	v_readlane_b32 s42, v207, 20
	global_store_short v202, v215, s[8:9]
	s_add_u32 s8, s8, s12
	s_addc_u32 s9, s9, s13
	v_add_f32_e32 v211, s44, v209
	v_max_f32_e32 v208, s43, v211
	v_sub_f32_e32 v212, v211, v208
	v_sub_f32_e32 v213, s43, v208
	v_mul_f32_e32 v212, 0x3fb8aa3b, v212
	v_mul_f32_e32 v213, 0x3fb8aa3b, v213
	v_exp_f32_e32 v213, v213
	v_exp_f32_e32 v212, v212
	s_nop 0
	v_mul_f32_e32 v214, v213, v19
	v_fma_f32 v210, v210, v212, v214
	v_cvt_pk_bf16_f32 v215, v210, v195
	v_readlane_b32 s43, v206, 21
	v_readlane_b32 s44, v207, 21
	global_store_short v202, v215, s[8:9]
	s_add_u32 s8, s8, s12
	s_addc_u32 s9, s9, s13
	v_add_f32_e32 v211, s42, v208
	v_max_f32_e32 v209, s41, v211
	v_sub_f32_e32 v212, v211, v209
	v_sub_f32_e32 v213, s41, v209
	v_mul_f32_e32 v212, 0x3fb8aa3b, v212
	v_mul_f32_e32 v213, 0x3fb8aa3b, v213
	v_exp_f32_e32 v213, v213
	v_exp_f32_e32 v212, v212
	s_nop 0
	v_mul_f32_e32 v214, v213, v20
	v_fma_f32 v210, v210, v212, v214
	v_cvt_pk_bf16_f32 v215, v210, v195
	v_readlane_b32 s41, v206, 22
	v_readlane_b32 s42, v207, 22
	global_store_short v202, v215, s[8:9]
	s_add_u32 s8, s8, s12
	s_addc_u32 s9, s9, s13
	v_add_f32_e32 v211, s44, v209
	v_max_f32_e32 v208, s43, v211
	v_sub_f32_e32 v212, v211, v208
	v_sub_f32_e32 v213, s43, v208
	v_mul_f32_e32 v212, 0x3fb8aa3b, v212
	v_mul_f32_e32 v213, 0x3fb8aa3b, v213
	v_exp_f32_e32 v213, v213
	v_exp_f32_e32 v212, v212
	s_nop 0
	v_mul_f32_e32 v214, v213, v21
	v_fma_f32 v210, v210, v212, v214
	v_cvt_pk_bf16_f32 v215, v210, v195
	v_readlane_b32 s43, v206, 23
	v_readlane_b32 s44, v207, 23
	global_store_short v202, v215, s[8:9]
	s_add_u32 s8, s8, s12
	s_addc_u32 s9, s9, s13
	v_add_f32_e32 v211, s42, v208
	v_max_f32_e32 v209, s41, v211
	v_sub_f32_e32 v212, v211, v209
	v_sub_f32_e32 v213, s41, v209
	v_mul_f32_e32 v212, 0x3fb8aa3b, v212
	v_mul_f32_e32 v213, 0x3fb8aa3b, v213
	v_exp_f32_e32 v213, v213
	v_exp_f32_e32 v212, v212
	s_nop 0
	v_mul_f32_e32 v214, v213, v22
	v_fma_f32 v210, v210, v212, v214
	v_cvt_pk_bf16_f32 v215, v210, v195
	v_readlane_b32 s41, v206, 24
	v_readlane_b32 s42, v207, 24
	global_store_short v202, v215, s[8:9]
	s_add_u32 s8, s8, s12
	s_addc_u32 s9, s9, s13
	v_add_f32_e32 v211, s44, v209
	v_max_f32_e32 v208, s43, v211
	v_sub_f32_e32 v212, v211, v208
	v_sub_f32_e32 v213, s43, v208
	v_mul_f32_e32 v212, 0x3fb8aa3b, v212
	v_mul_f32_e32 v213, 0x3fb8aa3b, v213
	v_exp_f32_e32 v213, v213
	v_exp_f32_e32 v212, v212
	s_nop 0
	v_mul_f32_e32 v214, v213, v23
	v_fma_f32 v210, v210, v212, v214
	v_cvt_pk_bf16_f32 v215, v210, v195
	v_readlane_b32 s43, v206, 25
	v_readlane_b32 s44, v207, 25
	global_store_short v202, v215, s[8:9]
	s_add_u32 s8, s8, s12
	s_addc_u32 s9, s9, s13
	v_add_f32_e32 v211, s42, v208
	v_max_f32_e32 v209, s41, v211
	v_sub_f32_e32 v212, v211, v209
	v_sub_f32_e32 v213, s41, v209
	v_mul_f32_e32 v212, 0x3fb8aa3b, v212
	v_mul_f32_e32 v213, 0x3fb8aa3b, v213
	v_exp_f32_e32 v213, v213
	v_exp_f32_e32 v212, v212
	s_nop 0
	v_mul_f32_e32 v214, v213, v24
	v_fma_f32 v210, v210, v212, v214
	v_cvt_pk_bf16_f32 v215, v210, v195
	v_readlane_b32 s41, v206, 26
	v_readlane_b32 s42, v207, 26
	global_store_short v202, v215, s[8:9]
	s_add_u32 s8, s8, s12
	s_addc_u32 s9, s9, s13
	v_add_f32_e32 v211, s44, v209
	v_max_f32_e32 v208, s43, v211
	v_sub_f32_e32 v212, v211, v208
	v_sub_f32_e32 v213, s43, v208
	v_mul_f32_e32 v212, 0x3fb8aa3b, v212
	v_mul_f32_e32 v213, 0x3fb8aa3b, v213
	v_exp_f32_e32 v213, v213
	v_exp_f32_e32 v212, v212
	s_nop 0
	v_mul_f32_e32 v214, v213, v25
	v_fma_f32 v210, v210, v212, v214
	v_cvt_pk_bf16_f32 v215, v210, v195
	v_readlane_b32 s43, v206, 27
	v_readlane_b32 s44, v207, 27
	global_store_short v202, v215, s[8:9]
	s_add_u32 s8, s8, s12
	s_addc_u32 s9, s9, s13
	v_add_f32_e32 v211, s42, v208
	v_max_f32_e32 v209, s41, v211
	v_sub_f32_e32 v212, v211, v209
	v_sub_f32_e32 v213, s41, v209
	v_mul_f32_e32 v212, 0x3fb8aa3b, v212
	v_mul_f32_e32 v213, 0x3fb8aa3b, v213
	v_exp_f32_e32 v213, v213
	v_exp_f32_e32 v212, v212
	s_nop 0
	v_mul_f32_e32 v214, v213, v26
	v_fma_f32 v210, v210, v212, v214
	v_cvt_pk_bf16_f32 v215, v210, v195
; __device__ __forceinline__ bf16_t f2bf(float f) { return (bf16_t)(cvt_pk_bf16(f, 0.f) & 0xffffu); }
; __device__ __forceinline__ void scan_phase(const Bufs& B) {
;     ...
;             for (int u = 0; u < 16; ++u) { const int ch = dir ? 63 - (s0 + u) : s0 + u, it = dh * 64 + ch;
;                 B.CST[(size_t)it * 16384 + idx] = f2bf(cst);
;                 if (idx < 128) { B.NST[(size_t)it * 128 + idx] = nst; if (idx == 0) B.MST[it] = m; }
;                 const float mnew = fmaxf(bl[u] + m, ml[u]), a = __expf(bl[u] + m - mnew), g = __expf(ml[u] - mnew);
;                 cst = a * cst + g * cl[u]; nst = a * nst + g * nl[u]; m = mnew; }
	v_readlane_b32 s41, v206, 28
	v_readlane_b32 s42, v207, 28
	global_store_short v202, v215, s[8:9]
	s_add_u32 s8, s8, s12
	s_addc_u32 s9, s9, s13
	v_add_f32_e32 v211, s44, v209
	v_max_f32_e32 v208, s43, v211
	v_sub_f32_e32 v212, v211, v208
	v_sub_f32_e32 v213, s43, v208
	v_mul_f32_e32 v212, 0x3fb8aa3b, v212
	v_mul_f32_e32 v213, 0x3fb8aa3b, v213
	v_exp_f32_e32 v213, v213
	v_exp_f32_e32 v212, v212
	s_nop 0
	v_mul_f32_e32 v214, v213, v27
	v_fma_f32 v210, v210, v212, v214
	v_cvt_pk_bf16_f32 v215, v210, v195
	v_readlane_b32 s43, v206, 29
	v_readlane_b32 s44, v207, 29
	global_store_short v202, v215, s[8:9]
	s_add_u32 s8, s8, s12
	s_addc_u32 s9, s9, s13
	v_add_f32_e32 v211, s42, v208
	v_max_f32_e32 v209, s41, v211
	v_sub_f32_e32 v212, v211, v209
	v_sub_f32_e32 v213, s41, v209
	v_mul_f32_e32 v212, 0x3fb8aa3b, v212
	v_mul_f32_e32 v213, 0x3fb8aa3b, v213
	v_exp_f32_e32 v213, v213
	v_exp_f32_e32 v212, v212
	s_nop 0
	v_mul_f32_e32 v214, v213, v28
	v_fma_f32 v210, v210, v212, v214
	v_cvt_pk_bf16_f32 v215, v210, v195
	v_readlane_b32 s41, v206, 30
	v_readlane_b32 s42, v207, 30
	global_store_short v202, v215, s[8:9]
	s_add_u32 s8, s8, s12
	s_addc_u32 s9, s9, s13
	v_add_f32_e32 v211, s44, v209
	v_max_f32_e32 v208, s43, v211
	v_sub_f32_e32 v212, v211, v208
	v_sub_f32_e32 v213, s43, v208
	v_mul_f32_e32 v212, 0x3fb8aa3b, v212
	v_mul_f32_e32 v213, 0x3fb8aa3b, v213
	v_exp_f32_e32 v213, v213
	v_exp_f32_e32 v212, v212
	s_nop 0
	v_mul_f32_e32 v214, v213, v29
	v_fma_f32 v210, v210, v212, v214
	v_cvt_pk_bf16_f32 v215, v210, v195
	v_readlane_b32 s43, v206, 31
	v_readlane_b32 s44, v207, 31
	global_store_short v202, v215, s[8:9]
	s_add_u32 s8, s8, s12
	s_addc_u32 s9, s9, s13
	v_add_f32_e32 v211, s42, v208
	v_max_f32_e32 v209, s41, v211
	v_sub_f32_e32 v212, v211, v209
	v_sub_f32_e32 v213, s41, v209
	v_mul_f32_e32 v212, 0x3fb8aa3b, v212
	v_mul_f32_e32 v213, 0x3fb8aa3b, v213
	v_exp_f32_e32 v213, v213
	v_exp_f32_e32 v212, v212
	s_nop 0
	v_mul_f32_e32 v214, v213, v30
	v_fma_f32 v210, v210, v212, v214
	v_cvt_pk_bf16_f32 v215, v210, v195
	v_readlane_b32 s41, v206, 32
	v_readlane_b32 s42, v207, 32
	global_store_short v202, v215, s[8:9]
	s_add_u32 s8, s8, s12
	s_addc_u32 s9, s9, s13
	v_add_f32_e32 v211, s44, v209
	v_max_f32_e32 v208, s43, v211
	v_sub_f32_e32 v212, v211, v208
	v_sub_f32_e32 v213, s43, v208
	v_mul_f32_e32 v212, 0x3fb8aa3b, v212
	v_mul_f32_e32 v213, 0x3fb8aa3b, v213
	v_exp_f32_e32 v213, v213
	v_exp_f32_e32 v212, v212
	s_nop 0
	v_mul_f32_e32 v214, v213, v31
	v_fma_f32 v210, v210, v212, v214
	s_waitcnt vmcnt(48)
	v_cvt_pk_bf16_f32 v215, v210, v195
	v_readlane_b32 s43, v206, 33
	v_readlane_b32 s44, v207, 33
	global_store_short v202, v215, s[8:9]
	s_add_u32 s8, s8, s12
	s_addc_u32 s9, s9, s13
	v_add_f32_e32 v211, s42, v208
	v_max_f32_e32 v209, s41, v211
	v_sub_f32_e32 v212, v211, v209
	v_sub_f32_e32 v213, s41, v209
	v_mul_f32_e32 v212, 0x3fb8aa3b, v212
	v_mul_f32_e32 v213, 0x3fb8aa3b, v213
	v_exp_f32_e32 v213, v213
	v_exp_f32_e32 v212, v212
	s_nop 0
	v_mul_f32_e32 v214, v213, v32
	v_fma_f32 v210, v210, v212, v214
	v_cvt_pk_bf16_f32 v215, v210, v195
	v_readlane_b32 s41, v206, 34
	v_readlane_b32 s42, v207, 34
	global_store_short v202, v215, s[8:9]
	s_add_u32 s8, s8, s12
	s_addc_u32 s9, s9, s13
	v_add_f32_e32 v211, s44, v209
	v_max_f32_e32 v208, s43, v211
	v_sub_f32_e32 v212, v211, v208
	v_sub_f32_e32 v213, s43, v208
	v_mul_f32_e32 v212, 0x3fb8aa3b, v212
	v_mul_f32_e32 v213, 0x3fb8aa3b, v213
	v_exp_f32_e32 v213, v213
	v_exp_f32_e32 v212, v212
	s_nop 0
	v_mul_f32_e32 v214, v213, v33
	v_fma_f32 v210, v210, v212, v214
	v_cvt_pk_bf16_f32 v215, v210, v195
	v_readlane_b32 s43, v206, 35
	v_readlane_b32 s44, v207, 35
	global_store_short v202, v215, s[8:9]
	s_add_u32 s8, s8, s12
	s_addc_u32 s9, s9, s13
	v_add_f32_e32 v211, s42, v208
	v_max_f32_e32 v209, s41, v211
	v_sub_f32_e32 v212, v211, v209
	v_sub_f32_e32 v213, s41, v209
	v_mul_f32_e32 v212, 0x3fb8aa3b, v212
	v_mul_f32_e32 v213, 0x3fb8aa3b, v213
	v_exp_f32_e32 v213, v213
	v_exp_f32_e32 v212, v212
	s_nop 0
	v_mul_f32_e32 v214, v213, v34
	v_fma_f32 v210, v210, v212, v214
	v_cvt_pk_bf16_f32 v215, v210, v195
	v_readlane_b32 s41, v206, 36
	v_readlane_b32 s42, v207, 36
	global_store_short v202, v215, s[8:9]
	s_add_u32 s8, s8, s12
	s_addc_u32 s9, s9, s13
	v_add_f32_e32 v211, s44, v209
	v_max_f32_e32 v208, s43, v211
	v_sub_f32_e32 v212, v211, v208
	v_sub_f32_e32 v213, s43, v208
	v_mul_f32_e32 v212, 0x3fb8aa3b, v212
	v_mul_f32_e32 v213, 0x3fb8aa3b, v213
	v_exp_f32_e32 v213, v213
	v_exp_f32_e32 v212, v212
	s_nop 0
	v_mul_f32_e32 v214, v213, v35
	v_fma_f32 v210, v210, v212, v214
	v_cvt_pk_bf16_f32 v215, v210, v195
	v_readlane_b32 s43, v206, 37
	v_readlane_b32 s44, v207, 37
	global_store_short v202, v215, s[8:9]
	s_add_u32 s8, s8, s12
	s_addc_u32 s9, s9, s13
	v_add_f32_e32 v211, s42, v208
	v_max_f32_e32 v209, s41, v211
	v_sub_f32_e32 v212, v211, v209
	v_sub_f32_e32 v213, s41, v209
	v_mul_f32_e32 v212, 0x3fb8aa3b, v212
	v_mul_f32_e32 v213, 0x3fb8aa3b, v213
	v_exp_f32_e32 v213, v213
	v_exp_f32_e32 v212, v212
	s_nop 0
	v_mul_f32_e32 v214, v213, v36
	v_fma_f32 v210, v210, v212, v214
	v_cvt_pk_bf16_f32 v215, v210, v195
	v_readlane_b32 s41, v206, 38
	v_readlane_b32 s42, v207, 38
	global_store_short v202, v215, s[8:9]
	s_add_u32 s8, s8, s12
	s_addc_u32 s9, s9, s13
	v_add_f32_e32 v211, s44, v209
	v_max_f32_e32 v208, s43, v211
	v_sub_f32_e32 v212, v211, v208
	v_sub_f32_e32 v213, s43, v208
	v_mul_f32_e32 v212, 0x3fb8aa3b, v212
	v_mul_f32_e32 v213, 0x3fb8aa3b, v213
	v_exp_f32_e32 v213, v213
	v_exp_f32_e32 v212, v212
	s_nop 0
	v_mul_f32_e32 v214, v213, v37
	v_fma_f32 v210, v210, v212, v214
	v_cvt_pk_bf16_f32 v215, v210, v195
	v_readlane_b32 s43, v206, 39
; __device__ __forceinline__ bf16_t f2bf(float f) { return (bf16_t)(cvt_pk_bf16(f, 0.f) & 0xffffu); }
; __device__ __forceinline__ void scan_phase(const Bufs& B) {
;     ...
;             for (int u = 0; u < 16; ++u) { const int ch = dir ? 63 - (s0 + u) : s0 + u, it = dh * 64 + ch;
;                 B.CST[(size_t)it * 16384 + idx] = f2bf(cst);
;                 if (idx < 128) { B.NST[(size_t)it * 128 + idx] = nst; if (idx == 0) B.MST[it] = m; }
;                 const float mnew = fmaxf(bl[u] + m, ml[u]), a = __expf(bl[u] + m - mnew), g = __expf(ml[u] - mnew);
;                 cst = a * cst + g * cl[u]; nst = a * nst + g * nl[u]; m = mnew; }
	v_readlane_b32 s44, v207, 39
	global_store_short v202, v215, s[8:9]
	s_add_u32 s8, s8, s12
	s_addc_u32 s9, s9, s13
	v_add_f32_e32 v211, s42, v208
	v_max_f32_e32 v209, s41, v211
	v_sub_f32_e32 v212, v211, v209
	v_sub_f32_e32 v213, s41, v209
	v_mul_f32_e32 v212, 0x3fb8aa3b, v212
	v_mul_f32_e32 v213, 0x3fb8aa3b, v213
	v_exp_f32_e32 v213, v213
	v_exp_f32_e32 v212, v212
	s_nop 0
	v_mul_f32_e32 v214, v213, v38
	v_fma_f32 v210, v210, v212, v214
	v_cvt_pk_bf16_f32 v215, v210, v195
	v_readlane_b32 s41, v206, 40
	v_readlane_b32 s42, v207, 40
	global_store_short v202, v215, s[8:9]
	s_add_u32 s8, s8, s12
	s_addc_u32 s9, s9, s13
	v_add_f32_e32 v211, s44, v209
	v_max_f32_e32 v208, s43, v211
	v_sub_f32_e32 v212, v211, v208
	v_sub_f32_e32 v213, s43, v208
	v_mul_f32_e32 v212, 0x3fb8aa3b, v212
	v_mul_f32_e32 v213, 0x3fb8aa3b, v213
	v_exp_f32_e32 v213, v213
	v_exp_f32_e32 v212, v212
	s_nop 0
	v_mul_f32_e32 v214, v213, v39
	v_fma_f32 v210, v210, v212, v214
	v_cvt_pk_bf16_f32 v215, v210, v195
	v_readlane_b32 s43, v206, 41
	v_readlane_b32 s44, v207, 41
	global_store_short v202, v215, s[8:9]
	s_add_u32 s8, s8, s12
	s_addc_u32 s9, s9, s13
	v_add_f32_e32 v211, s42, v208
	v_max_f32_e32 v209, s41, v211
	v_sub_f32_e32 v212, v211, v209
	v_sub_f32_e32 v213, s41, v209
	v_mul_f32_e32 v212, 0x3fb8aa3b, v212
	v_mul_f32_e32 v213, 0x3fb8aa3b, v213
	v_exp_f32_e32 v213, v213
	v_exp_f32_e32 v212, v212
	s_nop 0
	v_mul_f32_e32 v214, v213, v40
	v_fma_f32 v210, v210, v212, v214
	v_cvt_pk_bf16_f32 v215, v210, v195
	v_readlane_b32 s41, v206, 42
	v_readlane_b32 s42, v207, 42
	global_store_short v202, v215, s[8:9]
	s_add_u32 s8, s8, s12
	s_addc_u32 s9, s9, s13
	v_add_f32_e32 v211, s44, v209
	v_max_f32_e32 v208, s43, v211
	v_sub_f32_e32 v212, v211, v208
	v_sub_f32_e32 v213, s43, v208
	v_mul_f32_e32 v212, 0x3fb8aa3b, v212
	v_mul_f32_e32 v213, 0x3fb8aa3b, v213
	v_exp_f32_e32 v213, v213
	v_exp_f32_e32 v212, v212
	s_nop 0
	v_mul_f32_e32 v214, v213, v41
	v_fma_f32 v210, v210, v212, v214
	v_cvt_pk_bf16_f32 v215, v210, v195
	v_readlane_b32 s43, v206, 43
	v_readlane_b32 s44, v207, 43
	global_store_short v202, v215, s[8:9]
	s_add_u32 s8, s8, s12
	s_addc_u32 s9, s9, s13
	v_add_f32_e32 v211, s42, v208
	v_max_f32_e32 v209, s41, v211
	v_sub_f32_e32 v212, v211, v209
	v_sub_f32_e32 v213, s41, v209
	v_mul_f32_e32 v212, 0x3fb8aa3b, v212
	v_mul_f32_e32 v213, 0x3fb8aa3b, v213
	v_exp_f32_e32 v213, v213
	v_exp_f32_e32 v212, v212
	s_nop 0
	v_mul_f32_e32 v214, v213, v42
	v_fma_f32 v210, v210, v212, v214
	v_cvt_pk_bf16_f32 v215, v210, v195
	v_readlane_b32 s41, v206, 44
	v_readlane_b32 s42, v207, 44
	global_store_short v202, v215, s[8:9]
	s_add_u32 s8, s8, s12
	s_addc_u32 s9, s9, s13
	v_add_f32_e32 v211, s44, v209
	v_max_f32_e32 v208, s43, v211
	v_sub_f32_e32 v212, v211, v208
	v_sub_f32_e32 v213, s43, v208
	v_mul_f32_e32 v212, 0x3fb8aa3b, v212
	v_mul_f32_e32 v213, 0x3fb8aa3b, v213
	v_exp_f32_e32 v213, v213
	v_exp_f32_e32 v212, v212
	s_nop 0
	v_mul_f32_e32 v214, v213, v43
	v_fma_f32 v210, v210, v212, v214
	v_cvt_pk_bf16_f32 v215, v210, v195
	v_readlane_b32 s43, v206, 45
	v_readlane_b32 s44, v207, 45
	global_store_short v202, v215, s[8:9]
	s_add_u32 s8, s8, s12
	s_addc_u32 s9, s9, s13
	v_add_f32_e32 v211, s42, v208
	v_max_f32_e32 v209, s41, v211
	v_sub_f32_e32 v212, v211, v209
	v_sub_f32_e32 v213, s41, v209
	v_mul_f32_e32 v212, 0x3fb8aa3b, v212
	v_mul_f32_e32 v213, 0x3fb8aa3b, v213
	v_exp_f32_e32 v213, v213
	v_exp_f32_e32 v212, v212
	s_nop 0
	v_mul_f32_e32 v214, v213, v44
	v_fma_f32 v210, v210, v212, v214
	v_cvt_pk_bf16_f32 v215, v210, v195
	v_readlane_b32 s41, v206, 46
	v_readlane_b32 s42, v207, 46
	global_store_short v202, v215, s[8:9]
	s_add_u32 s8, s8, s12
	s_addc_u32 s9, s9, s13
	v_add_f32_e32 v211, s44, v209
	v_max_f32_e32 v208, s43, v211
	v_sub_f32_e32 v212, v211, v208
	v_sub_f32_e32 v213, s43, v208
	v_mul_f32_e32 v212, 0x3fb8aa3b, v212
	v_mul_f32_e32 v213, 0x3fb8aa3b, v213
	v_exp_f32_e32 v213, v213
	v_exp_f32_e32 v212, v212
	s_nop 0
	v_mul_f32_e32 v214, v213, v45
	v_fma_f32 v210, v210, v212, v214
	v_cvt_pk_bf16_f32 v215, v210, v195
	v_readlane_b32 s43, v206, 47
	v_readlane_b32 s44, v207, 47
	global_store_short v202, v215, s[8:9]
	s_add_u32 s8, s8, s12
	s_addc_u32 s9, s9, s13
	v_add_f32_e32 v211, s42, v208
	v_max_f32_e32 v209, s41, v211
	v_sub_f32_e32 v212, v211, v209
	v_sub_f32_e32 v213, s41, v209
	v_mul_f32_e32 v212, 0x3fb8aa3b, v212
	v_mul_f32_e32 v213, 0x3fb8aa3b, v213
	v_exp_f32_e32 v213, v213
	v_exp_f32_e32 v212, v212
	s_nop 0
	v_mul_f32_e32 v214, v213, v46
	v_fma_f32 v210, v210, v212, v214
	v_cvt_pk_bf16_f32 v215, v210, v195
	v_readlane_b32 s41, v206, 48
	v_readlane_b32 s42, v207, 48
	global_store_short v202, v215, s[8:9]
	s_add_u32 s8, s8, s12
	s_addc_u32 s9, s9, s13
	v_add_f32_e32 v211, s44, v209
	v_max_f32_e32 v208, s43, v211
	v_sub_f32_e32 v212, v211, v208
	v_sub_f32_e32 v213, s43, v208
	v_mul_f32_e32 v212, 0x3fb8aa3b, v212
	v_mul_f32_e32 v213, 0x3fb8aa3b, v213
	v_exp_f32_e32 v213, v213
	v_exp_f32_e32 v212, v212
	s_nop 0
	v_mul_f32_e32 v214, v213, v47
	v_fma_f32 v210, v210, v212, v214
	s_waitcnt vmcnt(48)
; __device__ __forceinline__ bf16_t f2bf(float f) { return (bf16_t)(cvt_pk_bf16(f, 0.f) & 0xffffu); }
; __device__ __forceinline__ void scan_phase(const Bufs& B) {
;     ...
;             for (int u = 0; u < 16; ++u) { const int ch = dir ? 63 - (s0 + u) : s0 + u, it = dh * 64 + ch;
;                 B.CST[(size_t)it * 16384 + idx] = f2bf(cst);
;                 if (idx < 128) { B.NST[(size_t)it * 128 + idx] = nst; if (idx == 0) B.MST[it] = m; }
;                 const float mnew = fmaxf(bl[u] + m, ml[u]), a = __expf(bl[u] + m - mnew), g = __expf(ml[u] - mnew);
;                 cst = a * cst + g * cl[u]; nst = a * nst + g * nl[u]; m = mnew; }
	v_cvt_pk_bf16_f32 v215, v210, v195
	v_readlane_b32 s43, v206, 49
	v_readlane_b32 s44, v207, 49
	global_store_short v202, v215, s[8:9]
	s_add_u32 s8, s8, s12
	s_addc_u32 s9, s9, s13
	v_add_f32_e32 v211, s42, v208
	v_max_f32_e32 v209, s41, v211
	v_sub_f32_e32 v212, v211, v209
	v_sub_f32_e32 v213, s41, v209
	v_mul_f32_e32 v212, 0x3fb8aa3b, v212
	v_mul_f32_e32 v213, 0x3fb8aa3b, v213
	v_exp_f32_e32 v213, v213
	v_exp_f32_e32 v212, v212
	s_nop 0
	v_mul_f32_e32 v214, v213, v48
	v_fma_f32 v210, v210, v212, v214
	v_cvt_pk_bf16_f32 v215, v210, v195
	v_readlane_b32 s41, v206, 50
	v_readlane_b32 s42, v207, 50
	global_store_short v202, v215, s[8:9]
	s_add_u32 s8, s8, s12
	s_addc_u32 s9, s9, s13
	v_add_f32_e32 v211, s44, v209
	v_max_f32_e32 v208, s43, v211
	v_sub_f32_e32 v212, v211, v208
	v_sub_f32_e32 v213, s43, v208
	v_mul_f32_e32 v212, 0x3fb8aa3b, v212
	v_mul_f32_e32 v213, 0x3fb8aa3b, v213
	v_exp_f32_e32 v213, v213
	v_exp_f32_e32 v212, v212
	s_nop 0
	v_mul_f32_e32 v214, v213, v49
	v_fma_f32 v210, v210, v212, v214
	v_cvt_pk_bf16_f32 v215, v210, v195
	v_readlane_b32 s43, v206, 51
	v_readlane_b32 s44, v207, 51
	global_store_short v202, v215, s[8:9]
	s_add_u32 s8, s8, s12
	s_addc_u32 s9, s9, s13
	v_add_f32_e32 v211, s42, v208
	v_max_f32_e32 v209, s41, v211
	v_sub_f32_e32 v212, v211, v209
	v_sub_f32_e32 v213, s41, v209
	v_mul_f32_e32 v212, 0x3fb8aa3b, v212
	v_mul_f32_e32 v213, 0x3fb8aa3b, v213
	v_exp_f32_e32 v213, v213
	v_exp_f32_e32 v212, v212
	s_nop 0
	v_mul_f32_e32 v214, v213, v50
	v_fma_f32 v210, v210, v212, v214
	v_cvt_pk_bf16_f32 v215, v210, v195
	v_readlane_b32 s41, v206, 52
	v_readlane_b32 s42, v207, 52
	global_store_short v202, v215, s[8:9]
	s_add_u32 s8, s8, s12
	s_addc_u32 s9, s9, s13
	v_add_f32_e32 v211, s44, v209
	v_max_f32_e32 v208, s43, v211
	v_sub_f32_e32 v212, v211, v208
	v_sub_f32_e32 v213, s43, v208
	v_mul_f32_e32 v212, 0x3fb8aa3b, v212
	v_mul_f32_e32 v213, 0x3fb8aa3b, v213
	v_exp_f32_e32 v213, v213
	v_exp_f32_e32 v212, v212
	s_nop 0
	v_mul_f32_e32 v214, v213, v51
	v_fma_f32 v210, v210, v212, v214
	v_cvt_pk_bf16_f32 v215, v210, v195
	v_readlane_b32 s43, v206, 53
	v_readlane_b32 s44, v207, 53
	global_store_short v202, v215, s[8:9]
	s_add_u32 s8, s8, s12
	s_addc_u32 s9, s9, s13
	v_add_f32_e32 v211, s42, v208
	v_max_f32_e32 v209, s41, v211
	v_sub_f32_e32 v212, v211, v209
	v_sub_f32_e32 v213, s41, v209
	v_mul_f32_e32 v212, 0x3fb8aa3b, v212
	v_mul_f32_e32 v213, 0x3fb8aa3b, v213
	v_exp_f32_e32 v213, v213
	v_exp_f32_e32 v212, v212
	s_nop 0
	v_mul_f32_e32 v214, v213, v52
	v_fma_f32 v210, v210, v212, v214
	v_cvt_pk_bf16_f32 v215, v210, v195
	v_readlane_b32 s41, v206, 54
	v_readlane_b32 s42, v207, 54
	global_store_short v202, v215, s[8:9]
	s_add_u32 s8, s8, s12
	s_addc_u32 s9, s9, s13
	v_add_f32_e32 v211, s44, v209
	v_max_f32_e32 v208, s43, v211
	v_sub_f32_e32 v212, v211, v208
	v_sub_f32_e32 v213, s43, v208
	v_mul_f32_e32 v212, 0x3fb8aa3b, v212
	v_mul_f32_e32 v213, 0x3fb8aa3b, v213
	v_exp_f32_e32 v213, v213
	v_exp_f32_e32 v212, v212
	s_nop 0
	v_mul_f32_e32 v214, v213, v53
	v_fma_f32 v210, v210, v212, v214
	v_cvt_pk_bf16_f32 v215, v210, v195
	v_readlane_b32 s43, v206, 55
	v_readlane_b32 s44, v207, 55
	global_store_short v202, v215, s[8:9]
	s_add_u32 s8, s8, s12
	s_addc_u32 s9, s9, s13
	v_add_f32_e32 v211, s42, v208
	v_max_f32_e32 v209, s41, v211
	v_sub_f32_e32 v212, v211, v209
	v_sub_f32_e32 v213, s41, v209
	v_mul_f32_e32 v212, 0x3fb8aa3b, v212
	v_mul_f32_e32 v213, 0x3fb8aa3b, v213
	v_exp_f32_e32 v213, v213
	v_exp_f32_e32 v212, v212
	s_nop 0
	v_mul_f32_e32 v214, v213, v54
	v_fma_f32 v210, v210, v212, v214
	v_cvt_pk_bf16_f32 v215, v210, v195
	v_readlane_b32 s41, v206, 56
	v_readlane_b32 s42, v207, 56
	global_store_short v202, v215, s[8:9]
	s_add_u32 s8, s8, s12
	s_addc_u32 s9, s9, s13
	v_add_f32_e32 v211, s44, v209
	v_max_f32_e32 v208, s43, v211
	v_sub_f32_e32 v212, v211, v208
	v_sub_f32_e32 v213, s43, v208
	v_mul_f32_e32 v212, 0x3fb8aa3b, v212
	v_mul_f32_e32 v213, 0x3fb8aa3b, v213
	v_exp_f32_e32 v213, v213
	v_exp_f32_e32 v212, v212
	s_nop 0
	v_mul_f32_e32 v214, v213, v55
	v_fma_f32 v210, v210, v212, v214
	v_cvt_pk_bf16_f32 v215, v210, v195
	v_readlane_b32 s43, v206, 57
	v_readlane_b32 s44, v207, 57
	global_store_short v202, v215, s[8:9]
	s_add_u32 s8, s8, s12
	s_addc_u32 s9, s9, s13
	v_add_f32_e32 v211, s42, v208
	v_max_f32_e32 v209, s41, v211
	v_sub_f32_e32 v212, v211, v209
	v_sub_f32_e32 v213, s41, v209
	v_mul_f32_e32 v212, 0x3fb8aa3b, v212
	v_mul_f32_e32 v213, 0x3fb8aa3b, v213
	v_exp_f32_e32 v213, v213
	v_exp_f32_e32 v212, v212
	s_nop 0
	v_mul_f32_e32 v214, v213, v56
	v_fma_f32 v210, v210, v212, v214
	v_cvt_pk_bf16_f32 v215, v210, v195
	v_readlane_b32 s41, v206, 58
	v_readlane_b32 s42, v207, 58
	global_store_short v202, v215, s[8:9]
	s_add_u32 s8, s8, s12
	s_addc_u32 s9, s9, s13
	v_add_f32_e32 v211, s44, v209
	v_max_f32_e32 v208, s43, v211
	v_sub_f32_e32 v212, v211, v208
	v_sub_f32_e32 v213, s43, v208
	v_mul_f32_e32 v212, 0x3fb8aa3b, v212
	v_mul_f32_e32 v213, 0x3fb8aa3b, v213
	v_exp_f32_e32 v213, v213
	v_exp_f32_e32 v212, v212
	s_nop 0
	v_mul_f32_e32 v214, v213, v57
	v_fma_f32 v210, v210, v212, v214
	v_cvt_pk_bf16_f32 v215, v210, v195
	v_readlane_b32 s43, v206, 59
	v_readlane_b32 s44, v207, 59
	global_store_short v202, v215, s[8:9]
	s_add_u32 s8, s8, s12
	s_addc_u32 s9, s9, s13
	v_add_f32_e32 v211, s42, v208
	v_max_f32_e32 v209, s41, v211
	v_sub_f32_e32 v212, v211, v209
	v_sub_f32_e32 v213, s41, v209
	v_mul_f32_e32 v212, 0x3fb8aa3b, v212
	v_mul_f32_e32 v213, 0x3fb8aa3b, v213
	v_exp_f32_e32 v213, v213
	v_exp_f32_e32 v212, v212
	s_nop 0
	v_mul_f32_e32 v214, v213, v58
	v_fma_f32 v210, v210, v212, v214
	v_cvt_pk_bf16_f32 v215, v210, v195
; __device__ __forceinline__ bf16_t f2bf(float f) { return (bf16_t)(cvt_pk_bf16(f, 0.f) & 0xffffu); }
; __device__ __forceinline__ void scan_phase(const Bufs& B) {
;     ...
;             for (int u = 0; u < 16; ++u) { const int ch = dir ? 63 - (s0 + u) : s0 + u, it = dh * 64 + ch;
;                 cl[u] = B.CLOC[(size_t)it * 16384 + idx]; ml[u] = B.MLOC[it]; bl[u] = B.BLAST[it]; nl[u] = idx < 128 ? B.NLOC[(size_t)it * 128 + idx] : 0.f; }
;     ...
;             for (int u = 0; u < 16; ++u) { const int ch = dir ? 63 - (s0 + u) : s0 + u, it = dh * 64 + ch;
;                 B.CST[(size_t)it * 16384 + idx] = f2bf(cst);
;                 if (idx < 128) { B.NST[(size_t)it * 128 + idx] = nst; if (idx == 0) B.MST[it] = m; }
;                 const float mnew = fmaxf(bl[u] + m, ml[u]), a = __expf(bl[u] + m - mnew), g = __expf(ml[u] - mnew);
;                 cst = a * cst + g * cl[u]; nst = a * nst + g * nl[u]; m = mnew; }
	v_readlane_b32 s41, v206, 60
	v_readlane_b32 s42, v207, 60
	global_store_short v202, v215, s[8:9]
	s_add_u32 s8, s8, s12
	s_addc_u32 s9, s9, s13
	v_add_f32_e32 v211, s44, v209
	v_max_f32_e32 v208, s43, v211
	v_sub_f32_e32 v212, v211, v208
	v_sub_f32_e32 v213, s43, v208
	v_mul_f32_e32 v212, 0x3fb8aa3b, v212
	v_mul_f32_e32 v213, 0x3fb8aa3b, v213
	v_exp_f32_e32 v213, v213
	v_exp_f32_e32 v212, v212
	s_nop 0
	v_mul_f32_e32 v214, v213, v59
	v_fma_f32 v210, v210, v212, v214
	v_cvt_pk_bf16_f32 v215, v210, v195
	v_readlane_b32 s43, v206, 61
	v_readlane_b32 s44, v207, 61
	global_store_short v202, v215, s[8:9]
	s_add_u32 s8, s8, s12
	s_addc_u32 s9, s9, s13
	v_add_f32_e32 v211, s42, v208
	v_max_f32_e32 v209, s41, v211
	v_sub_f32_e32 v212, v211, v209
	v_sub_f32_e32 v213, s41, v209
	v_mul_f32_e32 v212, 0x3fb8aa3b, v212
	v_mul_f32_e32 v213, 0x3fb8aa3b, v213
	v_exp_f32_e32 v213, v213
	v_exp_f32_e32 v212, v212
	s_nop 0
	v_mul_f32_e32 v214, v213, v60
	v_fma_f32 v210, v210, v212, v214
	v_cvt_pk_bf16_f32 v215, v210, v195
	v_readlane_b32 s41, v206, 62
	v_readlane_b32 s42, v207, 62
	global_store_short v202, v215, s[8:9]
	s_add_u32 s8, s8, s12
	s_addc_u32 s9, s9, s13
	v_add_f32_e32 v211, s44, v209
	v_max_f32_e32 v208, s43, v211
	v_sub_f32_e32 v212, v211, v208
	v_sub_f32_e32 v213, s43, v208
	v_mul_f32_e32 v212, 0x3fb8aa3b, v212
	v_mul_f32_e32 v213, 0x3fb8aa3b, v213
	v_exp_f32_e32 v213, v213
	v_exp_f32_e32 v212, v212
	s_nop 0
	v_mul_f32_e32 v214, v213, v61
	v_fma_f32 v210, v210, v212, v214
	v_cvt_pk_bf16_f32 v215, v210, v195
	v_readlane_b32 s43, v206, 63
	v_readlane_b32 s44, v207, 63
	global_store_short v202, v215, s[8:9]
	s_add_u32 s8, s8, s12
	s_addc_u32 s9, s9, s13
	v_add_f32_e32 v211, s42, v208
	v_max_f32_e32 v209, s41, v211
	v_sub_f32_e32 v212, v211, v209
	v_sub_f32_e32 v213, s41, v209
	v_mul_f32_e32 v212, 0x3fb8aa3b, v212
	v_mul_f32_e32 v213, 0x3fb8aa3b, v213
	v_exp_f32_e32 v213, v213
	v_exp_f32_e32 v212, v212
	s_nop 0
	v_mul_f32_e32 v214, v213, v62
	v_fma_f32 v210, v210, v212, v214
	v_cvt_pk_bf16_f32 v215, v210, v195
	global_store_short v202, v215, s[8:9]
	s_add_u32 s8, s8, s12
	s_addc_u32 s9, s9, s13
	v_add_f32_e32 v211, s44, v209
	v_max_f32_e32 v208, s43, v211
	v_sub_f32_e32 v212, v211, v208
	v_sub_f32_e32 v213, s43, v208
	v_mul_f32_e32 v212, 0x3fb8aa3b, v212
	v_mul_f32_e32 v213, 0x3fb8aa3b, v213
	v_exp_f32_e32 v213, v213
	v_exp_f32_e32 v212, v212
	s_nop 0
	v_mul_f32_e32 v214, v213, v63
	v_fma_f32 v210, v210, v212, v214
	s_branch .Lscan_done
.Lscan_v11:
	global_load_dword v206, v222, s[50:51]
	global_load_dword v207, v222, s[50:51] offset:2048
	global_load_dword v0, v201, s[6:7]
	s_add_u32 s6, s6, s10
	s_addc_u32 s7, s7, s11
	global_load_dword v128, v205, s[22:23]
	s_add_u32 s22, s22, s28
	s_addc_u32 s23, s23, s29
	global_load_dword v1, v201, s[6:7]
	s_add_u32 s6, s6, s10
	s_addc_u32 s7, s7, s11
	global_load_dword v129, v205, s[22:23]
	s_add_u32 s22, s22, s28
	s_addc_u32 s23, s23, s29
	global_load_dword v2, v201, s[6:7]
	s_add_u32 s6, s6, s10
	s_addc_u32 s7, s7, s11
	global_load_dword v130, v205, s[22:23]
	s_add_u32 s22, s22, s28
	s_addc_u32 s23, s23, s29
	global_load_dword v3, v201, s[6:7]
	s_add_u32 s6, s6, s10
	s_addc_u32 s7, s7, s11
	global_load_dword v131, v205, s[22:23]
	s_add_u32 s22, s22, s28
	s_addc_u32 s23, s23, s29
	global_load_dword v4, v201, s[6:7]
	s_add_u32 s6, s6, s10
	s_addc_u32 s7, s7, s11
	global_load_dword v132, v205, s[22:23]
	s_add_u32 s22, s22, s28
	s_addc_u32 s23, s23, s29
	global_load_dword v5, v201, s[6:7]
	s_add_u32 s6, s6, s10
	s_addc_u32 s7, s7, s11
	global_load_dword v133, v205, s[22:23]
	s_add_u32 s22, s22, s28
	s_addc_u32 s23, s23, s29
	global_load_dword v6, v201, s[6:7]
	s_add_u32 s6, s6, s10
	s_addc_u32 s7, s7, s11
	global_load_dword v134, v205, s[22:23]
	s_add_u32 s22, s22, s28
	s_addc_u32 s23, s23, s29
	global_load_dword v7, v201, s[6:7]
	s_add_u32 s6, s6, s10
	s_addc_u32 s7, s7, s11
	global_load_dword v135, v205, s[22:23]
	s_add_u32 s22, s22, s28
	s_addc_u32 s23, s23, s29
	global_load_dword v8, v201, s[6:7]
	s_add_u32 s6, s6, s10
	s_addc_u32 s7, s7, s11
	global_load_dword v136, v205, s[22:23]
	s_add_u32 s22, s22, s28
	s_addc_u32 s23, s23, s29
	global_load_dword v9, v201, s[6:7]
	s_add_u32 s6, s6, s10
	s_addc_u32 s7, s7, s11
	global_load_dword v137, v205, s[22:23]
	s_add_u32 s22, s22, s28
	s_addc_u32 s23, s23, s29
	global_load_dword v10, v201, s[6:7]
	s_add_u32 s6, s6, s10
	s_addc_u32 s7, s7, s11
	global_load_dword v138, v205, s[22:23]
	s_add_u32 s22, s22, s28
	s_addc_u32 s23, s23, s29
	global_load_dword v11, v201, s[6:7]
	s_add_u32 s6, s6, s10
	s_addc_u32 s7, s7, s11
	global_load_dword v139, v205, s[22:23]
	s_add_u32 s22, s22, s28
	s_addc_u32 s23, s23, s29
	global_load_dword v12, v201, s[6:7]
	s_add_u32 s6, s6, s10
	s_addc_u32 s7, s7, s11
	global_load_dword v140, v205, s[22:23]
	s_add_u32 s22, s22, s28
	s_addc_u32 s23, s23, s29
	global_load_dword v13, v201, s[6:7]
	s_add_u32 s6, s6, s10
	s_addc_u32 s7, s7, s11
	global_load_dword v141, v205, s[22:23]
	s_add_u32 s22, s22, s28
	s_addc_u32 s23, s23, s29
	global_load_dword v14, v201, s[6:7]
	s_add_u32 s6, s6, s10
	s_addc_u32 s7, s7, s11
	global_load_dword v142, v205, s[22:23]
	s_add_u32 s22, s22, s28
	s_addc_u32 s23, s23, s29
	global_load_dword v15, v201, s[6:7]
	s_add_u32 s6, s6, s10
	s_addc_u32 s7, s7, s11
	global_load_dword v143, v205, s[22:23]
	s_add_u32 s22, s22, s28
	s_addc_u32 s23, s23, s29
	global_load_dword v16, v201, s[6:7]
	s_add_u32 s6, s6, s10
	s_addc_u32 s7, s7, s11
	global_load_dword v144, v205, s[22:23]
	s_add_u32 s22, s22, s28
	s_addc_u32 s23, s23, s29
	global_load_dword v17, v201, s[6:7]
	s_add_u32 s6, s6, s10
	s_addc_u32 s7, s7, s11
; __device__ __forceinline__ void scan_phase(const Bufs& B) {
;     ...
;             for (int u = 0; u < 16; ++u) { const int ch = dir ? 63 - (s0 + u) : s0 + u, it = dh * 64 + ch;
;                 cl[u] = B.CLOC[(size_t)it * 16384 + idx]; ml[u] = B.MLOC[it]; bl[u] = B.BLAST[it]; nl[u] = idx < 128 ? B.NLOC[(size_t)it * 128 + idx] : 0.f; }
	global_load_dword v145, v205, s[22:23]
	s_add_u32 s22, s22, s28
	s_addc_u32 s23, s23, s29
	global_load_dword v18, v201, s[6:7]
	s_add_u32 s6, s6, s10
	s_addc_u32 s7, s7, s11
	global_load_dword v146, v205, s[22:23]
	s_add_u32 s22, s22, s28
	s_addc_u32 s23, s23, s29
	global_load_dword v19, v201, s[6:7]
	s_add_u32 s6, s6, s10
	s_addc_u32 s7, s7, s11
	global_load_dword v147, v205, s[22:23]
	s_add_u32 s22, s22, s28
	s_addc_u32 s23, s23, s29
	global_load_dword v20, v201, s[6:7]
	s_add_u32 s6, s6, s10
	s_addc_u32 s7, s7, s11
	global_load_dword v148, v205, s[22:23]
	s_add_u32 s22, s22, s28
	s_addc_u32 s23, s23, s29
	global_load_dword v21, v201, s[6:7]
	s_add_u32 s6, s6, s10
	s_addc_u32 s7, s7, s11
	global_load_dword v149, v205, s[22:23]
	s_add_u32 s22, s22, s28
	s_addc_u32 s23, s23, s29
	global_load_dword v22, v201, s[6:7]
	s_add_u32 s6, s6, s10
	s_addc_u32 s7, s7, s11
	global_load_dword v150, v205, s[22:23]
	s_add_u32 s22, s22, s28
	s_addc_u32 s23, s23, s29
	global_load_dword v23, v201, s[6:7]
	s_add_u32 s6, s6, s10
	s_addc_u32 s7, s7, s11
	global_load_dword v151, v205, s[22:23]
	s_add_u32 s22, s22, s28
	s_addc_u32 s23, s23, s29
	global_load_dword v24, v201, s[6:7]
	s_add_u32 s6, s6, s10
	s_addc_u32 s7, s7, s11
	global_load_dword v152, v205, s[22:23]
	s_add_u32 s22, s22, s28
	s_addc_u32 s23, s23, s29
	global_load_dword v25, v201, s[6:7]
	s_add_u32 s6, s6, s10
	s_addc_u32 s7, s7, s11
	global_load_dword v153, v205, s[22:23]
	s_add_u32 s22, s22, s28
	s_addc_u32 s23, s23, s29
	global_load_dword v26, v201, s[6:7]
	s_add_u32 s6, s6, s10
	s_addc_u32 s7, s7, s11
	global_load_dword v154, v205, s[22:23]
	s_add_u32 s22, s22, s28
	s_addc_u32 s23, s23, s29
	global_load_dword v27, v201, s[6:7]
	s_add_u32 s6, s6, s10
	s_addc_u32 s7, s7, s11
	global_load_dword v155, v205, s[22:23]
	s_add_u32 s22, s22, s28
	s_addc_u32 s23, s23, s29
	global_load_dword v28, v201, s[6:7]
	s_add_u32 s6, s6, s10
	s_addc_u32 s7, s7, s11
	global_load_dword v156, v205, s[22:23]
	s_add_u32 s22, s22, s28
	s_addc_u32 s23, s23, s29
	global_load_dword v29, v201, s[6:7]
	s_add_u32 s6, s6, s10
	s_addc_u32 s7, s7, s11
	global_load_dword v157, v205, s[22:23]
	s_add_u32 s22, s22, s28
	s_addc_u32 s23, s23, s29
	global_load_dword v30, v201, s[6:7]
	s_add_u32 s6, s6, s10
	s_addc_u32 s7, s7, s11
	global_load_dword v158, v205, s[22:23]
	s_add_u32 s22, s22, s28
	s_addc_u32 s23, s23, s29
	global_load_dword v31, v201, s[6:7]
	s_add_u32 s6, s6, s10
	s_addc_u32 s7, s7, s11
	global_load_dword v159, v205, s[22:23]
	s_add_u32 s22, s22, s28
	s_addc_u32 s23, s23, s29
	global_load_dword v32, v201, s[6:7]
	s_add_u32 s6, s6, s10
	s_addc_u32 s7, s7, s11
	global_load_dword v160, v205, s[22:23]
	s_add_u32 s22, s22, s28
	s_addc_u32 s23, s23, s29
	global_load_dword v33, v201, s[6:7]
	s_add_u32 s6, s6, s10
	s_addc_u32 s7, s7, s11
	global_load_dword v161, v205, s[22:23]
	s_add_u32 s22, s22, s28
	s_addc_u32 s23, s23, s29
	global_load_dword v34, v201, s[6:7]
	s_add_u32 s6, s6, s10
	s_addc_u32 s7, s7, s11
	global_load_dword v162, v205, s[22:23]
	s_add_u32 s22, s22, s28
	s_addc_u32 s23, s23, s29
	global_load_dword v35, v201, s[6:7]
	s_add_u32 s6, s6, s10
	s_addc_u32 s7, s7, s11
	global_load_dword v163, v205, s[22:23]
	s_add_u32 s22, s22, s28
	s_addc_u32 s23, s23, s29
	global_load_dword v36, v201, s[6:7]
	s_add_u32 s6, s6, s10
	s_addc_u32 s7, s7, s11
	global_load_dword v164, v205, s[22:23]
	s_add_u32 s22, s22, s28
	s_addc_u32 s23, s23, s29
	global_load_dword v37, v201, s[6:7]
	s_add_u32 s6, s6, s10
	s_addc_u32 s7, s7, s11
	global_load_dword v165, v205, s[22:23]
	s_add_u32 s22, s22, s28
	s_addc_u32 s23, s23, s29
	global_load_dword v38, v201, s[6:7]
	s_add_u32 s6, s6, s10
	s_addc_u32 s7, s7, s11
	global_load_dword v166, v205, s[22:23]
	s_add_u32 s22, s22, s28
	s_addc_u32 s23, s23, s29
	global_load_dword v39, v201, s[6:7]
	s_add_u32 s6, s6, s10
	s_addc_u32 s7, s7, s11
	global_load_dword v167, v205, s[22:23]
	s_add_u32 s22, s22, s28
	s_addc_u32 s23, s23, s29
	global_load_dword v40, v201, s[6:7]
	s_add_u32 s6, s6, s10
	s_addc_u32 s7, s7, s11
	global_load_dword v168, v205, s[22:23]
	s_add_u32 s22, s22, s28
	s_addc_u32 s23, s23, s29
	global_load_dword v41, v201, s[6:7]
	s_add_u32 s6, s6, s10
	s_addc_u32 s7, s7, s11
	global_load_dword v169, v205, s[22:23]
	s_add_u32 s22, s22, s28
	s_addc_u32 s23, s23, s29
	global_load_dword v42, v201, s[6:7]
	s_add_u32 s6, s6, s10
	s_addc_u32 s7, s7, s11
	global_load_dword v170, v205, s[22:23]
	s_add_u32 s22, s22, s28
	s_addc_u32 s23, s23, s29
	global_load_dword v43, v201, s[6:7]
	s_add_u32 s6, s6, s10
	s_addc_u32 s7, s7, s11
	global_load_dword v171, v205, s[22:23]
	s_add_u32 s22, s22, s28
	s_addc_u32 s23, s23, s29
	global_load_dword v44, v201, s[6:7]
	s_add_u32 s6, s6, s10
	s_addc_u32 s7, s7, s11
	global_load_dword v172, v205, s[22:23]
	s_add_u32 s22, s22, s28
	s_addc_u32 s23, s23, s29
	global_load_dword v45, v201, s[6:7]
	s_add_u32 s6, s6, s10
	s_addc_u32 s7, s7, s11
	global_load_dword v173, v205, s[22:23]
	s_add_u32 s22, s22, s28
	s_addc_u32 s23, s23, s29
	global_load_dword v46, v201, s[6:7]
	s_add_u32 s6, s6, s10
	s_addc_u32 s7, s7, s11
	global_load_dword v174, v205, s[22:23]
	s_add_u32 s22, s22, s28
	s_addc_u32 s23, s23, s29
	global_load_dword v47, v201, s[6:7]
	s_add_u32 s6, s6, s10
	s_addc_u32 s7, s7, s11
	global_load_dword v175, v205, s[22:23]
	s_add_u32 s22, s22, s28
	s_addc_u32 s23, s23, s29
	global_load_dword v48, v201, s[6:7]
	s_add_u32 s6, s6, s10
	s_addc_u32 s7, s7, s11
	global_load_dword v176, v205, s[22:23]
	s_add_u32 s22, s22, s28
	s_addc_u32 s23, s23, s29
	global_load_dword v49, v201, s[6:7]
	s_add_u32 s6, s6, s10
	s_addc_u32 s7, s7, s11
	global_load_dword v177, v205, s[22:23]
; __device__ __forceinline__ void scan_phase(const Bufs& B) {
;     ...
;             for (int u = 0; u < 16; ++u) { const int ch = dir ? 63 - (s0 + u) : s0 + u, it = dh * 64 + ch;
;                 cl[u] = B.CLOC[(size_t)it * 16384 + idx]; ml[u] = B.MLOC[it]; bl[u] = B.BLAST[it]; nl[u] = idx < 128 ? B.NLOC[(size_t)it * 128 + idx] : 0.f; }
;     ...
;             for (int u = 0; u < 16; ++u) { const int ch = dir ? 63 - (s0 + u) : s0 + u; rl[u] = B.RLOC[(size_t)(dh * 64 + ch) * 8192 + idx]; }
	s_add_u32 s22, s22, s28
	s_addc_u32 s23, s23, s29
	global_load_dword v50, v201, s[6:7]
	s_add_u32 s6, s6, s10
	s_addc_u32 s7, s7, s11
	global_load_dword v178, v205, s[22:23]
	s_add_u32 s22, s22, s28
	s_addc_u32 s23, s23, s29
	global_load_dword v51, v201, s[6:7]
	s_add_u32 s6, s6, s10
	s_addc_u32 s7, s7, s11
	global_load_dword v179, v205, s[22:23]
	s_add_u32 s22, s22, s28
	s_addc_u32 s23, s23, s29
	global_load_dword v52, v201, s[6:7]
	s_add_u32 s6, s6, s10
	s_addc_u32 s7, s7, s11
	global_load_dword v180, v205, s[22:23]
	s_add_u32 s22, s22, s28
	s_addc_u32 s23, s23, s29
	global_load_dword v53, v201, s[6:7]
	s_add_u32 s6, s6, s10
	s_addc_u32 s7, s7, s11
	global_load_dword v181, v205, s[22:23]
	s_add_u32 s22, s22, s28
	s_addc_u32 s23, s23, s29
	global_load_dword v54, v201, s[6:7]
	s_add_u32 s6, s6, s10
	s_addc_u32 s7, s7, s11
	global_load_dword v182, v205, s[22:23]
	s_add_u32 s22, s22, s28
	s_addc_u32 s23, s23, s29
	global_load_dword v55, v201, s[6:7]
	s_add_u32 s6, s6, s10
	s_addc_u32 s7, s7, s11
	global_load_dword v183, v205, s[22:23]
	s_add_u32 s22, s22, s28
	s_addc_u32 s23, s23, s29
	global_load_dword v56, v201, s[6:7]
	s_add_u32 s6, s6, s10
	s_addc_u32 s7, s7, s11
	global_load_dword v184, v205, s[22:23]
	s_add_u32 s22, s22, s28
	s_addc_u32 s23, s23, s29
	global_load_dword v57, v201, s[6:7]
	s_add_u32 s6, s6, s10
	s_addc_u32 s7, s7, s11
	global_load_dword v185, v205, s[22:23]
	s_add_u32 s22, s22, s28
	s_addc_u32 s23, s23, s29
	global_load_dword v58, v201, s[6:7]
	s_add_u32 s6, s6, s10
	s_addc_u32 s7, s7, s11
	global_load_dword v186, v205, s[22:23]
	s_add_u32 s22, s22, s28
	s_addc_u32 s23, s23, s29
	global_load_dword v59, v201, s[6:7]
	s_add_u32 s6, s6, s10
	s_addc_u32 s7, s7, s11
	global_load_dword v187, v205, s[22:23]
	s_add_u32 s22, s22, s28
	s_addc_u32 s23, s23, s29
	global_load_dword v60, v201, s[6:7]
	s_add_u32 s6, s6, s10
	s_addc_u32 s7, s7, s11
	global_load_dword v188, v205, s[22:23]
	s_add_u32 s22, s22, s28
	s_addc_u32 s23, s23, s29
	global_load_dword v61, v201, s[6:7]
	s_add_u32 s6, s6, s10
	s_addc_u32 s7, s7, s11
	global_load_dword v189, v205, s[22:23]
	s_add_u32 s22, s22, s28
	s_addc_u32 s23, s23, s29
	global_load_dword v62, v201, s[6:7]
	s_add_u32 s6, s6, s10
	s_addc_u32 s7, s7, s11
	global_load_dword v190, v205, s[22:23]
	s_add_u32 s22, s22, s28
	s_addc_u32 s23, s23, s29
	global_load_dword v63, v201, s[6:7]
	s_add_u32 s6, s6, s10
	s_addc_u32 s7, s7, s11
	global_load_dword v191, v205, s[22:23]
	s_add_u32 s22, s22, s28
	s_addc_u32 s23, s23, s29
	global_load_dword v64, v203, s[14:15]
	s_add_u32 s14, s14, s18
	s_addc_u32 s15, s15, s19
	global_load_dword v65, v203, s[14:15]
	s_add_u32 s14, s14, s18
	s_addc_u32 s15, s15, s19
	global_load_dword v66, v203, s[14:15]
	s_add_u32 s14, s14, s18
	s_addc_u32 s15, s15, s19
	global_load_dword v67, v203, s[14:15]
	s_add_u32 s14, s14, s18
	s_addc_u32 s15, s15, s19
	global_load_dword v68, v203, s[14:15]
	s_add_u32 s14, s14, s18
	s_addc_u32 s15, s15, s19
	global_load_dword v69, v203, s[14:15]
	s_add_u32 s14, s14, s18
	s_addc_u32 s15, s15, s19
	global_load_dword v70, v203, s[14:15]
	s_add_u32 s14, s14, s18
	s_addc_u32 s15, s15, s19
	global_load_dword v71, v203, s[14:15]
	s_add_u32 s14, s14, s18
	s_addc_u32 s15, s15, s19
	global_load_dword v72, v203, s[14:15]
	s_add_u32 s14, s14, s18
	s_addc_u32 s15, s15, s19
	global_load_dword v73, v203, s[14:15]
	s_add_u32 s14, s14, s18
	s_addc_u32 s15, s15, s19
	global_load_dword v74, v203, s[14:15]
	s_add_u32 s14, s14, s18
	s_addc_u32 s15, s15, s19
	global_load_dword v75, v203, s[14:15]
	s_add_u32 s14, s14, s18
	s_addc_u32 s15, s15, s19
	global_load_dword v76, v203, s[14:15]
	s_add_u32 s14, s14, s18
	s_addc_u32 s15, s15, s19
	global_load_dword v77, v203, s[14:15]
	s_add_u32 s14, s14, s18
	s_addc_u32 s15, s15, s19
	global_load_dword v78, v203, s[14:15]
	s_add_u32 s14, s14, s18
	s_addc_u32 s15, s15, s19
	global_load_dword v79, v203, s[14:15]
	s_add_u32 s14, s14, s18
	s_addc_u32 s15, s15, s19
	global_load_dword v80, v203, s[14:15]
	s_add_u32 s14, s14, s18
	s_addc_u32 s15, s15, s19
	global_load_dword v81, v203, s[14:15]
	s_add_u32 s14, s14, s18
	s_addc_u32 s15, s15, s19
	global_load_dword v82, v203, s[14:15]
	s_add_u32 s14, s14, s18
	s_addc_u32 s15, s15, s19
	global_load_dword v83, v203, s[14:15]
	s_add_u32 s14, s14, s18
	s_addc_u32 s15, s15, s19
	global_load_dword v84, v203, s[14:15]
	s_add_u32 s14, s14, s18
	s_addc_u32 s15, s15, s19
	global_load_dword v85, v203, s[14:15]
	s_add_u32 s14, s14, s18
	s_addc_u32 s15, s15, s19
	global_load_dword v86, v203, s[14:15]
	s_add_u32 s14, s14, s18
	s_addc_u32 s15, s15, s19
	global_load_dword v87, v203, s[14:15]
	s_add_u32 s14, s14, s18
	s_addc_u32 s15, s15, s19
	global_load_dword v88, v203, s[14:15]
	s_add_u32 s14, s14, s18
	s_addc_u32 s15, s15, s19
	global_load_dword v89, v203, s[14:15]
	s_add_u32 s14, s14, s18
	s_addc_u32 s15, s15, s19
	global_load_dword v90, v203, s[14:15]
	s_add_u32 s14, s14, s18
	s_addc_u32 s15, s15, s19
	global_load_dword v91, v203, s[14:15]
	s_add_u32 s14, s14, s18
	s_addc_u32 s15, s15, s19
	global_load_dword v92, v203, s[14:15]
	s_add_u32 s14, s14, s18
	s_addc_u32 s15, s15, s19
	global_load_dword v93, v203, s[14:15]
	s_add_u32 s14, s14, s18
	s_addc_u32 s15, s15, s19
	global_load_dword v94, v203, s[14:15]
	s_add_u32 s14, s14, s18
	s_addc_u32 s15, s15, s19
	global_load_dword v95, v203, s[14:15]
	s_add_u32 s14, s14, s18
	s_addc_u32 s15, s15, s19
	global_load_dword v96, v203, s[14:15]
	s_add_u32 s14, s14, s18
	s_addc_u32 s15, s15, s19
	global_load_dword v97, v203, s[14:15]
	s_add_u32 s14, s14, s18
	s_addc_u32 s15, s15, s19
	global_load_dword v98, v203, s[14:15]
	s_add_u32 s14, s14, s18
	s_addc_u32 s15, s15, s19
; __device__ __forceinline__ bf16_t f2bf(float f) { return (bf16_t)(cvt_pk_bf16(f, 0.f) & 0xffffu); }
; __device__ __forceinline__ void scan_phase(const Bufs& B) {
;     ...
;                 B.CST[(size_t)it * 16384 + idx] = f2bf(cst);
;                 if (idx < 128) { B.NST[(size_t)it * 128 + idx] = nst; if (idx == 0) B.MST[it] = m; }
;                 const float mnew = fmaxf(bl[u] + m, ml[u]), a = __expf(bl[u] + m - mnew), g = __expf(ml[u] - mnew);
;                 cst = a * cst + g * cl[u]; nst = a * nst + g * nl[u]; m = mnew; }
	global_load_dword v99, v203, s[14:15]
	s_add_u32 s14, s14, s18
	s_addc_u32 s15, s15, s19
	global_load_dword v100, v203, s[14:15]
	s_add_u32 s14, s14, s18
	s_addc_u32 s15, s15, s19
	global_load_dword v101, v203, s[14:15]
	s_add_u32 s14, s14, s18
	s_addc_u32 s15, s15, s19
	global_load_dword v102, v203, s[14:15]
	s_add_u32 s14, s14, s18
	s_addc_u32 s15, s15, s19
	global_load_dword v103, v203, s[14:15]
	s_add_u32 s14, s14, s18
	s_addc_u32 s15, s15, s19
	global_load_dword v104, v203, s[14:15]
	s_add_u32 s14, s14, s18
	s_addc_u32 s15, s15, s19
	global_load_dword v105, v203, s[14:15]
	s_add_u32 s14, s14, s18
	s_addc_u32 s15, s15, s19
	global_load_dword v106, v203, s[14:15]
	s_add_u32 s14, s14, s18
	s_addc_u32 s15, s15, s19
	global_load_dword v107, v203, s[14:15]
	s_add_u32 s14, s14, s18
	s_addc_u32 s15, s15, s19
	global_load_dword v108, v203, s[14:15]
	s_add_u32 s14, s14, s18
	s_addc_u32 s15, s15, s19
	global_load_dword v109, v203, s[14:15]
	s_add_u32 s14, s14, s18
	s_addc_u32 s15, s15, s19
	global_load_dword v110, v203, s[14:15]
	s_add_u32 s14, s14, s18
	s_addc_u32 s15, s15, s19
	global_load_dword v111, v203, s[14:15]
	s_add_u32 s14, s14, s18
	s_addc_u32 s15, s15, s19
	global_load_dword v112, v203, s[14:15]
	s_add_u32 s14, s14, s18
	s_addc_u32 s15, s15, s19
	global_load_dword v113, v203, s[14:15]
	s_add_u32 s14, s14, s18
	s_addc_u32 s15, s15, s19
	global_load_dword v114, v203, s[14:15]
	s_add_u32 s14, s14, s18
	s_addc_u32 s15, s15, s19
	global_load_dword v115, v203, s[14:15]
	s_add_u32 s14, s14, s18
	s_addc_u32 s15, s15, s19
	global_load_dword v116, v203, s[14:15]
	s_add_u32 s14, s14, s18
	s_addc_u32 s15, s15, s19
	global_load_dword v117, v203, s[14:15]
	s_add_u32 s14, s14, s18
	s_addc_u32 s15, s15, s19
	global_load_dword v118, v203, s[14:15]
	s_add_u32 s14, s14, s18
	s_addc_u32 s15, s15, s19
	global_load_dword v119, v203, s[14:15]
	s_add_u32 s14, s14, s18
	s_addc_u32 s15, s15, s19
	global_load_dword v120, v203, s[14:15]
	s_add_u32 s14, s14, s18
	s_addc_u32 s15, s15, s19
	global_load_dword v121, v203, s[14:15]
	s_add_u32 s14, s14, s18
	s_addc_u32 s15, s15, s19
	global_load_dword v122, v203, s[14:15]
	s_add_u32 s14, s14, s18
	s_addc_u32 s15, s15, s19
	global_load_dword v123, v203, s[14:15]
	s_add_u32 s14, s14, s18
	s_addc_u32 s15, s15, s19
	global_load_dword v124, v203, s[14:15]
	s_add_u32 s14, s14, s18
	s_addc_u32 s15, s15, s19
	global_load_dword v125, v203, s[14:15]
	s_add_u32 s14, s14, s18
	s_addc_u32 s15, s15, s19
	global_load_dword v126, v203, s[14:15]
	s_add_u32 s14, s14, s18
	s_addc_u32 s15, s15, s19
	global_load_dword v127, v203, s[14:15]
	s_add_u32 s14, s14, s18
	s_addc_u32 s15, s15, s19
	v_mov_b32_e32 v208, 0xf149f2ca
	v_mov_b32_e32 v210, 0
	v_mov_b32_e32 v216, 0
	v_mov_b32_e32 v218, 0
	s_waitcnt vmcnt(63)
	s_nop 0
	v_readlane_b32 s41, v206, 0
	v_readlane_b32 s42, v207, 0
	s_waitcnt vmcnt(63)
	v_cvt_pk_bf16_f32 v215, v210, v195
	v_readlane_b32 s43, v206, 1
	v_readlane_b32 s44, v207, 1
	global_store_short v202, v215, s[8:9]
	s_add_u32 s8, s8, s12
	s_addc_u32 s9, s9, s13
	global_store_dword v205, v216, s[24:25]
	s_add_u32 s24, s24, s28
	s_addc_u32 s25, s25, s29
	s_mov_b64 exec, s[46:47]
	global_store_dword v195, v208, s[26:27]
	s_mov_b64 exec, -1
	s_add_u32 s26, s26, s30
	s_addc_u32 s27, s27, s31
	v_add_f32_e32 v211, s42, v208
	v_max_f32_e32 v209, s41, v211
	v_sub_f32_e32 v212, v211, v209
	v_sub_f32_e32 v213, s41, v209
	v_mul_f32_e32 v212, 0x3fb8aa3b, v212
	v_mul_f32_e32 v213, 0x3fb8aa3b, v213
	v_exp_f32_e32 v213, v213
	v_exp_f32_e32 v212, v212
	s_nop 0
	v_mul_f32_e32 v214, v213, v0
	v_mul_f32_e32 v217, v213, v128
	v_fma_f32 v210, v210, v212, v214
	v_fma_f32 v216, v216, v212, v217
	v_cvt_pk_bf16_f32 v215, v210, v195
	v_readlane_b32 s41, v206, 2
	v_readlane_b32 s42, v207, 2
	global_store_short v202, v215, s[8:9]
	s_add_u32 s8, s8, s12
	s_addc_u32 s9, s9, s13
	global_store_dword v205, v216, s[24:25]
	s_add_u32 s24, s24, s28
	s_addc_u32 s25, s25, s29
	s_mov_b64 exec, s[46:47]
	global_store_dword v195, v209, s[26:27]
	s_mov_b64 exec, -1
	s_add_u32 s26, s26, s30
	s_addc_u32 s27, s27, s31
	v_add_f32_e32 v211, s44, v209
	v_max_f32_e32 v208, s43, v211
	v_sub_f32_e32 v212, v211, v208
	v_sub_f32_e32 v213, s43, v208
	v_mul_f32_e32 v212, 0x3fb8aa3b, v212
	v_mul_f32_e32 v213, 0x3fb8aa3b, v213
	v_exp_f32_e32 v213, v213
	v_exp_f32_e32 v212, v212
	s_nop 0
	v_mul_f32_e32 v214, v213, v1
	v_mul_f32_e32 v217, v213, v129
	v_fma_f32 v210, v210, v212, v214
	v_fma_f32 v216, v216, v212, v217
	v_cvt_pk_bf16_f32 v215, v210, v195
	v_readlane_b32 s43, v206, 3
	v_readlane_b32 s44, v207, 3
	global_store_short v202, v215, s[8:9]
	s_add_u32 s8, s8, s12
	s_addc_u32 s9, s9, s13
	global_store_dword v205, v216, s[24:25]
	s_add_u32 s24, s24, s28
	s_addc_u32 s25, s25, s29
	s_mov_b64 exec, s[46:47]
	global_store_dword v195, v208, s[26:27]
	s_mov_b64 exec, -1
	s_add_u32 s26, s26, s30
	s_addc_u32 s27, s27, s31
	v_add_f32_e32 v211, s42, v208
	v_max_f32_e32 v209, s41, v211
	v_sub_f32_e32 v212, v211, v209
	v_sub_f32_e32 v213, s41, v209
	v_mul_f32_e32 v212, 0x3fb8aa3b, v212
	v_mul_f32_e32 v213, 0x3fb8aa3b, v213
	v_exp_f32_e32 v213, v213
	v_exp_f32_e32 v212, v212
	s_nop 0
	v_mul_f32_e32 v214, v213, v2
	v_mul_f32_e32 v217, v213, v130
	v_fma_f32 v210, v210, v212, v214
	v_fma_f32 v216, v216, v212, v217
	v_cvt_pk_bf16_f32 v215, v210, v195
	v_readlane_b32 s41, v206, 4
	v_readlane_b32 s42, v207, 4
	global_store_short v202, v215, s[8:9]
	s_add_u32 s8, s8, s12
	s_addc_u32 s9, s9, s13
	global_store_dword v205, v216, s[24:25]
	s_add_u32 s24, s24, s28
	s_addc_u32 s25, s25, s29
	s_mov_b64 exec, s[46:47]
	global_store_dword v195, v209, s[26:27]
	s_mov_b64 exec, -1
	s_add_u32 s26, s26, s30
; __device__ __forceinline__ bf16_t f2bf(float f) { return (bf16_t)(cvt_pk_bf16(f, 0.f) & 0xffffu); }
; __device__ __forceinline__ void scan_phase(const Bufs& B) {
;     ...
;                 B.CST[(size_t)it * 16384 + idx] = f2bf(cst);
;                 if (idx < 128) { B.NST[(size_t)it * 128 + idx] = nst; if (idx == 0) B.MST[it] = m; }
;                 const float mnew = fmaxf(bl[u] + m, ml[u]), a = __expf(bl[u] + m - mnew), g = __expf(ml[u] - mnew);
;                 cst = a * cst + g * cl[u]; nst = a * nst + g * nl[u]; m = mnew; }
	s_addc_u32 s27, s27, s31
	v_add_f32_e32 v211, s44, v209
	v_max_f32_e32 v208, s43, v211
	v_sub_f32_e32 v212, v211, v208
	v_sub_f32_e32 v213, s43, v208
	v_mul_f32_e32 v212, 0x3fb8aa3b, v212
	v_mul_f32_e32 v213, 0x3fb8aa3b, v213
	v_exp_f32_e32 v213, v213
	v_exp_f32_e32 v212, v212
	s_nop 0
	v_mul_f32_e32 v214, v213, v3
	v_mul_f32_e32 v217, v213, v131
	v_fma_f32 v210, v210, v212, v214
	v_fma_f32 v216, v216, v212, v217
	v_cvt_pk_bf16_f32 v215, v210, v195
	v_readlane_b32 s43, v206, 5
	v_readlane_b32 s44, v207, 5
	global_store_short v202, v215, s[8:9]
	s_add_u32 s8, s8, s12
	s_addc_u32 s9, s9, s13
	global_store_dword v205, v216, s[24:25]
	s_add_u32 s24, s24, s28
	s_addc_u32 s25, s25, s29
	s_mov_b64 exec, s[46:47]
	global_store_dword v195, v208, s[26:27]
	s_mov_b64 exec, -1
	s_add_u32 s26, s26, s30
	s_addc_u32 s27, s27, s31
	v_add_f32_e32 v211, s42, v208
	v_max_f32_e32 v209, s41, v211
	v_sub_f32_e32 v212, v211, v209
	v_sub_f32_e32 v213, s41, v209
	v_mul_f32_e32 v212, 0x3fb8aa3b, v212
	v_mul_f32_e32 v213, 0x3fb8aa3b, v213
	v_exp_f32_e32 v213, v213
	v_exp_f32_e32 v212, v212
	s_nop 0
	v_mul_f32_e32 v214, v213, v4
	v_mul_f32_e32 v217, v213, v132
	v_fma_f32 v210, v210, v212, v214
	v_fma_f32 v216, v216, v212, v217
	v_cvt_pk_bf16_f32 v215, v210, v195
	v_readlane_b32 s41, v206, 6
	v_readlane_b32 s42, v207, 6
	global_store_short v202, v215, s[8:9]
	s_add_u32 s8, s8, s12
	s_addc_u32 s9, s9, s13
	global_store_dword v205, v216, s[24:25]
	s_add_u32 s24, s24, s28
	s_addc_u32 s25, s25, s29
	s_mov_b64 exec, s[46:47]
	global_store_dword v195, v209, s[26:27]
	s_mov_b64 exec, -1
	s_add_u32 s26, s26, s30
	s_addc_u32 s27, s27, s31
	v_add_f32_e32 v211, s44, v209
	v_max_f32_e32 v208, s43, v211
	v_sub_f32_e32 v212, v211, v208
	v_sub_f32_e32 v213, s43, v208
	v_mul_f32_e32 v212, 0x3fb8aa3b, v212
	v_mul_f32_e32 v213, 0x3fb8aa3b, v213
	v_exp_f32_e32 v213, v213
	v_exp_f32_e32 v212, v212
	s_nop 0
	v_mul_f32_e32 v214, v213, v5
	v_mul_f32_e32 v217, v213, v133
	v_fma_f32 v210, v210, v212, v214
	v_fma_f32 v216, v216, v212, v217
	v_cvt_pk_bf16_f32 v215, v210, v195
	v_readlane_b32 s43, v206, 7
	v_readlane_b32 s44, v207, 7
	global_store_short v202, v215, s[8:9]
	s_add_u32 s8, s8, s12
	s_addc_u32 s9, s9, s13
	global_store_dword v205, v216, s[24:25]
	s_add_u32 s24, s24, s28
	s_addc_u32 s25, s25, s29
	s_mov_b64 exec, s[46:47]
	global_store_dword v195, v208, s[26:27]
	s_mov_b64 exec, -1
	s_add_u32 s26, s26, s30
	s_addc_u32 s27, s27, s31
	v_add_f32_e32 v211, s42, v208
	v_max_f32_e32 v209, s41, v211
	v_sub_f32_e32 v212, v211, v209
	v_sub_f32_e32 v213, s41, v209
	v_mul_f32_e32 v212, 0x3fb8aa3b, v212
	v_mul_f32_e32 v213, 0x3fb8aa3b, v213
	v_exp_f32_e32 v213, v213
	v_exp_f32_e32 v212, v212
	s_nop 0
	v_mul_f32_e32 v214, v213, v6
	v_mul_f32_e32 v217, v213, v134
	v_fma_f32 v210, v210, v212, v214
	v_fma_f32 v216, v216, v212, v217
	v_cvt_pk_bf16_f32 v215, v210, v195
	v_readlane_b32 s41, v206, 8
	v_readlane_b32 s42, v207, 8
	global_store_short v202, v215, s[8:9]
	s_add_u32 s8, s8, s12
	s_addc_u32 s9, s9, s13
	global_store_dword v205, v216, s[24:25]
	s_add_u32 s24, s24, s28
	s_addc_u32 s25, s25, s29
	s_mov_b64 exec, s[46:47]
	global_store_dword v195, v209, s[26:27]
	s_mov_b64 exec, -1
	s_add_u32 s26, s26, s30
	s_addc_u32 s27, s27, s31
	v_add_f32_e32 v211, s44, v209
	v_max_f32_e32 v208, s43, v211
	v_sub_f32_e32 v212, v211, v208
	v_sub_f32_e32 v213, s43, v208
	v_mul_f32_e32 v212, 0x3fb8aa3b, v212
	v_mul_f32_e32 v213, 0x3fb8aa3b, v213
	v_exp_f32_e32 v213, v213
	v_exp_f32_e32 v212, v212
	s_nop 0
	v_mul_f32_e32 v214, v213, v7
	v_mul_f32_e32 v217, v213, v135
	v_fma_f32 v210, v210, v212, v214
	v_fma_f32 v216, v216, v212, v217
	v_cvt_pk_bf16_f32 v215, v210, v195
	v_readlane_b32 s43, v206, 9
	v_readlane_b32 s44, v207, 9
	global_store_short v202, v215, s[8:9]
	s_add_u32 s8, s8, s12
	s_addc_u32 s9, s9, s13
	global_store_dword v205, v216, s[24:25]
	s_add_u32 s24, s24, s28
	s_addc_u32 s25, s25, s29
	s_mov_b64 exec, s[46:47]
	global_store_dword v195, v208, s[26:27]
	s_mov_b64 exec, -1
	s_add_u32 s26, s26, s30
	s_addc_u32 s27, s27, s31
	v_add_f32_e32 v211, s42, v208
	v_max_f32_e32 v209, s41, v211
	v_sub_f32_e32 v212, v211, v209
	v_sub_f32_e32 v213, s41, v209
	v_mul_f32_e32 v212, 0x3fb8aa3b, v212
	v_mul_f32_e32 v213, 0x3fb8aa3b, v213
	v_exp_f32_e32 v213, v213
	v_exp_f32_e32 v212, v212
	s_nop 0
	v_mul_f32_e32 v214, v213, v8
	v_mul_f32_e32 v217, v213, v136
	v_fma_f32 v210, v210, v212, v214
	v_fma_f32 v216, v216, v212, v217
	v_cvt_pk_bf16_f32 v215, v210, v195
	v_readlane_b32 s41, v206, 10
	v_readlane_b32 s42, v207, 10
	global_store_short v202, v215, s[8:9]
	s_add_u32 s8, s8, s12
	s_addc_u32 s9, s9, s13
	global_store_dword v205, v216, s[24:25]
	s_add_u32 s24, s24, s28
	s_addc_u32 s25, s25, s29
	s_mov_b64 exec, s[46:47]
	global_store_dword v195, v209, s[26:27]
	s_mov_b64 exec, -1
	s_add_u32 s26, s26, s30
	s_addc_u32 s27, s27, s31
	v_add_f32_e32 v211, s44, v209
	v_max_f32_e32 v208, s43, v211
	v_sub_f32_e32 v212, v211, v208
	v_sub_f32_e32 v213, s43, v208
	v_mul_f32_e32 v212, 0x3fb8aa3b, v212
	v_mul_f32_e32 v213, 0x3fb8aa3b, v213
	v_exp_f32_e32 v213, v213
	v_exp_f32_e32 v212, v212
	s_nop 0
	v_mul_f32_e32 v214, v213, v9
	v_mul_f32_e32 v217, v213, v137
	v_fma_f32 v210, v210, v212, v214
	v_fma_f32 v216, v216, v212, v217
	v_cvt_pk_bf16_f32 v215, v210, v195
	v_readlane_b32 s43, v206, 11
	v_readlane_b32 s44, v207, 11
	global_store_short v202, v215, s[8:9]
	s_add_u32 s8, s8, s12
	s_addc_u32 s9, s9, s13
	global_store_dword v205, v216, s[24:25]
	s_add_u32 s24, s24, s28
	s_addc_u32 s25, s25, s29
	s_mov_b64 exec, s[46:47]
	global_store_dword v195, v208, s[26:27]
	s_mov_b64 exec, -1
	s_add_u32 s26, s26, s30
	s_addc_u32 s27, s27, s31
; __device__ __forceinline__ bf16_t f2bf(float f) { return (bf16_t)(cvt_pk_bf16(f, 0.f) & 0xffffu); }
; __device__ __forceinline__ void scan_phase(const Bufs& B) {
;     ...
;                 B.CST[(size_t)it * 16384 + idx] = f2bf(cst);
;                 if (idx < 128) { B.NST[(size_t)it * 128 + idx] = nst; if (idx == 0) B.MST[it] = m; }
;                 const float mnew = fmaxf(bl[u] + m, ml[u]), a = __expf(bl[u] + m - mnew), g = __expf(ml[u] - mnew);
;                 cst = a * cst + g * cl[u]; nst = a * nst + g * nl[u]; m = mnew; }
	v_add_f32_e32 v211, s42, v208
	v_max_f32_e32 v209, s41, v211
	v_sub_f32_e32 v212, v211, v209
	v_sub_f32_e32 v213, s41, v209
	v_mul_f32_e32 v212, 0x3fb8aa3b, v212
	v_mul_f32_e32 v213, 0x3fb8aa3b, v213
	v_exp_f32_e32 v213, v213
	v_exp_f32_e32 v212, v212
	s_nop 0
	v_mul_f32_e32 v214, v213, v10
	v_mul_f32_e32 v217, v213, v138
	v_fma_f32 v210, v210, v212, v214
	v_fma_f32 v216, v216, v212, v217
	v_cvt_pk_bf16_f32 v215, v210, v195
	v_readlane_b32 s41, v206, 12
	v_readlane_b32 s42, v207, 12
	global_store_short v202, v215, s[8:9]
	s_add_u32 s8, s8, s12
	s_addc_u32 s9, s9, s13
	global_store_dword v205, v216, s[24:25]
	s_add_u32 s24, s24, s28
	s_addc_u32 s25, s25, s29
	s_mov_b64 exec, s[46:47]
	global_store_dword v195, v209, s[26:27]
	s_mov_b64 exec, -1
	s_add_u32 s26, s26, s30
	s_addc_u32 s27, s27, s31
	v_add_f32_e32 v211, s44, v209
	v_max_f32_e32 v208, s43, v211
	v_sub_f32_e32 v212, v211, v208
	v_sub_f32_e32 v213, s43, v208
	v_mul_f32_e32 v212, 0x3fb8aa3b, v212
	v_mul_f32_e32 v213, 0x3fb8aa3b, v213
	v_exp_f32_e32 v213, v213
	v_exp_f32_e32 v212, v212
	s_nop 0
	v_mul_f32_e32 v214, v213, v11
	v_mul_f32_e32 v217, v213, v139
	v_fma_f32 v210, v210, v212, v214
	v_fma_f32 v216, v216, v212, v217
	v_cvt_pk_bf16_f32 v215, v210, v195
	v_readlane_b32 s43, v206, 13
	v_readlane_b32 s44, v207, 13
	global_store_short v202, v215, s[8:9]
	s_add_u32 s8, s8, s12
	s_addc_u32 s9, s9, s13
	global_store_dword v205, v216, s[24:25]
	s_add_u32 s24, s24, s28
	s_addc_u32 s25, s25, s29
	s_mov_b64 exec, s[46:47]
	global_store_dword v195, v208, s[26:27]
	s_mov_b64 exec, -1
	s_add_u32 s26, s26, s30
	s_addc_u32 s27, s27, s31
	v_add_f32_e32 v211, s42, v208
	v_max_f32_e32 v209, s41, v211
	v_sub_f32_e32 v212, v211, v209
	v_sub_f32_e32 v213, s41, v209
	v_mul_f32_e32 v212, 0x3fb8aa3b, v212
	v_mul_f32_e32 v213, 0x3fb8aa3b, v213
	v_exp_f32_e32 v213, v213
	v_exp_f32_e32 v212, v212
	s_nop 0
	v_mul_f32_e32 v214, v213, v12
	v_mul_f32_e32 v217, v213, v140
	v_fma_f32 v210, v210, v212, v214
	v_fma_f32 v216, v216, v212, v217
	v_cvt_pk_bf16_f32 v215, v210, v195
	v_readlane_b32 s41, v206, 14
	v_readlane_b32 s42, v207, 14
	global_store_short v202, v215, s[8:9]
	s_add_u32 s8, s8, s12
	s_addc_u32 s9, s9, s13
	global_store_dword v205, v216, s[24:25]
	s_add_u32 s24, s24, s28
	s_addc_u32 s25, s25, s29
	s_mov_b64 exec, s[46:47]
	global_store_dword v195, v209, s[26:27]
	s_mov_b64 exec, -1
	s_add_u32 s26, s26, s30
	s_addc_u32 s27, s27, s31
	v_add_f32_e32 v211, s44, v209
	v_max_f32_e32 v208, s43, v211
	v_sub_f32_e32 v212, v211, v208
	v_sub_f32_e32 v213, s43, v208
	v_mul_f32_e32 v212, 0x3fb8aa3b, v212
	v_mul_f32_e32 v213, 0x3fb8aa3b, v213
	v_exp_f32_e32 v213, v213
	v_exp_f32_e32 v212, v212
	s_nop 0
	v_mul_f32_e32 v214, v213, v13
	v_mul_f32_e32 v217, v213, v141
	v_fma_f32 v210, v210, v212, v214
	v_fma_f32 v216, v216, v212, v217
	v_cvt_pk_bf16_f32 v215, v210, v195
	v_readlane_b32 s43, v206, 15
	v_readlane_b32 s44, v207, 15
	global_store_short v202, v215, s[8:9]
	s_add_u32 s8, s8, s12
	s_addc_u32 s9, s9, s13
	global_store_dword v205, v216, s[24:25]
	s_add_u32 s24, s24, s28
	s_addc_u32 s25, s25, s29
	s_mov_b64 exec, s[46:47]
	global_store_dword v195, v208, s[26:27]
	s_mov_b64 exec, -1
	s_add_u32 s26, s26, s30
	s_addc_u32 s27, s27, s31
	v_add_f32_e32 v211, s42, v208
	v_max_f32_e32 v209, s41, v211
	v_sub_f32_e32 v212, v211, v209
	v_sub_f32_e32 v213, s41, v209
	v_mul_f32_e32 v212, 0x3fb8aa3b, v212
	v_mul_f32_e32 v213, 0x3fb8aa3b, v213
	v_exp_f32_e32 v213, v213
	v_exp_f32_e32 v212, v212
	s_nop 0
	v_mul_f32_e32 v214, v213, v14
	v_mul_f32_e32 v217, v213, v142
	v_fma_f32 v210, v210, v212, v214
	v_fma_f32 v216, v216, v212, v217
	v_cvt_pk_bf16_f32 v215, v210, v195
	v_readlane_b32 s41, v206, 16
	v_readlane_b32 s42, v207, 16
	global_store_short v202, v215, s[8:9]
	s_add_u32 s8, s8, s12
	s_addc_u32 s9, s9, s13
	global_store_dword v205, v216, s[24:25]
	s_add_u32 s24, s24, s28
	s_addc_u32 s25, s25, s29
	s_mov_b64 exec, s[46:47]
	global_store_dword v195, v209, s[26:27]
	s_mov_b64 exec, -1
	s_add_u32 s26, s26, s30
	s_addc_u32 s27, s27, s31
	v_add_f32_e32 v211, s44, v209
	v_max_f32_e32 v208, s43, v211
	v_sub_f32_e32 v212, v211, v208
	v_sub_f32_e32 v213, s43, v208
	v_mul_f32_e32 v212, 0x3fb8aa3b, v212
	v_mul_f32_e32 v213, 0x3fb8aa3b, v213
	v_exp_f32_e32 v213, v213
	v_exp_f32_e32 v212, v212
	s_nop 0
	v_mul_f32_e32 v214, v213, v15
	v_mul_f32_e32 v217, v213, v143
	v_fma_f32 v210, v210, v212, v214
	v_fma_f32 v216, v216, v212, v217
	s_waitcnt vmcnt(63)
; __device__ __forceinline__ bf16_t f2bf(float f) { return (bf16_t)(cvt_pk_bf16(f, 0.f) & 0xffffu); }
; __device__ __forceinline__ void scan_phase(const Bufs& B) {
;     ...
;                 B.CST[(size_t)it * 16384 + idx] = f2bf(cst);
;                 if (idx < 128) { B.NST[(size_t)it * 128 + idx] = nst; if (idx == 0) B.MST[it] = m; }
;                 const float mnew = fmaxf(bl[u] + m, ml[u]), a = __expf(bl[u] + m - mnew), g = __expf(ml[u] - mnew);
;                 cst = a * cst + g * cl[u]; nst = a * nst + g * nl[u]; m = mnew; }
	v_cvt_pk_bf16_f32 v215, v210, v195
	v_readlane_b32 s43, v206, 17
	v_readlane_b32 s44, v207, 17
	global_store_short v202, v215, s[8:9]
	s_add_u32 s8, s8, s12
	s_addc_u32 s9, s9, s13
	global_store_dword v205, v216, s[24:25]
	s_add_u32 s24, s24, s28
	s_addc_u32 s25, s25, s29
	s_mov_b64 exec, s[46:47]
	global_store_dword v195, v208, s[26:27]
	s_mov_b64 exec, -1
	s_add_u32 s26, s26, s30
	s_addc_u32 s27, s27, s31
	v_add_f32_e32 v211, s42, v208
	v_max_f32_e32 v209, s41, v211
	v_sub_f32_e32 v212, v211, v209
	v_sub_f32_e32 v213, s41, v209
	v_mul_f32_e32 v212, 0x3fb8aa3b, v212
	v_mul_f32_e32 v213, 0x3fb8aa3b, v213
	v_exp_f32_e32 v213, v213
	v_exp_f32_e32 v212, v212
	s_nop 0
	v_mul_f32_e32 v214, v213, v16
	v_mul_f32_e32 v217, v213, v144
	v_fma_f32 v210, v210, v212, v214
	v_fma_f32 v216, v216, v212, v217
	v_cvt_pk_bf16_f32 v215, v210, v195
	v_readlane_b32 s41, v206, 18
	v_readlane_b32 s42, v207, 18
	global_store_short v202, v215, s[8:9]
	s_add_u32 s8, s8, s12
	s_addc_u32 s9, s9, s13
	global_store_dword v205, v216, s[24:25]
	s_add_u32 s24, s24, s28
	s_addc_u32 s25, s25, s29
	s_mov_b64 exec, s[46:47]
	global_store_dword v195, v209, s[26:27]
	s_mov_b64 exec, -1
	s_add_u32 s26, s26, s30
	s_addc_u32 s27, s27, s31
	v_add_f32_e32 v211, s44, v209
	v_max_f32_e32 v208, s43, v211
	v_sub_f32_e32 v212, v211, v208
	v_sub_f32_e32 v213, s43, v208
	v_mul_f32_e32 v212, 0x3fb8aa3b, v212
	v_mul_f32_e32 v213, 0x3fb8aa3b, v213
	v_exp_f32_e32 v213, v213
	v_exp_f32_e32 v212, v212
	s_nop 0
	v_mul_f32_e32 v214, v213, v17
	v_mul_f32_e32 v217, v213, v145
	v_fma_f32 v210, v210, v212, v214
	v_fma_f32 v216, v216, v212, v217
	v_cvt_pk_bf16_f32 v215, v210, v195
	v_readlane_b32 s43, v206, 19
	v_readlane_b32 s44, v207, 19
	global_store_short v202, v215, s[8:9]
	s_add_u32 s8, s8, s12
	s_addc_u32 s9, s9, s13
	global_store_dword v205, v216, s[24:25]
	s_add_u32 s24, s24, s28
	s_addc_u32 s25, s25, s29
	s_mov_b64 exec, s[46:47]
	global_store_dword v195, v208, s[26:27]
	s_mov_b64 exec, -1
	s_add_u32 s26, s26, s30
	s_addc_u32 s27, s27, s31
	v_add_f32_e32 v211, s42, v208
	v_max_f32_e32 v209, s41, v211
	v_sub_f32_e32 v212, v211, v209
	v_sub_f32_e32 v213, s41, v209
	v_mul_f32_e32 v212, 0x3fb8aa3b, v212
	v_mul_f32_e32 v213, 0x3fb8aa3b, v213
	v_exp_f32_e32 v213, v213
	v_exp_f32_e32 v212, v212
	s_nop 0
	v_mul_f32_e32 v214, v213, v18
	v_mul_f32_e32 v217, v213, v146
	v_fma_f32 v210, v210, v212, v214
	v_fma_f32 v216, v216, v212, v217
	v_cvt_pk_bf16_f32 v215, v210, v195
	v_readlane_b32 s41, v206, 20
	v_readlane_b32 s42, v207, 20
	global_store_short v202, v215, s[8:9]
	s_add_u32 s8, s8, s12
	s_addc_u32 s9, s9, s13
	global_store_dword v205, v216, s[24:25]
	s_add_u32 s24, s24, s28
	s_addc_u32 s25, s25, s29
	s_mov_b64 exec, s[46:47]
	global_store_dword v195, v209, s[26:27]
	s_mov_b64 exec, -1
	s_add_u32 s26, s26, s30
	s_addc_u32 s27, s27, s31
	v_add_f32_e32 v211, s44, v209
	v_max_f32_e32 v208, s43, v211
	v_sub_f32_e32 v212, v211, v208
	v_sub_f32_e32 v213, s43, v208
	v_mul_f32_e32 v212, 0x3fb8aa3b, v212
	v_mul_f32_e32 v213, 0x3fb8aa3b, v213
	v_exp_f32_e32 v213, v213
	v_exp_f32_e32 v212, v212
	s_nop 0
	v_mul_f32_e32 v214, v213, v19
	v_mul_f32_e32 v217, v213, v147
	v_fma_f32 v210, v210, v212, v214
	v_fma_f32 v216, v216, v212, v217
	v_cvt_pk_bf16_f32 v215, v210, v195
	v_readlane_b32 s43, v206, 21
	v_readlane_b32 s44, v207, 21
	global_store_short v202, v215, s[8:9]
	s_add_u32 s8, s8, s12
	s_addc_u32 s9, s9, s13
	global_store_dword v205, v216, s[24:25]
	s_add_u32 s24, s24, s28
	s_addc_u32 s25, s25, s29
	s_mov_b64 exec, s[46:47]
	global_store_dword v195, v208, s[26:27]
	s_mov_b64 exec, -1
	s_add_u32 s26, s26, s30
	s_addc_u32 s27, s27, s31
	v_add_f32_e32 v211, s42, v208
	v_max_f32_e32 v209, s41, v211
	v_sub_f32_e32 v212, v211, v209
	v_sub_f32_e32 v213, s41, v209
	v_mul_f32_e32 v212, 0x3fb8aa3b, v212
	v_mul_f32_e32 v213, 0x3fb8aa3b, v213
	v_exp_f32_e32 v213, v213
	v_exp_f32_e32 v212, v212
	s_nop 0
	v_mul_f32_e32 v214, v213, v20
	v_mul_f32_e32 v217, v213, v148
	v_fma_f32 v210, v210, v212, v214
	v_fma_f32 v216, v216, v212, v217
	v_cvt_pk_bf16_f32 v215, v210, v195
	v_readlane_b32 s41, v206, 22
	v_readlane_b32 s42, v207, 22
	global_store_short v202, v215, s[8:9]
	s_add_u32 s8, s8, s12
	s_addc_u32 s9, s9, s13
	global_store_dword v205, v216, s[24:25]
	s_add_u32 s24, s24, s28
	s_addc_u32 s25, s25, s29
	s_mov_b64 exec, s[46:47]
	global_store_dword v195, v209, s[26:27]
	s_mov_b64 exec, -1
	s_add_u32 s26, s26, s30
	s_addc_u32 s27, s27, s31
	v_add_f32_e32 v211, s44, v209
	v_max_f32_e32 v208, s43, v211
	v_sub_f32_e32 v212, v211, v208
	v_sub_f32_e32 v213, s43, v208
	v_mul_f32_e32 v212, 0x3fb8aa3b, v212
	v_mul_f32_e32 v213, 0x3fb8aa3b, v213
	v_exp_f32_e32 v213, v213
	v_exp_f32_e32 v212, v212
	s_nop 0
	v_mul_f32_e32 v214, v213, v21
	v_mul_f32_e32 v217, v213, v149
	v_fma_f32 v210, v210, v212, v214
	v_fma_f32 v216, v216, v212, v217
	v_cvt_pk_bf16_f32 v215, v210, v195
	v_readlane_b32 s43, v206, 23
	v_readlane_b32 s44, v207, 23
	global_store_short v202, v215, s[8:9]
	s_add_u32 s8, s8, s12
	s_addc_u32 s9, s9, s13
	global_store_dword v205, v216, s[24:25]
	s_add_u32 s24, s24, s28
	s_addc_u32 s25, s25, s29
	s_mov_b64 exec, s[46:47]
	global_store_dword v195, v208, s[26:27]
	s_mov_b64 exec, -1
	s_add_u32 s26, s26, s30
	s_addc_u32 s27, s27, s31
	v_add_f32_e32 v211, s42, v208
	v_max_f32_e32 v209, s41, v211
	v_sub_f32_e32 v212, v211, v209
	v_sub_f32_e32 v213, s41, v209
	v_mul_f32_e32 v212, 0x3fb8aa3b, v212
	v_mul_f32_e32 v213, 0x3fb8aa3b, v213
	v_exp_f32_e32 v213, v213
	v_exp_f32_e32 v212, v212
	s_nop 0
	v_mul_f32_e32 v214, v213, v22
	v_mul_f32_e32 v217, v213, v150
	v_fma_f32 v210, v210, v212, v214
	v_fma_f32 v216, v216, v212, v217
; __device__ __forceinline__ bf16_t f2bf(float f) { return (bf16_t)(cvt_pk_bf16(f, 0.f) & 0xffffu); }
; __device__ __forceinline__ void scan_phase(const Bufs& B) {
;     ...
;                 B.CST[(size_t)it * 16384 + idx] = f2bf(cst);
;                 if (idx < 128) { B.NST[(size_t)it * 128 + idx] = nst; if (idx == 0) B.MST[it] = m; }
;                 const float mnew = fmaxf(bl[u] + m, ml[u]), a = __expf(bl[u] + m - mnew), g = __expf(ml[u] - mnew);
;                 cst = a * cst + g * cl[u]; nst = a * nst + g * nl[u]; m = mnew; }
	v_cvt_pk_bf16_f32 v215, v210, v195
	v_readlane_b32 s41, v206, 24
	v_readlane_b32 s42, v207, 24
	global_store_short v202, v215, s[8:9]
	s_add_u32 s8, s8, s12
	s_addc_u32 s9, s9, s13
	global_store_dword v205, v216, s[24:25]
	s_add_u32 s24, s24, s28
	s_addc_u32 s25, s25, s29
	s_mov_b64 exec, s[46:47]
	global_store_dword v195, v209, s[26:27]
	s_mov_b64 exec, -1
	s_add_u32 s26, s26, s30
	s_addc_u32 s27, s27, s31
	v_add_f32_e32 v211, s44, v209
	v_max_f32_e32 v208, s43, v211
	v_sub_f32_e32 v212, v211, v208
	v_sub_f32_e32 v213, s43, v208
	v_mul_f32_e32 v212, 0x3fb8aa3b, v212
	v_mul_f32_e32 v213, 0x3fb8aa3b, v213
	v_exp_f32_e32 v213, v213
	v_exp_f32_e32 v212, v212
	s_nop 0
	v_mul_f32_e32 v214, v213, v23
	v_mul_f32_e32 v217, v213, v151
	v_fma_f32 v210, v210, v212, v214
	v_fma_f32 v216, v216, v212, v217
	v_cvt_pk_bf16_f32 v215, v210, v195
	v_readlane_b32 s43, v206, 25
	v_readlane_b32 s44, v207, 25
	global_store_short v202, v215, s[8:9]
	s_add_u32 s8, s8, s12
	s_addc_u32 s9, s9, s13
	global_store_dword v205, v216, s[24:25]
	s_add_u32 s24, s24, s28
	s_addc_u32 s25, s25, s29
	s_mov_b64 exec, s[46:47]
	global_store_dword v195, v208, s[26:27]
	s_mov_b64 exec, -1
	s_add_u32 s26, s26, s30
	s_addc_u32 s27, s27, s31
	v_add_f32_e32 v211, s42, v208
	v_max_f32_e32 v209, s41, v211
	v_sub_f32_e32 v212, v211, v209
	v_sub_f32_e32 v213, s41, v209
	v_mul_f32_e32 v212, 0x3fb8aa3b, v212
	v_mul_f32_e32 v213, 0x3fb8aa3b, v213
	v_exp_f32_e32 v213, v213
	v_exp_f32_e32 v212, v212
	s_nop 0
	v_mul_f32_e32 v214, v213, v24
	v_mul_f32_e32 v217, v213, v152
	v_fma_f32 v210, v210, v212, v214
	v_fma_f32 v216, v216, v212, v217
	v_cvt_pk_bf16_f32 v215, v210, v195
	v_readlane_b32 s41, v206, 26
	v_readlane_b32 s42, v207, 26
	global_store_short v202, v215, s[8:9]
	s_add_u32 s8, s8, s12
	s_addc_u32 s9, s9, s13
	global_store_dword v205, v216, s[24:25]
	s_add_u32 s24, s24, s28
	s_addc_u32 s25, s25, s29
	s_mov_b64 exec, s[46:47]
	global_store_dword v195, v209, s[26:27]
	s_mov_b64 exec, -1
	s_add_u32 s26, s26, s30
	s_addc_u32 s27, s27, s31
	v_add_f32_e32 v211, s44, v209
	v_max_f32_e32 v208, s43, v211
	v_sub_f32_e32 v212, v211, v208
	v_sub_f32_e32 v213, s43, v208
	v_mul_f32_e32 v212, 0x3fb8aa3b, v212
	v_mul_f32_e32 v213, 0x3fb8aa3b, v213
	v_exp_f32_e32 v213, v213
	v_exp_f32_e32 v212, v212
	s_nop 0
	v_mul_f32_e32 v214, v213, v25
	v_mul_f32_e32 v217, v213, v153
	v_fma_f32 v210, v210, v212, v214
	v_fma_f32 v216, v216, v212, v217
	v_cvt_pk_bf16_f32 v215, v210, v195
	v_readlane_b32 s43, v206, 27
	v_readlane_b32 s44, v207, 27
	global_store_short v202, v215, s[8:9]
	s_add_u32 s8, s8, s12
	s_addc_u32 s9, s9, s13
	global_store_dword v205, v216, s[24:25]
	s_add_u32 s24, s24, s28
	s_addc_u32 s25, s25, s29
	s_mov_b64 exec, s[46:47]
	global_store_dword v195, v208, s[26:27]
	s_mov_b64 exec, -1
	s_add_u32 s26, s26, s30
	s_addc_u32 s27, s27, s31
	v_add_f32_e32 v211, s42, v208
	v_max_f32_e32 v209, s41, v211
	v_sub_f32_e32 v212, v211, v209
	v_sub_f32_e32 v213, s41, v209
	v_mul_f32_e32 v212, 0x3fb8aa3b, v212
	v_mul_f32_e32 v213, 0x3fb8aa3b, v213
	v_exp_f32_e32 v213, v213
	v_exp_f32_e32 v212, v212
	s_nop 0
	v_mul_f32_e32 v214, v213, v26
	v_mul_f32_e32 v217, v213, v154
	v_fma_f32 v210, v210, v212, v214
	v_fma_f32 v216, v216, v212, v217
	v_cvt_pk_bf16_f32 v215, v210, v195
	v_readlane_b32 s41, v206, 28
	v_readlane_b32 s42, v207, 28
	global_store_short v202, v215, s[8:9]
	s_add_u32 s8, s8, s12
	s_addc_u32 s9, s9, s13
	global_store_dword v205, v216, s[24:25]
	s_add_u32 s24, s24, s28
	s_addc_u32 s25, s25, s29
	s_mov_b64 exec, s[46:47]
	global_store_dword v195, v209, s[26:27]
	s_mov_b64 exec, -1
	s_add_u32 s26, s26, s30
	s_addc_u32 s27, s27, s31
	v_add_f32_e32 v211, s44, v209
	v_max_f32_e32 v208, s43, v211
	v_sub_f32_e32 v212, v211, v208
	v_sub_f32_e32 v213, s43, v208
	v_mul_f32_e32 v212, 0x3fb8aa3b, v212
	v_mul_f32_e32 v213, 0x3fb8aa3b, v213
	v_exp_f32_e32 v213, v213
	v_exp_f32_e32 v212, v212
	s_nop 0
	v_mul_f32_e32 v214, v213, v27
	v_mul_f32_e32 v217, v213, v155
	v_fma_f32 v210, v210, v212, v214
	v_fma_f32 v216, v216, v212, v217
	v_cvt_pk_bf16_f32 v215, v210, v195
	v_readlane_b32 s43, v206, 29
	v_readlane_b32 s44, v207, 29
	global_store_short v202, v215, s[8:9]
	s_add_u32 s8, s8, s12
	s_addc_u32 s9, s9, s13
	global_store_dword v205, v216, s[24:25]
	s_add_u32 s24, s24, s28
	s_addc_u32 s25, s25, s29
	s_mov_b64 exec, s[46:47]
	global_store_dword v195, v208, s[26:27]
	s_mov_b64 exec, -1
	s_add_u32 s26, s26, s30
	s_addc_u32 s27, s27, s31
	v_add_f32_e32 v211, s42, v208
	v_max_f32_e32 v209, s41, v211
	v_sub_f32_e32 v212, v211, v209
	v_sub_f32_e32 v213, s41, v209
	v_mul_f32_e32 v212, 0x3fb8aa3b, v212
	v_mul_f32_e32 v213, 0x3fb8aa3b, v213
	v_exp_f32_e32 v213, v213
	v_exp_f32_e32 v212, v212
	s_nop 0
	v_mul_f32_e32 v214, v213, v28
	v_mul_f32_e32 v217, v213, v156
	v_fma_f32 v210, v210, v212, v214
	v_fma_f32 v216, v216, v212, v217
	v_cvt_pk_bf16_f32 v215, v210, v195
	v_readlane_b32 s41, v206, 30
	v_readlane_b32 s42, v207, 30
	global_store_short v202, v215, s[8:9]
	s_add_u32 s8, s8, s12
	s_addc_u32 s9, s9, s13
	global_store_dword v205, v216, s[24:25]
	s_add_u32 s24, s24, s28
	s_addc_u32 s25, s25, s29
	s_mov_b64 exec, s[46:47]
	global_store_dword v195, v209, s[26:27]
	s_mov_b64 exec, -1
	s_add_u32 s26, s26, s30
	s_addc_u32 s27, s27, s31
	v_add_f32_e32 v211, s44, v209
	v_max_f32_e32 v208, s43, v211
	v_sub_f32_e32 v212, v211, v208
	v_sub_f32_e32 v213, s43, v208
	v_mul_f32_e32 v212, 0x3fb8aa3b, v212
	v_mul_f32_e32 v213, 0x3fb8aa3b, v213
	v_exp_f32_e32 v213, v213
	v_exp_f32_e32 v212, v212
	s_nop 0
	v_mul_f32_e32 v214, v213, v29
	v_mul_f32_e32 v217, v213, v157
	v_fma_f32 v210, v210, v212, v214
	v_fma_f32 v216, v216, v212, v217
; __device__ __forceinline__ bf16_t f2bf(float f) { return (bf16_t)(cvt_pk_bf16(f, 0.f) & 0xffffu); }
; __device__ __forceinline__ void scan_phase(const Bufs& B) {
;     ...
;                 B.CST[(size_t)it * 16384 + idx] = f2bf(cst);
;                 if (idx < 128) { B.NST[(size_t)it * 128 + idx] = nst; if (idx == 0) B.MST[it] = m; }
;                 const float mnew = fmaxf(bl[u] + m, ml[u]), a = __expf(bl[u] + m - mnew), g = __expf(ml[u] - mnew);
;                 cst = a * cst + g * cl[u]; nst = a * nst + g * nl[u]; m = mnew; }
	v_cvt_pk_bf16_f32 v215, v210, v195
	v_readlane_b32 s43, v206, 31
	v_readlane_b32 s44, v207, 31
	global_store_short v202, v215, s[8:9]
	s_add_u32 s8, s8, s12
	s_addc_u32 s9, s9, s13
	global_store_dword v205, v216, s[24:25]
	s_add_u32 s24, s24, s28
	s_addc_u32 s25, s25, s29
	s_mov_b64 exec, s[46:47]
	global_store_dword v195, v208, s[26:27]
	s_mov_b64 exec, -1
	s_add_u32 s26, s26, s30
	s_addc_u32 s27, s27, s31
	v_add_f32_e32 v211, s42, v208
	v_max_f32_e32 v209, s41, v211
	v_sub_f32_e32 v212, v211, v209
	v_sub_f32_e32 v213, s41, v209
	v_mul_f32_e32 v212, 0x3fb8aa3b, v212
	v_mul_f32_e32 v213, 0x3fb8aa3b, v213
	v_exp_f32_e32 v213, v213
	v_exp_f32_e32 v212, v212
	s_nop 0
	v_mul_f32_e32 v214, v213, v30
	v_mul_f32_e32 v217, v213, v158
	v_fma_f32 v210, v210, v212, v214
	v_fma_f32 v216, v216, v212, v217
	v_cvt_pk_bf16_f32 v215, v210, v195
	v_readlane_b32 s41, v206, 32
	v_readlane_b32 s42, v207, 32
	global_store_short v202, v215, s[8:9]
	s_add_u32 s8, s8, s12
	s_addc_u32 s9, s9, s13
	global_store_dword v205, v216, s[24:25]
	s_add_u32 s24, s24, s28
	s_addc_u32 s25, s25, s29
	s_mov_b64 exec, s[46:47]
	global_store_dword v195, v209, s[26:27]
	s_mov_b64 exec, -1
	s_add_u32 s26, s26, s30
	s_addc_u32 s27, s27, s31
	v_add_f32_e32 v211, s44, v209
	v_max_f32_e32 v208, s43, v211
	v_sub_f32_e32 v212, v211, v208
	v_sub_f32_e32 v213, s43, v208
	v_mul_f32_e32 v212, 0x3fb8aa3b, v212
	v_mul_f32_e32 v213, 0x3fb8aa3b, v213
	v_exp_f32_e32 v213, v213
	v_exp_f32_e32 v212, v212
	s_nop 0
	v_mul_f32_e32 v214, v213, v31
	v_mul_f32_e32 v217, v213, v159
	v_fma_f32 v210, v210, v212, v214
	v_fma_f32 v216, v216, v212, v217
	s_waitcnt vmcnt(63)
	v_cvt_pk_bf16_f32 v215, v210, v195
	v_readlane_b32 s43, v206, 33
	v_readlane_b32 s44, v207, 33
	global_store_short v202, v215, s[8:9]
	s_add_u32 s8, s8, s12
	s_addc_u32 s9, s9, s13
	global_store_dword v205, v216, s[24:25]
	s_add_u32 s24, s24, s28
	s_addc_u32 s25, s25, s29
	s_mov_b64 exec, s[46:47]
	global_store_dword v195, v208, s[26:27]
	s_mov_b64 exec, -1
	s_add_u32 s26, s26, s30
	s_addc_u32 s27, s27, s31
	v_add_f32_e32 v211, s42, v208
	v_max_f32_e32 v209, s41, v211
	v_sub_f32_e32 v212, v211, v209
	v_sub_f32_e32 v213, s41, v209
	v_mul_f32_e32 v212, 0x3fb8aa3b, v212
	v_mul_f32_e32 v213, 0x3fb8aa3b, v213
	v_exp_f32_e32 v213, v213
	v_exp_f32_e32 v212, v212
	s_nop 0
	v_mul_f32_e32 v214, v213, v32
	v_mul_f32_e32 v217, v213, v160
	v_fma_f32 v210, v210, v212, v214
	v_fma_f32 v216, v216, v212, v217
	v_cvt_pk_bf16_f32 v215, v210, v195
	v_readlane_b32 s41, v206, 34
	v_readlane_b32 s42, v207, 34
	global_store_short v202, v215, s[8:9]
	s_add_u32 s8, s8, s12
	s_addc_u32 s9, s9, s13
	global_store_dword v205, v216, s[24:25]
	s_add_u32 s24, s24, s28
	s_addc_u32 s25, s25, s29
	s_mov_b64 exec, s[46:47]
	global_store_dword v195, v209, s[26:27]
	s_mov_b64 exec, -1
	s_add_u32 s26, s26, s30
	s_addc_u32 s27, s27, s31
	v_add_f32_e32 v211, s44, v209
	v_max_f32_e32 v208, s43, v211
	v_sub_f32_e32 v212, v211, v208
	v_sub_f32_e32 v213, s43, v208
	v_mul_f32_e32 v212, 0x3fb8aa3b, v212
	v_mul_f32_e32 v213, 0x3fb8aa3b, v213
	v_exp_f32_e32 v213, v213
	v_exp_f32_e32 v212, v212
	s_nop 0
	v_mul_f32_e32 v214, v213, v33
	v_mul_f32_e32 v217, v213, v161
	v_fma_f32 v210, v210, v212, v214
	v_fma_f32 v216, v216, v212, v217
	v_cvt_pk_bf16_f32 v215, v210, v195
	v_readlane_b32 s43, v206, 35
	v_readlane_b32 s44, v207, 35
	global_store_short v202, v215, s[8:9]
	s_add_u32 s8, s8, s12
	s_addc_u32 s9, s9, s13
	global_store_dword v205, v216, s[24:25]
	s_add_u32 s24, s24, s28
	s_addc_u32 s25, s25, s29
	s_mov_b64 exec, s[46:47]
	global_store_dword v195, v208, s[26:27]
	s_mov_b64 exec, -1
	s_add_u32 s26, s26, s30
	s_addc_u32 s27, s27, s31
	v_add_f32_e32 v211, s42, v208
	v_max_f32_e32 v209, s41, v211
	v_sub_f32_e32 v212, v211, v209
	v_sub_f32_e32 v213, s41, v209
	v_mul_f32_e32 v212, 0x3fb8aa3b, v212
	v_mul_f32_e32 v213, 0x3fb8aa3b, v213
	v_exp_f32_e32 v213, v213
	v_exp_f32_e32 v212, v212
	s_nop 0
	v_mul_f32_e32 v214, v213, v34
	v_mul_f32_e32 v217, v213, v162
	v_fma_f32 v210, v210, v212, v214
	v_fma_f32 v216, v216, v212, v217
	v_cvt_pk_bf16_f32 v215, v210, v195
	v_readlane_b32 s41, v206, 36
	v_readlane_b32 s42, v207, 36
	global_store_short v202, v215, s[8:9]
	s_add_u32 s8, s8, s12
	s_addc_u32 s9, s9, s13
	global_store_dword v205, v216, s[24:25]
	s_add_u32 s24, s24, s28
	s_addc_u32 s25, s25, s29
	s_mov_b64 exec, s[46:47]
	global_store_dword v195, v209, s[26:27]
	s_mov_b64 exec, -1
	s_add_u32 s26, s26, s30
	s_addc_u32 s27, s27, s31
	v_add_f32_e32 v211, s44, v209
	v_max_f32_e32 v208, s43, v211
	v_sub_f32_e32 v212, v211, v208
	v_sub_f32_e32 v213, s43, v208
	v_mul_f32_e32 v212, 0x3fb8aa3b, v212
	v_mul_f32_e32 v213, 0x3fb8aa3b, v213
	v_exp_f32_e32 v213, v213
	v_exp_f32_e32 v212, v212
	s_nop 0
	v_mul_f32_e32 v214, v213, v35
	v_mul_f32_e32 v217, v213, v163
	v_fma_f32 v210, v210, v212, v214
	v_fma_f32 v216, v216, v212, v217
	v_cvt_pk_bf16_f32 v215, v210, v195
	v_readlane_b32 s43, v206, 37
	v_readlane_b32 s44, v207, 37
	global_store_short v202, v215, s[8:9]
	s_add_u32 s8, s8, s12
	s_addc_u32 s9, s9, s13
	global_store_dword v205, v216, s[24:25]
	s_add_u32 s24, s24, s28
	s_addc_u32 s25, s25, s29
	s_mov_b64 exec, s[46:47]
	global_store_dword v195, v208, s[26:27]
	s_mov_b64 exec, -1
	s_add_u32 s26, s26, s30
	s_addc_u32 s27, s27, s31
	v_add_f32_e32 v211, s42, v208
	v_max_f32_e32 v209, s41, v211
	v_sub_f32_e32 v212, v211, v209
	v_sub_f32_e32 v213, s41, v209
	v_mul_f32_e32 v212, 0x3fb8aa3b, v212
	v_mul_f32_e32 v213, 0x3fb8aa3b, v213
	v_exp_f32_e32 v213, v213
	v_exp_f32_e32 v212, v212
	s_nop 0
	v_mul_f32_e32 v214, v213, v36
	v_mul_f32_e32 v217, v213, v164
	v_fma_f32 v210, v210, v212, v214
	v_fma_f32 v216, v216, v212, v217
; __device__ __forceinline__ bf16_t f2bf(float f) { return (bf16_t)(cvt_pk_bf16(f, 0.f) & 0xffffu); }
; __device__ __forceinline__ void scan_phase(const Bufs& B) {
;     ...
;             for (int u = 0; u < 16; ++u) { const int ch = dir ? 63 - (s0 + u) : s0 + u, it = dh * 64 + ch;
;                 B.CST[(size_t)it * 16384 + idx] = f2bf(cst);
;                 if (idx < 128) { B.NST[(size_t)it * 128 + idx] = nst; if (idx == 0) B.MST[it] = m; }
;                 const float mnew = fmaxf(bl[u] + m, ml[u]), a = __expf(bl[u] + m - mnew), g = __expf(ml[u] - mnew);
;                 cst = a * cst + g * cl[u]; nst = a * nst + g * nl[u]; m = mnew; }
	v_cvt_pk_bf16_f32 v215, v210, v195
	v_readlane_b32 s41, v206, 38
	v_readlane_b32 s42, v207, 38
	global_store_short v202, v215, s[8:9]
	s_add_u32 s8, s8, s12
	s_addc_u32 s9, s9, s13
	global_store_dword v205, v216, s[24:25]
	s_add_u32 s24, s24, s28
	s_addc_u32 s25, s25, s29
	s_mov_b64 exec, s[46:47]
	global_store_dword v195, v209, s[26:27]
	s_mov_b64 exec, -1
	s_add_u32 s26, s26, s30
	s_addc_u32 s27, s27, s31
	v_add_f32_e32 v211, s44, v209
	v_max_f32_e32 v208, s43, v211
	v_sub_f32_e32 v212, v211, v208
	v_sub_f32_e32 v213, s43, v208
	v_mul_f32_e32 v212, 0x3fb8aa3b, v212
	v_mul_f32_e32 v213, 0x3fb8aa3b, v213
	v_exp_f32_e32 v213, v213
	v_exp_f32_e32 v212, v212
	s_nop 0
	v_mul_f32_e32 v214, v213, v37
	v_mul_f32_e32 v217, v213, v165
	v_fma_f32 v210, v210, v212, v214
	v_fma_f32 v216, v216, v212, v217
	v_cvt_pk_bf16_f32 v215, v210, v195
	v_readlane_b32 s43, v206, 39
	v_readlane_b32 s44, v207, 39
	global_store_short v202, v215, s[8:9]
	s_add_u32 s8, s8, s12
	s_addc_u32 s9, s9, s13
	global_store_dword v205, v216, s[24:25]
	s_add_u32 s24, s24, s28
	s_addc_u32 s25, s25, s29
	s_mov_b64 exec, s[46:47]
	global_store_dword v195, v208, s[26:27]
	s_mov_b64 exec, -1
	s_add_u32 s26, s26, s30
	s_addc_u32 s27, s27, s31
	v_add_f32_e32 v211, s42, v208
	v_max_f32_e32 v209, s41, v211
	v_sub_f32_e32 v212, v211, v209
	v_sub_f32_e32 v213, s41, v209
	v_mul_f32_e32 v212, 0x3fb8aa3b, v212
	v_mul_f32_e32 v213, 0x3fb8aa3b, v213
	v_exp_f32_e32 v213, v213
	v_exp_f32_e32 v212, v212
	s_nop 0
	v_mul_f32_e32 v214, v213, v38
	v_mul_f32_e32 v217, v213, v166
	v_fma_f32 v210, v210, v212, v214
	v_fma_f32 v216, v216, v212, v217
	v_cvt_pk_bf16_f32 v215, v210, v195
	v_readlane_b32 s41, v206, 40
	v_readlane_b32 s42, v207, 40
	global_store_short v202, v215, s[8:9]
	s_add_u32 s8, s8, s12
	s_addc_u32 s9, s9, s13
	global_store_dword v205, v216, s[24:25]
	s_add_u32 s24, s24, s28
	s_addc_u32 s25, s25, s29
	s_mov_b64 exec, s[46:47]
	global_store_dword v195, v209, s[26:27]
	s_mov_b64 exec, -1
	s_add_u32 s26, s26, s30
	s_addc_u32 s27, s27, s31
	v_add_f32_e32 v211, s44, v209
	v_max_f32_e32 v208, s43, v211
	v_sub_f32_e32 v212, v211, v208
	v_sub_f32_e32 v213, s43, v208
	v_mul_f32_e32 v212, 0x3fb8aa3b, v212
	v_mul_f32_e32 v213, 0x3fb8aa3b, v213
	v_exp_f32_e32 v213, v213
	v_exp_f32_e32 v212, v212
	s_nop 0
	v_mul_f32_e32 v214, v213, v39
	v_mul_f32_e32 v217, v213, v167
	v_fma_f32 v210, v210, v212, v214
	v_fma_f32 v216, v216, v212, v217
	v_cvt_pk_bf16_f32 v215, v210, v195
	v_readlane_b32 s43, v206, 41
	v_readlane_b32 s44, v207, 41
	global_store_short v202, v215, s[8:9]
	s_add_u32 s8, s8, s12
	s_addc_u32 s9, s9, s13
	global_store_dword v205, v216, s[24:25]
	s_add_u32 s24, s24, s28
	s_addc_u32 s25, s25, s29
	s_mov_b64 exec, s[46:47]
	global_store_dword v195, v208, s[26:27]
	s_mov_b64 exec, -1
	s_add_u32 s26, s26, s30
	s_addc_u32 s27, s27, s31
	v_add_f32_e32 v211, s42, v208
	v_max_f32_e32 v209, s41, v211
	v_sub_f32_e32 v212, v211, v209
	v_sub_f32_e32 v213, s41, v209
	v_mul_f32_e32 v212, 0x3fb8aa3b, v212
	v_mul_f32_e32 v213, 0x3fb8aa3b, v213
	v_exp_f32_e32 v213, v213
	v_exp_f32_e32 v212, v212
	s_nop 0
	v_mul_f32_e32 v214, v213, v40
	v_mul_f32_e32 v217, v213, v168
	v_fma_f32 v210, v210, v212, v214
	v_fma_f32 v216, v216, v212, v217
	v_cvt_pk_bf16_f32 v215, v210, v195
	v_readlane_b32 s41, v206, 42
	v_readlane_b32 s42, v207, 42
	global_store_short v202, v215, s[8:9]
	s_add_u32 s8, s8, s12
	s_addc_u32 s9, s9, s13
	global_store_dword v205, v216, s[24:25]
	s_add_u32 s24, s24, s28
	s_addc_u32 s25, s25, s29
	s_mov_b64 exec, s[46:47]
	global_store_dword v195, v209, s[26:27]
	s_mov_b64 exec, -1
	s_add_u32 s26, s26, s30
	s_addc_u32 s27, s27, s31
	v_add_f32_e32 v211, s44, v209
	v_max_f32_e32 v208, s43, v211
	v_sub_f32_e32 v212, v211, v208
	v_sub_f32_e32 v213, s43, v208
	v_mul_f32_e32 v212, 0x3fb8aa3b, v212
	v_mul_f32_e32 v213, 0x3fb8aa3b, v213
	v_exp_f32_e32 v213, v213
	v_exp_f32_e32 v212, v212
	s_nop 0
	v_mul_f32_e32 v214, v213, v41
	v_mul_f32_e32 v217, v213, v169
	v_fma_f32 v210, v210, v212, v214
	v_fma_f32 v216, v216, v212, v217
	v_cvt_pk_bf16_f32 v215, v210, v195
	v_readlane_b32 s43, v206, 43
	v_readlane_b32 s44, v207, 43
	global_store_short v202, v215, s[8:9]
	s_add_u32 s8, s8, s12
	s_addc_u32 s9, s9, s13
	global_store_dword v205, v216, s[24:25]
	s_add_u32 s24, s24, s28
	s_addc_u32 s25, s25, s29
	s_mov_b64 exec, s[46:47]
	global_store_dword v195, v208, s[26:27]
	s_mov_b64 exec, -1
	s_add_u32 s26, s26, s30
	s_addc_u32 s27, s27, s31
	v_add_f32_e32 v211, s42, v208
	v_max_f32_e32 v209, s41, v211
	v_sub_f32_e32 v212, v211, v209
	v_sub_f32_e32 v213, s41, v209
	v_mul_f32_e32 v212, 0x3fb8aa3b, v212
	v_mul_f32_e32 v213, 0x3fb8aa3b, v213
	v_exp_f32_e32 v213, v213
	v_exp_f32_e32 v212, v212
	s_nop 0
	v_mul_f32_e32 v214, v213, v42
	v_mul_f32_e32 v217, v213, v170
	v_fma_f32 v210, v210, v212, v214
	v_fma_f32 v216, v216, v212, v217
	v_cvt_pk_bf16_f32 v215, v210, v195
	v_readlane_b32 s41, v206, 44
	v_readlane_b32 s42, v207, 44
	global_store_short v202, v215, s[8:9]
	s_add_u32 s8, s8, s12
	s_addc_u32 s9, s9, s13
	global_store_dword v205, v216, s[24:25]
	s_add_u32 s24, s24, s28
	s_addc_u32 s25, s25, s29
	s_mov_b64 exec, s[46:47]
	global_store_dword v195, v209, s[26:27]
	s_mov_b64 exec, -1
	s_add_u32 s26, s26, s30
	s_addc_u32 s27, s27, s31
	v_add_f32_e32 v211, s44, v209
	v_max_f32_e32 v208, s43, v211
	v_sub_f32_e32 v212, v211, v208
	v_sub_f32_e32 v213, s43, v208
	v_mul_f32_e32 v212, 0x3fb8aa3b, v212
	v_mul_f32_e32 v213, 0x3fb8aa3b, v213
	v_exp_f32_e32 v213, v213
	v_exp_f32_e32 v212, v212
	s_nop 0
	v_mul_f32_e32 v214, v213, v43
	v_mul_f32_e32 v217, v213, v171
	v_fma_f32 v210, v210, v212, v214
	v_fma_f32 v216, v216, v212, v217
; __device__ __forceinline__ bf16_t f2bf(float f) { return (bf16_t)(cvt_pk_bf16(f, 0.f) & 0xffffu); }
; __device__ __forceinline__ void scan_phase(const Bufs& B) {
;     ...
;             for (int u = 0; u < 16; ++u) { const int ch = dir ? 63 - (s0 + u) : s0 + u, it = dh * 64 + ch;
;                 B.CST[(size_t)it * 16384 + idx] = f2bf(cst);
;                 if (idx < 128) { B.NST[(size_t)it * 128 + idx] = nst; if (idx == 0) B.MST[it] = m; }
;                 const float mnew = fmaxf(bl[u] + m, ml[u]), a = __expf(bl[u] + m - mnew), g = __expf(ml[u] - mnew);
;                 cst = a * cst + g * cl[u]; nst = a * nst + g * nl[u]; m = mnew; }
	v_cvt_pk_bf16_f32 v215, v210, v195
	v_readlane_b32 s43, v206, 45
	v_readlane_b32 s44, v207, 45
	global_store_short v202, v215, s[8:9]
	s_add_u32 s8, s8, s12
	s_addc_u32 s9, s9, s13
	global_store_dword v205, v216, s[24:25]
	s_add_u32 s24, s24, s28
	s_addc_u32 s25, s25, s29
	s_mov_b64 exec, s[46:47]
	global_store_dword v195, v208, s[26:27]
	s_mov_b64 exec, -1
	s_add_u32 s26, s26, s30
	s_addc_u32 s27, s27, s31
	v_add_f32_e32 v211, s42, v208
	v_max_f32_e32 v209, s41, v211
	v_sub_f32_e32 v212, v211, v209
	v_sub_f32_e32 v213, s41, v209
	v_mul_f32_e32 v212, 0x3fb8aa3b, v212
	v_mul_f32_e32 v213, 0x3fb8aa3b, v213
	v_exp_f32_e32 v213, v213
	v_exp_f32_e32 v212, v212
	s_nop 0
	v_mul_f32_e32 v214, v213, v44
	v_mul_f32_e32 v217, v213, v172
	v_fma_f32 v210, v210, v212, v214
	v_fma_f32 v216, v216, v212, v217
	v_cvt_pk_bf16_f32 v215, v210, v195
	v_readlane_b32 s41, v206, 46
	v_readlane_b32 s42, v207, 46
	global_store_short v202, v215, s[8:9]
	s_add_u32 s8, s8, s12
	s_addc_u32 s9, s9, s13
	global_store_dword v205, v216, s[24:25]
	s_add_u32 s24, s24, s28
	s_addc_u32 s25, s25, s29
	s_mov_b64 exec, s[46:47]
	global_store_dword v195, v209, s[26:27]
	s_mov_b64 exec, -1
	s_add_u32 s26, s26, s30
	s_addc_u32 s27, s27, s31
	v_add_f32_e32 v211, s44, v209
	v_max_f32_e32 v208, s43, v211
	v_sub_f32_e32 v212, v211, v208
	v_sub_f32_e32 v213, s43, v208
	v_mul_f32_e32 v212, 0x3fb8aa3b, v212
	v_mul_f32_e32 v213, 0x3fb8aa3b, v213
	v_exp_f32_e32 v213, v213
	v_exp_f32_e32 v212, v212
	s_nop 0
	v_mul_f32_e32 v214, v213, v45
	v_mul_f32_e32 v217, v213, v173
	v_fma_f32 v210, v210, v212, v214
	v_fma_f32 v216, v216, v212, v217
	v_cvt_pk_bf16_f32 v215, v210, v195
	v_readlane_b32 s43, v206, 47
	v_readlane_b32 s44, v207, 47
	global_store_short v202, v215, s[8:9]
	s_add_u32 s8, s8, s12
	s_addc_u32 s9, s9, s13
	global_store_dword v205, v216, s[24:25]
	s_add_u32 s24, s24, s28
	s_addc_u32 s25, s25, s29
	s_mov_b64 exec, s[46:47]
	global_store_dword v195, v208, s[26:27]
	s_mov_b64 exec, -1
	s_add_u32 s26, s26, s30
	s_addc_u32 s27, s27, s31
	v_add_f32_e32 v211, s42, v208
	v_max_f32_e32 v209, s41, v211
	v_sub_f32_e32 v212, v211, v209
	v_sub_f32_e32 v213, s41, v209
	v_mul_f32_e32 v212, 0x3fb8aa3b, v212
	v_mul_f32_e32 v213, 0x3fb8aa3b, v213
	v_exp_f32_e32 v213, v213
	v_exp_f32_e32 v212, v212
	s_nop 0
	v_mul_f32_e32 v214, v213, v46
	v_mul_f32_e32 v217, v213, v174
	v_fma_f32 v210, v210, v212, v214
	v_fma_f32 v216, v216, v212, v217
	v_cvt_pk_bf16_f32 v215, v210, v195
	v_readlane_b32 s41, v206, 48
	v_readlane_b32 s42, v207, 48
	global_store_short v202, v215, s[8:9]
	s_add_u32 s8, s8, s12
	s_addc_u32 s9, s9, s13
	global_store_dword v205, v216, s[24:25]
	s_add_u32 s24, s24, s28
	s_addc_u32 s25, s25, s29
	s_mov_b64 exec, s[46:47]
	global_store_dword v195, v209, s[26:27]
	s_mov_b64 exec, -1
	s_add_u32 s26, s26, s30
	s_addc_u32 s27, s27, s31
	v_add_f32_e32 v211, s44, v209
	v_max_f32_e32 v208, s43, v211
	v_sub_f32_e32 v212, v211, v208
	v_sub_f32_e32 v213, s43, v208
	v_mul_f32_e32 v212, 0x3fb8aa3b, v212
	v_mul_f32_e32 v213, 0x3fb8aa3b, v213
	v_exp_f32_e32 v213, v213
	v_exp_f32_e32 v212, v212
	s_nop 0
	v_mul_f32_e32 v214, v213, v47
	v_mul_f32_e32 v217, v213, v175
	v_fma_f32 v210, v210, v212, v214
	v_fma_f32 v216, v216, v212, v217
	s_waitcnt vmcnt(63)
	v_cvt_pk_bf16_f32 v215, v210, v195
	v_readlane_b32 s43, v206, 49
	v_readlane_b32 s44, v207, 49
	global_store_short v202, v215, s[8:9]
	s_add_u32 s8, s8, s12
	s_addc_u32 s9, s9, s13
	global_store_dword v205, v216, s[24:25]
	s_add_u32 s24, s24, s28
	s_addc_u32 s25, s25, s29
	s_mov_b64 exec, s[46:47]
	global_store_dword v195, v208, s[26:27]
	s_mov_b64 exec, -1
	s_add_u32 s26, s26, s30
	s_addc_u32 s27, s27, s31
	v_add_f32_e32 v211, s42, v208
	v_max_f32_e32 v209, s41, v211
	v_sub_f32_e32 v212, v211, v209
	v_sub_f32_e32 v213, s41, v209
	v_mul_f32_e32 v212, 0x3fb8aa3b, v212
	v_mul_f32_e32 v213, 0x3fb8aa3b, v213
	v_exp_f32_e32 v213, v213
	v_exp_f32_e32 v212, v212
	s_nop 0
	v_mul_f32_e32 v214, v213, v48
	v_mul_f32_e32 v217, v213, v176
	v_fma_f32 v210, v210, v212, v214
	v_fma_f32 v216, v216, v212, v217
	v_cvt_pk_bf16_f32 v215, v210, v195
	v_readlane_b32 s41, v206, 50
	v_readlane_b32 s42, v207, 50
	global_store_short v202, v215, s[8:9]
	s_add_u32 s8, s8, s12
	s_addc_u32 s9, s9, s13
	global_store_dword v205, v216, s[24:25]
	s_add_u32 s24, s24, s28
	s_addc_u32 s25, s25, s29
	s_mov_b64 exec, s[46:47]
	global_store_dword v195, v209, s[26:27]
	s_mov_b64 exec, -1
	s_add_u32 s26, s26, s30
	s_addc_u32 s27, s27, s31
	v_add_f32_e32 v211, s44, v209
	v_max_f32_e32 v208, s43, v211
	v_sub_f32_e32 v212, v211, v208
	v_sub_f32_e32 v213, s43, v208
	v_mul_f32_e32 v212, 0x3fb8aa3b, v212
	v_mul_f32_e32 v213, 0x3fb8aa3b, v213
	v_exp_f32_e32 v213, v213
	v_exp_f32_e32 v212, v212
	s_nop 0
	v_mul_f32_e32 v214, v213, v49
	v_mul_f32_e32 v217, v213, v177
	v_fma_f32 v210, v210, v212, v214
	v_fma_f32 v216, v216, v212, v217
	v_cvt_pk_bf16_f32 v215, v210, v195
	v_readlane_b32 s43, v206, 51
	v_readlane_b32 s44, v207, 51
	global_store_short v202, v215, s[8:9]
	s_add_u32 s8, s8, s12
	s_addc_u32 s9, s9, s13
	global_store_dword v205, v216, s[24:25]
	s_add_u32 s24, s24, s28
	s_addc_u32 s25, s25, s29
	s_mov_b64 exec, s[46:47]
	global_store_dword v195, v208, s[26:27]
	s_mov_b64 exec, -1
	s_add_u32 s26, s26, s30
	s_addc_u32 s27, s27, s31
	v_add_f32_e32 v211, s42, v208
	v_max_f32_e32 v209, s41, v211
	v_sub_f32_e32 v212, v211, v209
	v_sub_f32_e32 v213, s41, v209
	v_mul_f32_e32 v212, 0x3fb8aa3b, v212
	v_mul_f32_e32 v213, 0x3fb8aa3b, v213
	v_exp_f32_e32 v213, v213
	v_exp_f32_e32 v212, v212
	s_nop 0
	v_mul_f32_e32 v214, v213, v50
	v_mul_f32_e32 v217, v213, v178
	v_fma_f32 v210, v210, v212, v214
	v_fma_f32 v216, v216, v212, v217
; __device__ __forceinline__ bf16_t f2bf(float f) { return (bf16_t)(cvt_pk_bf16(f, 0.f) & 0xffffu); }
; __device__ __forceinline__ void scan_phase(const Bufs& B) {
;     ...
;             for (int u = 0; u < 16; ++u) { const int ch = dir ? 63 - (s0 + u) : s0 + u, it = dh * 64 + ch;
;                 B.CST[(size_t)it * 16384 + idx] = f2bf(cst);
;                 if (idx < 128) { B.NST[(size_t)it * 128 + idx] = nst; if (idx == 0) B.MST[it] = m; }
;                 const float mnew = fmaxf(bl[u] + m, ml[u]), a = __expf(bl[u] + m - mnew), g = __expf(ml[u] - mnew);
;                 cst = a * cst + g * cl[u]; nst = a * nst + g * nl[u]; m = mnew; }
	v_cvt_pk_bf16_f32 v215, v210, v195
	v_readlane_b32 s41, v206, 52
	v_readlane_b32 s42, v207, 52
	global_store_short v202, v215, s[8:9]
	s_add_u32 s8, s8, s12
	s_addc_u32 s9, s9, s13
	global_store_dword v205, v216, s[24:25]
	s_add_u32 s24, s24, s28
	s_addc_u32 s25, s25, s29
	s_mov_b64 exec, s[46:47]
	global_store_dword v195, v209, s[26:27]
	s_mov_b64 exec, -1
	s_add_u32 s26, s26, s30
	s_addc_u32 s27, s27, s31
	v_add_f32_e32 v211, s44, v209
	v_max_f32_e32 v208, s43, v211
	v_sub_f32_e32 v212, v211, v208
	v_sub_f32_e32 v213, s43, v208
	v_mul_f32_e32 v212, 0x3fb8aa3b, v212
	v_mul_f32_e32 v213, 0x3fb8aa3b, v213
	v_exp_f32_e32 v213, v213
	v_exp_f32_e32 v212, v212
	s_nop 0
	v_mul_f32_e32 v214, v213, v51
	v_mul_f32_e32 v217, v213, v179
	v_fma_f32 v210, v210, v212, v214
	v_fma_f32 v216, v216, v212, v217
	v_cvt_pk_bf16_f32 v215, v210, v195
	v_readlane_b32 s43, v206, 53
	v_readlane_b32 s44, v207, 53
	global_store_short v202, v215, s[8:9]
	s_add_u32 s8, s8, s12
	s_addc_u32 s9, s9, s13
	global_store_dword v205, v216, s[24:25]
	s_add_u32 s24, s24, s28
	s_addc_u32 s25, s25, s29
	s_mov_b64 exec, s[46:47]
	global_store_dword v195, v208, s[26:27]
	s_mov_b64 exec, -1
	s_add_u32 s26, s26, s30
	s_addc_u32 s27, s27, s31
	v_add_f32_e32 v211, s42, v208
	v_max_f32_e32 v209, s41, v211
	v_sub_f32_e32 v212, v211, v209
	v_sub_f32_e32 v213, s41, v209
	v_mul_f32_e32 v212, 0x3fb8aa3b, v212
	v_mul_f32_e32 v213, 0x3fb8aa3b, v213
	v_exp_f32_e32 v213, v213
	v_exp_f32_e32 v212, v212
	s_nop 0
	v_mul_f32_e32 v214, v213, v52
	v_mul_f32_e32 v217, v213, v180
	v_fma_f32 v210, v210, v212, v214
	v_fma_f32 v216, v216, v212, v217
	v_cvt_pk_bf16_f32 v215, v210, v195
	v_readlane_b32 s41, v206, 54
	v_readlane_b32 s42, v207, 54
	global_store_short v202, v215, s[8:9]
	s_add_u32 s8, s8, s12
	s_addc_u32 s9, s9, s13
	global_store_dword v205, v216, s[24:25]
	s_add_u32 s24, s24, s28
	s_addc_u32 s25, s25, s29
	s_mov_b64 exec, s[46:47]
	global_store_dword v195, v209, s[26:27]
	s_mov_b64 exec, -1
	s_add_u32 s26, s26, s30
	s_addc_u32 s27, s27, s31
	v_add_f32_e32 v211, s44, v209
	v_max_f32_e32 v208, s43, v211
	v_sub_f32_e32 v212, v211, v208
	v_sub_f32_e32 v213, s43, v208
	v_mul_f32_e32 v212, 0x3fb8aa3b, v212
	v_mul_f32_e32 v213, 0x3fb8aa3b, v213
	v_exp_f32_e32 v213, v213
	v_exp_f32_e32 v212, v212
	s_nop 0
	v_mul_f32_e32 v214, v213, v53
	v_mul_f32_e32 v217, v213, v181
	v_fma_f32 v210, v210, v212, v214
	v_fma_f32 v216, v216, v212, v217
	v_cvt_pk_bf16_f32 v215, v210, v195
	v_readlane_b32 s43, v206, 55
	v_readlane_b32 s44, v207, 55
	global_store_short v202, v215, s[8:9]
	s_add_u32 s8, s8, s12
	s_addc_u32 s9, s9, s13
	global_store_dword v205, v216, s[24:25]
	s_add_u32 s24, s24, s28
	s_addc_u32 s25, s25, s29
	s_mov_b64 exec, s[46:47]
	global_store_dword v195, v208, s[26:27]
	s_mov_b64 exec, -1
	s_add_u32 s26, s26, s30
	s_addc_u32 s27, s27, s31
	v_add_f32_e32 v211, s42, v208
	v_max_f32_e32 v209, s41, v211
	v_sub_f32_e32 v212, v211, v209
	v_sub_f32_e32 v213, s41, v209
	v_mul_f32_e32 v212, 0x3fb8aa3b, v212
	v_mul_f32_e32 v213, 0x3fb8aa3b, v213
	v_exp_f32_e32 v213, v213
	v_exp_f32_e32 v212, v212
	s_nop 0
	v_mul_f32_e32 v214, v213, v54
	v_mul_f32_e32 v217, v213, v182
	v_fma_f32 v210, v210, v212, v214
	v_fma_f32 v216, v216, v212, v217
	v_cvt_pk_bf16_f32 v215, v210, v195
	v_readlane_b32 s41, v206, 56
	v_readlane_b32 s42, v207, 56
	global_store_short v202, v215, s[8:9]
	s_add_u32 s8, s8, s12
	s_addc_u32 s9, s9, s13
	global_store_dword v205, v216, s[24:25]
	s_add_u32 s24, s24, s28
	s_addc_u32 s25, s25, s29
	s_mov_b64 exec, s[46:47]
	global_store_dword v195, v209, s[26:27]
	s_mov_b64 exec, -1
	s_add_u32 s26, s26, s30
	s_addc_u32 s27, s27, s31
	v_add_f32_e32 v211, s44, v209
	v_max_f32_e32 v208, s43, v211
	v_sub_f32_e32 v212, v211, v208
	v_sub_f32_e32 v213, s43, v208
	v_mul_f32_e32 v212, 0x3fb8aa3b, v212
	v_mul_f32_e32 v213, 0x3fb8aa3b, v213
	v_exp_f32_e32 v213, v213
	v_exp_f32_e32 v212, v212
	s_nop 0
	v_mul_f32_e32 v214, v213, v55
	v_mul_f32_e32 v217, v213, v183
	v_fma_f32 v210, v210, v212, v214
	v_fma_f32 v216, v216, v212, v217
	v_cvt_pk_bf16_f32 v215, v210, v195
	v_readlane_b32 s43, v206, 57
	v_readlane_b32 s44, v207, 57
	global_store_short v202, v215, s[8:9]
	s_add_u32 s8, s8, s12
	s_addc_u32 s9, s9, s13
	global_store_dword v205, v216, s[24:25]
	s_add_u32 s24, s24, s28
	s_addc_u32 s25, s25, s29
	s_mov_b64 exec, s[46:47]
	global_store_dword v195, v208, s[26:27]
	s_mov_b64 exec, -1
	s_add_u32 s26, s26, s30
	s_addc_u32 s27, s27, s31
	v_add_f32_e32 v211, s42, v208
	v_max_f32_e32 v209, s41, v211
	v_sub_f32_e32 v212, v211, v209
	v_sub_f32_e32 v213, s41, v209
	v_mul_f32_e32 v212, 0x3fb8aa3b, v212
	v_mul_f32_e32 v213, 0x3fb8aa3b, v213
	v_exp_f32_e32 v213, v213
	v_exp_f32_e32 v212, v212
	s_nop 0
	v_mul_f32_e32 v214, v213, v56
	v_mul_f32_e32 v217, v213, v184
	v_fma_f32 v210, v210, v212, v214
	v_fma_f32 v216, v216, v212, v217
	v_cvt_pk_bf16_f32 v215, v210, v195
	v_readlane_b32 s41, v206, 58
	v_readlane_b32 s42, v207, 58
	global_store_short v202, v215, s[8:9]
	s_add_u32 s8, s8, s12
	s_addc_u32 s9, s9, s13
	global_store_dword v205, v216, s[24:25]
	s_add_u32 s24, s24, s28
	s_addc_u32 s25, s25, s29
	s_mov_b64 exec, s[46:47]
	global_store_dword v195, v209, s[26:27]
	s_mov_b64 exec, -1
	s_add_u32 s26, s26, s30
	s_addc_u32 s27, s27, s31
	v_add_f32_e32 v211, s44, v209
	v_max_f32_e32 v208, s43, v211
	v_sub_f32_e32 v212, v211, v208
	v_sub_f32_e32 v213, s43, v208
	v_mul_f32_e32 v212, 0x3fb8aa3b, v212
	v_mul_f32_e32 v213, 0x3fb8aa3b, v213
	v_exp_f32_e32 v213, v213
	v_exp_f32_e32 v212, v212
	s_nop 0
	v_mul_f32_e32 v214, v213, v57
	v_mul_f32_e32 v217, v213, v185
	v_fma_f32 v210, v210, v212, v214
	v_fma_f32 v216, v216, v212, v217
; __device__ __forceinline__ bf16_t f2bf(float f) { return (bf16_t)(cvt_pk_bf16(f, 0.f) & 0xffffu); }
; __device__ __forceinline__ void scan_phase(const Bufs& B) {
;     ...
;             for (int u = 0; u < 16; ++u) { const int ch = dir ? 63 - (s0 + u) : s0 + u, it = dh * 64 + ch;
;                 B.CST[(size_t)it * 16384 + idx] = f2bf(cst);
;                 if (idx < 128) { B.NST[(size_t)it * 128 + idx] = nst; if (idx == 0) B.MST[it] = m; }
;                 const float mnew = fmaxf(bl[u] + m, ml[u]), a = __expf(bl[u] + m - mnew), g = __expf(ml[u] - mnew);
;                 cst = a * cst + g * cl[u]; nst = a * nst + g * nl[u]; m = mnew; }
;     ...
;             for (int u = 0; u < 16; ++u) { const int ch = dir ? 63 - (s0 + u) : s0 + u; B.RST[(size_t)(dh * 64 + ch) * 8192 + idx] = f2bf(r); r = cd * r + rl[u]; }
	v_cvt_pk_bf16_f32 v215, v210, v195
	v_readlane_b32 s43, v206, 59
	v_readlane_b32 s44, v207, 59
	global_store_short v202, v215, s[8:9]
	s_add_u32 s8, s8, s12
	s_addc_u32 s9, s9, s13
	global_store_dword v205, v216, s[24:25]
	s_add_u32 s24, s24, s28
	s_addc_u32 s25, s25, s29
	s_mov_b64 exec, s[46:47]
	global_store_dword v195, v208, s[26:27]
	s_mov_b64 exec, -1
	s_add_u32 s26, s26, s30
	s_addc_u32 s27, s27, s31
	v_add_f32_e32 v211, s42, v208
	v_max_f32_e32 v209, s41, v211
	v_sub_f32_e32 v212, v211, v209
	v_sub_f32_e32 v213, s41, v209
	v_mul_f32_e32 v212, 0x3fb8aa3b, v212
	v_mul_f32_e32 v213, 0x3fb8aa3b, v213
	v_exp_f32_e32 v213, v213
	v_exp_f32_e32 v212, v212
	s_nop 0
	v_mul_f32_e32 v214, v213, v58
	v_mul_f32_e32 v217, v213, v186
	v_fma_f32 v210, v210, v212, v214
	v_fma_f32 v216, v216, v212, v217
	v_cvt_pk_bf16_f32 v215, v210, v195
	v_readlane_b32 s41, v206, 60
	v_readlane_b32 s42, v207, 60
	global_store_short v202, v215, s[8:9]
	s_add_u32 s8, s8, s12
	s_addc_u32 s9, s9, s13
	global_store_dword v205, v216, s[24:25]
	s_add_u32 s24, s24, s28
	s_addc_u32 s25, s25, s29
	s_mov_b64 exec, s[46:47]
	global_store_dword v195, v209, s[26:27]
	s_mov_b64 exec, -1
	s_add_u32 s26, s26, s30
	s_addc_u32 s27, s27, s31
	v_add_f32_e32 v211, s44, v209
	v_max_f32_e32 v208, s43, v211
	v_sub_f32_e32 v212, v211, v208
	v_sub_f32_e32 v213, s43, v208
	v_mul_f32_e32 v212, 0x3fb8aa3b, v212
	v_mul_f32_e32 v213, 0x3fb8aa3b, v213
	v_exp_f32_e32 v213, v213
	v_exp_f32_e32 v212, v212
	s_nop 0
	v_mul_f32_e32 v214, v213, v59
	v_mul_f32_e32 v217, v213, v187
	v_fma_f32 v210, v210, v212, v214
	v_fma_f32 v216, v216, v212, v217
	v_cvt_pk_bf16_f32 v215, v210, v195
	v_readlane_b32 s43, v206, 61
	v_readlane_b32 s44, v207, 61
	global_store_short v202, v215, s[8:9]
	s_add_u32 s8, s8, s12
	s_addc_u32 s9, s9, s13
	global_store_dword v205, v216, s[24:25]
	s_add_u32 s24, s24, s28
	s_addc_u32 s25, s25, s29
	s_mov_b64 exec, s[46:47]
	global_store_dword v195, v208, s[26:27]
	s_mov_b64 exec, -1
	s_add_u32 s26, s26, s30
	s_addc_u32 s27, s27, s31
	v_add_f32_e32 v211, s42, v208
	v_max_f32_e32 v209, s41, v211
	v_sub_f32_e32 v212, v211, v209
	v_sub_f32_e32 v213, s41, v209
	v_mul_f32_e32 v212, 0x3fb8aa3b, v212
	v_mul_f32_e32 v213, 0x3fb8aa3b, v213
	v_exp_f32_e32 v213, v213
	v_exp_f32_e32 v212, v212
	s_nop 0
	v_mul_f32_e32 v214, v213, v60
	v_mul_f32_e32 v217, v213, v188
	v_fma_f32 v210, v210, v212, v214
	v_fma_f32 v216, v216, v212, v217
	v_cvt_pk_bf16_f32 v215, v210, v195
	v_readlane_b32 s41, v206, 62
	v_readlane_b32 s42, v207, 62
	global_store_short v202, v215, s[8:9]
	s_add_u32 s8, s8, s12
	s_addc_u32 s9, s9, s13
	global_store_dword v205, v216, s[24:25]
	s_add_u32 s24, s24, s28
	s_addc_u32 s25, s25, s29
	s_mov_b64 exec, s[46:47]
	global_store_dword v195, v209, s[26:27]
	s_mov_b64 exec, -1
	s_add_u32 s26, s26, s30
	s_addc_u32 s27, s27, s31
	v_add_f32_e32 v211, s44, v209
	v_max_f32_e32 v208, s43, v211
	v_sub_f32_e32 v212, v211, v208
	v_sub_f32_e32 v213, s43, v208
	v_mul_f32_e32 v212, 0x3fb8aa3b, v212
	v_mul_f32_e32 v213, 0x3fb8aa3b, v213
	v_exp_f32_e32 v213, v213
	v_exp_f32_e32 v212, v212
	s_nop 0
	v_mul_f32_e32 v214, v213, v61
	v_mul_f32_e32 v217, v213, v189
	v_fma_f32 v210, v210, v212, v214
	v_fma_f32 v216, v216, v212, v217
	v_cvt_pk_bf16_f32 v215, v210, v195
	v_readlane_b32 s43, v206, 63
	v_readlane_b32 s44, v207, 63
	global_store_short v202, v215, s[8:9]
	s_add_u32 s8, s8, s12
	s_addc_u32 s9, s9, s13
	global_store_dword v205, v216, s[24:25]
	s_add_u32 s24, s24, s28
	s_addc_u32 s25, s25, s29
	s_mov_b64 exec, s[46:47]
	global_store_dword v195, v208, s[26:27]
	s_mov_b64 exec, -1
	s_add_u32 s26, s26, s30
	s_addc_u32 s27, s27, s31
	v_add_f32_e32 v211, s42, v208
	v_max_f32_e32 v209, s41, v211
	v_sub_f32_e32 v212, v211, v209
	v_sub_f32_e32 v213, s41, v209
	v_mul_f32_e32 v212, 0x3fb8aa3b, v212
	v_mul_f32_e32 v213, 0x3fb8aa3b, v213
	v_exp_f32_e32 v213, v213
	v_exp_f32_e32 v212, v212
	s_nop 0
	v_mul_f32_e32 v214, v213, v62
	v_mul_f32_e32 v217, v213, v190
	v_fma_f32 v210, v210, v212, v214
	v_fma_f32 v216, v216, v212, v217
	v_cvt_pk_bf16_f32 v215, v210, v195
	global_store_short v202, v215, s[8:9]
	s_add_u32 s8, s8, s12
	s_addc_u32 s9, s9, s13
	global_store_dword v205, v216, s[24:25]
	s_add_u32 s24, s24, s28
	s_addc_u32 s25, s25, s29
	s_mov_b64 exec, s[46:47]
	global_store_dword v195, v209, s[26:27]
	s_mov_b64 exec, -1
	s_add_u32 s26, s26, s30
	s_addc_u32 s27, s27, s31
	v_add_f32_e32 v211, s44, v209
	v_max_f32_e32 v208, s43, v211
	v_sub_f32_e32 v212, v211, v208
	v_sub_f32_e32 v213, s43, v208
	v_mul_f32_e32 v212, 0x3fb8aa3b, v212
	v_mul_f32_e32 v213, 0x3fb8aa3b, v213
	v_exp_f32_e32 v213, v213
	v_exp_f32_e32 v212, v212
	s_nop 0
	v_mul_f32_e32 v214, v213, v63
	v_mul_f32_e32 v217, v213, v191
	v_fma_f32 v210, v210, v212, v214
	v_fma_f32 v216, v216, v212, v217
	s_waitcnt vmcnt(63)
; __device__ __forceinline__ bf16_t f2bf(float f) { return (bf16_t)(cvt_pk_bf16(f, 0.f) & 0xffffu); }
; __device__ __forceinline__ void scan_phase(const Bufs& B) {
;     ...
;             for (int u = 0; u < 16; ++u) { const int ch = dir ? 63 - (s0 + u) : s0 + u; rl[u] = B.RLOC[(size_t)(dh * 64 + ch) * 8192 + idx]; }
; #pragma unroll
;             for (int u = 0; u < 16; ++u) { const int ch = dir ? 63 - (s0 + u) : s0 + u; B.RST[(size_t)(dh * 64 + ch) * 8192 + idx] = f2bf(r); r = cd * r + rl[u]; }
	v_cvt_pk_bf16_f32 v220, v218, v195
	v_fma_f32 v218, v219, v218, v64
	global_store_short v204, v220, s[16:17]
	s_add_u32 s16, s16, s20
	s_addc_u32 s17, s17, s21
	v_cvt_pk_bf16_f32 v220, v218, v195
	v_fma_f32 v218, v219, v218, v65
	global_store_short v204, v220, s[16:17]
	s_add_u32 s16, s16, s20
	s_addc_u32 s17, s17, s21
	v_cvt_pk_bf16_f32 v220, v218, v195
	v_fma_f32 v218, v219, v218, v66
	global_store_short v204, v220, s[16:17]
	s_add_u32 s16, s16, s20
	s_addc_u32 s17, s17, s21
	v_cvt_pk_bf16_f32 v220, v218, v195
	v_fma_f32 v218, v219, v218, v67
	global_store_short v204, v220, s[16:17]
	s_add_u32 s16, s16, s20
	s_addc_u32 s17, s17, s21
	v_cvt_pk_bf16_f32 v220, v218, v195
	v_fma_f32 v218, v219, v218, v68
	global_store_short v204, v220, s[16:17]
	s_add_u32 s16, s16, s20
	s_addc_u32 s17, s17, s21
	v_cvt_pk_bf16_f32 v220, v218, v195
	v_fma_f32 v218, v219, v218, v69
	global_store_short v204, v220, s[16:17]
	s_add_u32 s16, s16, s20
	s_addc_u32 s17, s17, s21
	v_cvt_pk_bf16_f32 v220, v218, v195
	v_fma_f32 v218, v219, v218, v70
	global_store_short v204, v220, s[16:17]
	s_add_u32 s16, s16, s20
	s_addc_u32 s17, s17, s21
	v_cvt_pk_bf16_f32 v220, v218, v195
	v_fma_f32 v218, v219, v218, v71
	global_store_short v204, v220, s[16:17]
	s_add_u32 s16, s16, s20
	s_addc_u32 s17, s17, s21
	v_cvt_pk_bf16_f32 v220, v218, v195
	v_fma_f32 v218, v219, v218, v72
	global_store_short v204, v220, s[16:17]
	s_add_u32 s16, s16, s20
	s_addc_u32 s17, s17, s21
	v_cvt_pk_bf16_f32 v220, v218, v195
	v_fma_f32 v218, v219, v218, v73
	global_store_short v204, v220, s[16:17]
	s_add_u32 s16, s16, s20
	s_addc_u32 s17, s17, s21
	v_cvt_pk_bf16_f32 v220, v218, v195
	v_fma_f32 v218, v219, v218, v74
	global_store_short v204, v220, s[16:17]
	s_add_u32 s16, s16, s20
	s_addc_u32 s17, s17, s21
	v_cvt_pk_bf16_f32 v220, v218, v195
	v_fma_f32 v218, v219, v218, v75
	global_store_short v204, v220, s[16:17]
	s_add_u32 s16, s16, s20
	s_addc_u32 s17, s17, s21
	v_cvt_pk_bf16_f32 v220, v218, v195
	v_fma_f32 v218, v219, v218, v76
	global_store_short v204, v220, s[16:17]
	s_add_u32 s16, s16, s20
	s_addc_u32 s17, s17, s21
	v_cvt_pk_bf16_f32 v220, v218, v195
	v_fma_f32 v218, v219, v218, v77
	global_store_short v204, v220, s[16:17]
	s_add_u32 s16, s16, s20
	s_addc_u32 s17, s17, s21
	v_cvt_pk_bf16_f32 v220, v218, v195
	v_fma_f32 v218, v219, v218, v78
	global_store_short v204, v220, s[16:17]
	s_add_u32 s16, s16, s20
	s_addc_u32 s17, s17, s21
	v_cvt_pk_bf16_f32 v220, v218, v195
	v_fma_f32 v218, v219, v218, v79
	global_store_short v204, v220, s[16:17]
	s_add_u32 s16, s16, s20
	s_addc_u32 s17, s17, s21
	s_waitcnt vmcnt(63)
	v_cvt_pk_bf16_f32 v220, v218, v195
	v_fma_f32 v218, v219, v218, v80
	global_store_short v204, v220, s[16:17]
	s_add_u32 s16, s16, s20
	s_addc_u32 s17, s17, s21
	v_cvt_pk_bf16_f32 v220, v218, v195
	v_fma_f32 v218, v219, v218, v81
	global_store_short v204, v220, s[16:17]
	s_add_u32 s16, s16, s20
	s_addc_u32 s17, s17, s21
	v_cvt_pk_bf16_f32 v220, v218, v195
	v_fma_f32 v218, v219, v218, v82
	global_store_short v204, v220, s[16:17]
	s_add_u32 s16, s16, s20
	s_addc_u32 s17, s17, s21
	v_cvt_pk_bf16_f32 v220, v218, v195
	v_fma_f32 v218, v219, v218, v83
	global_store_short v204, v220, s[16:17]
	s_add_u32 s16, s16, s20
	s_addc_u32 s17, s17, s21
	v_cvt_pk_bf16_f32 v220, v218, v195
	v_fma_f32 v218, v219, v218, v84
	global_store_short v204, v220, s[16:17]
	s_add_u32 s16, s16, s20
	s_addc_u32 s17, s17, s21
	v_cvt_pk_bf16_f32 v220, v218, v195
	v_fma_f32 v218, v219, v218, v85
	global_store_short v204, v220, s[16:17]
	s_add_u32 s16, s16, s20
	s_addc_u32 s17, s17, s21
	v_cvt_pk_bf16_f32 v220, v218, v195
	v_fma_f32 v218, v219, v218, v86
	global_store_short v204, v220, s[16:17]
	s_add_u32 s16, s16, s20
	s_addc_u32 s17, s17, s21
	v_cvt_pk_bf16_f32 v220, v218, v195
	v_fma_f32 v218, v219, v218, v87
	global_store_short v204, v220, s[16:17]
	s_add_u32 s16, s16, s20
	s_addc_u32 s17, s17, s21
	v_cvt_pk_bf16_f32 v220, v218, v195
	v_fma_f32 v218, v219, v218, v88
	global_store_short v204, v220, s[16:17]
	s_add_u32 s16, s16, s20
	s_addc_u32 s17, s17, s21
	v_cvt_pk_bf16_f32 v220, v218, v195
	v_fma_f32 v218, v219, v218, v89
	global_store_short v204, v220, s[16:17]
	s_add_u32 s16, s16, s20
	s_addc_u32 s17, s17, s21
	v_cvt_pk_bf16_f32 v220, v218, v195
	v_fma_f32 v218, v219, v218, v90
	global_store_short v204, v220, s[16:17]
	s_add_u32 s16, s16, s20
	s_addc_u32 s17, s17, s21
	v_cvt_pk_bf16_f32 v220, v218, v195
	v_fma_f32 v218, v219, v218, v91
	global_store_short v204, v220, s[16:17]
	s_add_u32 s16, s16, s20
	s_addc_u32 s17, s17, s21
	v_cvt_pk_bf16_f32 v220, v218, v195
	v_fma_f32 v218, v219, v218, v92
	global_store_short v204, v220, s[16:17]
	s_add_u32 s16, s16, s20
	s_addc_u32 s17, s17, s21
	v_cvt_pk_bf16_f32 v220, v218, v195
	v_fma_f32 v218, v219, v218, v93
	global_store_short v204, v220, s[16:17]
	s_add_u32 s16, s16, s20
	s_addc_u32 s17, s17, s21
	v_cvt_pk_bf16_f32 v220, v218, v195
	v_fma_f32 v218, v219, v218, v94
	global_store_short v204, v220, s[16:17]
	s_add_u32 s16, s16, s20
	s_addc_u32 s17, s17, s21
	v_cvt_pk_bf16_f32 v220, v218, v195
	v_fma_f32 v218, v219, v218, v95
	global_store_short v204, v220, s[16:17]
	s_add_u32 s16, s16, s20
	s_addc_u32 s17, s17, s21
	s_waitcnt vmcnt(63)
; __device__ __forceinline__ bf16_t f2bf(float f) { return (bf16_t)(cvt_pk_bf16(f, 0.f) & 0xffffu); }
; __device__ __forceinline__ void scan_phase(const Bufs& B) {
;     ...
;             for (int u = 0; u < 16; ++u) { const int ch = dir ? 63 - (s0 + u) : s0 + u; rl[u] = B.RLOC[(size_t)(dh * 64 + ch) * 8192 + idx]; }
; #pragma unroll
;             for (int u = 0; u < 16; ++u) { const int ch = dir ? 63 - (s0 + u) : s0 + u; B.RST[(size_t)(dh * 64 + ch) * 8192 + idx] = f2bf(r); r = cd * r + rl[u]; }
	v_cvt_pk_bf16_f32 v220, v218, v195
	v_fma_f32 v218, v219, v218, v96
	global_store_short v204, v220, s[16:17]
	s_add_u32 s16, s16, s20
	s_addc_u32 s17, s17, s21
	v_cvt_pk_bf16_f32 v220, v218, v195
	v_fma_f32 v218, v219, v218, v97
	global_store_short v204, v220, s[16:17]
	s_add_u32 s16, s16, s20
	s_addc_u32 s17, s17, s21
	v_cvt_pk_bf16_f32 v220, v218, v195
	v_fma_f32 v218, v219, v218, v98
	global_store_short v204, v220, s[16:17]
	s_add_u32 s16, s16, s20
	s_addc_u32 s17, s17, s21
	v_cvt_pk_bf16_f32 v220, v218, v195
	v_fma_f32 v218, v219, v218, v99
	global_store_short v204, v220, s[16:17]
	s_add_u32 s16, s16, s20
	s_addc_u32 s17, s17, s21
	v_cvt_pk_bf16_f32 v220, v218, v195
	v_fma_f32 v218, v219, v218, v100
	global_store_short v204, v220, s[16:17]
	s_add_u32 s16, s16, s20
	s_addc_u32 s17, s17, s21
	v_cvt_pk_bf16_f32 v220, v218, v195
	v_fma_f32 v218, v219, v218, v101
	global_store_short v204, v220, s[16:17]
	s_add_u32 s16, s16, s20
	s_addc_u32 s17, s17, s21
	v_cvt_pk_bf16_f32 v220, v218, v195
	v_fma_f32 v218, v219, v218, v102
	global_store_short v204, v220, s[16:17]
	s_add_u32 s16, s16, s20
	s_addc_u32 s17, s17, s21
	v_cvt_pk_bf16_f32 v220, v218, v195
	v_fma_f32 v218, v219, v218, v103
	global_store_short v204, v220, s[16:17]
	s_add_u32 s16, s16, s20
	s_addc_u32 s17, s17, s21
	v_cvt_pk_bf16_f32 v220, v218, v195
	v_fma_f32 v218, v219, v218, v104
	global_store_short v204, v220, s[16:17]
	s_add_u32 s16, s16, s20
	s_addc_u32 s17, s17, s21
	v_cvt_pk_bf16_f32 v220, v218, v195
	v_fma_f32 v218, v219, v218, v105
	global_store_short v204, v220, s[16:17]
	s_add_u32 s16, s16, s20
	s_addc_u32 s17, s17, s21
	v_cvt_pk_bf16_f32 v220, v218, v195
	v_fma_f32 v218, v219, v218, v106
	global_store_short v204, v220, s[16:17]
	s_add_u32 s16, s16, s20
	s_addc_u32 s17, s17, s21
	v_cvt_pk_bf16_f32 v220, v218, v195
	v_fma_f32 v218, v219, v218, v107
	global_store_short v204, v220, s[16:17]
	s_add_u32 s16, s16, s20
	s_addc_u32 s17, s17, s21
	v_cvt_pk_bf16_f32 v220, v218, v195
	v_fma_f32 v218, v219, v218, v108
	global_store_short v204, v220, s[16:17]
	s_add_u32 s16, s16, s20
	s_addc_u32 s17, s17, s21
	v_cvt_pk_bf16_f32 v220, v218, v195
	v_fma_f32 v218, v219, v218, v109
	global_store_short v204, v220, s[16:17]
	s_add_u32 s16, s16, s20
	s_addc_u32 s17, s17, s21
	v_cvt_pk_bf16_f32 v220, v218, v195
	v_fma_f32 v218, v219, v218, v110
	global_store_short v204, v220, s[16:17]
	s_add_u32 s16, s16, s20
	s_addc_u32 s17, s17, s21
	v_cvt_pk_bf16_f32 v220, v218, v195
	v_fma_f32 v218, v219, v218, v111
	global_store_short v204, v220, s[16:17]
	s_add_u32 s16, s16, s20
	s_addc_u32 s17, s17, s21
	s_waitcnt vmcnt(63)
	v_cvt_pk_bf16_f32 v220, v218, v195
	v_fma_f32 v218, v219, v218, v112
	global_store_short v204, v220, s[16:17]
	s_add_u32 s16, s16, s20
	s_addc_u32 s17, s17, s21
	v_cvt_pk_bf16_f32 v220, v218, v195
	v_fma_f32 v218, v219, v218, v113
	global_store_short v204, v220, s[16:17]
	s_add_u32 s16, s16, s20
	s_addc_u32 s17, s17, s21
	v_cvt_pk_bf16_f32 v220, v218, v195
	v_fma_f32 v218, v219, v218, v114
	global_store_short v204, v220, s[16:17]
	s_add_u32 s16, s16, s20
	s_addc_u32 s17, s17, s21
	v_cvt_pk_bf16_f32 v220, v218, v195
	v_fma_f32 v218, v219, v218, v115
	global_store_short v204, v220, s[16:17]
	s_add_u32 s16, s16, s20
	s_addc_u32 s17, s17, s21
	v_cvt_pk_bf16_f32 v220, v218, v195
	v_fma_f32 v218, v219, v218, v116
	global_store_short v204, v220, s[16:17]
	s_add_u32 s16, s16, s20
	s_addc_u32 s17, s17, s21
	v_cvt_pk_bf16_f32 v220, v218, v195
	v_fma_f32 v218, v219, v218, v117
	global_store_short v204, v220, s[16:17]
	s_add_u32 s16, s16, s20
	s_addc_u32 s17, s17, s21
	v_cvt_pk_bf16_f32 v220, v218, v195
	v_fma_f32 v218, v219, v218, v118
	global_store_short v204, v220, s[16:17]
	s_add_u32 s16, s16, s20
	s_addc_u32 s17, s17, s21
	v_cvt_pk_bf16_f32 v220, v218, v195
	v_fma_f32 v218, v219, v218, v119
	global_store_short v204, v220, s[16:17]
	s_add_u32 s16, s16, s20
	s_addc_u32 s17, s17, s21
	v_cvt_pk_bf16_f32 v220, v218, v195
	v_fma_f32 v218, v219, v218, v120
	global_store_short v204, v220, s[16:17]
	s_add_u32 s16, s16, s20
	s_addc_u32 s17, s17, s21
	v_cvt_pk_bf16_f32 v220, v218, v195
	v_fma_f32 v218, v219, v218, v121
	global_store_short v204, v220, s[16:17]
	s_add_u32 s16, s16, s20
	s_addc_u32 s17, s17, s21
	v_cvt_pk_bf16_f32 v220, v218, v195
	v_fma_f32 v218, v219, v218, v122
	global_store_short v204, v220, s[16:17]
	s_add_u32 s16, s16, s20
	s_addc_u32 s17, s17, s21
	v_cvt_pk_bf16_f32 v220, v218, v195
	v_fma_f32 v218, v219, v218, v123
	global_store_short v204, v220, s[16:17]
	s_add_u32 s16, s16, s20
	s_addc_u32 s17, s17, s21
	v_cvt_pk_bf16_f32 v220, v218, v195
	v_fma_f32 v218, v219, v218, v124
	global_store_short v204, v220, s[16:17]
	s_add_u32 s16, s16, s20
	s_addc_u32 s17, s17, s21
	v_cvt_pk_bf16_f32 v220, v218, v195
	v_fma_f32 v218, v219, v218, v125
	global_store_short v204, v220, s[16:17]
	s_add_u32 s16, s16, s20
	s_addc_u32 s17, s17, s21
	v_cvt_pk_bf16_f32 v220, v218, v195
	v_fma_f32 v218, v219, v218, v126
	global_store_short v204, v220, s[16:17]
	s_add_u32 s16, s16, s20
	s_addc_u32 s17, s17, s21
	v_cvt_pk_bf16_f32 v220, v218, v195
	v_fma_f32 v218, v219, v218, v127
	global_store_short v204, v220, s[16:17]
	s_add_u32 s16, s16, s20
	s_addc_u32 s17, s17, s21
	s_branch .Lscan_done
; __device__ __forceinline__ void scan_phase(const Bufs& B) {
;     ...
;             for (int u = 0; u < 16; ++u) { const int ch = dir ? 63 - (s0 + u) : s0 + u, it = dh * 64 + ch;
;                 cl[u] = B.CLOC[(size_t)it * 16384 + idx]; ml[u] = B.MLOC[it]; bl[u] = B.BLAST[it]; nl[u] = idx < 128 ? B.NLOC[(size_t)it * 128 + idx] : 0.f; }
.Lscan_v10:
	global_load_dword v206, v222, s[50:51]
	global_load_dword v207, v222, s[50:51] offset:2048
	global_load_dword v0, v201, s[6:7]
	s_add_u32 s6, s6, s10
	s_addc_u32 s7, s7, s11
	global_load_dword v128, v205, s[22:23]
	s_add_u32 s22, s22, s28
	s_addc_u32 s23, s23, s29
	global_load_dword v1, v201, s[6:7]
	s_add_u32 s6, s6, s10
	s_addc_u32 s7, s7, s11
	global_load_dword v129, v205, s[22:23]
	s_add_u32 s22, s22, s28
	s_addc_u32 s23, s23, s29
	global_load_dword v2, v201, s[6:7]
	s_add_u32 s6, s6, s10
	s_addc_u32 s7, s7, s11
	global_load_dword v130, v205, s[22:23]
	s_add_u32 s22, s22, s28
	s_addc_u32 s23, s23, s29
	global_load_dword v3, v201, s[6:7]
	s_add_u32 s6, s6, s10
	s_addc_u32 s7, s7, s11
	global_load_dword v131, v205, s[22:23]
	s_add_u32 s22, s22, s28
	s_addc_u32 s23, s23, s29
	global_load_dword v4, v201, s[6:7]
	s_add_u32 s6, s6, s10
	s_addc_u32 s7, s7, s11
	global_load_dword v132, v205, s[22:23]
	s_add_u32 s22, s22, s28
	s_addc_u32 s23, s23, s29
	global_load_dword v5, v201, s[6:7]
	s_add_u32 s6, s6, s10
	s_addc_u32 s7, s7, s11
	global_load_dword v133, v205, s[22:23]
	s_add_u32 s22, s22, s28
	s_addc_u32 s23, s23, s29
	global_load_dword v6, v201, s[6:7]
	s_add_u32 s6, s6, s10
	s_addc_u32 s7, s7, s11
	global_load_dword v134, v205, s[22:23]
	s_add_u32 s22, s22, s28
	s_addc_u32 s23, s23, s29
	global_load_dword v7, v201, s[6:7]
	s_add_u32 s6, s6, s10
	s_addc_u32 s7, s7, s11
	global_load_dword v135, v205, s[22:23]
	s_add_u32 s22, s22, s28
	s_addc_u32 s23, s23, s29
	global_load_dword v8, v201, s[6:7]
	s_add_u32 s6, s6, s10
	s_addc_u32 s7, s7, s11
	global_load_dword v136, v205, s[22:23]
	s_add_u32 s22, s22, s28
	s_addc_u32 s23, s23, s29
	global_load_dword v9, v201, s[6:7]
	s_add_u32 s6, s6, s10
	s_addc_u32 s7, s7, s11
	global_load_dword v137, v205, s[22:23]
	s_add_u32 s22, s22, s28
	s_addc_u32 s23, s23, s29
	global_load_dword v10, v201, s[6:7]
	s_add_u32 s6, s6, s10
	s_addc_u32 s7, s7, s11
	global_load_dword v138, v205, s[22:23]
	s_add_u32 s22, s22, s28
	s_addc_u32 s23, s23, s29
	global_load_dword v11, v201, s[6:7]
	s_add_u32 s6, s6, s10
	s_addc_u32 s7, s7, s11
	global_load_dword v139, v205, s[22:23]
	s_add_u32 s22, s22, s28
	s_addc_u32 s23, s23, s29
	global_load_dword v12, v201, s[6:7]
	s_add_u32 s6, s6, s10
	s_addc_u32 s7, s7, s11
	global_load_dword v140, v205, s[22:23]
	s_add_u32 s22, s22, s28
	s_addc_u32 s23, s23, s29
	global_load_dword v13, v201, s[6:7]
	s_add_u32 s6, s6, s10
	s_addc_u32 s7, s7, s11
	global_load_dword v141, v205, s[22:23]
	s_add_u32 s22, s22, s28
	s_addc_u32 s23, s23, s29
	global_load_dword v14, v201, s[6:7]
	s_add_u32 s6, s6, s10
	s_addc_u32 s7, s7, s11
	global_load_dword v142, v205, s[22:23]
	s_add_u32 s22, s22, s28
	s_addc_u32 s23, s23, s29
	global_load_dword v15, v201, s[6:7]
	s_add_u32 s6, s6, s10
	s_addc_u32 s7, s7, s11
	global_load_dword v143, v205, s[22:23]
	s_add_u32 s22, s22, s28
	s_addc_u32 s23, s23, s29
	global_load_dword v16, v201, s[6:7]
	s_add_u32 s6, s6, s10
	s_addc_u32 s7, s7, s11
	global_load_dword v144, v205, s[22:23]
	s_add_u32 s22, s22, s28
	s_addc_u32 s23, s23, s29
	global_load_dword v17, v201, s[6:7]
	s_add_u32 s6, s6, s10
	s_addc_u32 s7, s7, s11
	global_load_dword v145, v205, s[22:23]
	s_add_u32 s22, s22, s28
	s_addc_u32 s23, s23, s29
	global_load_dword v18, v201, s[6:7]
	s_add_u32 s6, s6, s10
	s_addc_u32 s7, s7, s11
	global_load_dword v146, v205, s[22:23]
	s_add_u32 s22, s22, s28
	s_addc_u32 s23, s23, s29
	global_load_dword v19, v201, s[6:7]
	s_add_u32 s6, s6, s10
	s_addc_u32 s7, s7, s11
	global_load_dword v147, v205, s[22:23]
	s_add_u32 s22, s22, s28
	s_addc_u32 s23, s23, s29
	global_load_dword v20, v201, s[6:7]
	s_add_u32 s6, s6, s10
	s_addc_u32 s7, s7, s11
	global_load_dword v148, v205, s[22:23]
	s_add_u32 s22, s22, s28
	s_addc_u32 s23, s23, s29
	global_load_dword v21, v201, s[6:7]
	s_add_u32 s6, s6, s10
	s_addc_u32 s7, s7, s11
	global_load_dword v149, v205, s[22:23]
	s_add_u32 s22, s22, s28
	s_addc_u32 s23, s23, s29
	global_load_dword v22, v201, s[6:7]
	s_add_u32 s6, s6, s10
	s_addc_u32 s7, s7, s11
	global_load_dword v150, v205, s[22:23]
	s_add_u32 s22, s22, s28
	s_addc_u32 s23, s23, s29
	global_load_dword v23, v201, s[6:7]
	s_add_u32 s6, s6, s10
	s_addc_u32 s7, s7, s11
	global_load_dword v151, v205, s[22:23]
	s_add_u32 s22, s22, s28
	s_addc_u32 s23, s23, s29
	global_load_dword v24, v201, s[6:7]
	s_add_u32 s6, s6, s10
	s_addc_u32 s7, s7, s11
	global_load_dword v152, v205, s[22:23]
	s_add_u32 s22, s22, s28
	s_addc_u32 s23, s23, s29
	global_load_dword v25, v201, s[6:7]
	s_add_u32 s6, s6, s10
	s_addc_u32 s7, s7, s11
	global_load_dword v153, v205, s[22:23]
	s_add_u32 s22, s22, s28
	s_addc_u32 s23, s23, s29
	global_load_dword v26, v201, s[6:7]
	s_add_u32 s6, s6, s10
	s_addc_u32 s7, s7, s11
	global_load_dword v154, v205, s[22:23]
	s_add_u32 s22, s22, s28
	s_addc_u32 s23, s23, s29
	global_load_dword v27, v201, s[6:7]
	s_add_u32 s6, s6, s10
	s_addc_u32 s7, s7, s11
	global_load_dword v155, v205, s[22:23]
	s_add_u32 s22, s22, s28
	s_addc_u32 s23, s23, s29
	global_load_dword v28, v201, s[6:7]
	s_add_u32 s6, s6, s10
	s_addc_u32 s7, s7, s11
	global_load_dword v156, v205, s[22:23]
	s_add_u32 s22, s22, s28
	s_addc_u32 s23, s23, s29
	global_load_dword v29, v201, s[6:7]
	s_add_u32 s6, s6, s10
	s_addc_u32 s7, s7, s11
	global_load_dword v157, v205, s[22:23]
	s_add_u32 s22, s22, s28
	s_addc_u32 s23, s23, s29
	global_load_dword v30, v201, s[6:7]
	s_add_u32 s6, s6, s10
	s_addc_u32 s7, s7, s11
	global_load_dword v158, v205, s[22:23]
	s_add_u32 s22, s22, s28
	s_addc_u32 s23, s23, s29
	global_load_dword v31, v201, s[6:7]
	s_add_u32 s6, s6, s10
	s_addc_u32 s7, s7, s11
	global_load_dword v159, v205, s[22:23]
; __device__ __forceinline__ void scan_phase(const Bufs& B) {
;     ...
;         float cst = 0.f, nst = 0.f, m = -1e30f;
;     ...
;             for (int u = 0; u < 16; ++u) { const int ch = dir ? 63 - (s0 + u) : s0 + u, it = dh * 64 + ch;
;                 cl[u] = B.CLOC[(size_t)it * 16384 + idx]; ml[u] = B.MLOC[it]; bl[u] = B.BLAST[it]; nl[u] = idx < 128 ? B.NLOC[(size_t)it * 128 + idx] : 0.f; }
	s_add_u32 s22, s22, s28
	s_addc_u32 s23, s23, s29
	global_load_dword v32, v201, s[6:7]
	s_add_u32 s6, s6, s10
	s_addc_u32 s7, s7, s11
	global_load_dword v160, v205, s[22:23]
	s_add_u32 s22, s22, s28
	s_addc_u32 s23, s23, s29
	global_load_dword v33, v201, s[6:7]
	s_add_u32 s6, s6, s10
	s_addc_u32 s7, s7, s11
	global_load_dword v161, v205, s[22:23]
	s_add_u32 s22, s22, s28
	s_addc_u32 s23, s23, s29
	global_load_dword v34, v201, s[6:7]
	s_add_u32 s6, s6, s10
	s_addc_u32 s7, s7, s11
	global_load_dword v162, v205, s[22:23]
	s_add_u32 s22, s22, s28
	s_addc_u32 s23, s23, s29
	global_load_dword v35, v201, s[6:7]
	s_add_u32 s6, s6, s10
	s_addc_u32 s7, s7, s11
	global_load_dword v163, v205, s[22:23]
	s_add_u32 s22, s22, s28
	s_addc_u32 s23, s23, s29
	global_load_dword v36, v201, s[6:7]
	s_add_u32 s6, s6, s10
	s_addc_u32 s7, s7, s11
	global_load_dword v164, v205, s[22:23]
	s_add_u32 s22, s22, s28
	s_addc_u32 s23, s23, s29
	global_load_dword v37, v201, s[6:7]
	s_add_u32 s6, s6, s10
	s_addc_u32 s7, s7, s11
	global_load_dword v165, v205, s[22:23]
	s_add_u32 s22, s22, s28
	s_addc_u32 s23, s23, s29
	global_load_dword v38, v201, s[6:7]
	s_add_u32 s6, s6, s10
	s_addc_u32 s7, s7, s11
	global_load_dword v166, v205, s[22:23]
	s_add_u32 s22, s22, s28
	s_addc_u32 s23, s23, s29
	global_load_dword v39, v201, s[6:7]
	s_add_u32 s6, s6, s10
	s_addc_u32 s7, s7, s11
	global_load_dword v167, v205, s[22:23]
	s_add_u32 s22, s22, s28
	s_addc_u32 s23, s23, s29
	global_load_dword v40, v201, s[6:7]
	s_add_u32 s6, s6, s10
	s_addc_u32 s7, s7, s11
	global_load_dword v168, v205, s[22:23]
	s_add_u32 s22, s22, s28
	s_addc_u32 s23, s23, s29
	global_load_dword v41, v201, s[6:7]
	s_add_u32 s6, s6, s10
	s_addc_u32 s7, s7, s11
	global_load_dword v169, v205, s[22:23]
	s_add_u32 s22, s22, s28
	s_addc_u32 s23, s23, s29
	global_load_dword v42, v201, s[6:7]
	s_add_u32 s6, s6, s10
	s_addc_u32 s7, s7, s11
	global_load_dword v170, v205, s[22:23]
	s_add_u32 s22, s22, s28
	s_addc_u32 s23, s23, s29
	global_load_dword v43, v201, s[6:7]
	s_add_u32 s6, s6, s10
	s_addc_u32 s7, s7, s11
	global_load_dword v171, v205, s[22:23]
	s_add_u32 s22, s22, s28
	s_addc_u32 s23, s23, s29
	global_load_dword v44, v201, s[6:7]
	s_add_u32 s6, s6, s10
	s_addc_u32 s7, s7, s11
	global_load_dword v172, v205, s[22:23]
	s_add_u32 s22, s22, s28
	s_addc_u32 s23, s23, s29
	global_load_dword v45, v201, s[6:7]
	s_add_u32 s6, s6, s10
	s_addc_u32 s7, s7, s11
	global_load_dword v173, v205, s[22:23]
	s_add_u32 s22, s22, s28
	s_addc_u32 s23, s23, s29
	global_load_dword v46, v201, s[6:7]
	s_add_u32 s6, s6, s10
	s_addc_u32 s7, s7, s11
	global_load_dword v174, v205, s[22:23]
	s_add_u32 s22, s22, s28
	s_addc_u32 s23, s23, s29
	global_load_dword v47, v201, s[6:7]
	s_add_u32 s6, s6, s10
	s_addc_u32 s7, s7, s11
	global_load_dword v175, v205, s[22:23]
	s_add_u32 s22, s22, s28
	s_addc_u32 s23, s23, s29
	global_load_dword v48, v201, s[6:7]
	s_add_u32 s6, s6, s10
	s_addc_u32 s7, s7, s11
	global_load_dword v176, v205, s[22:23]
	s_add_u32 s22, s22, s28
	s_addc_u32 s23, s23, s29
	global_load_dword v49, v201, s[6:7]
	s_add_u32 s6, s6, s10
	s_addc_u32 s7, s7, s11
	global_load_dword v177, v205, s[22:23]
	s_add_u32 s22, s22, s28
	s_addc_u32 s23, s23, s29
	global_load_dword v50, v201, s[6:7]
	s_add_u32 s6, s6, s10
	s_addc_u32 s7, s7, s11
	global_load_dword v178, v205, s[22:23]
	s_add_u32 s22, s22, s28
	s_addc_u32 s23, s23, s29
	global_load_dword v51, v201, s[6:7]
	s_add_u32 s6, s6, s10
	s_addc_u32 s7, s7, s11
	global_load_dword v179, v205, s[22:23]
	s_add_u32 s22, s22, s28
	s_addc_u32 s23, s23, s29
	global_load_dword v52, v201, s[6:7]
	s_add_u32 s6, s6, s10
	s_addc_u32 s7, s7, s11
	global_load_dword v180, v205, s[22:23]
	s_add_u32 s22, s22, s28
	s_addc_u32 s23, s23, s29
	global_load_dword v53, v201, s[6:7]
	s_add_u32 s6, s6, s10
	s_addc_u32 s7, s7, s11
	global_load_dword v181, v205, s[22:23]
	s_add_u32 s22, s22, s28
	s_addc_u32 s23, s23, s29
	global_load_dword v54, v201, s[6:7]
	s_add_u32 s6, s6, s10
	s_addc_u32 s7, s7, s11
	global_load_dword v182, v205, s[22:23]
	s_add_u32 s22, s22, s28
	s_addc_u32 s23, s23, s29
	global_load_dword v55, v201, s[6:7]
	s_add_u32 s6, s6, s10
	s_addc_u32 s7, s7, s11
	global_load_dword v183, v205, s[22:23]
	s_add_u32 s22, s22, s28
	s_addc_u32 s23, s23, s29
	global_load_dword v56, v201, s[6:7]
	s_add_u32 s6, s6, s10
	s_addc_u32 s7, s7, s11
	global_load_dword v184, v205, s[22:23]
	s_add_u32 s22, s22, s28
	s_addc_u32 s23, s23, s29
	global_load_dword v57, v201, s[6:7]
	s_add_u32 s6, s6, s10
	s_addc_u32 s7, s7, s11
	global_load_dword v185, v205, s[22:23]
	s_add_u32 s22, s22, s28
	s_addc_u32 s23, s23, s29
	global_load_dword v58, v201, s[6:7]
	s_add_u32 s6, s6, s10
	s_addc_u32 s7, s7, s11
	global_load_dword v186, v205, s[22:23]
	s_add_u32 s22, s22, s28
	s_addc_u32 s23, s23, s29
	global_load_dword v59, v201, s[6:7]
	s_add_u32 s6, s6, s10
	s_addc_u32 s7, s7, s11
	global_load_dword v187, v205, s[22:23]
	s_add_u32 s22, s22, s28
	s_addc_u32 s23, s23, s29
	global_load_dword v60, v201, s[6:7]
	s_add_u32 s6, s6, s10
	s_addc_u32 s7, s7, s11
	global_load_dword v188, v205, s[22:23]
	s_add_u32 s22, s22, s28
	s_addc_u32 s23, s23, s29
	global_load_dword v61, v201, s[6:7]
	s_add_u32 s6, s6, s10
	s_addc_u32 s7, s7, s11
	global_load_dword v189, v205, s[22:23]
	s_add_u32 s22, s22, s28
	s_addc_u32 s23, s23, s29
	global_load_dword v62, v201, s[6:7]
	s_add_u32 s6, s6, s10
	s_addc_u32 s7, s7, s11
	global_load_dword v190, v205, s[22:23]
	s_add_u32 s22, s22, s28
	s_addc_u32 s23, s23, s29
	global_load_dword v63, v201, s[6:7]
	s_add_u32 s6, s6, s10
	s_addc_u32 s7, s7, s11
	global_load_dword v191, v205, s[22:23]
	s_add_u32 s22, s22, s28
	s_addc_u32 s23, s23, s29
	v_mov_b32_e32 v208, 0xf149f2ca
	v_mov_b32_e32 v210, 0
	v_mov_b32_e32 v216, 0
	s_waitcnt vmcnt(63)
; __device__ __forceinline__ bf16_t f2bf(float f) { return (bf16_t)(cvt_pk_bf16(f, 0.f) & 0xffffu); }
; __device__ __forceinline__ void scan_phase(const Bufs& B) {
;     ...
;             for (int u = 0; u < 16; ++u) { const int ch = dir ? 63 - (s0 + u) : s0 + u, it = dh * 64 + ch;
;                 B.CST[(size_t)it * 16384 + idx] = f2bf(cst);
;                 if (idx < 128) { B.NST[(size_t)it * 128 + idx] = nst; if (idx == 0) B.MST[it] = m; }
;                 const float mnew = fmaxf(bl[u] + m, ml[u]), a = __expf(bl[u] + m - mnew), g = __expf(ml[u] - mnew);
;                 cst = a * cst + g * cl[u]; nst = a * nst + g * nl[u]; m = mnew; }
	s_nop 0
	v_readlane_b32 s41, v206, 0
	v_readlane_b32 s42, v207, 0
	s_waitcnt vmcnt(63)
	v_cvt_pk_bf16_f32 v215, v210, v195
	v_readlane_b32 s43, v206, 1
	v_readlane_b32 s44, v207, 1
	global_store_short v202, v215, s[8:9]
	s_add_u32 s8, s8, s12
	s_addc_u32 s9, s9, s13
	global_store_dword v205, v216, s[24:25]
	s_add_u32 s24, s24, s28
	s_addc_u32 s25, s25, s29
	s_mov_b64 exec, s[46:47]
	global_store_dword v195, v208, s[26:27]
	s_mov_b64 exec, -1
	s_add_u32 s26, s26, s30
	s_addc_u32 s27, s27, s31
	v_add_f32_e32 v211, s42, v208
	v_max_f32_e32 v209, s41, v211
	v_sub_f32_e32 v212, v211, v209
	v_sub_f32_e32 v213, s41, v209
	v_mul_f32_e32 v212, 0x3fb8aa3b, v212
	v_mul_f32_e32 v213, 0x3fb8aa3b, v213
	v_exp_f32_e32 v213, v213
	v_exp_f32_e32 v212, v212
	s_nop 0
	v_mul_f32_e32 v214, v213, v0
	v_mul_f32_e32 v217, v213, v128
	v_fma_f32 v210, v210, v212, v214
	v_fma_f32 v216, v216, v212, v217
	v_cvt_pk_bf16_f32 v215, v210, v195
	v_readlane_b32 s41, v206, 2
	v_readlane_b32 s42, v207, 2
	global_store_short v202, v215, s[8:9]
	s_add_u32 s8, s8, s12
	s_addc_u32 s9, s9, s13
	global_store_dword v205, v216, s[24:25]
	s_add_u32 s24, s24, s28
	s_addc_u32 s25, s25, s29
	s_mov_b64 exec, s[46:47]
	global_store_dword v195, v209, s[26:27]
	s_mov_b64 exec, -1
	s_add_u32 s26, s26, s30
	s_addc_u32 s27, s27, s31
	v_add_f32_e32 v211, s44, v209
	v_max_f32_e32 v208, s43, v211
	v_sub_f32_e32 v212, v211, v208
	v_sub_f32_e32 v213, s43, v208
	v_mul_f32_e32 v212, 0x3fb8aa3b, v212
	v_mul_f32_e32 v213, 0x3fb8aa3b, v213
	v_exp_f32_e32 v213, v213
	v_exp_f32_e32 v212, v212
	s_nop 0
	v_mul_f32_e32 v214, v213, v1
	v_mul_f32_e32 v217, v213, v129
	v_fma_f32 v210, v210, v212, v214
	v_fma_f32 v216, v216, v212, v217
	v_cvt_pk_bf16_f32 v215, v210, v195
	v_readlane_b32 s43, v206, 3
	v_readlane_b32 s44, v207, 3
	global_store_short v202, v215, s[8:9]
	s_add_u32 s8, s8, s12
	s_addc_u32 s9, s9, s13
	global_store_dword v205, v216, s[24:25]
	s_add_u32 s24, s24, s28
	s_addc_u32 s25, s25, s29
	s_mov_b64 exec, s[46:47]
	global_store_dword v195, v208, s[26:27]
	s_mov_b64 exec, -1
	s_add_u32 s26, s26, s30
	s_addc_u32 s27, s27, s31
	v_add_f32_e32 v211, s42, v208
	v_max_f32_e32 v209, s41, v211
	v_sub_f32_e32 v212, v211, v209
	v_sub_f32_e32 v213, s41, v209
	v_mul_f32_e32 v212, 0x3fb8aa3b, v212
	v_mul_f32_e32 v213, 0x3fb8aa3b, v213
	v_exp_f32_e32 v213, v213
	v_exp_f32_e32 v212, v212
	s_nop 0
	v_mul_f32_e32 v214, v213, v2
	v_mul_f32_e32 v217, v213, v130
	v_fma_f32 v210, v210, v212, v214
	v_fma_f32 v216, v216, v212, v217
	v_cvt_pk_bf16_f32 v215, v210, v195
	v_readlane_b32 s41, v206, 4
	v_readlane_b32 s42, v207, 4
	global_store_short v202, v215, s[8:9]
	s_add_u32 s8, s8, s12
	s_addc_u32 s9, s9, s13
	global_store_dword v205, v216, s[24:25]
	s_add_u32 s24, s24, s28
	s_addc_u32 s25, s25, s29
	s_mov_b64 exec, s[46:47]
	global_store_dword v195, v209, s[26:27]
	s_mov_b64 exec, -1
	s_add_u32 s26, s26, s30
	s_addc_u32 s27, s27, s31
	v_add_f32_e32 v211, s44, v209
	v_max_f32_e32 v208, s43, v211
	v_sub_f32_e32 v212, v211, v208
	v_sub_f32_e32 v213, s43, v208
	v_mul_f32_e32 v212, 0x3fb8aa3b, v212
	v_mul_f32_e32 v213, 0x3fb8aa3b, v213
	v_exp_f32_e32 v213, v213
	v_exp_f32_e32 v212, v212
	s_nop 0
	v_mul_f32_e32 v214, v213, v3
	v_mul_f32_e32 v217, v213, v131
	v_fma_f32 v210, v210, v212, v214
	v_fma_f32 v216, v216, v212, v217
	v_cvt_pk_bf16_f32 v215, v210, v195
	v_readlane_b32 s43, v206, 5
	v_readlane_b32 s44, v207, 5
	global_store_short v202, v215, s[8:9]
	s_add_u32 s8, s8, s12
	s_addc_u32 s9, s9, s13
	global_store_dword v205, v216, s[24:25]
	s_add_u32 s24, s24, s28
	s_addc_u32 s25, s25, s29
	s_mov_b64 exec, s[46:47]
	global_store_dword v195, v208, s[26:27]
	s_mov_b64 exec, -1
	s_add_u32 s26, s26, s30
	s_addc_u32 s27, s27, s31
	v_add_f32_e32 v211, s42, v208
	v_max_f32_e32 v209, s41, v211
	v_sub_f32_e32 v212, v211, v209
	v_sub_f32_e32 v213, s41, v209
	v_mul_f32_e32 v212, 0x3fb8aa3b, v212
	v_mul_f32_e32 v213, 0x3fb8aa3b, v213
	v_exp_f32_e32 v213, v213
	v_exp_f32_e32 v212, v212
	s_nop 0
	v_mul_f32_e32 v214, v213, v4
	v_mul_f32_e32 v217, v213, v132
	v_fma_f32 v210, v210, v212, v214
	v_fma_f32 v216, v216, v212, v217
	v_cvt_pk_bf16_f32 v215, v210, v195
	v_readlane_b32 s41, v206, 6
	v_readlane_b32 s42, v207, 6
	global_store_short v202, v215, s[8:9]
	s_add_u32 s8, s8, s12
	s_addc_u32 s9, s9, s13
	global_store_dword v205, v216, s[24:25]
	s_add_u32 s24, s24, s28
	s_addc_u32 s25, s25, s29
	s_mov_b64 exec, s[46:47]
	global_store_dword v195, v209, s[26:27]
	s_mov_b64 exec, -1
	s_add_u32 s26, s26, s30
	s_addc_u32 s27, s27, s31
	v_add_f32_e32 v211, s44, v209
	v_max_f32_e32 v208, s43, v211
	v_sub_f32_e32 v212, v211, v208
	v_sub_f32_e32 v213, s43, v208
	v_mul_f32_e32 v212, 0x3fb8aa3b, v212
	v_mul_f32_e32 v213, 0x3fb8aa3b, v213
	v_exp_f32_e32 v213, v213
	v_exp_f32_e32 v212, v212
	s_nop 0
	v_mul_f32_e32 v214, v213, v5
	v_mul_f32_e32 v217, v213, v133
	v_fma_f32 v210, v210, v212, v214
	v_fma_f32 v216, v216, v212, v217
	v_cvt_pk_bf16_f32 v215, v210, v195
	v_readlane_b32 s43, v206, 7
	v_readlane_b32 s44, v207, 7
	global_store_short v202, v215, s[8:9]
	s_add_u32 s8, s8, s12
	s_addc_u32 s9, s9, s13
	global_store_dword v205, v216, s[24:25]
	s_add_u32 s24, s24, s28
	s_addc_u32 s25, s25, s29
	s_mov_b64 exec, s[46:47]
	global_store_dword v195, v208, s[26:27]
	s_mov_b64 exec, -1
	s_add_u32 s26, s26, s30
	s_addc_u32 s27, s27, s31
	v_add_f32_e32 v211, s42, v208
	v_max_f32_e32 v209, s41, v211
	v_sub_f32_e32 v212, v211, v209
	v_sub_f32_e32 v213, s41, v209
	v_mul_f32_e32 v212, 0x3fb8aa3b, v212
	v_mul_f32_e32 v213, 0x3fb8aa3b, v213
	v_exp_f32_e32 v213, v213
	v_exp_f32_e32 v212, v212
	s_nop 0
	v_mul_f32_e32 v214, v213, v6
	v_mul_f32_e32 v217, v213, v134
; __device__ __forceinline__ bf16_t f2bf(float f) { return (bf16_t)(cvt_pk_bf16(f, 0.f) & 0xffffu); }
; __device__ __forceinline__ void scan_phase(const Bufs& B) {
;     ...
;             for (int u = 0; u < 16; ++u) { const int ch = dir ? 63 - (s0 + u) : s0 + u, it = dh * 64 + ch;
;                 B.CST[(size_t)it * 16384 + idx] = f2bf(cst);
;                 if (idx < 128) { B.NST[(size_t)it * 128 + idx] = nst; if (idx == 0) B.MST[it] = m; }
;                 const float mnew = fmaxf(bl[u] + m, ml[u]), a = __expf(bl[u] + m - mnew), g = __expf(ml[u] - mnew);
;                 cst = a * cst + g * cl[u]; nst = a * nst + g * nl[u]; m = mnew; }
	v_fma_f32 v210, v210, v212, v214
	v_fma_f32 v216, v216, v212, v217
	v_cvt_pk_bf16_f32 v215, v210, v195
	v_readlane_b32 s41, v206, 8
	v_readlane_b32 s42, v207, 8
	global_store_short v202, v215, s[8:9]
	s_add_u32 s8, s8, s12
	s_addc_u32 s9, s9, s13
	global_store_dword v205, v216, s[24:25]
	s_add_u32 s24, s24, s28
	s_addc_u32 s25, s25, s29
	s_mov_b64 exec, s[46:47]
	global_store_dword v195, v209, s[26:27]
	s_mov_b64 exec, -1
	s_add_u32 s26, s26, s30
	s_addc_u32 s27, s27, s31
	v_add_f32_e32 v211, s44, v209
	v_max_f32_e32 v208, s43, v211
	v_sub_f32_e32 v212, v211, v208
	v_sub_f32_e32 v213, s43, v208
	v_mul_f32_e32 v212, 0x3fb8aa3b, v212
	v_mul_f32_e32 v213, 0x3fb8aa3b, v213
	v_exp_f32_e32 v213, v213
	v_exp_f32_e32 v212, v212
	s_nop 0
	v_mul_f32_e32 v214, v213, v7
	v_mul_f32_e32 v217, v213, v135
	v_fma_f32 v210, v210, v212, v214
	v_fma_f32 v216, v216, v212, v217
	v_cvt_pk_bf16_f32 v215, v210, v195
	v_readlane_b32 s43, v206, 9
	v_readlane_b32 s44, v207, 9
	global_store_short v202, v215, s[8:9]
	s_add_u32 s8, s8, s12
	s_addc_u32 s9, s9, s13
	global_store_dword v205, v216, s[24:25]
	s_add_u32 s24, s24, s28
	s_addc_u32 s25, s25, s29
	s_mov_b64 exec, s[46:47]
	global_store_dword v195, v208, s[26:27]
	s_mov_b64 exec, -1
	s_add_u32 s26, s26, s30
	s_addc_u32 s27, s27, s31
	v_add_f32_e32 v211, s42, v208
	v_max_f32_e32 v209, s41, v211
	v_sub_f32_e32 v212, v211, v209
	v_sub_f32_e32 v213, s41, v209
	v_mul_f32_e32 v212, 0x3fb8aa3b, v212
	v_mul_f32_e32 v213, 0x3fb8aa3b, v213
	v_exp_f32_e32 v213, v213
	v_exp_f32_e32 v212, v212
	s_nop 0
	v_mul_f32_e32 v214, v213, v8
	v_mul_f32_e32 v217, v213, v136
	v_fma_f32 v210, v210, v212, v214
	v_fma_f32 v216, v216, v212, v217
	v_cvt_pk_bf16_f32 v215, v210, v195
	v_readlane_b32 s41, v206, 10
	v_readlane_b32 s42, v207, 10
	global_store_short v202, v215, s[8:9]
	s_add_u32 s8, s8, s12
	s_addc_u32 s9, s9, s13
	global_store_dword v205, v216, s[24:25]
	s_add_u32 s24, s24, s28
	s_addc_u32 s25, s25, s29
	s_mov_b64 exec, s[46:47]
	global_store_dword v195, v209, s[26:27]
	s_mov_b64 exec, -1
	s_add_u32 s26, s26, s30
	s_addc_u32 s27, s27, s31
	v_add_f32_e32 v211, s44, v209
	v_max_f32_e32 v208, s43, v211
	v_sub_f32_e32 v212, v211, v208
	v_sub_f32_e32 v213, s43, v208
	v_mul_f32_e32 v212, 0x3fb8aa3b, v212
	v_mul_f32_e32 v213, 0x3fb8aa3b, v213
	v_exp_f32_e32 v213, v213
	v_exp_f32_e32 v212, v212
	s_nop 0
	v_mul_f32_e32 v214, v213, v9
	v_mul_f32_e32 v217, v213, v137
	v_fma_f32 v210, v210, v212, v214
	v_fma_f32 v216, v216, v212, v217
	v_cvt_pk_bf16_f32 v215, v210, v195
	v_readlane_b32 s43, v206, 11
	v_readlane_b32 s44, v207, 11
	global_store_short v202, v215, s[8:9]
	s_add_u32 s8, s8, s12
	s_addc_u32 s9, s9, s13
	global_store_dword v205, v216, s[24:25]
	s_add_u32 s24, s24, s28
	s_addc_u32 s25, s25, s29
	s_mov_b64 exec, s[46:47]
	global_store_dword v195, v208, s[26:27]
	s_mov_b64 exec, -1
	s_add_u32 s26, s26, s30
	s_addc_u32 s27, s27, s31
	v_add_f32_e32 v211, s42, v208
	v_max_f32_e32 v209, s41, v211
	v_sub_f32_e32 v212, v211, v209
	v_sub_f32_e32 v213, s41, v209
	v_mul_f32_e32 v212, 0x3fb8aa3b, v212
	v_mul_f32_e32 v213, 0x3fb8aa3b, v213
	v_exp_f32_e32 v213, v213
	v_exp_f32_e32 v212, v212
	s_nop 0
	v_mul_f32_e32 v214, v213, v10
	v_mul_f32_e32 v217, v213, v138
	v_fma_f32 v210, v210, v212, v214
	v_fma_f32 v216, v216, v212, v217
	v_cvt_pk_bf16_f32 v215, v210, v195
	v_readlane_b32 s41, v206, 12
	v_readlane_b32 s42, v207, 12
	global_store_short v202, v215, s[8:9]
	s_add_u32 s8, s8, s12
	s_addc_u32 s9, s9, s13
	global_store_dword v205, v216, s[24:25]
	s_add_u32 s24, s24, s28
	s_addc_u32 s25, s25, s29
	s_mov_b64 exec, s[46:47]
	global_store_dword v195, v209, s[26:27]
	s_mov_b64 exec, -1
	s_add_u32 s26, s26, s30
	s_addc_u32 s27, s27, s31
	v_add_f32_e32 v211, s44, v209
	v_max_f32_e32 v208, s43, v211
	v_sub_f32_e32 v212, v211, v208
	v_sub_f32_e32 v213, s43, v208
	v_mul_f32_e32 v212, 0x3fb8aa3b, v212
	v_mul_f32_e32 v213, 0x3fb8aa3b, v213
	v_exp_f32_e32 v213, v213
	v_exp_f32_e32 v212, v212
	s_nop 0
	v_mul_f32_e32 v214, v213, v11
	v_mul_f32_e32 v217, v213, v139
	v_fma_f32 v210, v210, v212, v214
	v_fma_f32 v216, v216, v212, v217
	v_cvt_pk_bf16_f32 v215, v210, v195
	v_readlane_b32 s43, v206, 13
	v_readlane_b32 s44, v207, 13
	global_store_short v202, v215, s[8:9]
	s_add_u32 s8, s8, s12
	s_addc_u32 s9, s9, s13
	global_store_dword v205, v216, s[24:25]
	s_add_u32 s24, s24, s28
	s_addc_u32 s25, s25, s29
	s_mov_b64 exec, s[46:47]
	global_store_dword v195, v208, s[26:27]
	s_mov_b64 exec, -1
	s_add_u32 s26, s26, s30
	s_addc_u32 s27, s27, s31
	v_add_f32_e32 v211, s42, v208
	v_max_f32_e32 v209, s41, v211
	v_sub_f32_e32 v212, v211, v209
	v_sub_f32_e32 v213, s41, v209
	v_mul_f32_e32 v212, 0x3fb8aa3b, v212
	v_mul_f32_e32 v213, 0x3fb8aa3b, v213
	v_exp_f32_e32 v213, v213
	v_exp_f32_e32 v212, v212
	s_nop 0
	v_mul_f32_e32 v214, v213, v12
	v_mul_f32_e32 v217, v213, v140
	v_fma_f32 v210, v210, v212, v214
	v_fma_f32 v216, v216, v212, v217
	v_cvt_pk_bf16_f32 v215, v210, v195
	v_readlane_b32 s41, v206, 14
	v_readlane_b32 s42, v207, 14
	global_store_short v202, v215, s[8:9]
	s_add_u32 s8, s8, s12
	s_addc_u32 s9, s9, s13
	global_store_dword v205, v216, s[24:25]
	s_add_u32 s24, s24, s28
	s_addc_u32 s25, s25, s29
	s_mov_b64 exec, s[46:47]
	global_store_dword v195, v209, s[26:27]
	s_mov_b64 exec, -1
	s_add_u32 s26, s26, s30
	s_addc_u32 s27, s27, s31
	v_add_f32_e32 v211, s44, v209
	v_max_f32_e32 v208, s43, v211
	v_sub_f32_e32 v212, v211, v208
	v_sub_f32_e32 v213, s43, v208
	v_mul_f32_e32 v212, 0x3fb8aa3b, v212
	v_mul_f32_e32 v213, 0x3fb8aa3b, v213
	v_exp_f32_e32 v213, v213
	v_exp_f32_e32 v212, v212
	s_nop 0
	v_mul_f32_e32 v214, v213, v13
	v_mul_f32_e32 v217, v213, v141
; __device__ __forceinline__ bf16_t f2bf(float f) { return (bf16_t)(cvt_pk_bf16(f, 0.f) & 0xffffu); }
; __device__ __forceinline__ void scan_phase(const Bufs& B) {
;     ...
;             for (int u = 0; u < 16; ++u) { const int ch = dir ? 63 - (s0 + u) : s0 + u, it = dh * 64 + ch;
;                 B.CST[(size_t)it * 16384 + idx] = f2bf(cst);
;                 if (idx < 128) { B.NST[(size_t)it * 128 + idx] = nst; if (idx == 0) B.MST[it] = m; }
;                 const float mnew = fmaxf(bl[u] + m, ml[u]), a = __expf(bl[u] + m - mnew), g = __expf(ml[u] - mnew);
;                 cst = a * cst + g * cl[u]; nst = a * nst + g * nl[u]; m = mnew; }
	v_fma_f32 v210, v210, v212, v214
	v_fma_f32 v216, v216, v212, v217
	v_cvt_pk_bf16_f32 v215, v210, v195
	v_readlane_b32 s43, v206, 15
	v_readlane_b32 s44, v207, 15
	global_store_short v202, v215, s[8:9]
	s_add_u32 s8, s8, s12
	s_addc_u32 s9, s9, s13
	global_store_dword v205, v216, s[24:25]
	s_add_u32 s24, s24, s28
	s_addc_u32 s25, s25, s29
	s_mov_b64 exec, s[46:47]
	global_store_dword v195, v208, s[26:27]
	s_mov_b64 exec, -1
	s_add_u32 s26, s26, s30
	s_addc_u32 s27, s27, s31
	v_add_f32_e32 v211, s42, v208
	v_max_f32_e32 v209, s41, v211
	v_sub_f32_e32 v212, v211, v209
	v_sub_f32_e32 v213, s41, v209
	v_mul_f32_e32 v212, 0x3fb8aa3b, v212
	v_mul_f32_e32 v213, 0x3fb8aa3b, v213
	v_exp_f32_e32 v213, v213
	v_exp_f32_e32 v212, v212
	s_nop 0
	v_mul_f32_e32 v214, v213, v14
	v_mul_f32_e32 v217, v213, v142
	v_fma_f32 v210, v210, v212, v214
	v_fma_f32 v216, v216, v212, v217
	v_cvt_pk_bf16_f32 v215, v210, v195
	v_readlane_b32 s41, v206, 16
	v_readlane_b32 s42, v207, 16
	global_store_short v202, v215, s[8:9]
	s_add_u32 s8, s8, s12
	s_addc_u32 s9, s9, s13
	global_store_dword v205, v216, s[24:25]
	s_add_u32 s24, s24, s28
	s_addc_u32 s25, s25, s29
	s_mov_b64 exec, s[46:47]
	global_store_dword v195, v209, s[26:27]
	s_mov_b64 exec, -1
	s_add_u32 s26, s26, s30
	s_addc_u32 s27, s27, s31
	v_add_f32_e32 v211, s44, v209
	v_max_f32_e32 v208, s43, v211
	v_sub_f32_e32 v212, v211, v208
	v_sub_f32_e32 v213, s43, v208
	v_mul_f32_e32 v212, 0x3fb8aa3b, v212
	v_mul_f32_e32 v213, 0x3fb8aa3b, v213
	v_exp_f32_e32 v213, v213
	v_exp_f32_e32 v212, v212
	s_nop 0
	v_mul_f32_e32 v214, v213, v15
	v_mul_f32_e32 v217, v213, v143
	v_fma_f32 v210, v210, v212, v214
	v_fma_f32 v216, v216, v212, v217
	s_waitcnt vmcnt(63)
	v_cvt_pk_bf16_f32 v215, v210, v195
	v_readlane_b32 s43, v206, 17
	v_readlane_b32 s44, v207, 17
	global_store_short v202, v215, s[8:9]
	s_add_u32 s8, s8, s12
	s_addc_u32 s9, s9, s13
	global_store_dword v205, v216, s[24:25]
	s_add_u32 s24, s24, s28
	s_addc_u32 s25, s25, s29
	s_mov_b64 exec, s[46:47]
	global_store_dword v195, v208, s[26:27]
	s_mov_b64 exec, -1
	s_add_u32 s26, s26, s30
	s_addc_u32 s27, s27, s31
	v_add_f32_e32 v211, s42, v208
	v_max_f32_e32 v209, s41, v211
	v_sub_f32_e32 v212, v211, v209
	v_sub_f32_e32 v213, s41, v209
	v_mul_f32_e32 v212, 0x3fb8aa3b, v212
	v_mul_f32_e32 v213, 0x3fb8aa3b, v213
	v_exp_f32_e32 v213, v213
	v_exp_f32_e32 v212, v212
	s_nop 0
	v_mul_f32_e32 v214, v213, v16
	v_mul_f32_e32 v217, v213, v144
	v_fma_f32 v210, v210, v212, v214
	v_fma_f32 v216, v216, v212, v217
	v_cvt_pk_bf16_f32 v215, v210, v195
	v_readlane_b32 s41, v206, 18
	v_readlane_b32 s42, v207, 18
	global_store_short v202, v215, s[8:9]
	s_add_u32 s8, s8, s12
	s_addc_u32 s9, s9, s13
	global_store_dword v205, v216, s[24:25]
	s_add_u32 s24, s24, s28
	s_addc_u32 s25, s25, s29
	s_mov_b64 exec, s[46:47]
	global_store_dword v195, v209, s[26:27]
	s_mov_b64 exec, -1
	s_add_u32 s26, s26, s30
	s_addc_u32 s27, s27, s31
	v_add_f32_e32 v211, s44, v209
	v_max_f32_e32 v208, s43, v211
	v_sub_f32_e32 v212, v211, v208
	v_sub_f32_e32 v213, s43, v208
	v_mul_f32_e32 v212, 0x3fb8aa3b, v212
	v_mul_f32_e32 v213, 0x3fb8aa3b, v213
	v_exp_f32_e32 v213, v213
	v_exp_f32_e32 v212, v212
	s_nop 0
	v_mul_f32_e32 v214, v213, v17
	v_mul_f32_e32 v217, v213, v145
	v_fma_f32 v210, v210, v212, v214
	v_fma_f32 v216, v216, v212, v217
	v_cvt_pk_bf16_f32 v215, v210, v195
	v_readlane_b32 s43, v206, 19
	v_readlane_b32 s44, v207, 19
	global_store_short v202, v215, s[8:9]
	s_add_u32 s8, s8, s12
	s_addc_u32 s9, s9, s13
	global_store_dword v205, v216, s[24:25]
	s_add_u32 s24, s24, s28
	s_addc_u32 s25, s25, s29
	s_mov_b64 exec, s[46:47]
	global_store_dword v195, v208, s[26:27]
	s_mov_b64 exec, -1
	s_add_u32 s26, s26, s30
	s_addc_u32 s27, s27, s31
	v_add_f32_e32 v211, s42, v208
	v_max_f32_e32 v209, s41, v211
	v_sub_f32_e32 v212, v211, v209
	v_sub_f32_e32 v213, s41, v209
	v_mul_f32_e32 v212, 0x3fb8aa3b, v212
	v_mul_f32_e32 v213, 0x3fb8aa3b, v213
	v_exp_f32_e32 v213, v213
	v_exp_f32_e32 v212, v212
	s_nop 0
	v_mul_f32_e32 v214, v213, v18
	v_mul_f32_e32 v217, v213, v146
	v_fma_f32 v210, v210, v212, v214
	v_fma_f32 v216, v216, v212, v217
	v_cvt_pk_bf16_f32 v215, v210, v195
	v_readlane_b32 s41, v206, 20
	v_readlane_b32 s42, v207, 20
	global_store_short v202, v215, s[8:9]
	s_add_u32 s8, s8, s12
	s_addc_u32 s9, s9, s13
	global_store_dword v205, v216, s[24:25]
	s_add_u32 s24, s24, s28
	s_addc_u32 s25, s25, s29
	s_mov_b64 exec, s[46:47]
	global_store_dword v195, v209, s[26:27]
	s_mov_b64 exec, -1
	s_add_u32 s26, s26, s30
	s_addc_u32 s27, s27, s31
	v_add_f32_e32 v211, s44, v209
	v_max_f32_e32 v208, s43, v211
	v_sub_f32_e32 v212, v211, v208
	v_sub_f32_e32 v213, s43, v208
	v_mul_f32_e32 v212, 0x3fb8aa3b, v212
	v_mul_f32_e32 v213, 0x3fb8aa3b, v213
	v_exp_f32_e32 v213, v213
	v_exp_f32_e32 v212, v212
	s_nop 0
	v_mul_f32_e32 v214, v213, v19
	v_mul_f32_e32 v217, v213, v147
	v_fma_f32 v210, v210, v212, v214
	v_fma_f32 v216, v216, v212, v217
	v_cvt_pk_bf16_f32 v215, v210, v195
	v_readlane_b32 s43, v206, 21
	v_readlane_b32 s44, v207, 21
	global_store_short v202, v215, s[8:9]
	s_add_u32 s8, s8, s12
	s_addc_u32 s9, s9, s13
	global_store_dword v205, v216, s[24:25]
	s_add_u32 s24, s24, s28
	s_addc_u32 s25, s25, s29
	s_mov_b64 exec, s[46:47]
	global_store_dword v195, v208, s[26:27]
	s_mov_b64 exec, -1
	s_add_u32 s26, s26, s30
	s_addc_u32 s27, s27, s31
	v_add_f32_e32 v211, s42, v208
	v_max_f32_e32 v209, s41, v211
	v_sub_f32_e32 v212, v211, v209
	v_sub_f32_e32 v213, s41, v209
	v_mul_f32_e32 v212, 0x3fb8aa3b, v212
	v_mul_f32_e32 v213, 0x3fb8aa3b, v213
	v_exp_f32_e32 v213, v213
	v_exp_f32_e32 v212, v212
	s_nop 0
	v_mul_f32_e32 v214, v213, v20
; __device__ __forceinline__ bf16_t f2bf(float f) { return (bf16_t)(cvt_pk_bf16(f, 0.f) & 0xffffu); }
; __device__ __forceinline__ void scan_phase(const Bufs& B) {
;     ...
;             for (int u = 0; u < 16; ++u) { const int ch = dir ? 63 - (s0 + u) : s0 + u, it = dh * 64 + ch;
;                 B.CST[(size_t)it * 16384 + idx] = f2bf(cst);
;                 if (idx < 128) { B.NST[(size_t)it * 128 + idx] = nst; if (idx == 0) B.MST[it] = m; }
;                 const float mnew = fmaxf(bl[u] + m, ml[u]), a = __expf(bl[u] + m - mnew), g = __expf(ml[u] - mnew);
;                 cst = a * cst + g * cl[u]; nst = a * nst + g * nl[u]; m = mnew; }
	v_mul_f32_e32 v217, v213, v148
	v_fma_f32 v210, v210, v212, v214
	v_fma_f32 v216, v216, v212, v217
	v_cvt_pk_bf16_f32 v215, v210, v195
	v_readlane_b32 s41, v206, 22
	v_readlane_b32 s42, v207, 22
	global_store_short v202, v215, s[8:9]
	s_add_u32 s8, s8, s12
	s_addc_u32 s9, s9, s13
	global_store_dword v205, v216, s[24:25]
	s_add_u32 s24, s24, s28
	s_addc_u32 s25, s25, s29
	s_mov_b64 exec, s[46:47]
	global_store_dword v195, v209, s[26:27]
	s_mov_b64 exec, -1
	s_add_u32 s26, s26, s30
	s_addc_u32 s27, s27, s31
	v_add_f32_e32 v211, s44, v209
	v_max_f32_e32 v208, s43, v211
	v_sub_f32_e32 v212, v211, v208
	v_sub_f32_e32 v213, s43, v208
	v_mul_f32_e32 v212, 0x3fb8aa3b, v212
	v_mul_f32_e32 v213, 0x3fb8aa3b, v213
	v_exp_f32_e32 v213, v213
	v_exp_f32_e32 v212, v212
	s_nop 0
	v_mul_f32_e32 v214, v213, v21
	v_mul_f32_e32 v217, v213, v149
	v_fma_f32 v210, v210, v212, v214
	v_fma_f32 v216, v216, v212, v217
	v_cvt_pk_bf16_f32 v215, v210, v195
	v_readlane_b32 s43, v206, 23
	v_readlane_b32 s44, v207, 23
	global_store_short v202, v215, s[8:9]
	s_add_u32 s8, s8, s12
	s_addc_u32 s9, s9, s13
	global_store_dword v205, v216, s[24:25]
	s_add_u32 s24, s24, s28
	s_addc_u32 s25, s25, s29
	s_mov_b64 exec, s[46:47]
	global_store_dword v195, v208, s[26:27]
	s_mov_b64 exec, -1
	s_add_u32 s26, s26, s30
	s_addc_u32 s27, s27, s31
	v_add_f32_e32 v211, s42, v208
	v_max_f32_e32 v209, s41, v211
	v_sub_f32_e32 v212, v211, v209
	v_sub_f32_e32 v213, s41, v209
	v_mul_f32_e32 v212, 0x3fb8aa3b, v212
	v_mul_f32_e32 v213, 0x3fb8aa3b, v213
	v_exp_f32_e32 v213, v213
	v_exp_f32_e32 v212, v212
	s_nop 0
	v_mul_f32_e32 v214, v213, v22
	v_mul_f32_e32 v217, v213, v150
	v_fma_f32 v210, v210, v212, v214
	v_fma_f32 v216, v216, v212, v217
	v_cvt_pk_bf16_f32 v215, v210, v195
	v_readlane_b32 s41, v206, 24
	v_readlane_b32 s42, v207, 24
	global_store_short v202, v215, s[8:9]
	s_add_u32 s8, s8, s12
	s_addc_u32 s9, s9, s13
	global_store_dword v205, v216, s[24:25]
	s_add_u32 s24, s24, s28
	s_addc_u32 s25, s25, s29
	s_mov_b64 exec, s[46:47]
	global_store_dword v195, v209, s[26:27]
	s_mov_b64 exec, -1
	s_add_u32 s26, s26, s30
	s_addc_u32 s27, s27, s31
	v_add_f32_e32 v211, s44, v209
	v_max_f32_e32 v208, s43, v211
	v_sub_f32_e32 v212, v211, v208
	v_sub_f32_e32 v213, s43, v208
	v_mul_f32_e32 v212, 0x3fb8aa3b, v212
	v_mul_f32_e32 v213, 0x3fb8aa3b, v213
	v_exp_f32_e32 v213, v213
	v_exp_f32_e32 v212, v212
	s_nop 0
	v_mul_f32_e32 v214, v213, v23
	v_mul_f32_e32 v217, v213, v151
	v_fma_f32 v210, v210, v212, v214
	v_fma_f32 v216, v216, v212, v217
	v_cvt_pk_bf16_f32 v215, v210, v195
	v_readlane_b32 s43, v206, 25
	v_readlane_b32 s44, v207, 25
	global_store_short v202, v215, s[8:9]
	s_add_u32 s8, s8, s12
	s_addc_u32 s9, s9, s13
	global_store_dword v205, v216, s[24:25]
	s_add_u32 s24, s24, s28
	s_addc_u32 s25, s25, s29
	s_mov_b64 exec, s[46:47]
	global_store_dword v195, v208, s[26:27]
	s_mov_b64 exec, -1
	s_add_u32 s26, s26, s30
	s_addc_u32 s27, s27, s31
	v_add_f32_e32 v211, s42, v208
	v_max_f32_e32 v209, s41, v211
	v_sub_f32_e32 v212, v211, v209
	v_sub_f32_e32 v213, s41, v209
	v_mul_f32_e32 v212, 0x3fb8aa3b, v212
	v_mul_f32_e32 v213, 0x3fb8aa3b, v213
	v_exp_f32_e32 v213, v213
	v_exp_f32_e32 v212, v212
	s_nop 0
	v_mul_f32_e32 v214, v213, v24
	v_mul_f32_e32 v217, v213, v152
	v_fma_f32 v210, v210, v212, v214
	v_fma_f32 v216, v216, v212, v217
	v_cvt_pk_bf16_f32 v215, v210, v195
	v_readlane_b32 s41, v206, 26
	v_readlane_b32 s42, v207, 26
	global_store_short v202, v215, s[8:9]
	s_add_u32 s8, s8, s12
	s_addc_u32 s9, s9, s13
	global_store_dword v205, v216, s[24:25]
	s_add_u32 s24, s24, s28
	s_addc_u32 s25, s25, s29
	s_mov_b64 exec, s[46:47]
	global_store_dword v195, v209, s[26:27]
	s_mov_b64 exec, -1
	s_add_u32 s26, s26, s30
	s_addc_u32 s27, s27, s31
	v_add_f32_e32 v211, s44, v209
	v_max_f32_e32 v208, s43, v211
	v_sub_f32_e32 v212, v211, v208
	v_sub_f32_e32 v213, s43, v208
	v_mul_f32_e32 v212, 0x3fb8aa3b, v212
	v_mul_f32_e32 v213, 0x3fb8aa3b, v213
	v_exp_f32_e32 v213, v213
	v_exp_f32_e32 v212, v212
	s_nop 0
	v_mul_f32_e32 v214, v213, v25
	v_mul_f32_e32 v217, v213, v153
	v_fma_f32 v210, v210, v212, v214
	v_fma_f32 v216, v216, v212, v217
	v_cvt_pk_bf16_f32 v215, v210, v195
	v_readlane_b32 s43, v206, 27
	v_readlane_b32 s44, v207, 27
	global_store_short v202, v215, s[8:9]
	s_add_u32 s8, s8, s12
	s_addc_u32 s9, s9, s13
	global_store_dword v205, v216, s[24:25]
	s_add_u32 s24, s24, s28
	s_addc_u32 s25, s25, s29
	s_mov_b64 exec, s[46:47]
	global_store_dword v195, v208, s[26:27]
	s_mov_b64 exec, -1
	s_add_u32 s26, s26, s30
	s_addc_u32 s27, s27, s31
	v_add_f32_e32 v211, s42, v208
	v_max_f32_e32 v209, s41, v211
	v_sub_f32_e32 v212, v211, v209
	v_sub_f32_e32 v213, s41, v209
	v_mul_f32_e32 v212, 0x3fb8aa3b, v212
	v_mul_f32_e32 v213, 0x3fb8aa3b, v213
	v_exp_f32_e32 v213, v213
	v_exp_f32_e32 v212, v212
	s_nop 0
	v_mul_f32_e32 v214, v213, v26
	v_mul_f32_e32 v217, v213, v154
	v_fma_f32 v210, v210, v212, v214
	v_fma_f32 v216, v216, v212, v217
	v_cvt_pk_bf16_f32 v215, v210, v195
	v_readlane_b32 s41, v206, 28
	v_readlane_b32 s42, v207, 28
	global_store_short v202, v215, s[8:9]
	s_add_u32 s8, s8, s12
	s_addc_u32 s9, s9, s13
	global_store_dword v205, v216, s[24:25]
	s_add_u32 s24, s24, s28
	s_addc_u32 s25, s25, s29
	s_mov_b64 exec, s[46:47]
	global_store_dword v195, v209, s[26:27]
	s_mov_b64 exec, -1
	s_add_u32 s26, s26, s30
	s_addc_u32 s27, s27, s31
	v_add_f32_e32 v211, s44, v209
	v_max_f32_e32 v208, s43, v211
	v_sub_f32_e32 v212, v211, v208
	v_sub_f32_e32 v213, s43, v208
	v_mul_f32_e32 v212, 0x3fb8aa3b, v212
	v_mul_f32_e32 v213, 0x3fb8aa3b, v213
	v_exp_f32_e32 v213, v213
	v_exp_f32_e32 v212, v212
	s_nop 0
	v_mul_f32_e32 v214, v213, v27
; __device__ __forceinline__ bf16_t f2bf(float f) { return (bf16_t)(cvt_pk_bf16(f, 0.f) & 0xffffu); }
; __device__ __forceinline__ void scan_phase(const Bufs& B) {
;     ...
;             for (int u = 0; u < 16; ++u) { const int ch = dir ? 63 - (s0 + u) : s0 + u, it = dh * 64 + ch;
;                 B.CST[(size_t)it * 16384 + idx] = f2bf(cst);
;                 if (idx < 128) { B.NST[(size_t)it * 128 + idx] = nst; if (idx == 0) B.MST[it] = m; }
;                 const float mnew = fmaxf(bl[u] + m, ml[u]), a = __expf(bl[u] + m - mnew), g = __expf(ml[u] - mnew);
;                 cst = a * cst + g * cl[u]; nst = a * nst + g * nl[u]; m = mnew; }
	v_mul_f32_e32 v217, v213, v155
	v_fma_f32 v210, v210, v212, v214
	v_fma_f32 v216, v216, v212, v217
	v_cvt_pk_bf16_f32 v215, v210, v195
	v_readlane_b32 s43, v206, 29
	v_readlane_b32 s44, v207, 29
	global_store_short v202, v215, s[8:9]
	s_add_u32 s8, s8, s12
	s_addc_u32 s9, s9, s13
	global_store_dword v205, v216, s[24:25]
	s_add_u32 s24, s24, s28
	s_addc_u32 s25, s25, s29
	s_mov_b64 exec, s[46:47]
	global_store_dword v195, v208, s[26:27]
	s_mov_b64 exec, -1
	s_add_u32 s26, s26, s30
	s_addc_u32 s27, s27, s31
	v_add_f32_e32 v211, s42, v208
	v_max_f32_e32 v209, s41, v211
	v_sub_f32_e32 v212, v211, v209
	v_sub_f32_e32 v213, s41, v209
	v_mul_f32_e32 v212, 0x3fb8aa3b, v212
	v_mul_f32_e32 v213, 0x3fb8aa3b, v213
	v_exp_f32_e32 v213, v213
	v_exp_f32_e32 v212, v212
	s_nop 0
	v_mul_f32_e32 v214, v213, v28
	v_mul_f32_e32 v217, v213, v156
	v_fma_f32 v210, v210, v212, v214
	v_fma_f32 v216, v216, v212, v217
	v_cvt_pk_bf16_f32 v215, v210, v195
	v_readlane_b32 s41, v206, 30
	v_readlane_b32 s42, v207, 30
	global_store_short v202, v215, s[8:9]
	s_add_u32 s8, s8, s12
	s_addc_u32 s9, s9, s13
	global_store_dword v205, v216, s[24:25]
	s_add_u32 s24, s24, s28
	s_addc_u32 s25, s25, s29
	s_mov_b64 exec, s[46:47]
	global_store_dword v195, v209, s[26:27]
	s_mov_b64 exec, -1
	s_add_u32 s26, s26, s30
	s_addc_u32 s27, s27, s31
	v_add_f32_e32 v211, s44, v209
	v_max_f32_e32 v208, s43, v211
	v_sub_f32_e32 v212, v211, v208
	v_sub_f32_e32 v213, s43, v208
	v_mul_f32_e32 v212, 0x3fb8aa3b, v212
	v_mul_f32_e32 v213, 0x3fb8aa3b, v213
	v_exp_f32_e32 v213, v213
	v_exp_f32_e32 v212, v212
	s_nop 0
	v_mul_f32_e32 v214, v213, v29
	v_mul_f32_e32 v217, v213, v157
	v_fma_f32 v210, v210, v212, v214
	v_fma_f32 v216, v216, v212, v217
	v_cvt_pk_bf16_f32 v215, v210, v195
	v_readlane_b32 s43, v206, 31
	v_readlane_b32 s44, v207, 31
	global_store_short v202, v215, s[8:9]
	s_add_u32 s8, s8, s12
	s_addc_u32 s9, s9, s13
	global_store_dword v205, v216, s[24:25]
	s_add_u32 s24, s24, s28
	s_addc_u32 s25, s25, s29
	s_mov_b64 exec, s[46:47]
	global_store_dword v195, v208, s[26:27]
	s_mov_b64 exec, -1
	s_add_u32 s26, s26, s30
	s_addc_u32 s27, s27, s31
	v_add_f32_e32 v211, s42, v208
	v_max_f32_e32 v209, s41, v211
	v_sub_f32_e32 v212, v211, v209
	v_sub_f32_e32 v213, s41, v209
	v_mul_f32_e32 v212, 0x3fb8aa3b, v212
	v_mul_f32_e32 v213, 0x3fb8aa3b, v213
	v_exp_f32_e32 v213, v213
	v_exp_f32_e32 v212, v212
	s_nop 0
	v_mul_f32_e32 v214, v213, v30
	v_mul_f32_e32 v217, v213, v158
	v_fma_f32 v210, v210, v212, v214
	v_fma_f32 v216, v216, v212, v217
	v_cvt_pk_bf16_f32 v215, v210, v195
	v_readlane_b32 s41, v206, 32
	v_readlane_b32 s42, v207, 32
	global_store_short v202, v215, s[8:9]
	s_add_u32 s8, s8, s12
	s_addc_u32 s9, s9, s13
	global_store_dword v205, v216, s[24:25]
	s_add_u32 s24, s24, s28
	s_addc_u32 s25, s25, s29
	s_mov_b64 exec, s[46:47]
	global_store_dword v195, v209, s[26:27]
	s_mov_b64 exec, -1
	s_add_u32 s26, s26, s30
	s_addc_u32 s27, s27, s31
	v_add_f32_e32 v211, s44, v209
	v_max_f32_e32 v208, s43, v211
	v_sub_f32_e32 v212, v211, v208
	v_sub_f32_e32 v213, s43, v208
	v_mul_f32_e32 v212, 0x3fb8aa3b, v212
	v_mul_f32_e32 v213, 0x3fb8aa3b, v213
	v_exp_f32_e32 v213, v213
	v_exp_f32_e32 v212, v212
	s_nop 0
	v_mul_f32_e32 v214, v213, v31
	v_mul_f32_e32 v217, v213, v159
	v_fma_f32 v210, v210, v212, v214
	v_fma_f32 v216, v216, v212, v217
	s_waitcnt vmcnt(63)
	v_cvt_pk_bf16_f32 v215, v210, v195
	v_readlane_b32 s43, v206, 33
	v_readlane_b32 s44, v207, 33
	global_store_short v202, v215, s[8:9]
	s_add_u32 s8, s8, s12
	s_addc_u32 s9, s9, s13
	global_store_dword v205, v216, s[24:25]
	s_add_u32 s24, s24, s28
	s_addc_u32 s25, s25, s29
	s_mov_b64 exec, s[46:47]
	global_store_dword v195, v208, s[26:27]
	s_mov_b64 exec, -1
	s_add_u32 s26, s26, s30
	s_addc_u32 s27, s27, s31
	v_add_f32_e32 v211, s42, v208
	v_max_f32_e32 v209, s41, v211
	v_sub_f32_e32 v212, v211, v209
	v_sub_f32_e32 v213, s41, v209
	v_mul_f32_e32 v212, 0x3fb8aa3b, v212
	v_mul_f32_e32 v213, 0x3fb8aa3b, v213
	v_exp_f32_e32 v213, v213
	v_exp_f32_e32 v212, v212
	s_nop 0
	v_mul_f32_e32 v214, v213, v32
	v_mul_f32_e32 v217, v213, v160
	v_fma_f32 v210, v210, v212, v214
	v_fma_f32 v216, v216, v212, v217
	v_cvt_pk_bf16_f32 v215, v210, v195
	v_readlane_b32 s41, v206, 34
	v_readlane_b32 s42, v207, 34
	global_store_short v202, v215, s[8:9]
	s_add_u32 s8, s8, s12
	s_addc_u32 s9, s9, s13
	global_store_dword v205, v216, s[24:25]
	s_add_u32 s24, s24, s28
	s_addc_u32 s25, s25, s29
	s_mov_b64 exec, s[46:47]
	global_store_dword v195, v209, s[26:27]
	s_mov_b64 exec, -1
	s_add_u32 s26, s26, s30
	s_addc_u32 s27, s27, s31
	v_add_f32_e32 v211, s44, v209
	v_max_f32_e32 v208, s43, v211
	v_sub_f32_e32 v212, v211, v208
	v_sub_f32_e32 v213, s43, v208
	v_mul_f32_e32 v212, 0x3fb8aa3b, v212
	v_mul_f32_e32 v213, 0x3fb8aa3b, v213
	v_exp_f32_e32 v213, v213
	v_exp_f32_e32 v212, v212
	s_nop 0
	v_mul_f32_e32 v214, v213, v33
	v_mul_f32_e32 v217, v213, v161
	v_fma_f32 v210, v210, v212, v214
	v_fma_f32 v216, v216, v212, v217
	v_cvt_pk_bf16_f32 v215, v210, v195
	v_readlane_b32 s43, v206, 35
	v_readlane_b32 s44, v207, 35
	global_store_short v202, v215, s[8:9]
	s_add_u32 s8, s8, s12
	s_addc_u32 s9, s9, s13
	global_store_dword v205, v216, s[24:25]
	s_add_u32 s24, s24, s28
	s_addc_u32 s25, s25, s29
	s_mov_b64 exec, s[46:47]
	global_store_dword v195, v208, s[26:27]
	s_mov_b64 exec, -1
	s_add_u32 s26, s26, s30
	s_addc_u32 s27, s27, s31
	v_add_f32_e32 v211, s42, v208
	v_max_f32_e32 v209, s41, v211
	v_sub_f32_e32 v212, v211, v209
	v_sub_f32_e32 v213, s41, v209
	v_mul_f32_e32 v212, 0x3fb8aa3b, v212
	v_mul_f32_e32 v213, 0x3fb8aa3b, v213
	v_exp_f32_e32 v213, v213
	v_exp_f32_e32 v212, v212
	s_nop 0
; __device__ __forceinline__ bf16_t f2bf(float f) { return (bf16_t)(cvt_pk_bf16(f, 0.f) & 0xffffu); }
; __device__ __forceinline__ void scan_phase(const Bufs& B) {
;     ...
;             for (int u = 0; u < 16; ++u) { const int ch = dir ? 63 - (s0 + u) : s0 + u, it = dh * 64 + ch;
;                 B.CST[(size_t)it * 16384 + idx] = f2bf(cst);
;                 if (idx < 128) { B.NST[(size_t)it * 128 + idx] = nst; if (idx == 0) B.MST[it] = m; }
;                 const float mnew = fmaxf(bl[u] + m, ml[u]), a = __expf(bl[u] + m - mnew), g = __expf(ml[u] - mnew);
;                 cst = a * cst + g * cl[u]; nst = a * nst + g * nl[u]; m = mnew; }
	v_mul_f32_e32 v214, v213, v34
	v_mul_f32_e32 v217, v213, v162
	v_fma_f32 v210, v210, v212, v214
	v_fma_f32 v216, v216, v212, v217
	v_cvt_pk_bf16_f32 v215, v210, v195
	v_readlane_b32 s41, v206, 36
	v_readlane_b32 s42, v207, 36
	global_store_short v202, v215, s[8:9]
	s_add_u32 s8, s8, s12
	s_addc_u32 s9, s9, s13
	global_store_dword v205, v216, s[24:25]
	s_add_u32 s24, s24, s28
	s_addc_u32 s25, s25, s29
	s_mov_b64 exec, s[46:47]
	global_store_dword v195, v209, s[26:27]
	s_mov_b64 exec, -1
	s_add_u32 s26, s26, s30
	s_addc_u32 s27, s27, s31
	v_add_f32_e32 v211, s44, v209
	v_max_f32_e32 v208, s43, v211
	v_sub_f32_e32 v212, v211, v208
	v_sub_f32_e32 v213, s43, v208
	v_mul_f32_e32 v212, 0x3fb8aa3b, v212
	v_mul_f32_e32 v213, 0x3fb8aa3b, v213
	v_exp_f32_e32 v213, v213
	v_exp_f32_e32 v212, v212
	s_nop 0
	v_mul_f32_e32 v214, v213, v35
	v_mul_f32_e32 v217, v213, v163
	v_fma_f32 v210, v210, v212, v214
	v_fma_f32 v216, v216, v212, v217
	v_cvt_pk_bf16_f32 v215, v210, v195
	v_readlane_b32 s43, v206, 37
	v_readlane_b32 s44, v207, 37
	global_store_short v202, v215, s[8:9]
	s_add_u32 s8, s8, s12
	s_addc_u32 s9, s9, s13
	global_store_dword v205, v216, s[24:25]
	s_add_u32 s24, s24, s28
	s_addc_u32 s25, s25, s29
	s_mov_b64 exec, s[46:47]
	global_store_dword v195, v208, s[26:27]
	s_mov_b64 exec, -1
	s_add_u32 s26, s26, s30
	s_addc_u32 s27, s27, s31
	v_add_f32_e32 v211, s42, v208
	v_max_f32_e32 v209, s41, v211
	v_sub_f32_e32 v212, v211, v209
	v_sub_f32_e32 v213, s41, v209
	v_mul_f32_e32 v212, 0x3fb8aa3b, v212
	v_mul_f32_e32 v213, 0x3fb8aa3b, v213
	v_exp_f32_e32 v213, v213
	v_exp_f32_e32 v212, v212
	s_nop 0
	v_mul_f32_e32 v214, v213, v36
	v_mul_f32_e32 v217, v213, v164
	v_fma_f32 v210, v210, v212, v214
	v_fma_f32 v216, v216, v212, v217
	v_cvt_pk_bf16_f32 v215, v210, v195
	v_readlane_b32 s41, v206, 38
	v_readlane_b32 s42, v207, 38
	global_store_short v202, v215, s[8:9]
	s_add_u32 s8, s8, s12
	s_addc_u32 s9, s9, s13
	global_store_dword v205, v216, s[24:25]
	s_add_u32 s24, s24, s28
	s_addc_u32 s25, s25, s29
	s_mov_b64 exec, s[46:47]
	global_store_dword v195, v209, s[26:27]
	s_mov_b64 exec, -1
	s_add_u32 s26, s26, s30
	s_addc_u32 s27, s27, s31
	v_add_f32_e32 v211, s44, v209
	v_max_f32_e32 v208, s43, v211
	v_sub_f32_e32 v212, v211, v208
	v_sub_f32_e32 v213, s43, v208
	v_mul_f32_e32 v212, 0x3fb8aa3b, v212
	v_mul_f32_e32 v213, 0x3fb8aa3b, v213
	v_exp_f32_e32 v213, v213
	v_exp_f32_e32 v212, v212
	s_nop 0
	v_mul_f32_e32 v214, v213, v37
	v_mul_f32_e32 v217, v213, v165
	v_fma_f32 v210, v210, v212, v214
	v_fma_f32 v216, v216, v212, v217
	v_cvt_pk_bf16_f32 v215, v210, v195
	v_readlane_b32 s43, v206, 39
	v_readlane_b32 s44, v207, 39
	global_store_short v202, v215, s[8:9]
	s_add_u32 s8, s8, s12
	s_addc_u32 s9, s9, s13
	global_store_dword v205, v216, s[24:25]
	s_add_u32 s24, s24, s28
	s_addc_u32 s25, s25, s29
	s_mov_b64 exec, s[46:47]
	global_store_dword v195, v208, s[26:27]
	s_mov_b64 exec, -1
	s_add_u32 s26, s26, s30
	s_addc_u32 s27, s27, s31
	v_add_f32_e32 v211, s42, v208
	v_max_f32_e32 v209, s41, v211
	v_sub_f32_e32 v212, v211, v209
	v_sub_f32_e32 v213, s41, v209
	v_mul_f32_e32 v212, 0x3fb8aa3b, v212
	v_mul_f32_e32 v213, 0x3fb8aa3b, v213
	v_exp_f32_e32 v213, v213
	v_exp_f32_e32 v212, v212
	s_nop 0
	v_mul_f32_e32 v214, v213, v38
	v_mul_f32_e32 v217, v213, v166
	v_fma_f32 v210, v210, v212, v214
	v_fma_f32 v216, v216, v212, v217
	v_cvt_pk_bf16_f32 v215, v210, v195
	v_readlane_b32 s41, v206, 40
	v_readlane_b32 s42, v207, 40
	global_store_short v202, v215, s[8:9]
	s_add_u32 s8, s8, s12
	s_addc_u32 s9, s9, s13
	global_store_dword v205, v216, s[24:25]
	s_add_u32 s24, s24, s28
	s_addc_u32 s25, s25, s29
	s_mov_b64 exec, s[46:47]
	global_store_dword v195, v209, s[26:27]
	s_mov_b64 exec, -1
	s_add_u32 s26, s26, s30
	s_addc_u32 s27, s27, s31
	v_add_f32_e32 v211, s44, v209
	v_max_f32_e32 v208, s43, v211
	v_sub_f32_e32 v212, v211, v208
	v_sub_f32_e32 v213, s43, v208
	v_mul_f32_e32 v212, 0x3fb8aa3b, v212
	v_mul_f32_e32 v213, 0x3fb8aa3b, v213
	v_exp_f32_e32 v213, v213
	v_exp_f32_e32 v212, v212
	s_nop 0
	v_mul_f32_e32 v214, v213, v39
	v_mul_f32_e32 v217, v213, v167
	v_fma_f32 v210, v210, v212, v214
	v_fma_f32 v216, v216, v212, v217
	v_cvt_pk_bf16_f32 v215, v210, v195
	v_readlane_b32 s43, v206, 41
	v_readlane_b32 s44, v207, 41
	global_store_short v202, v215, s[8:9]
	s_add_u32 s8, s8, s12
	s_addc_u32 s9, s9, s13
	global_store_dword v205, v216, s[24:25]
	s_add_u32 s24, s24, s28
	s_addc_u32 s25, s25, s29
	s_mov_b64 exec, s[46:47]
	global_store_dword v195, v208, s[26:27]
	s_mov_b64 exec, -1
	s_add_u32 s26, s26, s30
	s_addc_u32 s27, s27, s31
	v_add_f32_e32 v211, s42, v208
	v_max_f32_e32 v209, s41, v211
	v_sub_f32_e32 v212, v211, v209
	v_sub_f32_e32 v213, s41, v209
	v_mul_f32_e32 v212, 0x3fb8aa3b, v212
	v_mul_f32_e32 v213, 0x3fb8aa3b, v213
	v_exp_f32_e32 v213, v213
	v_exp_f32_e32 v212, v212
	s_nop 0
	v_mul_f32_e32 v214, v213, v40
	v_mul_f32_e32 v217, v213, v168
	v_fma_f32 v210, v210, v212, v214
	v_fma_f32 v216, v216, v212, v217
	v_cvt_pk_bf16_f32 v215, v210, v195
	v_readlane_b32 s41, v206, 42
	v_readlane_b32 s42, v207, 42
	global_store_short v202, v215, s[8:9]
	s_add_u32 s8, s8, s12
	s_addc_u32 s9, s9, s13
	global_store_dword v205, v216, s[24:25]
	s_add_u32 s24, s24, s28
	s_addc_u32 s25, s25, s29
	s_mov_b64 exec, s[46:47]
	global_store_dword v195, v209, s[26:27]
	s_mov_b64 exec, -1
	s_add_u32 s26, s26, s30
	s_addc_u32 s27, s27, s31
	v_add_f32_e32 v211, s44, v209
	v_max_f32_e32 v208, s43, v211
	v_sub_f32_e32 v212, v211, v208
	v_sub_f32_e32 v213, s43, v208
	v_mul_f32_e32 v212, 0x3fb8aa3b, v212
	v_mul_f32_e32 v213, 0x3fb8aa3b, v213
	v_exp_f32_e32 v213, v213
	v_exp_f32_e32 v212, v212
	s_nop 0
; __device__ __forceinline__ bf16_t f2bf(float f) { return (bf16_t)(cvt_pk_bf16(f, 0.f) & 0xffffu); }
; __device__ __forceinline__ void scan_phase(const Bufs& B) {
;     ...
;             for (int u = 0; u < 16; ++u) { const int ch = dir ? 63 - (s0 + u) : s0 + u, it = dh * 64 + ch;
;                 B.CST[(size_t)it * 16384 + idx] = f2bf(cst);
;                 if (idx < 128) { B.NST[(size_t)it * 128 + idx] = nst; if (idx == 0) B.MST[it] = m; }
;                 const float mnew = fmaxf(bl[u] + m, ml[u]), a = __expf(bl[u] + m - mnew), g = __expf(ml[u] - mnew);
;                 cst = a * cst + g * cl[u]; nst = a * nst + g * nl[u]; m = mnew; }
	v_mul_f32_e32 v214, v213, v41
	v_mul_f32_e32 v217, v213, v169
	v_fma_f32 v210, v210, v212, v214
	v_fma_f32 v216, v216, v212, v217
	v_cvt_pk_bf16_f32 v215, v210, v195
	v_readlane_b32 s43, v206, 43
	v_readlane_b32 s44, v207, 43
	global_store_short v202, v215, s[8:9]
	s_add_u32 s8, s8, s12
	s_addc_u32 s9, s9, s13
	global_store_dword v205, v216, s[24:25]
	s_add_u32 s24, s24, s28
	s_addc_u32 s25, s25, s29
	s_mov_b64 exec, s[46:47]
	global_store_dword v195, v208, s[26:27]
	s_mov_b64 exec, -1
	s_add_u32 s26, s26, s30
	s_addc_u32 s27, s27, s31
	v_add_f32_e32 v211, s42, v208
	v_max_f32_e32 v209, s41, v211
	v_sub_f32_e32 v212, v211, v209
	v_sub_f32_e32 v213, s41, v209
	v_mul_f32_e32 v212, 0x3fb8aa3b, v212
	v_mul_f32_e32 v213, 0x3fb8aa3b, v213
	v_exp_f32_e32 v213, v213
	v_exp_f32_e32 v212, v212
	s_nop 0
	v_mul_f32_e32 v214, v213, v42
	v_mul_f32_e32 v217, v213, v170
	v_fma_f32 v210, v210, v212, v214
	v_fma_f32 v216, v216, v212, v217
	v_cvt_pk_bf16_f32 v215, v210, v195
	v_readlane_b32 s41, v206, 44
	v_readlane_b32 s42, v207, 44
	global_store_short v202, v215, s[8:9]
	s_add_u32 s8, s8, s12
	s_addc_u32 s9, s9, s13
	global_store_dword v205, v216, s[24:25]
	s_add_u32 s24, s24, s28
	s_addc_u32 s25, s25, s29
	s_mov_b64 exec, s[46:47]
	global_store_dword v195, v209, s[26:27]
	s_mov_b64 exec, -1
	s_add_u32 s26, s26, s30
	s_addc_u32 s27, s27, s31
	v_add_f32_e32 v211, s44, v209
	v_max_f32_e32 v208, s43, v211
	v_sub_f32_e32 v212, v211, v208
	v_sub_f32_e32 v213, s43, v208
	v_mul_f32_e32 v212, 0x3fb8aa3b, v212
	v_mul_f32_e32 v213, 0x3fb8aa3b, v213
	v_exp_f32_e32 v213, v213
	v_exp_f32_e32 v212, v212
	s_nop 0
	v_mul_f32_e32 v214, v213, v43
	v_mul_f32_e32 v217, v213, v171
	v_fma_f32 v210, v210, v212, v214
	v_fma_f32 v216, v216, v212, v217
	v_cvt_pk_bf16_f32 v215, v210, v195
	v_readlane_b32 s43, v206, 45
	v_readlane_b32 s44, v207, 45
	global_store_short v202, v215, s[8:9]
	s_add_u32 s8, s8, s12
	s_addc_u32 s9, s9, s13
	global_store_dword v205, v216, s[24:25]
	s_add_u32 s24, s24, s28
	s_addc_u32 s25, s25, s29
	s_mov_b64 exec, s[46:47]
	global_store_dword v195, v208, s[26:27]
	s_mov_b64 exec, -1
	s_add_u32 s26, s26, s30
	s_addc_u32 s27, s27, s31
	v_add_f32_e32 v211, s42, v208
	v_max_f32_e32 v209, s41, v211
	v_sub_f32_e32 v212, v211, v209
	v_sub_f32_e32 v213, s41, v209
	v_mul_f32_e32 v212, 0x3fb8aa3b, v212
	v_mul_f32_e32 v213, 0x3fb8aa3b, v213
	v_exp_f32_e32 v213, v213
	v_exp_f32_e32 v212, v212
	s_nop 0
	v_mul_f32_e32 v214, v213, v44
	v_mul_f32_e32 v217, v213, v172
	v_fma_f32 v210, v210, v212, v214
	v_fma_f32 v216, v216, v212, v217
	v_cvt_pk_bf16_f32 v215, v210, v195
	v_readlane_b32 s41, v206, 46
	v_readlane_b32 s42, v207, 46
	global_store_short v202, v215, s[8:9]
	s_add_u32 s8, s8, s12
	s_addc_u32 s9, s9, s13
	global_store_dword v205, v216, s[24:25]
	s_add_u32 s24, s24, s28
	s_addc_u32 s25, s25, s29
	s_mov_b64 exec, s[46:47]
	global_store_dword v195, v209, s[26:27]
	s_mov_b64 exec, -1
	s_add_u32 s26, s26, s30
	s_addc_u32 s27, s27, s31
	v_add_f32_e32 v211, s44, v209
	v_max_f32_e32 v208, s43, v211
	v_sub_f32_e32 v212, v211, v208
	v_sub_f32_e32 v213, s43, v208
	v_mul_f32_e32 v212, 0x3fb8aa3b, v212
	v_mul_f32_e32 v213, 0x3fb8aa3b, v213
	v_exp_f32_e32 v213, v213
	v_exp_f32_e32 v212, v212
	s_nop 0
	v_mul_f32_e32 v214, v213, v45
	v_mul_f32_e32 v217, v213, v173
	v_fma_f32 v210, v210, v212, v214
	v_fma_f32 v216, v216, v212, v217
	v_cvt_pk_bf16_f32 v215, v210, v195
	v_readlane_b32 s43, v206, 47
	v_readlane_b32 s44, v207, 47
	global_store_short v202, v215, s[8:9]
	s_add_u32 s8, s8, s12
	s_addc_u32 s9, s9, s13
	global_store_dword v205, v216, s[24:25]
	s_add_u32 s24, s24, s28
	s_addc_u32 s25, s25, s29
	s_mov_b64 exec, s[46:47]
	global_store_dword v195, v208, s[26:27]
	s_mov_b64 exec, -1
	s_add_u32 s26, s26, s30
	s_addc_u32 s27, s27, s31
	v_add_f32_e32 v211, s42, v208
	v_max_f32_e32 v209, s41, v211
	v_sub_f32_e32 v212, v211, v209
	v_sub_f32_e32 v213, s41, v209
	v_mul_f32_e32 v212, 0x3fb8aa3b, v212
	v_mul_f32_e32 v213, 0x3fb8aa3b, v213
	v_exp_f32_e32 v213, v213
	v_exp_f32_e32 v212, v212
	s_nop 0
	v_mul_f32_e32 v214, v213, v46
	v_mul_f32_e32 v217, v213, v174
	v_fma_f32 v210, v210, v212, v214
	v_fma_f32 v216, v216, v212, v217
	v_cvt_pk_bf16_f32 v215, v210, v195
	v_readlane_b32 s41, v206, 48
	v_readlane_b32 s42, v207, 48
	global_store_short v202, v215, s[8:9]
	s_add_u32 s8, s8, s12
	s_addc_u32 s9, s9, s13
	global_store_dword v205, v216, s[24:25]
	s_add_u32 s24, s24, s28
	s_addc_u32 s25, s25, s29
	s_mov_b64 exec, s[46:47]
	global_store_dword v195, v209, s[26:27]
	s_mov_b64 exec, -1
	s_add_u32 s26, s26, s30
	s_addc_u32 s27, s27, s31
	v_add_f32_e32 v211, s44, v209
	v_max_f32_e32 v208, s43, v211
	v_sub_f32_e32 v212, v211, v208
	v_sub_f32_e32 v213, s43, v208
	v_mul_f32_e32 v212, 0x3fb8aa3b, v212
	v_mul_f32_e32 v213, 0x3fb8aa3b, v213
	v_exp_f32_e32 v213, v213
	v_exp_f32_e32 v212, v212
	s_nop 0
	v_mul_f32_e32 v214, v213, v47
	v_mul_f32_e32 v217, v213, v175
	v_fma_f32 v210, v210, v212, v214
	v_fma_f32 v216, v216, v212, v217
	s_waitcnt vmcnt(63)
; __device__ __forceinline__ bf16_t f2bf(float f) { return (bf16_t)(cvt_pk_bf16(f, 0.f) & 0xffffu); }
; __device__ __forceinline__ void scan_phase(const Bufs& B) {
;     ...
;             for (int u = 0; u < 16; ++u) { const int ch = dir ? 63 - (s0 + u) : s0 + u, it = dh * 64 + ch;
;                 B.CST[(size_t)it * 16384 + idx] = f2bf(cst);
;                 if (idx < 128) { B.NST[(size_t)it * 128 + idx] = nst; if (idx == 0) B.MST[it] = m; }
;                 const float mnew = fmaxf(bl[u] + m, ml[u]), a = __expf(bl[u] + m - mnew), g = __expf(ml[u] - mnew);
;                 cst = a * cst + g * cl[u]; nst = a * nst + g * nl[u]; m = mnew; }
	v_cvt_pk_bf16_f32 v215, v210, v195
	v_readlane_b32 s43, v206, 49
	v_readlane_b32 s44, v207, 49
	global_store_short v202, v215, s[8:9]
	s_add_u32 s8, s8, s12
	s_addc_u32 s9, s9, s13
	global_store_dword v205, v216, s[24:25]
	s_add_u32 s24, s24, s28
	s_addc_u32 s25, s25, s29
	s_mov_b64 exec, s[46:47]
	global_store_dword v195, v208, s[26:27]
	s_mov_b64 exec, -1
	s_add_u32 s26, s26, s30
	s_addc_u32 s27, s27, s31
	v_add_f32_e32 v211, s42, v208
	v_max_f32_e32 v209, s41, v211
	v_sub_f32_e32 v212, v211, v209
	v_sub_f32_e32 v213, s41, v209
	v_mul_f32_e32 v212, 0x3fb8aa3b, v212
	v_mul_f32_e32 v213, 0x3fb8aa3b, v213
	v_exp_f32_e32 v213, v213
	v_exp_f32_e32 v212, v212
	s_nop 0
	v_mul_f32_e32 v214, v213, v48
	v_mul_f32_e32 v217, v213, v176
	v_fma_f32 v210, v210, v212, v214
	v_fma_f32 v216, v216, v212, v217
	v_cvt_pk_bf16_f32 v215, v210, v195
	v_readlane_b32 s41, v206, 50
	v_readlane_b32 s42, v207, 50
	global_store_short v202, v215, s[8:9]
	s_add_u32 s8, s8, s12
	s_addc_u32 s9, s9, s13
	global_store_dword v205, v216, s[24:25]
	s_add_u32 s24, s24, s28
	s_addc_u32 s25, s25, s29
	s_mov_b64 exec, s[46:47]
	global_store_dword v195, v209, s[26:27]
	s_mov_b64 exec, -1
	s_add_u32 s26, s26, s30
	s_addc_u32 s27, s27, s31
	v_add_f32_e32 v211, s44, v209
	v_max_f32_e32 v208, s43, v211
	v_sub_f32_e32 v212, v211, v208
	v_sub_f32_e32 v213, s43, v208
	v_mul_f32_e32 v212, 0x3fb8aa3b, v212
	v_mul_f32_e32 v213, 0x3fb8aa3b, v213
	v_exp_f32_e32 v213, v213
	v_exp_f32_e32 v212, v212
	s_nop 0
	v_mul_f32_e32 v214, v213, v49
	v_mul_f32_e32 v217, v213, v177
	v_fma_f32 v210, v210, v212, v214
	v_fma_f32 v216, v216, v212, v217
	v_cvt_pk_bf16_f32 v215, v210, v195
	v_readlane_b32 s43, v206, 51
	v_readlane_b32 s44, v207, 51
	global_store_short v202, v215, s[8:9]
	s_add_u32 s8, s8, s12
	s_addc_u32 s9, s9, s13
	global_store_dword v205, v216, s[24:25]
	s_add_u32 s24, s24, s28
	s_addc_u32 s25, s25, s29
	s_mov_b64 exec, s[46:47]
	global_store_dword v195, v208, s[26:27]
	s_mov_b64 exec, -1
	s_add_u32 s26, s26, s30
	s_addc_u32 s27, s27, s31
	v_add_f32_e32 v211, s42, v208
	v_max_f32_e32 v209, s41, v211
	v_sub_f32_e32 v212, v211, v209
	v_sub_f32_e32 v213, s41, v209
	v_mul_f32_e32 v212, 0x3fb8aa3b, v212
	v_mul_f32_e32 v213, 0x3fb8aa3b, v213
	v_exp_f32_e32 v213, v213
	v_exp_f32_e32 v212, v212
	s_nop 0
	v_mul_f32_e32 v214, v213, v50
	v_mul_f32_e32 v217, v213, v178
	v_fma_f32 v210, v210, v212, v214
	v_fma_f32 v216, v216, v212, v217
	v_cvt_pk_bf16_f32 v215, v210, v195
	v_readlane_b32 s41, v206, 52
	v_readlane_b32 s42, v207, 52
	global_store_short v202, v215, s[8:9]
	s_add_u32 s8, s8, s12
	s_addc_u32 s9, s9, s13
	global_store_dword v205, v216, s[24:25]
	s_add_u32 s24, s24, s28
	s_addc_u32 s25, s25, s29
	s_mov_b64 exec, s[46:47]
	global_store_dword v195, v209, s[26:27]
	s_mov_b64 exec, -1
	s_add_u32 s26, s26, s30
	s_addc_u32 s27, s27, s31
	v_add_f32_e32 v211, s44, v209
	v_max_f32_e32 v208, s43, v211
	v_sub_f32_e32 v212, v211, v208
	v_sub_f32_e32 v213, s43, v208
	v_mul_f32_e32 v212, 0x3fb8aa3b, v212
	v_mul_f32_e32 v213, 0x3fb8aa3b, v213
	v_exp_f32_e32 v213, v213
	v_exp_f32_e32 v212, v212
	s_nop 0
	v_mul_f32_e32 v214, v213, v51
	v_mul_f32_e32 v217, v213, v179
	v_fma_f32 v210, v210, v212, v214
	v_fma_f32 v216, v216, v212, v217
	v_cvt_pk_bf16_f32 v215, v210, v195
	v_readlane_b32 s43, v206, 53
	v_readlane_b32 s44, v207, 53
	global_store_short v202, v215, s[8:9]
	s_add_u32 s8, s8, s12
	s_addc_u32 s9, s9, s13
	global_store_dword v205, v216, s[24:25]
	s_add_u32 s24, s24, s28
	s_addc_u32 s25, s25, s29
	s_mov_b64 exec, s[46:47]
	global_store_dword v195, v208, s[26:27]
	s_mov_b64 exec, -1
	s_add_u32 s26, s26, s30
	s_addc_u32 s27, s27, s31
	v_add_f32_e32 v211, s42, v208
	v_max_f32_e32 v209, s41, v211
	v_sub_f32_e32 v212, v211, v209
	v_sub_f32_e32 v213, s41, v209
	v_mul_f32_e32 v212, 0x3fb8aa3b, v212
	v_mul_f32_e32 v213, 0x3fb8aa3b, v213
	v_exp_f32_e32 v213, v213
	v_exp_f32_e32 v212, v212
	s_nop 0
	v_mul_f32_e32 v214, v213, v52
	v_mul_f32_e32 v217, v213, v180
	v_fma_f32 v210, v210, v212, v214
	v_fma_f32 v216, v216, v212, v217
	v_cvt_pk_bf16_f32 v215, v210, v195
	v_readlane_b32 s41, v206, 54
	v_readlane_b32 s42, v207, 54
	global_store_short v202, v215, s[8:9]
	s_add_u32 s8, s8, s12
	s_addc_u32 s9, s9, s13
	global_store_dword v205, v216, s[24:25]
	s_add_u32 s24, s24, s28
	s_addc_u32 s25, s25, s29
	s_mov_b64 exec, s[46:47]
	global_store_dword v195, v209, s[26:27]
	s_mov_b64 exec, -1
	s_add_u32 s26, s26, s30
	s_addc_u32 s27, s27, s31
	v_add_f32_e32 v211, s44, v209
	v_max_f32_e32 v208, s43, v211
	v_sub_f32_e32 v212, v211, v208
	v_sub_f32_e32 v213, s43, v208
	v_mul_f32_e32 v212, 0x3fb8aa3b, v212
	v_mul_f32_e32 v213, 0x3fb8aa3b, v213
	v_exp_f32_e32 v213, v213
	v_exp_f32_e32 v212, v212
	s_nop 0
	v_mul_f32_e32 v214, v213, v53
	v_mul_f32_e32 v217, v213, v181
	v_fma_f32 v210, v210, v212, v214
	v_fma_f32 v216, v216, v212, v217
	v_cvt_pk_bf16_f32 v215, v210, v195
	v_readlane_b32 s43, v206, 55
	v_readlane_b32 s44, v207, 55
	global_store_short v202, v215, s[8:9]
	s_add_u32 s8, s8, s12
	s_addc_u32 s9, s9, s13
	global_store_dword v205, v216, s[24:25]
	s_add_u32 s24, s24, s28
	s_addc_u32 s25, s25, s29
	s_mov_b64 exec, s[46:47]
	global_store_dword v195, v208, s[26:27]
	s_mov_b64 exec, -1
	s_add_u32 s26, s26, s30
	s_addc_u32 s27, s27, s31
	v_add_f32_e32 v211, s42, v208
	v_max_f32_e32 v209, s41, v211
	v_sub_f32_e32 v212, v211, v209
	v_sub_f32_e32 v213, s41, v209
	v_mul_f32_e32 v212, 0x3fb8aa3b, v212
	v_mul_f32_e32 v213, 0x3fb8aa3b, v213
	v_exp_f32_e32 v213, v213
	v_exp_f32_e32 v212, v212
	s_nop 0
	v_mul_f32_e32 v214, v213, v54
	v_mul_f32_e32 v217, v213, v182
	v_fma_f32 v210, v210, v212, v214
	v_fma_f32 v216, v216, v212, v217
; __device__ __forceinline__ bf16_t f2bf(float f) { return (bf16_t)(cvt_pk_bf16(f, 0.f) & 0xffffu); }
; __device__ __forceinline__ void scan_phase(const Bufs& B) {
;     ...
;             for (int u = 0; u < 16; ++u) { const int ch = dir ? 63 - (s0 + u) : s0 + u, it = dh * 64 + ch;
;                 B.CST[(size_t)it * 16384 + idx] = f2bf(cst);
;                 if (idx < 128) { B.NST[(size_t)it * 128 + idx] = nst; if (idx == 0) B.MST[it] = m; }
;                 const float mnew = fmaxf(bl[u] + m, ml[u]), a = __expf(bl[u] + m - mnew), g = __expf(ml[u] - mnew);
;                 cst = a * cst + g * cl[u]; nst = a * nst + g * nl[u]; m = mnew; }
	v_cvt_pk_bf16_f32 v215, v210, v195
	v_readlane_b32 s41, v206, 56
	v_readlane_b32 s42, v207, 56
	global_store_short v202, v215, s[8:9]
	s_add_u32 s8, s8, s12
	s_addc_u32 s9, s9, s13
	global_store_dword v205, v216, s[24:25]
	s_add_u32 s24, s24, s28
	s_addc_u32 s25, s25, s29
	s_mov_b64 exec, s[46:47]
	global_store_dword v195, v209, s[26:27]
	s_mov_b64 exec, -1
	s_add_u32 s26, s26, s30
	s_addc_u32 s27, s27, s31
	v_add_f32_e32 v211, s44, v209
	v_max_f32_e32 v208, s43, v211
	v_sub_f32_e32 v212, v211, v208
	v_sub_f32_e32 v213, s43, v208
	v_mul_f32_e32 v212, 0x3fb8aa3b, v212
	v_mul_f32_e32 v213, 0x3fb8aa3b, v213
	v_exp_f32_e32 v213, v213
	v_exp_f32_e32 v212, v212
	s_nop 0
	v_mul_f32_e32 v214, v213, v55
	v_mul_f32_e32 v217, v213, v183
	v_fma_f32 v210, v210, v212, v214
	v_fma_f32 v216, v216, v212, v217
	v_cvt_pk_bf16_f32 v215, v210, v195
	v_readlane_b32 s43, v206, 57
	v_readlane_b32 s44, v207, 57
	global_store_short v202, v215, s[8:9]
	s_add_u32 s8, s8, s12
	s_addc_u32 s9, s9, s13
	global_store_dword v205, v216, s[24:25]
	s_add_u32 s24, s24, s28
	s_addc_u32 s25, s25, s29
	s_mov_b64 exec, s[46:47]
	global_store_dword v195, v208, s[26:27]
	s_mov_b64 exec, -1
	s_add_u32 s26, s26, s30
	s_addc_u32 s27, s27, s31
	v_add_f32_e32 v211, s42, v208
	v_max_f32_e32 v209, s41, v211
	v_sub_f32_e32 v212, v211, v209
	v_sub_f32_e32 v213, s41, v209
	v_mul_f32_e32 v212, 0x3fb8aa3b, v212
	v_mul_f32_e32 v213, 0x3fb8aa3b, v213
	v_exp_f32_e32 v213, v213
	v_exp_f32_e32 v212, v212
	s_nop 0
	v_mul_f32_e32 v214, v213, v56
	v_mul_f32_e32 v217, v213, v184
	v_fma_f32 v210, v210, v212, v214
	v_fma_f32 v216, v216, v212, v217
	v_cvt_pk_bf16_f32 v215, v210, v195
	v_readlane_b32 s41, v206, 58
	v_readlane_b32 s42, v207, 58
	global_store_short v202, v215, s[8:9]
	s_add_u32 s8, s8, s12
	s_addc_u32 s9, s9, s13
	global_store_dword v205, v216, s[24:25]
	s_add_u32 s24, s24, s28
	s_addc_u32 s25, s25, s29
	s_mov_b64 exec, s[46:47]
	global_store_dword v195, v209, s[26:27]
	s_mov_b64 exec, -1
	s_add_u32 s26, s26, s30
	s_addc_u32 s27, s27, s31
	v_add_f32_e32 v211, s44, v209
	v_max_f32_e32 v208, s43, v211
	v_sub_f32_e32 v212, v211, v208
	v_sub_f32_e32 v213, s43, v208
	v_mul_f32_e32 v212, 0x3fb8aa3b, v212
	v_mul_f32_e32 v213, 0x3fb8aa3b, v213
	v_exp_f32_e32 v213, v213
	v_exp_f32_e32 v212, v212
	s_nop 0
	v_mul_f32_e32 v214, v213, v57
	v_mul_f32_e32 v217, v213, v185
	v_fma_f32 v210, v210, v212, v214
	v_fma_f32 v216, v216, v212, v217
	v_cvt_pk_bf16_f32 v215, v210, v195
	v_readlane_b32 s43, v206, 59
	v_readlane_b32 s44, v207, 59
	global_store_short v202, v215, s[8:9]
	s_add_u32 s8, s8, s12
	s_addc_u32 s9, s9, s13
	global_store_dword v205, v216, s[24:25]
	s_add_u32 s24, s24, s28
	s_addc_u32 s25, s25, s29
	s_mov_b64 exec, s[46:47]
	global_store_dword v195, v208, s[26:27]
	s_mov_b64 exec, -1
	s_add_u32 s26, s26, s30
	s_addc_u32 s27, s27, s31
	v_add_f32_e32 v211, s42, v208
	v_max_f32_e32 v209, s41, v211
	v_sub_f32_e32 v212, v211, v209
	v_sub_f32_e32 v213, s41, v209
	v_mul_f32_e32 v212, 0x3fb8aa3b, v212
	v_mul_f32_e32 v213, 0x3fb8aa3b, v213
	v_exp_f32_e32 v213, v213
	v_exp_f32_e32 v212, v212
	s_nop 0
	v_mul_f32_e32 v214, v213, v58
	v_mul_f32_e32 v217, v213, v186
	v_fma_f32 v210, v210, v212, v214
	v_fma_f32 v216, v216, v212, v217
	v_cvt_pk_bf16_f32 v215, v210, v195
	v_readlane_b32 s41, v206, 60
	v_readlane_b32 s42, v207, 60
	global_store_short v202, v215, s[8:9]
	s_add_u32 s8, s8, s12
	s_addc_u32 s9, s9, s13
	global_store_dword v205, v216, s[24:25]
	s_add_u32 s24, s24, s28
	s_addc_u32 s25, s25, s29
	s_mov_b64 exec, s[46:47]
	global_store_dword v195, v209, s[26:27]
	s_mov_b64 exec, -1
	s_add_u32 s26, s26, s30
	s_addc_u32 s27, s27, s31
; __device__ __forceinline__ bf16_t f2bf(float f) { return (bf16_t)(cvt_pk_bf16(f, 0.f) & 0xffffu); }
; __device__ __forceinline__ void scan_phase(const Bufs& B) {
;     ...
;             for (int u = 0; u < 16; ++u) { const int ch = dir ? 63 - (s0 + u) : s0 + u, it = dh * 64 + ch;
;                 B.CST[(size_t)it * 16384 + idx] = f2bf(cst);
;                 if (idx < 128) { B.NST[(size_t)it * 128 + idx] = nst; if (idx == 0) B.MST[it] = m; }
;                 const float mnew = fmaxf(bl[u] + m, ml[u]), a = __expf(bl[u] + m - mnew), g = __expf(ml[u] - mnew);
;                 cst = a * cst + g * cl[u]; nst = a * nst + g * nl[u]; m = mnew; }
	v_add_f32_e32 v211, s44, v209
	v_max_f32_e32 v208, s43, v211
	v_sub_f32_e32 v212, v211, v208
	v_sub_f32_e32 v213, s43, v208
	v_mul_f32_e32 v212, 0x3fb8aa3b, v212
	v_mul_f32_e32 v213, 0x3fb8aa3b, v213
	v_exp_f32_e32 v213, v213
	v_exp_f32_e32 v212, v212
	s_nop 0
	v_mul_f32_e32 v214, v213, v59
	v_mul_f32_e32 v217, v213, v187
	v_fma_f32 v210, v210, v212, v214
	v_fma_f32 v216, v216, v212, v217
	v_cvt_pk_bf16_f32 v215, v210, v195
	v_readlane_b32 s43, v206, 61
	v_readlane_b32 s44, v207, 61
	global_store_short v202, v215, s[8:9]
	s_add_u32 s8, s8, s12
	s_addc_u32 s9, s9, s13
	global_store_dword v205, v216, s[24:25]
	s_add_u32 s24, s24, s28
	s_addc_u32 s25, s25, s29
	s_mov_b64 exec, s[46:47]
	global_store_dword v195, v208, s[26:27]
	s_mov_b64 exec, -1
	s_add_u32 s26, s26, s30
	s_addc_u32 s27, s27, s31
	v_add_f32_e32 v211, s42, v208
	v_max_f32_e32 v209, s41, v211
	v_sub_f32_e32 v212, v211, v209
	v_sub_f32_e32 v213, s41, v209
	v_mul_f32_e32 v212, 0x3fb8aa3b, v212
	v_mul_f32_e32 v213, 0x3fb8aa3b, v213
	v_exp_f32_e32 v213, v213
	v_exp_f32_e32 v212, v212
	s_nop 0
	v_mul_f32_e32 v214, v213, v60
	v_mul_f32_e32 v217, v213, v188
	v_fma_f32 v210, v210, v212, v214
	v_fma_f32 v216, v216, v212, v217
	v_cvt_pk_bf16_f32 v215, v210, v195
	v_readlane_b32 s41, v206, 62
	v_readlane_b32 s42, v207, 62
	global_store_short v202, v215, s[8:9]
	s_add_u32 s8, s8, s12
	s_addc_u32 s9, s9, s13
	global_store_dword v205, v216, s[24:25]
	s_add_u32 s24, s24, s28
	s_addc_u32 s25, s25, s29
	s_mov_b64 exec, s[46:47]
	global_store_dword v195, v209, s[26:27]
	s_mov_b64 exec, -1
	s_add_u32 s26, s26, s30
	s_addc_u32 s27, s27, s31
	v_add_f32_e32 v211, s44, v209
	v_max_f32_e32 v208, s43, v211
	v_sub_f32_e32 v212, v211, v208
	v_sub_f32_e32 v213, s43, v208
	v_mul_f32_e32 v212, 0x3fb8aa3b, v212
	v_mul_f32_e32 v213, 0x3fb8aa3b, v213
	v_exp_f32_e32 v213, v213
	v_exp_f32_e32 v212, v212
	s_nop 0
	v_mul_f32_e32 v214, v213, v61
	v_mul_f32_e32 v217, v213, v189
	v_fma_f32 v210, v210, v212, v214
	v_fma_f32 v216, v216, v212, v217
	v_cvt_pk_bf16_f32 v215, v210, v195
	v_readlane_b32 s43, v206, 63
	v_readlane_b32 s44, v207, 63
	global_store_short v202, v215, s[8:9]
	s_add_u32 s8, s8, s12
	s_addc_u32 s9, s9, s13
	global_store_dword v205, v216, s[24:25]
	s_add_u32 s24, s24, s28
	s_addc_u32 s25, s25, s29
	s_mov_b64 exec, s[46:47]
	global_store_dword v195, v208, s[26:27]
	s_mov_b64 exec, -1
	s_add_u32 s26, s26, s30
	s_addc_u32 s27, s27, s31
	v_add_f32_e32 v211, s42, v208
	v_max_f32_e32 v209, s41, v211
	v_sub_f32_e32 v212, v211, v209
	v_sub_f32_e32 v213, s41, v209
	v_mul_f32_e32 v212, 0x3fb8aa3b, v212
	v_mul_f32_e32 v213, 0x3fb8aa3b, v213
	v_exp_f32_e32 v213, v213
	v_exp_f32_e32 v212, v212
	s_nop 0
	v_mul_f32_e32 v214, v213, v62
	v_mul_f32_e32 v217, v213, v190
	v_fma_f32 v210, v210, v212, v214
	v_fma_f32 v216, v216, v212, v217
	v_cvt_pk_bf16_f32 v215, v210, v195
	global_store_short v202, v215, s[8:9]
	s_add_u32 s8, s8, s12
	s_addc_u32 s9, s9, s13
	global_store_dword v205, v216, s[24:25]
	s_add_u32 s24, s24, s28
	s_addc_u32 s25, s25, s29
	s_mov_b64 exec, s[46:47]
	global_store_dword v195, v209, s[26:27]
	s_mov_b64 exec, -1
	s_add_u32 s26, s26, s30
	s_addc_u32 s27, s27, s31
	v_add_f32_e32 v211, s44, v209
	v_max_f32_e32 v208, s43, v211
	v_sub_f32_e32 v212, v211, v208
	v_sub_f32_e32 v213, s43, v208
	v_mul_f32_e32 v212, 0x3fb8aa3b, v212
	v_mul_f32_e32 v213, 0x3fb8aa3b, v213
	v_exp_f32_e32 v213, v213
	v_exp_f32_e32 v212, v212
	s_nop 0
	v_mul_f32_e32 v214, v213, v63
	v_mul_f32_e32 v217, v213, v191
	v_fma_f32 v210, v210, v212, v214
	v_fma_f32 v216, v216, v212, v217
	s_branch .Lscan_done
.Lscan_done:
	s_mov_b64 exec, -1
